# baseline (speedup 1.0000x reference)
; #define STAGE(P, GP, ktrel) do { const GAS char* _g = (GP) + (ktrel) * (BK * 2); \
;     __builtin_amdgcn_global_load_lds((const GAS unsigned*)(_g + so0), (unsigned*)((char*)(P) + tid_ * 16), 16, 0, 0); \
;     __builtin_amdgcn_global_load_lds((const GAS unsigned*)(_g + so1), (unsigned*)((char*)(P) + tid_ * 16 + 8192), 16, 0, 0); } while (0)
; #define WAIT_V(n) asm volatile("s_waitcnt vmcnt(" #n ")" ::: "memory")
; #define WAIT_L(n) asm volatile("s_waitcnt lgkmcnt(" #n ")" ::: "memory")
; #define BAR __builtin_amdgcn_s_barrier()
; #define SCHED __builtin_amdgcn_sched_barrier(0)
; #define LDA(dst, b, h) for (int m = 0; m < 4; ++m) for (int k = 0; k < 2; ++k) \
;     dst[m][k] = *reinterpret_cast<const bf16x8*>((char*)SA(b, h) + lds_byte(wr * 64 + m * 16 + fr, k * 32 + fq * 8))
; #define LDB(dst, b, h) for (int n = 0; n < 2; ++n) for (int k = 0; k < 2; ++k) \
;     dst[n][k] = *reinterpret_cast<const bf16x8*>((char*)SB(b, h) + lds_byte(wc * 32 + n * 16 + fr, k * 32 + fq * 8))
; #define MMA(ai, bj, At_, Bt_) do { __builtin_amdgcn_s_setprio(1); \
;     for (int m = 0; m < 4; ++m) for (int n = 0; n < 2; ++n) for (int k = 0; k < 2; ++k) \
;       acc[ai][bj][m][n] = __builtin_amdgcn_mfma_f32_16x16x32_bf16(At_[m][k], Bt_[n][k], acc[ai][bj][m][n], 0, 0, 0); \
;     __builtin_amdgcn_s_setprio(0); } while (0)
; template <int K, int LD = K>
; __device__ __forceinline__ void gemm_main(const GAS bf16* A, const GAS bf16* Bt, int brow, int bcol, f32x4 (&acc)[2][2][4][2]) {
;     ...
;   for (int t = 0; t < nt - 2; t += 2) {
;     LDB(B0, 0, 0); SCHED; LDA(At, 0, 0); STAGE(SA(1, 1), pA1, 1);
;     WAIT_L(8); BAR; WAIT_L(0); MMA(0, 0, At, B0); BAR; SCHED;
;     LDB(B1, 0, 1); STAGE(SB(0, 0), pB0, 2);
;     BAR; WAIT_L(0); MMA(0, 1, At, B1); BAR;
;     LDA(At, 0, 1); STAGE(SA(0, 0), pA0, 2);
;     BAR; WAIT_L(0); MMA(1, 0, At, B0); BAR; SCHED;
;     STAGE(SB(0, 1), pB1, 2);
;     WAIT_V(6); BAR; MMA(1, 1, At, B1); BAR;
.LBB0_89:
	ds_read_b128 v[162:165], v144
	ds_read_b128 v[166:169], v144 offset:1024
	ds_read_b128 v[174:177], v144 offset:2048
	ds_read_b128 v[178:181], v144 offset:3072
	v_lshl_add_u64 v[230:231], s[14:15], 0, v[130:131]
	v_readfirstlane_b32 s24, v151
	v_lshl_add_u64 v[214:215], v[230:231], 0, s[8:9]
	s_mov_b32 m0, s24
	v_lshl_add_u64 v[232:233], s[14:15], 0, v[132:133]
	v_readfirstlane_b32 s24, v150
	ds_read_b128 v[182:185], v140
	ds_read_b128 v[186:189], v140 offset:1024
	ds_read_b128 v[190:193], v139
	ds_read_b128 v[194:197], v139 offset:1024
	ds_read_b128 v[198:201], v138
	ds_read_b128 v[202:205], v138 offset:1024
	ds_read_b128 v[206:209], v137
	ds_read_b128 v[210:213], v137 offset:1024
	global_load_lds_dwordx4 v[214:215], off
	v_lshl_add_u64 v[214:215], v[232:233], 0, s[8:9]
	s_mov_b32 m0, s24
	s_nop 0
	global_load_lds_dwordx4 v[214:215], off
	s_waitcnt lgkmcnt(8)
	s_waitcnt vmcnt(10)
	s_barrier
	s_waitcnt lgkmcnt(0)
	v_mfma_f32_16x16x32_bf16 v[126:129], v[182:185], v[162:165], v[126:129]
	v_mfma_f32_16x16x32_bf16 v[122:125], v[182:185], v[174:177], v[122:125]
	v_mfma_f32_16x16x32_bf16 v[118:121], v[190:193], v[162:165], v[118:121]
	v_mfma_f32_16x16x32_bf16 v[114:117], v[190:193], v[174:177], v[114:117]
	v_mfma_f32_16x16x32_bf16 v[110:113], v[198:201], v[162:165], v[110:113]
	v_mfma_f32_16x16x32_bf16 v[106:109], v[198:201], v[174:177], v[106:109]
	v_mfma_f32_16x16x32_bf16 v[102:105], v[206:209], v[162:165], v[102:105]
	v_mfma_f32_16x16x32_bf16 v[98:101], v[206:209], v[174:177], v[98:101]
	v_mfma_f32_16x16x32_bf16 v[126:129], v[186:189], v[166:169], v[126:129]
	v_mfma_f32_16x16x32_bf16 v[122:125], v[186:189], v[178:181], v[122:125]
	v_mfma_f32_16x16x32_bf16 v[118:121], v[194:197], v[166:169], v[118:121]
	v_mfma_f32_16x16x32_bf16 v[114:117], v[194:197], v[178:181], v[114:117]
	v_mfma_f32_16x16x32_bf16 v[110:113], v[202:205], v[166:169], v[110:113]
	v_mfma_f32_16x16x32_bf16 v[106:109], v[202:205], v[178:181], v[106:109]
	v_mfma_f32_16x16x32_bf16 v[102:105], v[210:213], v[166:169], v[102:105]
	v_mfma_f32_16x16x32_bf16 v[98:101], v[210:213], v[178:181], v[98:101]
	s_barrier
	v_lshl_add_u64 v[234:235], s[22:23], 0, v[130:131]
	v_readfirstlane_b32 s24, v146
	v_lshl_add_u64 v[236:237], v[234:235], 0, s[10:11]
	s_mov_b32 m0, s24
	ds_read_b128 v[214:217], v143
	ds_read_b128 v[218:221], v143 offset:1024
	ds_read_b128 v[222:225], v143 offset:2048
	ds_read_b128 v[226:229], v143 offset:3072
	global_load_lds_dwordx4 v[236:237], off
	v_lshl_add_u64 v[236:237], s[22:23], 0, v[132:133]
	v_readfirstlane_b32 s24, v157
	v_lshl_add_u64 v[238:239], v[236:237], 0, s[10:11]
	s_mov_b32 m0, s24
	s_add_u32 s22, s22, 0x100
	global_load_lds_dwordx4 v[238:239], off
	s_waitcnt vmcnt(10)
	s_barrier
	s_waitcnt lgkmcnt(0)
	s_addc_u32 s23, s23, 0
	s_waitcnt lgkmcnt(0)
	v_mfma_f32_16x16x32_bf16 v[94:97], v[182:185], v[214:217], v[94:97]
	v_mfma_f32_16x16x32_bf16 v[90:93], v[182:185], v[222:225], v[90:93]
	v_mfma_f32_16x16x32_bf16 v[86:89], v[190:193], v[214:217], v[86:89]
	v_mfma_f32_16x16x32_bf16 v[82:85], v[190:193], v[222:225], v[82:85]
	v_mfma_f32_16x16x32_bf16 v[78:81], v[198:201], v[214:217], v[78:81]
	v_mfma_f32_16x16x32_bf16 v[74:77], v[198:201], v[222:225], v[74:77]
	v_mfma_f32_16x16x32_bf16 v[70:73], v[206:209], v[214:217], v[70:73]
	v_mfma_f32_16x16x32_bf16 v[66:69], v[206:209], v[222:225], v[66:69]
	v_mfma_f32_16x16x32_bf16 v[94:97], v[186:189], v[218:221], v[94:97]
	v_mfma_f32_16x16x32_bf16 v[90:93], v[186:189], v[226:229], v[90:93]
	v_mfma_f32_16x16x32_bf16 v[86:89], v[194:197], v[218:221], v[86:89]
	v_mfma_f32_16x16x32_bf16 v[82:85], v[194:197], v[226:229], v[82:85]
	v_mfma_f32_16x16x32_bf16 v[78:81], v[202:205], v[218:221], v[78:81]
	v_mfma_f32_16x16x32_bf16 v[74:77], v[202:205], v[226:229], v[74:77]
	v_mfma_f32_16x16x32_bf16 v[70:73], v[210:213], v[218:221], v[70:73]
	v_mfma_f32_16x16x32_bf16 v[66:69], v[210:213], v[226:229], v[66:69]
	v_lshl_add_u64 v[238:239], s[20:21], 0, v[130:131]
	v_readfirstlane_b32 s24, v145
	v_lshl_add_u64 v[240:241], v[238:239], 0, s[10:11]
	s_mov_b32 m0, s24
	s_barrier
	ds_read_b128 v[182:185], v140 offset:16384
	ds_read_b128 v[186:189], v140 offset:17408
	ds_read_b128 v[190:193], v139 offset:16384
	ds_read_b128 v[194:197], v139 offset:17408
	ds_read_b128 v[198:201], v138 offset:16384
	ds_read_b128 v[202:205], v138 offset:17408
	ds_read_b128 v[206:209], v137 offset:16384
	ds_read_b128 v[210:213], v137 offset:17408
	global_load_lds_dwordx4 v[240:241], off
	v_lshl_add_u64 v[240:241], s[20:21], 0, v[132:133]
	v_readfirstlane_b32 s24, v152
	v_lshl_add_u64 v[242:243], v[240:241], 0, s[10:11]
	s_mov_b32 m0, s24
	s_add_u32 s20, s20, 0x100
	global_load_lds_dwordx4 v[242:243], off
	s_barrier
	s_waitcnt lgkmcnt(0)
	s_addc_u32 s21, s21, 0
	s_waitcnt lgkmcnt(0)
	v_mfma_f32_16x16x32_bf16 v[62:65], v[182:185], v[162:165], v[62:65]
	v_mfma_f32_16x16x32_bf16 v[58:61], v[182:185], v[174:177], v[58:61]
	v_mfma_f32_16x16x32_bf16 v[54:57], v[190:193], v[162:165], v[54:57]
	v_mfma_f32_16x16x32_bf16 v[50:53], v[190:193], v[174:177], v[50:53]
	v_mfma_f32_16x16x32_bf16 v[46:49], v[198:201], v[162:165], v[46:49]
	v_mfma_f32_16x16x32_bf16 v[42:45], v[198:201], v[174:177], v[42:45]
	v_mfma_f32_16x16x32_bf16 v[38:41], v[206:209], v[162:165], v[38:41]
	v_mfma_f32_16x16x32_bf16 v[34:37], v[206:209], v[174:177], v[34:37]
	v_mfma_f32_16x16x32_bf16 v[62:65], v[186:189], v[166:169], v[62:65]
	v_mfma_f32_16x16x32_bf16 v[58:61], v[186:189], v[178:181], v[58:61]
	v_mfma_f32_16x16x32_bf16 v[54:57], v[194:197], v[166:169], v[54:57]
	v_mfma_f32_16x16x32_bf16 v[50:53], v[194:197], v[178:181], v[50:53]
	v_mfma_f32_16x16x32_bf16 v[46:49], v[202:205], v[166:169], v[46:49]
	v_mfma_f32_16x16x32_bf16 v[42:45], v[202:205], v[178:181], v[42:45]
	v_mfma_f32_16x16x32_bf16 v[38:41], v[210:213], v[166:169], v[38:41]
	v_mfma_f32_16x16x32_bf16 v[34:37], v[210:213], v[178:181], v[34:37]
	s_barrier
; #define STAGE(P, GP, ktrel) do { const GAS char* _g = (GP) + (ktrel) * (BK * 2); \
;     __builtin_amdgcn_global_load_lds((const GAS unsigned*)(_g + so0), (unsigned*)((char*)(P) + tid_ * 16), 16, 0, 0); \
;     __builtin_amdgcn_global_load_lds((const GAS unsigned*)(_g + so1), (unsigned*)((char*)(P) + tid_ * 16 + 8192), 16, 0, 0); } while (0)
; #define WAIT_V(n) asm volatile("s_waitcnt vmcnt(" #n ")" ::: "memory")
; #define WAIT_L(n) asm volatile("s_waitcnt lgkmcnt(" #n ")" ::: "memory")
; #define BAR __builtin_amdgcn_s_barrier()
; #define SCHED __builtin_amdgcn_sched_barrier(0)
; #define LDA(dst, b, h) for (int m = 0; m < 4; ++m) for (int k = 0; k < 2; ++k) \
;     dst[m][k] = *reinterpret_cast<const bf16x8*>((char*)SA(b, h) + lds_byte(wr * 64 + m * 16 + fr, k * 32 + fq * 8))
; #define LDB(dst, b, h) for (int n = 0; n < 2; ++n) for (int k = 0; k < 2; ++k) \
;     dst[n][k] = *reinterpret_cast<const bf16x8*>((char*)SB(b, h) + lds_byte(wc * 32 + n * 16 + fr, k * 32 + fq * 8))
; #define MMA(ai, bj, At_, Bt_) do { __builtin_amdgcn_s_setprio(1); \
;     for (int m = 0; m < 4; ++m) for (int n = 0; n < 2; ++n) for (int k = 0; k < 2; ++k) \
;       acc[ai][bj][m][n] = __builtin_amdgcn_mfma_f32_16x16x32_bf16(At_[m][k], Bt_[n][k], acc[ai][bj][m][n], 0, 0, 0); \
;     __builtin_amdgcn_s_setprio(0); } while (0)
; template <int K, int LD = K>
; __device__ __forceinline__ void gemm_main(const GAS bf16* A, const GAS bf16* Bt, int brow, int bcol, f32x4 (&acc)[2][2][4][2]) {
;     ...
;     WAIT_V(6); BAR; MMA(1, 1, At, B1); BAR;
;     LDB(B0, 1, 0); SCHED; LDA(At, 1, 0); STAGE(SA(0, 1), pA1, 2);
;     WAIT_L(8); BAR; WAIT_L(0); MMA(0, 0, At, B0); BAR; SCHED;
;     LDB(B1, 1, 1); STAGE(SB(1, 0), pB0, 3);
;     BAR; WAIT_L(0); MMA(0, 1, At, B1); BAR;
;     LDA(At, 1, 1); STAGE(SA(1, 0), pA0, 3);
	v_lshl_add_u64 v[242:243], s[18:19], 0, v[130:131]
	v_readfirstlane_b32 s24, v147
	v_lshl_add_u64 v[162:163], v[242:243], 0, s[10:11]
	s_mov_b32 m0, s24
	v_lshl_add_u64 v[244:245], s[18:19], 0, v[132:133]
	v_readfirstlane_b32 s24, v158
	global_load_lds_dwordx4 v[162:163], off
	v_lshl_add_u64 v[162:163], v[244:245], 0, s[10:11]
	s_mov_b32 m0, s24
	s_add_u32 s18, s18, 0x100
	global_load_lds_dwordx4 v[162:163], off
	s_waitcnt vmcnt(10)
	s_addc_u32 s19, s19, 0
	s_barrier
	v_mfma_f32_16x16x32_bf16 v[30:33], v[182:185], v[214:217], v[30:33]
	v_mfma_f32_16x16x32_bf16 v[26:29], v[182:185], v[222:225], v[26:29]
	v_mfma_f32_16x16x32_bf16 v[22:25], v[190:193], v[214:217], v[22:25]
	v_mfma_f32_16x16x32_bf16 v[18:21], v[190:193], v[222:225], v[18:21]
	v_mfma_f32_16x16x32_bf16 v[14:17], v[198:201], v[214:217], v[14:17]
	v_mfma_f32_16x16x32_bf16 v[10:13], v[198:201], v[222:225], v[10:13]
	v_mfma_f32_16x16x32_bf16 v[6:9], v[206:209], v[214:217], v[6:9]
	v_mfma_f32_16x16x32_bf16 v[2:5], v[206:209], v[222:225], v[2:5]
	v_mfma_f32_16x16x32_bf16 v[30:33], v[186:189], v[218:221], v[30:33]
	v_mfma_f32_16x16x32_bf16 v[26:29], v[186:189], v[226:229], v[26:29]
	v_mfma_f32_16x16x32_bf16 v[22:25], v[194:197], v[218:221], v[22:25]
	v_mfma_f32_16x16x32_bf16 v[18:21], v[194:197], v[226:229], v[18:21]
	v_mfma_f32_16x16x32_bf16 v[14:17], v[202:205], v[218:221], v[14:17]
	v_mfma_f32_16x16x32_bf16 v[10:13], v[202:205], v[226:229], v[10:13]
	v_mfma_f32_16x16x32_bf16 v[6:9], v[210:213], v[218:221], v[6:9]
	v_mfma_f32_16x16x32_bf16 v[2:5], v[210:213], v[226:229], v[2:5]
	s_barrier
	ds_read_b128 v[162:165], v142
	ds_read_b128 v[166:169], v142 offset:1024
	ds_read_b128 v[174:177], v142 offset:2048
	ds_read_b128 v[178:181], v142 offset:3072
	v_readfirstlane_b32 s24, v153
	v_lshl_add_u64 v[214:215], v[230:231], 0, s[10:11]
	s_mov_b32 m0, s24
	v_readfirstlane_b32 s24, v154
	ds_read_b128 v[182:185], v140 offset:32768
	ds_read_b128 v[186:189], v140 offset:33792
	ds_read_b128 v[190:193], v139 offset:32768
	ds_read_b128 v[194:197], v139 offset:33792
	ds_read_b128 v[198:201], v138 offset:32768
	ds_read_b128 v[202:205], v138 offset:33792
	ds_read_b128 v[206:209], v137 offset:32768
	ds_read_b128 v[210:213], v137 offset:33792
	global_load_lds_dwordx4 v[214:215], off
	v_lshl_add_u64 v[214:215], v[232:233], 0, s[10:11]
	s_mov_b32 m0, s24
	s_add_u32 s14, s14, 0x100
	global_load_lds_dwordx4 v[214:215], off
	s_waitcnt lgkmcnt(8)
	s_waitcnt vmcnt(10)
	s_barrier
	s_waitcnt lgkmcnt(0)
	s_addc_u32 s15, s15, 0
	s_waitcnt lgkmcnt(0)
	v_mfma_f32_16x16x32_bf16 v[126:129], v[182:185], v[162:165], v[126:129]
	v_mfma_f32_16x16x32_bf16 v[122:125], v[182:185], v[174:177], v[122:125]
	v_mfma_f32_16x16x32_bf16 v[118:121], v[190:193], v[162:165], v[118:121]
	v_mfma_f32_16x16x32_bf16 v[114:117], v[190:193], v[174:177], v[114:117]
	v_mfma_f32_16x16x32_bf16 v[110:113], v[198:201], v[162:165], v[110:113]
	v_mfma_f32_16x16x32_bf16 v[106:109], v[198:201], v[174:177], v[106:109]
	v_mfma_f32_16x16x32_bf16 v[102:105], v[206:209], v[162:165], v[102:105]
	v_mfma_f32_16x16x32_bf16 v[98:101], v[206:209], v[174:177], v[98:101]
	v_mfma_f32_16x16x32_bf16 v[126:129], v[186:189], v[166:169], v[126:129]
	v_mfma_f32_16x16x32_bf16 v[122:125], v[186:189], v[178:181], v[122:125]
	v_mfma_f32_16x16x32_bf16 v[118:121], v[194:197], v[166:169], v[118:121]
	v_mfma_f32_16x16x32_bf16 v[114:117], v[194:197], v[178:181], v[114:117]
	v_mfma_f32_16x16x32_bf16 v[110:113], v[202:205], v[166:169], v[110:113]
	v_mfma_f32_16x16x32_bf16 v[106:109], v[202:205], v[178:181], v[106:109]
	v_mfma_f32_16x16x32_bf16 v[102:105], v[210:213], v[166:169], v[102:105]
	v_mfma_f32_16x16x32_bf16 v[98:101], v[210:213], v[178:181], v[98:101]
	s_barrier
	v_readfirstlane_b32 s24, v148
	v_lshl_add_u64 v[230:231], v[234:235], 0, s[12:13]
	s_mov_b32 m0, s24
	v_readfirstlane_b32 s24, v159
	ds_read_b128 v[214:217], v141
	ds_read_b128 v[218:221], v141 offset:1024
	ds_read_b128 v[222:225], v141 offset:2048
	ds_read_b128 v[226:229], v141 offset:3072
	global_load_lds_dwordx4 v[230:231], off
	v_lshl_add_u64 v[230:231], v[236:237], 0, s[12:13]
	s_mov_b32 m0, s24
	s_nop 0
	global_load_lds_dwordx4 v[230:231], off
	s_waitcnt vmcnt(10)
	s_barrier
	s_waitcnt lgkmcnt(0)
	v_mfma_f32_16x16x32_bf16 v[94:97], v[182:185], v[214:217], v[94:97]
	v_mfma_f32_16x16x32_bf16 v[90:93], v[182:185], v[222:225], v[90:93]
	v_mfma_f32_16x16x32_bf16 v[86:89], v[190:193], v[214:217], v[86:89]
	v_mfma_f32_16x16x32_bf16 v[82:85], v[190:193], v[222:225], v[82:85]
	v_mfma_f32_16x16x32_bf16 v[78:81], v[198:201], v[214:217], v[78:81]
	v_mfma_f32_16x16x32_bf16 v[74:77], v[198:201], v[222:225], v[74:77]
	v_mfma_f32_16x16x32_bf16 v[70:73], v[206:209], v[214:217], v[70:73]
	v_mfma_f32_16x16x32_bf16 v[66:69], v[206:209], v[222:225], v[66:69]
	v_mfma_f32_16x16x32_bf16 v[94:97], v[186:189], v[218:221], v[94:97]
	v_mfma_f32_16x16x32_bf16 v[90:93], v[186:189], v[226:229], v[90:93]
	v_mfma_f32_16x16x32_bf16 v[86:89], v[194:197], v[218:221], v[86:89]
	v_mfma_f32_16x16x32_bf16 v[82:85], v[194:197], v[226:229], v[82:85]
	v_mfma_f32_16x16x32_bf16 v[78:81], v[202:205], v[218:221], v[78:81]
	v_mfma_f32_16x16x32_bf16 v[74:77], v[202:205], v[226:229], v[74:77]
	v_mfma_f32_16x16x32_bf16 v[70:73], v[210:213], v[218:221], v[70:73]
	v_mfma_f32_16x16x32_bf16 v[66:69], v[210:213], v[226:229], v[66:69]
	v_readfirstlane_b32 s24, v155
	v_lshl_add_u64 v[230:231], v[238:239], 0, s[12:13]
	s_mov_b32 m0, s24
	v_readfirstlane_b32 s24, v156
	s_barrier
; #define STAGE(P, GP, ktrel) do { const GAS char* _g = (GP) + (ktrel) * (BK * 2); \
;     __builtin_amdgcn_global_load_lds((const GAS unsigned*)(_g + so0), (unsigned*)((char*)(P) + tid_ * 16), 16, 0, 0); \
;     __builtin_amdgcn_global_load_lds((const GAS unsigned*)(_g + so1), (unsigned*)((char*)(P) + tid_ * 16 + 8192), 16, 0, 0); } while (0)
; #define WAIT_V(n) asm volatile("s_waitcnt vmcnt(" #n ")" ::: "memory")
; #define WAIT_L(n) asm volatile("s_waitcnt lgkmcnt(" #n ")" ::: "memory")
; #define BAR __builtin_amdgcn_s_barrier()
; #define SCHED __builtin_amdgcn_sched_barrier(0)
; #define LDA(dst, b, h) for (int m = 0; m < 4; ++m) for (int k = 0; k < 2; ++k) \
;     dst[m][k] = *reinterpret_cast<const bf16x8*>((char*)SA(b, h) + lds_byte(wr * 64 + m * 16 + fr, k * 32 + fq * 8))
; #define LDB(dst, b, h) for (int n = 0; n < 2; ++n) for (int k = 0; k < 2; ++k) \
;     dst[n][k] = *reinterpret_cast<const bf16x8*>((char*)SB(b, h) + lds_byte(wc * 32 + n * 16 + fr, k * 32 + fq * 8))
; #define MMA(ai, bj, At_, Bt_) do { __builtin_amdgcn_s_setprio(1); \
;     for (int m = 0; m < 4; ++m) for (int n = 0; n < 2; ++n) for (int k = 0; k < 2; ++k) \
;       acc[ai][bj][m][n] = __builtin_amdgcn_mfma_f32_16x16x32_bf16(At_[m][k], Bt_[n][k], acc[ai][bj][m][n], 0, 0, 0); \
;     __builtin_amdgcn_s_setprio(0); } while (0)
; template <int K, int LD = K>
; __device__ __forceinline__ void gemm_main(const GAS bf16* A, const GAS bf16* Bt, int brow, int bcol, f32x4 (&acc)[2][2][4][2]) {
;     ...
;     LDA(At, 1, 1); STAGE(SA(1, 0), pA0, 3);
;     BAR; WAIT_L(0); MMA(1, 0, At, B0); BAR; SCHED;
;     STAGE(SB(1, 1), pB1, 3);
;     WAIT_V(6); BAR; MMA(1, 1, At, B1); BAR;
;     pA0 += 4 * BK; pA1 += 4 * BK; pB0 += 4 * BK; pB1 += 4 * BK;
;     asm volatile("" : "+s"(pA0), "+s"(pA1), "+s"(pB0), "+s"(pB1));
;   }
;   { LDB(B0, 0, 0); LDA(At, 0, 0); STAGE(SA(1, 1), pA1, 1);
;     BAR; WAIT_L(0); MMA(0, 0, At, B0); BAR;
;     LDB(B1, 0, 1); BAR; WAIT_L(0); MMA(0, 1, At, B1); BAR;
;     LDA(At, 0, 1); WAIT_V(4); BAR; WAIT_L(0); MMA(1, 0, At, B0); MMA(1, 1, At, B1); BAR; }
	ds_read_b128 v[182:185], v140 offset:49152
	ds_read_b128 v[186:189], v140 offset:50176
	ds_read_b128 v[190:193], v139 offset:49152
	ds_read_b128 v[194:197], v139 offset:50176
	ds_read_b128 v[198:201], v138 offset:49152
	ds_read_b128 v[202:205], v138 offset:50176
	ds_read_b128 v[206:209], v137 offset:49152
	ds_read_b128 v[210:213], v137 offset:50176
	global_load_lds_dwordx4 v[230:231], off
	v_lshl_add_u64 v[230:231], v[240:241], 0, s[12:13]
	s_mov_b32 m0, s24
	s_nop 0
	global_load_lds_dwordx4 v[230:231], off
	s_barrier
	s_waitcnt lgkmcnt(0)
	v_mfma_f32_16x16x32_bf16 v[62:65], v[182:185], v[162:165], v[62:65]
	v_mfma_f32_16x16x32_bf16 v[58:61], v[182:185], v[174:177], v[58:61]
	v_mfma_f32_16x16x32_bf16 v[54:57], v[190:193], v[162:165], v[54:57]
	v_mfma_f32_16x16x32_bf16 v[50:53], v[190:193], v[174:177], v[50:53]
	v_mfma_f32_16x16x32_bf16 v[46:49], v[198:201], v[162:165], v[46:49]
	v_mfma_f32_16x16x32_bf16 v[42:45], v[198:201], v[174:177], v[42:45]
	v_mfma_f32_16x16x32_bf16 v[38:41], v[206:209], v[162:165], v[38:41]
	v_mfma_f32_16x16x32_bf16 v[34:37], v[206:209], v[174:177], v[34:37]
	v_mfma_f32_16x16x32_bf16 v[62:65], v[186:189], v[166:169], v[62:65]
	v_mfma_f32_16x16x32_bf16 v[58:61], v[186:189], v[178:181], v[58:61]
	v_mfma_f32_16x16x32_bf16 v[54:57], v[194:197], v[166:169], v[54:57]
	v_mfma_f32_16x16x32_bf16 v[50:53], v[194:197], v[178:181], v[50:53]
	v_mfma_f32_16x16x32_bf16 v[46:49], v[202:205], v[166:169], v[46:49]
	v_mfma_f32_16x16x32_bf16 v[42:45], v[202:205], v[178:181], v[42:45]
	v_mfma_f32_16x16x32_bf16 v[38:41], v[210:213], v[166:169], v[38:41]
	v_mfma_f32_16x16x32_bf16 v[34:37], v[210:213], v[178:181], v[34:37]
	s_barrier
	v_readfirstlane_b32 s24, v149
	v_lshl_add_u64 v[162:163], v[242:243], 0, s[12:13]
	s_mov_b32 m0, s24
	v_readfirstlane_b32 s24, v160
	global_load_lds_dwordx4 v[162:163], off
	v_lshl_add_u64 v[162:163], v[244:245], 0, s[12:13]
	s_mov_b32 m0, s24
	s_nop 0
	global_load_lds_dwordx4 v[162:163], off
	s_waitcnt vmcnt(10)
	s_barrier
	v_mfma_f32_16x16x32_bf16 v[30:33], v[182:185], v[214:217], v[30:33]
	v_mfma_f32_16x16x32_bf16 v[26:29], v[182:185], v[222:225], v[26:29]
	v_mfma_f32_16x16x32_bf16 v[22:25], v[190:193], v[214:217], v[22:25]
	v_mfma_f32_16x16x32_bf16 v[18:21], v[190:193], v[222:225], v[18:21]
	v_mfma_f32_16x16x32_bf16 v[14:17], v[198:201], v[214:217], v[14:17]
	v_mfma_f32_16x16x32_bf16 v[10:13], v[198:201], v[222:225], v[10:13]
	v_mfma_f32_16x16x32_bf16 v[6:9], v[206:209], v[214:217], v[6:9]
	v_mfma_f32_16x16x32_bf16 v[2:5], v[206:209], v[222:225], v[2:5]
	v_mfma_f32_16x16x32_bf16 v[30:33], v[186:189], v[218:221], v[30:33]
	v_mfma_f32_16x16x32_bf16 v[26:29], v[186:189], v[226:229], v[26:29]
	v_mfma_f32_16x16x32_bf16 v[22:25], v[194:197], v[218:221], v[22:25]
	v_mfma_f32_16x16x32_bf16 v[18:21], v[194:197], v[226:229], v[18:21]
	v_mfma_f32_16x16x32_bf16 v[14:17], v[202:205], v[218:221], v[14:17]
	v_mfma_f32_16x16x32_bf16 v[10:13], v[202:205], v[226:229], v[10:13]
	v_mfma_f32_16x16x32_bf16 v[6:9], v[210:213], v[218:221], v[6:9]
	v_mfma_f32_16x16x32_bf16 v[2:5], v[210:213], v[226:229], v[2:5]
	s_add_i32 s17, s17, 2
	s_cmp_lt_u32 s17, 12
	s_barrier
	s_cbranch_scc1 .LBB0_89
	ds_read_b128 v[146:149], v144
	ds_read_b128 v[152:155], v144 offset:1024
	ds_read_b128 v[156:159], v144 offset:2048
	ds_read_b128 v[160:163], v144 offset:3072
	ds_read_b128 v[164:167], v140
	ds_read_b128 v[174:177], v140 offset:1024
	ds_read_b128 v[178:181], v139
	ds_read_b128 v[182:185], v139 offset:1024
	ds_read_b128 v[186:189], v138
	ds_read_b128 v[190:193], v138 offset:1024
	ds_read_b128 v[194:197], v137
	ds_read_b128 v[198:201], v137 offset:1024
	v_lshl_add_u64 v[144:145], s[14:15], 0, v[130:131]
	v_readfirstlane_b32 s17, v151
	v_lshl_add_u64 v[144:145], v[144:145], 0, s[8:9]
	s_mov_b32 m0, s17
	v_lshl_add_u64 v[132:133], s[14:15], 0, v[132:133]
	v_readfirstlane_b32 s14, v150
	global_load_lds_dwordx4 v[144:145], off
	v_lshl_add_u64 v[132:133], v[132:133], 0, s[8:9]
	s_mov_b32 m0, s14
	s_nop 0
	global_load_lds_dwordx4 v[132:133], off
	s_waitcnt vmcnt(10)
	s_barrier
	s_waitcnt lgkmcnt(0)
	v_mfma_f32_16x16x32_bf16 v[126:129], v[164:167], v[146:149], v[126:129]
	v_mfma_f32_16x16x32_bf16 v[122:125], v[164:167], v[156:159], v[122:125]
	v_mfma_f32_16x16x32_bf16 v[110:113], v[186:189], v[146:149], v[110:113]
	v_mfma_f32_16x16x32_bf16 v[106:109], v[186:189], v[156:159], v[106:109]
	v_mfma_f32_16x16x32_bf16 v[126:129], v[174:177], v[152:155], v[126:129]
	v_mfma_f32_16x16x32_bf16 v[122:125], v[174:177], v[160:163], v[122:125]
	v_mfma_f32_16x16x32_bf16 v[118:121], v[178:181], v[146:149], v[118:121]
	v_mfma_f32_16x16x32_bf16 v[114:117], v[178:181], v[156:159], v[114:117]
	v_mfma_f32_16x16x32_bf16 v[110:113], v[190:193], v[152:155], v[110:113]
	v_mfma_f32_16x16x32_bf16 v[106:109], v[190:193], v[160:163], v[106:109]
	v_mfma_f32_16x16x32_bf16 v[102:105], v[194:197], v[146:149], v[102:105]
	v_mfma_f32_16x16x32_bf16 v[98:101], v[194:197], v[156:159], v[98:101]
	v_mfma_f32_16x16x32_bf16 v[202:205], v[182:185], v[152:155], v[118:121]
	v_mfma_f32_16x16x32_bf16 v[206:209], v[182:185], v[160:163], v[114:117]
	v_mfma_f32_16x16x32_bf16 v[210:213], v[198:201], v[152:155], v[102:105]
	v_mfma_f32_16x16x32_bf16 v[214:217], v[198:201], v[160:163], v[98:101]
	s_barrier
	s_nop 1
	ds_read_b128 v[98:101], v143
	ds_read_b128 v[102:105], v143 offset:1024
	ds_read_b128 v[114:117], v143 offset:2048
	ds_read_b128 v[118:121], v143 offset:3072
	s_waitcnt vmcnt(8)
	s_barrier
; #define WAIT_V(n) asm volatile("s_waitcnt vmcnt(" #n ")" ::: "memory")
; #define WAIT_L(n) asm volatile("s_waitcnt lgkmcnt(" #n ")" ::: "memory")
; #define BAR __builtin_amdgcn_s_barrier()
; #define LDA(dst, b, h) for (int m = 0; m < 4; ++m) for (int k = 0; k < 2; ++k) \
;     dst[m][k] = *reinterpret_cast<const bf16x8*>((char*)SA(b, h) + lds_byte(wr * 64 + m * 16 + fr, k * 32 + fq * 8))
; #define LDB(dst, b, h) for (int n = 0; n < 2; ++n) for (int k = 0; k < 2; ++k) \
;     dst[n][k] = *reinterpret_cast<const bf16x8*>((char*)SB(b, h) + lds_byte(wc * 32 + n * 16 + fr, k * 32 + fq * 8))
; #define MMA(ai, bj, At_, Bt_) do { __builtin_amdgcn_s_setprio(1); \
;     for (int m = 0; m < 4; ++m) for (int n = 0; n < 2; ++n) for (int k = 0; k < 2; ++k) \
;       acc[ai][bj][m][n] = __builtin_amdgcn_mfma_f32_16x16x32_bf16(At_[m][k], Bt_[n][k], acc[ai][bj][m][n], 0, 0, 0); \
;     __builtin_amdgcn_s_setprio(0); } while (0)
; template <int K, int LD = K>
; __device__ __forceinline__ void gemm_main(const GAS bf16* A, const GAS bf16* Bt, int brow, int bcol, f32x4 (&acc)[2][2][4][2]) {
;     ...
;     LDA(At, 0, 1); WAIT_V(4); BAR; WAIT_L(0); MMA(1, 0, At, B0); MMA(1, 1, At, B1); BAR; }
;   { LDB(B0, 1, 0); LDA(At, 1, 0); WAIT_V(2); BAR; WAIT_L(0); MMA(0, 0, At, B0); BAR;
;     LDB(B1, 1, 1); WAIT_V(0); BAR; WAIT_L(0); MMA(0, 1, At, B1); BAR;
	s_waitcnt lgkmcnt(0)
	v_mfma_f32_16x16x32_bf16 v[94:97], v[164:167], v[98:101], v[94:97]
	v_mfma_f32_16x16x32_bf16 v[90:93], v[164:167], v[114:117], v[90:93]
	v_mfma_f32_16x16x32_bf16 v[78:81], v[186:189], v[98:101], v[78:81]
	v_mfma_f32_16x16x32_bf16 v[74:77], v[186:189], v[114:117], v[74:77]
	v_mfma_f32_16x16x32_bf16 v[94:97], v[174:177], v[102:105], v[94:97]
	v_mfma_f32_16x16x32_bf16 v[90:93], v[174:177], v[118:121], v[90:93]
	v_mfma_f32_16x16x32_bf16 v[86:89], v[178:181], v[98:101], v[86:89]
	v_mfma_f32_16x16x32_bf16 v[82:85], v[178:181], v[114:117], v[82:85]
	v_mfma_f32_16x16x32_bf16 v[78:81], v[190:193], v[102:105], v[78:81]
	v_mfma_f32_16x16x32_bf16 v[74:77], v[190:193], v[118:121], v[74:77]
	v_mfma_f32_16x16x32_bf16 v[70:73], v[194:197], v[98:101], v[70:73]
	v_mfma_f32_16x16x32_bf16 v[66:69], v[194:197], v[114:117], v[66:69]
	v_mfma_f32_16x16x32_bf16 v[164:167], v[182:185], v[102:105], v[86:89]
	v_mfma_f32_16x16x32_bf16 v[174:177], v[182:185], v[118:121], v[82:85]
	v_mfma_f32_16x16x32_bf16 v[178:181], v[198:201], v[102:105], v[70:73]
	v_mfma_f32_16x16x32_bf16 v[182:185], v[198:201], v[118:121], v[66:69]
	s_barrier
	s_nop 1
	ds_read_b128 v[66:69], v140 offset:16384
	ds_read_b128 v[70:73], v140 offset:17408
	ds_read_b128 v[82:85], v139 offset:16384
	ds_read_b128 v[86:89], v139 offset:17408
	ds_read_b128 v[186:189], v138 offset:16384
	ds_read_b128 v[190:193], v138 offset:17408
	ds_read_b128 v[194:197], v137 offset:16384
	ds_read_b128 v[198:201], v137 offset:17408
	s_waitcnt vmcnt(4)
	s_barrier
	s_waitcnt lgkmcnt(0)
	v_mfma_f32_16x16x32_bf16 v[62:65], v[66:69], v[146:149], v[62:65]
	v_mfma_f32_16x16x32_bf16 v[58:61], v[66:69], v[156:159], v[58:61]
	v_mfma_f32_16x16x32_bf16 v[46:49], v[186:189], v[146:149], v[46:49]
	v_mfma_f32_16x16x32_bf16 v[38:41], v[194:197], v[146:149], v[38:41]
	v_mfma_f32_16x16x32_bf16 v[62:65], v[70:73], v[152:155], v[62:65]
	v_mfma_f32_16x16x32_bf16 v[58:61], v[70:73], v[160:163], v[58:61]
	v_mfma_f32_16x16x32_bf16 v[54:57], v[82:85], v[146:149], v[54:57]
	v_mfma_f32_16x16x32_bf16 v[50:53], v[82:85], v[156:159], v[50:53]
	v_mfma_f32_16x16x32_bf16 v[46:49], v[190:193], v[152:155], v[46:49]
	v_mfma_f32_16x16x32_bf16 v[42:45], v[186:189], v[156:159], v[42:45]
	v_mfma_f32_16x16x32_bf16 v[38:41], v[198:201], v[152:155], v[38:41]
	v_mfma_f32_16x16x32_bf16 v[34:37], v[194:197], v[156:159], v[34:37]
	v_mfma_f32_16x16x32_bf16 v[218:221], v[86:89], v[152:155], v[54:57]
	v_mfma_f32_16x16x32_bf16 v[222:225], v[86:89], v[160:163], v[50:53]
	v_mfma_f32_16x16x32_bf16 v[226:229], v[190:193], v[160:163], v[42:45]
	v_mfma_f32_16x16x32_bf16 v[144:147], v[198:201], v[160:163], v[34:37]
	v_mfma_f32_16x16x32_bf16 v[30:33], v[66:69], v[98:101], v[30:33]
	v_mfma_f32_16x16x32_bf16 v[26:29], v[66:69], v[114:117], v[26:29]
	v_mfma_f32_16x16x32_bf16 v[14:17], v[186:189], v[98:101], v[14:17]
	v_mfma_f32_16x16x32_bf16 v[6:9], v[194:197], v[98:101], v[6:9]
	v_mfma_f32_16x16x32_bf16 v[30:33], v[70:73], v[102:105], v[30:33]
	v_mfma_f32_16x16x32_bf16 v[26:29], v[70:73], v[118:121], v[26:29]
	v_mfma_f32_16x16x32_bf16 v[22:25], v[82:85], v[98:101], v[22:25]
	v_mfma_f32_16x16x32_bf16 v[18:21], v[82:85], v[114:117], v[18:21]
	v_mfma_f32_16x16x32_bf16 v[14:17], v[190:193], v[102:105], v[14:17]
	v_mfma_f32_16x16x32_bf16 v[10:13], v[186:189], v[114:117], v[10:13]
	v_mfma_f32_16x16x32_bf16 v[6:9], v[198:201], v[102:105], v[6:9]
	v_mfma_f32_16x16x32_bf16 v[2:5], v[194:197], v[114:117], v[2:5]
	v_mfma_f32_16x16x32_bf16 v[148:151], v[86:89], v[102:105], v[22:25]
	v_mfma_f32_16x16x32_bf16 v[152:155], v[86:89], v[118:121], v[18:21]
	v_mfma_f32_16x16x32_bf16 v[156:159], v[190:193], v[118:121], v[10:13]
	v_mfma_f32_16x16x32_bf16 v[160:163], v[198:201], v[118:121], v[2:5]
	s_barrier
	s_nop 1
	ds_read_b128 v[2:5], v142
	ds_read_b128 v[10:13], v142 offset:1024
	ds_read_b128 v[186:189], v142 offset:2048
	ds_read_b128 v[190:193], v142 offset:3072
	ds_read_b128 v[18:21], v140 offset:32768
	ds_read_b128 v[22:25], v140 offset:33792
	ds_read_b128 v[34:37], v139 offset:32768
	ds_read_b128 v[42:45], v139 offset:33792
	ds_read_b128 v[50:53], v138 offset:32768
	ds_read_b128 v[54:57], v138 offset:33792
	ds_read_b128 v[194:197], v137 offset:32768
	ds_read_b128 v[198:201], v137 offset:33792
	s_waitcnt vmcnt(2)
	s_barrier
; #define WAIT_V(n) asm volatile("s_waitcnt vmcnt(" #n ")" ::: "memory")
; #define WAIT_L(n) asm volatile("s_waitcnt lgkmcnt(" #n ")" ::: "memory")
; #define BAR __builtin_amdgcn_s_barrier()
; #define LDA(dst, b, h) for (int m = 0; m < 4; ++m) for (int k = 0; k < 2; ++k) \
;     dst[m][k] = *reinterpret_cast<const bf16x8*>((char*)SA(b, h) + lds_byte(wr * 64 + m * 16 + fr, k * 32 + fq * 8))
; #define LDB(dst, b, h) for (int n = 0; n < 2; ++n) for (int k = 0; k < 2; ++k) \
;     dst[n][k] = *reinterpret_cast<const bf16x8*>((char*)SB(b, h) + lds_byte(wc * 32 + n * 16 + fr, k * 32 + fq * 8))
; #define MMA(ai, bj, At_, Bt_) do { __builtin_amdgcn_s_setprio(1); \
;     for (int m = 0; m < 4; ++m) for (int n = 0; n < 2; ++n) for (int k = 0; k < 2; ++k) \
;       acc[ai][bj][m][n] = __builtin_amdgcn_mfma_f32_16x16x32_bf16(At_[m][k], Bt_[n][k], acc[ai][bj][m][n], 0, 0, 0); \
;     __builtin_amdgcn_s_setprio(0); } while (0)
; template <int K, int LD = K>
; __device__ __forceinline__ void gemm_main(const GAS bf16* A, const GAS bf16* Bt, int brow, int bcol, f32x4 (&acc)[2][2][4][2]) {
;     ...
;     LDB(B1, 1, 1); WAIT_V(0); BAR; WAIT_L(0); MMA(0, 1, At, B1); BAR;
;     LDA(At, 1, 1); BAR; WAIT_L(0); MMA(1, 0, At, B0); MMA(1, 1, At, B1); BAR; }
;   if (wr == 0) BAR;
	s_waitcnt lgkmcnt(0)
	v_mfma_f32_16x16x32_bf16 v[66:69], v[18:21], v[2:5], v[126:129]
	v_mfma_f32_16x16x32_bf16 v[118:121], v[22:25], v[10:13], v[66:69]
	v_mfma_f32_16x16x32_bf16 v[66:69], v[18:21], v[186:189], v[122:125]
	v_mfma_f32_16x16x32_bf16 v[114:117], v[22:25], v[190:193], v[66:69]
	v_mfma_f32_16x16x32_bf16 v[66:69], v[34:37], v[2:5], v[202:205]
	v_mfma_f32_16x16x32_bf16 v[102:105], v[42:45], v[10:13], v[66:69]
	v_mfma_f32_16x16x32_bf16 v[66:69], v[34:37], v[186:189], v[206:209]
	v_mfma_f32_16x16x32_bf16 v[98:101], v[42:45], v[190:193], v[66:69]
	v_mfma_f32_16x16x32_bf16 v[66:69], v[50:53], v[2:5], v[110:113]
	v_mfma_f32_16x16x32_bf16 v[86:89], v[54:57], v[10:13], v[66:69]
	v_mfma_f32_16x16x32_bf16 v[66:69], v[50:53], v[186:189], v[106:109]
	v_mfma_f32_16x16x32_bf16 v[82:85], v[54:57], v[190:193], v[66:69]
	v_mfma_f32_16x16x32_bf16 v[66:69], v[194:197], v[2:5], v[210:213]
	v_mfma_f32_16x16x32_bf16 v[70:73], v[198:201], v[10:13], v[66:69]
	v_mfma_f32_16x16x32_bf16 v[66:69], v[194:197], v[186:189], v[214:217]
	v_mfma_f32_16x16x32_bf16 v[66:69], v[198:201], v[190:193], v[66:69]
	s_barrier
	ds_read_b128 v[202:205], v141
	ds_read_b128 v[206:209], v141 offset:1024
	ds_read_b128 v[210:213], v141 offset:2048
	ds_read_b128 v[214:217], v141 offset:3072
	s_waitcnt vmcnt(0)
	s_barrier
	s_waitcnt lgkmcnt(0)
	v_mfma_f32_16x16x32_bf16 v[94:97], v[18:21], v[202:205], v[94:97]
	v_mfma_f32_16x16x32_bf16 v[18:21], v[18:21], v[210:213], v[90:93]
	v_mfma_f32_16x16x32_bf16 v[122:125], v[22:25], v[214:217], v[18:21]
	v_mfma_f32_16x16x32_bf16 v[18:21], v[34:37], v[202:205], v[164:167]
	v_mfma_f32_16x16x32_bf16 v[110:113], v[42:45], v[206:209], v[18:21]
	v_mfma_f32_16x16x32_bf16 v[18:21], v[34:37], v[210:213], v[174:177]
	v_mfma_f32_16x16x32_bf16 v[106:109], v[42:45], v[214:217], v[18:21]
	v_mfma_f32_16x16x32_bf16 v[18:21], v[50:53], v[202:205], v[78:81]
	v_mfma_f32_16x16x32_bf16 v[126:129], v[22:25], v[206:209], v[94:97]
	v_mfma_f32_16x16x32_bf16 v[94:97], v[54:57], v[206:209], v[18:21]
	v_mfma_f32_16x16x32_bf16 v[18:21], v[50:53], v[210:213], v[74:77]
	v_mfma_f32_16x16x32_bf16 v[90:93], v[54:57], v[214:217], v[18:21]
	v_mfma_f32_16x16x32_bf16 v[18:21], v[194:197], v[202:205], v[178:181]
	v_mfma_f32_16x16x32_bf16 v[78:81], v[198:201], v[206:209], v[18:21]
	v_mfma_f32_16x16x32_bf16 v[18:21], v[194:197], v[210:213], v[182:185]
	v_mfma_f32_16x16x32_bf16 v[74:77], v[198:201], v[214:217], v[18:21]
	s_barrier
	ds_read_b128 v[164:167], v140 offset:49152
	ds_read_b128 v[140:143], v140 offset:50176
	ds_read_b128 v[174:177], v139 offset:49152
	ds_read_b128 v[178:181], v139 offset:50176
	ds_read_b128 v[182:185], v138 offset:49152
	ds_read_b128 v[194:197], v138 offset:50176
	ds_read_b128 v[198:201], v137 offset:49152
	ds_read_b128 v[230:233], v137 offset:50176
	s_barrier
	s_waitcnt lgkmcnt(0)
	v_mfma_f32_16x16x32_bf16 v[18:21], v[164:167], v[2:5], v[62:65]
	v_mfma_f32_16x16x32_bf16 v[54:57], v[140:143], v[10:13], v[18:21]
	v_mfma_f32_16x16x32_bf16 v[18:21], v[164:167], v[186:189], v[58:61]
	v_mfma_f32_16x16x32_bf16 v[50:53], v[140:143], v[190:193], v[18:21]
	v_mfma_f32_16x16x32_bf16 v[18:21], v[174:177], v[2:5], v[218:221]
	v_mfma_f32_16x16x32_bf16 v[42:45], v[178:181], v[10:13], v[18:21]
	v_mfma_f32_16x16x32_bf16 v[18:21], v[174:177], v[186:189], v[222:225]
	v_mfma_f32_16x16x32_bf16 v[34:37], v[178:181], v[190:193], v[18:21]
	v_mfma_f32_16x16x32_bf16 v[18:21], v[182:185], v[2:5], v[46:49]
	v_mfma_f32_16x16x32_bf16 v[2:5], v[198:201], v[2:5], v[38:41]
	v_mfma_f32_16x16x32_bf16 v[22:25], v[194:197], v[10:13], v[18:21]
	v_mfma_f32_16x16x32_bf16 v[18:21], v[182:185], v[186:189], v[226:229]
	v_mfma_f32_16x16x32_bf16 v[10:13], v[230:233], v[10:13], v[2:5]
	v_mfma_f32_16x16x32_bf16 v[2:5], v[198:201], v[186:189], v[144:147]
	v_mfma_f32_16x16x32_bf16 v[18:21], v[194:197], v[190:193], v[18:21]
	v_mfma_f32_16x16x32_bf16 v[2:5], v[230:233], v[190:193], v[2:5]
	v_mfma_f32_16x16x32_bf16 v[26:29], v[164:167], v[210:213], v[26:29]
	v_mfma_f32_16x16x32_bf16 v[30:33], v[164:167], v[202:205], v[30:33]
	v_mfma_f32_16x16x32_bf16 v[58:61], v[140:143], v[214:217], v[26:29]
	v_mfma_f32_16x16x32_bf16 v[26:29], v[174:177], v[202:205], v[148:151]
	v_mfma_f32_16x16x32_bf16 v[14:17], v[182:185], v[202:205], v[14:17]
	v_mfma_f32_16x16x32_bf16 v[62:65], v[140:143], v[206:209], v[30:33]
	v_mfma_f32_16x16x32_bf16 v[46:49], v[178:181], v[206:209], v[26:29]
	v_mfma_f32_16x16x32_bf16 v[26:29], v[174:177], v[210:213], v[152:155]
	v_mfma_f32_16x16x32_bf16 v[30:33], v[194:197], v[206:209], v[14:17]
	v_mfma_f32_16x16x32_bf16 v[14:17], v[182:185], v[210:213], v[156:159]
	v_mfma_f32_16x16x32_bf16 v[6:9], v[198:201], v[202:205], v[6:9]
	v_mfma_f32_16x16x32_bf16 v[38:41], v[178:181], v[214:217], v[26:29]
	v_mfma_f32_16x16x32_bf16 v[26:29], v[194:197], v[214:217], v[14:17]
	v_mfma_f32_16x16x32_bf16 v[14:17], v[230:233], v[206:209], v[6:9]
	v_mfma_f32_16x16x32_bf16 v[6:9], v[198:201], v[210:213], v[160:163]
	v_mfma_f32_16x16x32_bf16 v[6:9], v[230:233], v[214:217], v[6:9]
	v_cmp_gt_u32_e32 vcc, s34, v136
	s_barrier
	s_and_saveexec_b64 s[14:15], vcc
	s_cbranch_execz .LBB0_92
	s_barrier

; #define PARAMS_LOCAL KParams PP_ = kparams(); const __attribute__((address_space(4))) Params& P = *PP_;
; __device__ __forceinline__ unsigned xb_add(unsigned* p, unsigned v) { return __hip_atomic_fetch_add(p, v, __ATOMIC_RELAXED, __HIP_MEMORY_SCOPE_AGENT); }
; __device__ __forceinline__ void xcd_barrier() {
;   asm volatile("s_waitcnt vmcnt(0)" ::: "memory");
;   __syncthreads();
;   if (threadIdx.x == 0) {
;     PARAMS_LOCAL
;     unsigned* bar = (unsigned*)(P.ws + OFF_BAR);
;     const unsigned* st = (const unsigned*)(smem_raw + LDS_XB);
;     const unsigned bx = st[0], nloc = st[1], nx = st[2];
;     __builtin_amdgcn_s_waitcnt(0);
;     const unsigned old = xb_add(&bar[XB_XSUB(bx)], 1u);
;     const unsigned gen = old / nloc;
;     if (old + 1u == (gen + 1u) * nloc) {
;       __builtin_amdgcn_fence(__ATOMIC_RELEASE, "agent");
;       asm volatile("s_waitcnt vmcnt(0)" ::: "memory");
;       const unsigned og = xb_add(&bar[XB_TOP], 1u);
.LBB0_183:
	s_waitcnt vmcnt(0)
	s_barrier
	s_and_saveexec_b64 s[4:5], s[94:95]
	s_cbranch_execz .LBB0_220
	s_mov_b64 s[6:7], s[0:1]
	s_load_dwordx2 s[6:7], s[6:7], 0xb0
	s_mov_b32 s10, 0x20800
	s_mov_b64 s[8:9], exec
	v_mbcnt_lo_u32_b32 v5, s8, 0
	v_mbcnt_hi_u32_b32 v5, s9, v5
	s_waitcnt lgkmcnt(0)
	s_add_u32 s3, s6, 0xfc00000
	s_addc_u32 s26, s7, 0
	s_addk_i32 s10, 0x100
	v_mov_b32_e32 v2, s10
	ds_read_b96 v[2:4], v2
	s_mov_b32 s13, 0
	v_cmp_eq_u32_e32 vcc, 0, v5
	s_waitcnt vmcnt(0) expcnt(0) lgkmcnt(0)
	v_readfirstlane_b32 s10, v2
	s_lshl_b32 s27, s10, 6
	s_and_saveexec_b64 s[10:11], vcc
	s_cbranch_execz .LBB0_186
	s_add_i32 s12, s27, 0x500
	s_lshl_b64 s[12:13], s[12:13], 2
	s_add_u32 s12, s3, s12
	s_addc_u32 s13, s26, s13
	s_bcnt1_i32_b64 s8, s[8:9]
	v_mov_b32_e32 v2, 0
	v_mov_b32_e32 v6, s8
	global_atomic_add v2, v2, v6, s[12:13] sc0

; #define STAGE(P, GP, ktrel) do { const GAS char* _g = (GP) + (ktrel) * (BK * 2); \
;     __builtin_amdgcn_global_load_lds((const GAS unsigned*)(_g + so0), (unsigned*)((char*)(P) + tid_ * 16), 16, 0, 0); \
;     __builtin_amdgcn_global_load_lds((const GAS unsigned*)(_g + so1), (unsigned*)((char*)(P) + tid_ * 16 + 8192), 16, 0, 0); } while (0)
; #define WAIT_V(n) asm volatile("s_waitcnt vmcnt(" #n ")" ::: "memory")
; #define WAIT_L(n) asm volatile("s_waitcnt lgkmcnt(" #n ")" ::: "memory")
; #define BAR __builtin_amdgcn_s_barrier()
; #define SCHED __builtin_amdgcn_sched_barrier(0)
; #define LDA(dst, b, h) for (int m = 0; m < 4; ++m) for (int k = 0; k < 2; ++k) \
;     dst[m][k] = *reinterpret_cast<const bf16x8*>((char*)SA(b, h) + lds_byte(wr * 64 + m * 16 + fr, k * 32 + fq * 8))
; #define LDB(dst, b, h) for (int n = 0; n < 2; ++n) for (int k = 0; k < 2; ++k) \
;     dst[n][k] = *reinterpret_cast<const bf16x8*>((char*)SB(b, h) + lds_byte(wc * 32 + n * 16 + fr, k * 32 + fq * 8))
; #define MMA(ai, bj, At_, Bt_) do { __builtin_amdgcn_s_setprio(1); \
;     for (int m = 0; m < 4; ++m) for (int n = 0; n < 2; ++n) for (int k = 0; k < 2; ++k) \
;       acc[ai][bj][m][n] = __builtin_amdgcn_mfma_f32_16x16x32_bf16(At_[m][k], Bt_[n][k], acc[ai][bj][m][n], 0, 0, 0); \
;     __builtin_amdgcn_s_setprio(0); } while (0)
; template <int K, int LD = K>
; __device__ __forceinline__ void gemm_main(const GAS bf16* A, const GAS bf16* Bt, int brow, int bcol, f32x4 (&acc)[2][2][4][2]) {
;     ...
;     LDB(B0, 0, 0); SCHED; LDA(At, 0, 0); STAGE(SA(1, 1), pA1, 1);
;     WAIT_L(8); BAR; WAIT_L(0); MMA(0, 0, At, B0); BAR; SCHED;
;     LDB(B1, 0, 1); STAGE(SB(0, 0), pB0, 2);
;     BAR; WAIT_L(0); MMA(0, 1, At, B1); BAR;
;     LDA(At, 0, 1); STAGE(SA(0, 0), pA0, 2);
;     BAR; WAIT_L(0); MMA(1, 0, At, B0); BAR; SCHED;
;     STAGE(SB(0, 1), pB1, 2);
;     WAIT_V(6); BAR; MMA(1, 1, At, B1); BAR;
.LBB0_230:
	ds_read_b128 v[160:163], v144
	ds_read_b128 v[164:167], v144 offset:1024
	ds_read_b128 v[174:177], v144 offset:2048
	ds_read_b128 v[178:181], v144 offset:3072
	v_lshl_add_u64 v[168:169], s[12:13], 0, v[130:131]
	v_readfirstlane_b32 s23, v143
	v_lshl_add_u64 v[214:215], v[168:169], 0, s[6:7]
	s_mov_b32 m0, s23
	v_lshl_add_u64 v[230:231], s[12:13], 0, v[132:133]
	v_readfirstlane_b32 s23, v142
	ds_read_b128 v[182:185], v138
	ds_read_b128 v[186:189], v138 offset:1024
	ds_read_b128 v[190:193], v137
	ds_read_b128 v[194:197], v137 offset:1024
	ds_read_b128 v[198:201], v136
	ds_read_b128 v[202:205], v136 offset:1024
	ds_read_b128 v[206:209], v135
	ds_read_b128 v[210:213], v135 offset:1024
	global_load_lds_dwordx4 v[214:215], off
	v_lshl_add_u64 v[214:215], v[230:231], 0, s[6:7]
	s_mov_b32 m0, s23
	s_nop 0
	global_load_lds_dwordx4 v[214:215], off
	s_waitcnt lgkmcnt(8)
	s_waitcnt vmcnt(10)
	s_barrier
	s_waitcnt lgkmcnt(0)
	v_mfma_f32_16x16x32_bf16 v[126:129], v[182:185], v[160:163], v[126:129]
	v_mfma_f32_16x16x32_bf16 v[122:125], v[182:185], v[174:177], v[122:125]
	v_mfma_f32_16x16x32_bf16 v[118:121], v[190:193], v[160:163], v[118:121]
	v_mfma_f32_16x16x32_bf16 v[114:117], v[190:193], v[174:177], v[114:117]
	v_mfma_f32_16x16x32_bf16 v[110:113], v[198:201], v[160:163], v[110:113]
	v_mfma_f32_16x16x32_bf16 v[106:109], v[198:201], v[174:177], v[106:109]
	v_mfma_f32_16x16x32_bf16 v[102:105], v[206:209], v[160:163], v[102:105]
	v_mfma_f32_16x16x32_bf16 v[98:101], v[206:209], v[174:177], v[98:101]
	v_mfma_f32_16x16x32_bf16 v[126:129], v[186:189], v[164:167], v[126:129]
	v_mfma_f32_16x16x32_bf16 v[122:125], v[186:189], v[178:181], v[122:125]
	v_mfma_f32_16x16x32_bf16 v[118:121], v[194:197], v[164:167], v[118:121]
	v_mfma_f32_16x16x32_bf16 v[114:117], v[194:197], v[178:181], v[114:117]
	v_mfma_f32_16x16x32_bf16 v[110:113], v[202:205], v[164:167], v[110:113]
	v_mfma_f32_16x16x32_bf16 v[106:109], v[202:205], v[178:181], v[106:109]
	v_mfma_f32_16x16x32_bf16 v[102:105], v[210:213], v[164:167], v[102:105]
	v_mfma_f32_16x16x32_bf16 v[98:101], v[210:213], v[178:181], v[98:101]
	s_barrier
	v_lshl_add_u64 v[232:233], s[20:21], 0, v[130:131]
	v_readfirstlane_b32 s23, v151
	v_lshl_add_u64 v[234:235], v[232:233], 0, s[8:9]
	s_mov_b32 m0, s23
	ds_read_b128 v[214:217], v141
	ds_read_b128 v[218:221], v141 offset:1024
	ds_read_b128 v[222:225], v141 offset:2048
	ds_read_b128 v[226:229], v141 offset:3072
	global_load_lds_dwordx4 v[234:235], off
	v_lshl_add_u64 v[234:235], s[20:21], 0, v[132:133]
	v_readfirstlane_b32 s23, v152
	v_lshl_add_u64 v[236:237], v[234:235], 0, s[8:9]
	s_mov_b32 m0, s23
	s_add_u32 s20, s20, 0x100
	global_load_lds_dwordx4 v[236:237], off
	s_waitcnt vmcnt(10)
	s_barrier
	s_waitcnt lgkmcnt(0)
	s_addc_u32 s21, s21, 0
	s_waitcnt lgkmcnt(0)
	v_mfma_f32_16x16x32_bf16 v[94:97], v[182:185], v[214:217], v[94:97]
	v_mfma_f32_16x16x32_bf16 v[90:93], v[182:185], v[222:225], v[90:93]
	v_mfma_f32_16x16x32_bf16 v[86:89], v[190:193], v[214:217], v[86:89]
	v_mfma_f32_16x16x32_bf16 v[82:85], v[190:193], v[222:225], v[82:85]
	v_mfma_f32_16x16x32_bf16 v[78:81], v[198:201], v[214:217], v[78:81]
	v_mfma_f32_16x16x32_bf16 v[74:77], v[198:201], v[222:225], v[74:77]
	v_mfma_f32_16x16x32_bf16 v[70:73], v[206:209], v[214:217], v[70:73]
	v_mfma_f32_16x16x32_bf16 v[66:69], v[206:209], v[222:225], v[66:69]
	v_mfma_f32_16x16x32_bf16 v[94:97], v[186:189], v[218:221], v[94:97]
	v_mfma_f32_16x16x32_bf16 v[90:93], v[186:189], v[226:229], v[90:93]
	v_mfma_f32_16x16x32_bf16 v[86:89], v[194:197], v[218:221], v[86:89]
	v_mfma_f32_16x16x32_bf16 v[82:85], v[194:197], v[226:229], v[82:85]
	v_mfma_f32_16x16x32_bf16 v[78:81], v[202:205], v[218:221], v[78:81]
	v_mfma_f32_16x16x32_bf16 v[74:77], v[202:205], v[226:229], v[74:77]
	v_mfma_f32_16x16x32_bf16 v[70:73], v[210:213], v[218:221], v[70:73]
	v_mfma_f32_16x16x32_bf16 v[66:69], v[210:213], v[226:229], v[66:69]
	v_lshl_add_u64 v[236:237], s[18:19], 0, v[130:131]
	v_readfirstlane_b32 s23, v145
	v_lshl_add_u64 v[238:239], v[236:237], 0, s[8:9]
	s_mov_b32 m0, s23
	s_barrier
	ds_read_b128 v[182:185], v138 offset:16384
	ds_read_b128 v[186:189], v138 offset:17408
	ds_read_b128 v[190:193], v137 offset:16384
	ds_read_b128 v[194:197], v137 offset:17408
	ds_read_b128 v[198:201], v136 offset:16384
	ds_read_b128 v[202:205], v136 offset:17408
	ds_read_b128 v[206:209], v135 offset:16384
	ds_read_b128 v[210:213], v135 offset:17408
	global_load_lds_dwordx4 v[238:239], off
	v_lshl_add_u64 v[238:239], s[18:19], 0, v[132:133]
	v_readfirstlane_b32 s23, v146
	v_lshl_add_u64 v[240:241], v[238:239], 0, s[8:9]
	s_mov_b32 m0, s23
	s_add_u32 s18, s18, 0x100
	global_load_lds_dwordx4 v[240:241], off
	s_barrier
	s_waitcnt lgkmcnt(0)
	s_addc_u32 s19, s19, 0
	s_waitcnt lgkmcnt(0)
	v_mfma_f32_16x16x32_bf16 v[62:65], v[182:185], v[160:163], v[62:65]
	v_mfma_f32_16x16x32_bf16 v[58:61], v[182:185], v[174:177], v[58:61]
	v_mfma_f32_16x16x32_bf16 v[54:57], v[190:193], v[160:163], v[54:57]
	v_mfma_f32_16x16x32_bf16 v[50:53], v[190:193], v[174:177], v[50:53]
	v_mfma_f32_16x16x32_bf16 v[46:49], v[198:201], v[160:163], v[46:49]
	v_mfma_f32_16x16x32_bf16 v[42:45], v[198:201], v[174:177], v[42:45]
	v_mfma_f32_16x16x32_bf16 v[38:41], v[206:209], v[160:163], v[38:41]
	v_mfma_f32_16x16x32_bf16 v[34:37], v[206:209], v[174:177], v[34:37]
	v_mfma_f32_16x16x32_bf16 v[62:65], v[186:189], v[164:167], v[62:65]
	v_mfma_f32_16x16x32_bf16 v[58:61], v[186:189], v[178:181], v[58:61]
	v_mfma_f32_16x16x32_bf16 v[54:57], v[194:197], v[164:167], v[54:57]
	v_mfma_f32_16x16x32_bf16 v[50:53], v[194:197], v[178:181], v[50:53]
	v_mfma_f32_16x16x32_bf16 v[46:49], v[202:205], v[164:167], v[46:49]
	v_mfma_f32_16x16x32_bf16 v[42:45], v[202:205], v[178:181], v[42:45]
	v_mfma_f32_16x16x32_bf16 v[38:41], v[210:213], v[164:167], v[38:41]
	v_mfma_f32_16x16x32_bf16 v[34:37], v[210:213], v[178:181], v[34:37]
	s_barrier
; #define STAGE(P, GP, ktrel) do { const GAS char* _g = (GP) + (ktrel) * (BK * 2); \
;     __builtin_amdgcn_global_load_lds((const GAS unsigned*)(_g + so0), (unsigned*)((char*)(P) + tid_ * 16), 16, 0, 0); \
;     __builtin_amdgcn_global_load_lds((const GAS unsigned*)(_g + so1), (unsigned*)((char*)(P) + tid_ * 16 + 8192), 16, 0, 0); } while (0)
; #define WAIT_V(n) asm volatile("s_waitcnt vmcnt(" #n ")" ::: "memory")
; #define WAIT_L(n) asm volatile("s_waitcnt lgkmcnt(" #n ")" ::: "memory")
; #define BAR __builtin_amdgcn_s_barrier()
; #define SCHED __builtin_amdgcn_sched_barrier(0)
; #define LDA(dst, b, h) for (int m = 0; m < 4; ++m) for (int k = 0; k < 2; ++k) \
;     dst[m][k] = *reinterpret_cast<const bf16x8*>((char*)SA(b, h) + lds_byte(wr * 64 + m * 16 + fr, k * 32 + fq * 8))
; #define LDB(dst, b, h) for (int n = 0; n < 2; ++n) for (int k = 0; k < 2; ++k) \
;     dst[n][k] = *reinterpret_cast<const bf16x8*>((char*)SB(b, h) + lds_byte(wc * 32 + n * 16 + fr, k * 32 + fq * 8))
; #define MMA(ai, bj, At_, Bt_) do { __builtin_amdgcn_s_setprio(1); \
;     for (int m = 0; m < 4; ++m) for (int n = 0; n < 2; ++n) for (int k = 0; k < 2; ++k) \
;       acc[ai][bj][m][n] = __builtin_amdgcn_mfma_f32_16x16x32_bf16(At_[m][k], Bt_[n][k], acc[ai][bj][m][n], 0, 0, 0); \
;     __builtin_amdgcn_s_setprio(0); } while (0)
; template <int K, int LD = K>
; __device__ __forceinline__ void gemm_main(const GAS bf16* A, const GAS bf16* Bt, int brow, int bcol, f32x4 (&acc)[2][2][4][2]) {
;     ...
;     WAIT_V(6); BAR; MMA(1, 1, At, B1); BAR;
;     LDB(B0, 1, 0); SCHED; LDA(At, 1, 0); STAGE(SA(0, 1), pA1, 2);
;     WAIT_L(8); BAR; WAIT_L(0); MMA(0, 0, At, B0); BAR; SCHED;
;     LDB(B1, 1, 1); STAGE(SB(1, 0), pB0, 3);
;     BAR; WAIT_L(0); MMA(0, 1, At, B1); BAR;
;     LDA(At, 1, 1); STAGE(SA(1, 0), pA0, 3);
	v_lshl_add_u64 v[240:241], s[16:17], 0, v[130:131]
	v_readfirstlane_b32 s23, v153
	v_lshl_add_u64 v[160:161], v[240:241], 0, s[8:9]
	s_mov_b32 m0, s23
	v_lshl_add_u64 v[242:243], s[16:17], 0, v[132:133]
	v_readfirstlane_b32 s23, v155
	global_load_lds_dwordx4 v[160:161], off
	v_lshl_add_u64 v[160:161], v[242:243], 0, s[8:9]
	s_mov_b32 m0, s23
	s_add_u32 s16, s16, 0x100
	global_load_lds_dwordx4 v[160:161], off
	s_waitcnt vmcnt(10)
	s_addc_u32 s17, s17, 0
	s_barrier
	v_mfma_f32_16x16x32_bf16 v[30:33], v[182:185], v[214:217], v[30:33]
	v_mfma_f32_16x16x32_bf16 v[26:29], v[182:185], v[222:225], v[26:29]
	v_mfma_f32_16x16x32_bf16 v[22:25], v[190:193], v[214:217], v[22:25]
	v_mfma_f32_16x16x32_bf16 v[18:21], v[190:193], v[222:225], v[18:21]
	v_mfma_f32_16x16x32_bf16 v[14:17], v[198:201], v[214:217], v[14:17]
	v_mfma_f32_16x16x32_bf16 v[10:13], v[198:201], v[222:225], v[10:13]
	v_mfma_f32_16x16x32_bf16 v[6:9], v[206:209], v[214:217], v[6:9]
	v_mfma_f32_16x16x32_bf16 v[2:5], v[206:209], v[222:225], v[2:5]
	v_mfma_f32_16x16x32_bf16 v[30:33], v[186:189], v[218:221], v[30:33]
	v_mfma_f32_16x16x32_bf16 v[26:29], v[186:189], v[226:229], v[26:29]
	v_mfma_f32_16x16x32_bf16 v[22:25], v[194:197], v[218:221], v[22:25]
	v_mfma_f32_16x16x32_bf16 v[18:21], v[194:197], v[226:229], v[18:21]
	v_mfma_f32_16x16x32_bf16 v[14:17], v[202:205], v[218:221], v[14:17]
	v_mfma_f32_16x16x32_bf16 v[10:13], v[202:205], v[226:229], v[10:13]
	v_mfma_f32_16x16x32_bf16 v[6:9], v[210:213], v[218:221], v[6:9]
	v_mfma_f32_16x16x32_bf16 v[2:5], v[210:213], v[226:229], v[2:5]
	s_barrier
	ds_read_b128 v[160:163], v140
	ds_read_b128 v[164:167], v140 offset:1024
	ds_read_b128 v[174:177], v140 offset:2048
	ds_read_b128 v[178:181], v140 offset:3072
	v_readfirstlane_b32 s23, v147
	v_lshl_add_u64 v[168:169], v[168:169], 0, s[8:9]
	s_mov_b32 m0, s23
	v_readfirstlane_b32 s23, v148
	ds_read_b128 v[182:185], v138 offset:32768
	ds_read_b128 v[186:189], v138 offset:33792
	ds_read_b128 v[190:193], v137 offset:32768
	ds_read_b128 v[194:197], v137 offset:33792
	ds_read_b128 v[198:201], v136 offset:32768
	ds_read_b128 v[202:205], v136 offset:33792
	ds_read_b128 v[206:209], v135 offset:32768
	ds_read_b128 v[210:213], v135 offset:33792
	global_load_lds_dwordx4 v[168:169], off
	v_lshl_add_u64 v[168:169], v[230:231], 0, s[8:9]
	s_mov_b32 m0, s23
	s_add_u32 s12, s12, 0x100
	global_load_lds_dwordx4 v[168:169], off
	s_waitcnt lgkmcnt(8)
	s_waitcnt vmcnt(10)
	s_barrier
	s_waitcnt lgkmcnt(0)
	s_addc_u32 s13, s13, 0
	s_waitcnt lgkmcnt(0)
	v_mfma_f32_16x16x32_bf16 v[126:129], v[182:185], v[160:163], v[126:129]
	v_mfma_f32_16x16x32_bf16 v[122:125], v[182:185], v[174:177], v[122:125]
	v_mfma_f32_16x16x32_bf16 v[118:121], v[190:193], v[160:163], v[118:121]
	v_mfma_f32_16x16x32_bf16 v[114:117], v[190:193], v[174:177], v[114:117]
	v_mfma_f32_16x16x32_bf16 v[110:113], v[198:201], v[160:163], v[110:113]
	v_mfma_f32_16x16x32_bf16 v[106:109], v[198:201], v[174:177], v[106:109]
	v_mfma_f32_16x16x32_bf16 v[102:105], v[206:209], v[160:163], v[102:105]
	v_mfma_f32_16x16x32_bf16 v[98:101], v[206:209], v[174:177], v[98:101]
	v_mfma_f32_16x16x32_bf16 v[126:129], v[186:189], v[164:167], v[126:129]
	v_mfma_f32_16x16x32_bf16 v[122:125], v[186:189], v[178:181], v[122:125]
	v_mfma_f32_16x16x32_bf16 v[118:121], v[194:197], v[164:167], v[118:121]
	v_mfma_f32_16x16x32_bf16 v[114:117], v[194:197], v[178:181], v[114:117]
	v_mfma_f32_16x16x32_bf16 v[110:113], v[202:205], v[164:167], v[110:113]
	v_mfma_f32_16x16x32_bf16 v[106:109], v[202:205], v[178:181], v[106:109]
	v_mfma_f32_16x16x32_bf16 v[102:105], v[210:213], v[164:167], v[102:105]
	v_mfma_f32_16x16x32_bf16 v[98:101], v[210:213], v[178:181], v[98:101]
	s_barrier
	v_readfirstlane_b32 s23, v156
	v_lshl_add_u64 v[168:169], v[232:233], 0, s[10:11]
	s_mov_b32 m0, s23
	v_readfirstlane_b32 s23, v157
	ds_read_b128 v[214:217], v139
	ds_read_b128 v[218:221], v139 offset:1024
	ds_read_b128 v[222:225], v139 offset:2048
	ds_read_b128 v[226:229], v139 offset:3072
	global_load_lds_dwordx4 v[168:169], off
	v_lshl_add_u64 v[168:169], v[234:235], 0, s[10:11]
	s_mov_b32 m0, s23
	s_nop 0
	global_load_lds_dwordx4 v[168:169], off
	s_waitcnt vmcnt(10)
	s_barrier
	s_waitcnt lgkmcnt(0)
	v_mfma_f32_16x16x32_bf16 v[94:97], v[182:185], v[214:217], v[94:97]
	v_mfma_f32_16x16x32_bf16 v[90:93], v[182:185], v[222:225], v[90:93]
	v_mfma_f32_16x16x32_bf16 v[86:89], v[190:193], v[214:217], v[86:89]
	v_mfma_f32_16x16x32_bf16 v[82:85], v[190:193], v[222:225], v[82:85]
	v_mfma_f32_16x16x32_bf16 v[78:81], v[198:201], v[214:217], v[78:81]
	v_mfma_f32_16x16x32_bf16 v[74:77], v[198:201], v[222:225], v[74:77]
	v_mfma_f32_16x16x32_bf16 v[70:73], v[206:209], v[214:217], v[70:73]
	v_mfma_f32_16x16x32_bf16 v[66:69], v[206:209], v[222:225], v[66:69]
	v_mfma_f32_16x16x32_bf16 v[94:97], v[186:189], v[218:221], v[94:97]
	v_mfma_f32_16x16x32_bf16 v[90:93], v[186:189], v[226:229], v[90:93]
	v_mfma_f32_16x16x32_bf16 v[86:89], v[194:197], v[218:221], v[86:89]
	v_mfma_f32_16x16x32_bf16 v[82:85], v[194:197], v[226:229], v[82:85]
	v_mfma_f32_16x16x32_bf16 v[78:81], v[202:205], v[218:221], v[78:81]
	v_mfma_f32_16x16x32_bf16 v[74:77], v[202:205], v[226:229], v[74:77]
	v_mfma_f32_16x16x32_bf16 v[70:73], v[210:213], v[218:221], v[70:73]
	v_mfma_f32_16x16x32_bf16 v[66:69], v[210:213], v[226:229], v[66:69]
	v_readfirstlane_b32 s23, v149
	v_lshl_add_u64 v[168:169], v[236:237], 0, s[10:11]
	s_mov_b32 m0, s23
	v_readfirstlane_b32 s23, v150
	s_barrier
; #define STAGE(P, GP, ktrel) do { const GAS char* _g = (GP) + (ktrel) * (BK * 2); \
;     __builtin_amdgcn_global_load_lds((const GAS unsigned*)(_g + so0), (unsigned*)((char*)(P) + tid_ * 16), 16, 0, 0); \
;     __builtin_amdgcn_global_load_lds((const GAS unsigned*)(_g + so1), (unsigned*)((char*)(P) + tid_ * 16 + 8192), 16, 0, 0); } while (0)
; #define WAIT_V(n) asm volatile("s_waitcnt vmcnt(" #n ")" ::: "memory")
; #define WAIT_L(n) asm volatile("s_waitcnt lgkmcnt(" #n ")" ::: "memory")
; #define BAR __builtin_amdgcn_s_barrier()
; #define SCHED __builtin_amdgcn_sched_barrier(0)
; #define LDA(dst, b, h) for (int m = 0; m < 4; ++m) for (int k = 0; k < 2; ++k) \
;     dst[m][k] = *reinterpret_cast<const bf16x8*>((char*)SA(b, h) + lds_byte(wr * 64 + m * 16 + fr, k * 32 + fq * 8))
; #define LDB(dst, b, h) for (int n = 0; n < 2; ++n) for (int k = 0; k < 2; ++k) \
;     dst[n][k] = *reinterpret_cast<const bf16x8*>((char*)SB(b, h) + lds_byte(wc * 32 + n * 16 + fr, k * 32 + fq * 8))
; #define MMA(ai, bj, At_, Bt_) do { __builtin_amdgcn_s_setprio(1); \
;     for (int m = 0; m < 4; ++m) for (int n = 0; n < 2; ++n) for (int k = 0; k < 2; ++k) \
;       acc[ai][bj][m][n] = __builtin_amdgcn_mfma_f32_16x16x32_bf16(At_[m][k], Bt_[n][k], acc[ai][bj][m][n], 0, 0, 0); \
;     __builtin_amdgcn_s_setprio(0); } while (0)
; template <int K, int LD = K>
; __device__ __forceinline__ void gemm_main(const GAS bf16* A, const GAS bf16* Bt, int brow, int bcol, f32x4 (&acc)[2][2][4][2]) {
;     ...
;     LDA(At, 1, 1); STAGE(SA(1, 0), pA0, 3);
;     BAR; WAIT_L(0); MMA(1, 0, At, B0); BAR; SCHED;
;     STAGE(SB(1, 1), pB1, 3);
;     WAIT_V(6); BAR; MMA(1, 1, At, B1); BAR;
;     pA0 += 4 * BK; pA1 += 4 * BK; pB0 += 4 * BK; pB1 += 4 * BK;
;     asm volatile("" : "+s"(pA0), "+s"(pA1), "+s"(pB0), "+s"(pB1));
;   }
;   { LDB(B0, 0, 0); LDA(At, 0, 0); STAGE(SA(1, 1), pA1, 1);
;     BAR; WAIT_L(0); MMA(0, 0, At, B0); BAR;
;     LDB(B1, 0, 1); BAR; WAIT_L(0); MMA(0, 1, At, B1); BAR;
;     LDA(At, 0, 1); WAIT_V(4); BAR; WAIT_L(0); MMA(1, 0, At, B0); MMA(1, 1, At, B1); BAR; }
	ds_read_b128 v[182:185], v138 offset:49152
	ds_read_b128 v[186:189], v138 offset:50176
	ds_read_b128 v[190:193], v137 offset:49152
	ds_read_b128 v[194:197], v137 offset:50176
	ds_read_b128 v[198:201], v136 offset:49152
	ds_read_b128 v[202:205], v136 offset:50176
	ds_read_b128 v[206:209], v135 offset:49152
	ds_read_b128 v[210:213], v135 offset:50176
	global_load_lds_dwordx4 v[168:169], off
	v_lshl_add_u64 v[168:169], v[238:239], 0, s[10:11]
	s_mov_b32 m0, s23
	s_nop 0
	global_load_lds_dwordx4 v[168:169], off
	s_barrier
	s_waitcnt lgkmcnt(0)
	v_mfma_f32_16x16x32_bf16 v[62:65], v[182:185], v[160:163], v[62:65]
	v_mfma_f32_16x16x32_bf16 v[58:61], v[182:185], v[174:177], v[58:61]
	v_mfma_f32_16x16x32_bf16 v[54:57], v[190:193], v[160:163], v[54:57]
	v_mfma_f32_16x16x32_bf16 v[50:53], v[190:193], v[174:177], v[50:53]
	v_mfma_f32_16x16x32_bf16 v[46:49], v[198:201], v[160:163], v[46:49]
	v_mfma_f32_16x16x32_bf16 v[42:45], v[198:201], v[174:177], v[42:45]
	v_mfma_f32_16x16x32_bf16 v[38:41], v[206:209], v[160:163], v[38:41]
	v_mfma_f32_16x16x32_bf16 v[34:37], v[206:209], v[174:177], v[34:37]
	v_mfma_f32_16x16x32_bf16 v[62:65], v[186:189], v[164:167], v[62:65]
	v_mfma_f32_16x16x32_bf16 v[58:61], v[186:189], v[178:181], v[58:61]
	v_mfma_f32_16x16x32_bf16 v[54:57], v[194:197], v[164:167], v[54:57]
	v_mfma_f32_16x16x32_bf16 v[50:53], v[194:197], v[178:181], v[50:53]
	v_mfma_f32_16x16x32_bf16 v[46:49], v[202:205], v[164:167], v[46:49]
	v_mfma_f32_16x16x32_bf16 v[42:45], v[202:205], v[178:181], v[42:45]
	v_mfma_f32_16x16x32_bf16 v[38:41], v[210:213], v[164:167], v[38:41]
	v_mfma_f32_16x16x32_bf16 v[34:37], v[210:213], v[178:181], v[34:37]
	s_barrier
	v_readfirstlane_b32 s23, v158
	v_lshl_add_u64 v[160:161], v[240:241], 0, s[10:11]
	s_mov_b32 m0, s23
	v_readfirstlane_b32 s23, v159
	global_load_lds_dwordx4 v[160:161], off
	v_lshl_add_u64 v[160:161], v[242:243], 0, s[10:11]
	s_mov_b32 m0, s23
	s_nop 0
	global_load_lds_dwordx4 v[160:161], off
	s_waitcnt vmcnt(10)
	s_barrier
	v_mfma_f32_16x16x32_bf16 v[30:33], v[182:185], v[214:217], v[30:33]
	v_mfma_f32_16x16x32_bf16 v[26:29], v[182:185], v[222:225], v[26:29]
	v_mfma_f32_16x16x32_bf16 v[22:25], v[190:193], v[214:217], v[22:25]
	v_mfma_f32_16x16x32_bf16 v[18:21], v[190:193], v[222:225], v[18:21]
	v_mfma_f32_16x16x32_bf16 v[14:17], v[198:201], v[214:217], v[14:17]
	v_mfma_f32_16x16x32_bf16 v[10:13], v[198:201], v[222:225], v[10:13]
	v_mfma_f32_16x16x32_bf16 v[6:9], v[206:209], v[214:217], v[6:9]
	v_mfma_f32_16x16x32_bf16 v[2:5], v[206:209], v[222:225], v[2:5]
	v_mfma_f32_16x16x32_bf16 v[30:33], v[186:189], v[218:221], v[30:33]
	v_mfma_f32_16x16x32_bf16 v[26:29], v[186:189], v[226:229], v[26:29]
	v_mfma_f32_16x16x32_bf16 v[22:25], v[194:197], v[218:221], v[22:25]
	v_mfma_f32_16x16x32_bf16 v[18:21], v[194:197], v[226:229], v[18:21]
	v_mfma_f32_16x16x32_bf16 v[14:17], v[202:205], v[218:221], v[14:17]
	v_mfma_f32_16x16x32_bf16 v[10:13], v[202:205], v[226:229], v[10:13]
	v_mfma_f32_16x16x32_bf16 v[6:9], v[210:213], v[218:221], v[6:9]
	v_mfma_f32_16x16x32_bf16 v[2:5], v[210:213], v[226:229], v[2:5]
	s_add_i32 s22, s22, 2
	s_cmp_lt_u32 s22, 40
	s_barrier
	s_cbranch_scc1 .LBB0_230
	ds_read_b128 v[146:149], v144
	ds_read_b128 v[150:153], v144 offset:1024
	ds_read_b128 v[156:159], v144 offset:2048
	ds_read_b128 v[160:163], v144 offset:3072
	ds_read_b128 v[164:167], v138
	ds_read_b128 v[174:177], v138 offset:1024
	ds_read_b128 v[178:181], v137
	ds_read_b128 v[182:185], v137 offset:1024
	ds_read_b128 v[186:189], v136
	ds_read_b128 v[190:193], v136 offset:1024
	ds_read_b128 v[194:197], v135
	ds_read_b128 v[198:201], v135 offset:1024
	v_lshl_add_u64 v[144:145], s[12:13], 0, v[130:131]
	v_readfirstlane_b32 s16, v143
	v_lshl_add_u64 v[144:145], v[144:145], 0, s[6:7]
	s_mov_b32 m0, s16
	v_lshl_add_u64 v[132:133], s[12:13], 0, v[132:133]
	v_readfirstlane_b32 s12, v142
	global_load_lds_dwordx4 v[144:145], off
	v_lshl_add_u64 v[132:133], v[132:133], 0, s[6:7]
	s_mov_b32 m0, s12
	s_nop 0
	global_load_lds_dwordx4 v[132:133], off
	s_waitcnt vmcnt(10)
	s_barrier
	s_waitcnt lgkmcnt(0)
	v_mfma_f32_16x16x32_bf16 v[126:129], v[164:167], v[146:149], v[126:129]
	v_mfma_f32_16x16x32_bf16 v[122:125], v[164:167], v[156:159], v[122:125]
	v_mfma_f32_16x16x32_bf16 v[110:113], v[186:189], v[146:149], v[110:113]
	v_mfma_f32_16x16x32_bf16 v[106:109], v[186:189], v[156:159], v[106:109]
	v_mfma_f32_16x16x32_bf16 v[126:129], v[174:177], v[150:153], v[126:129]
	v_mfma_f32_16x16x32_bf16 v[122:125], v[174:177], v[160:163], v[122:125]
	v_mfma_f32_16x16x32_bf16 v[118:121], v[178:181], v[146:149], v[118:121]
	v_mfma_f32_16x16x32_bf16 v[114:117], v[178:181], v[156:159], v[114:117]
	v_mfma_f32_16x16x32_bf16 v[110:113], v[190:193], v[150:153], v[110:113]
	v_mfma_f32_16x16x32_bf16 v[106:109], v[190:193], v[160:163], v[106:109]
	v_mfma_f32_16x16x32_bf16 v[102:105], v[194:197], v[146:149], v[102:105]
	v_mfma_f32_16x16x32_bf16 v[98:101], v[194:197], v[156:159], v[98:101]
	v_mfma_f32_16x16x32_bf16 v[142:145], v[182:185], v[150:153], v[118:121]
	v_mfma_f32_16x16x32_bf16 v[202:205], v[182:185], v[160:163], v[114:117]
	v_mfma_f32_16x16x32_bf16 v[206:209], v[198:201], v[150:153], v[102:105]
	v_mfma_f32_16x16x32_bf16 v[210:213], v[198:201], v[160:163], v[98:101]
	s_barrier
	s_nop 1
	ds_read_b128 v[98:101], v141
	ds_read_b128 v[102:105], v141 offset:1024
	ds_read_b128 v[114:117], v141 offset:2048
	ds_read_b128 v[118:121], v141 offset:3072
	s_waitcnt vmcnt(8)
	s_barrier
; #define WAIT_V(n) asm volatile("s_waitcnt vmcnt(" #n ")" ::: "memory")
; #define WAIT_L(n) asm volatile("s_waitcnt lgkmcnt(" #n ")" ::: "memory")
; #define BAR __builtin_amdgcn_s_barrier()
; #define LDA(dst, b, h) for (int m = 0; m < 4; ++m) for (int k = 0; k < 2; ++k) \
;     dst[m][k] = *reinterpret_cast<const bf16x8*>((char*)SA(b, h) + lds_byte(wr * 64 + m * 16 + fr, k * 32 + fq * 8))
; #define LDB(dst, b, h) for (int n = 0; n < 2; ++n) for (int k = 0; k < 2; ++k) \
;     dst[n][k] = *reinterpret_cast<const bf16x8*>((char*)SB(b, h) + lds_byte(wc * 32 + n * 16 + fr, k * 32 + fq * 8))
; #define MMA(ai, bj, At_, Bt_) do { __builtin_amdgcn_s_setprio(1); \
;     for (int m = 0; m < 4; ++m) for (int n = 0; n < 2; ++n) for (int k = 0; k < 2; ++k) \
;       acc[ai][bj][m][n] = __builtin_amdgcn_mfma_f32_16x16x32_bf16(At_[m][k], Bt_[n][k], acc[ai][bj][m][n], 0, 0, 0); \
;     __builtin_amdgcn_s_setprio(0); } while (0)
; template <int K, int LD = K>
; __device__ __forceinline__ void gemm_main(const GAS bf16* A, const GAS bf16* Bt, int brow, int bcol, f32x4 (&acc)[2][2][4][2]) {
;     ...
;     LDA(At, 0, 1); WAIT_V(4); BAR; WAIT_L(0); MMA(1, 0, At, B0); MMA(1, 1, At, B1); BAR; }
;   { LDB(B0, 1, 0); LDA(At, 1, 0); WAIT_V(2); BAR; WAIT_L(0); MMA(0, 0, At, B0); BAR;
;     LDB(B1, 1, 1); WAIT_V(0); BAR; WAIT_L(0); MMA(0, 1, At, B1); BAR;
	s_waitcnt lgkmcnt(0)
	v_mfma_f32_16x16x32_bf16 v[94:97], v[164:167], v[98:101], v[94:97]
	v_mfma_f32_16x16x32_bf16 v[90:93], v[164:167], v[114:117], v[90:93]
	v_mfma_f32_16x16x32_bf16 v[78:81], v[186:189], v[98:101], v[78:81]
	v_mfma_f32_16x16x32_bf16 v[74:77], v[186:189], v[114:117], v[74:77]
	v_mfma_f32_16x16x32_bf16 v[94:97], v[174:177], v[102:105], v[94:97]
	v_mfma_f32_16x16x32_bf16 v[90:93], v[174:177], v[118:121], v[90:93]
	v_mfma_f32_16x16x32_bf16 v[86:89], v[178:181], v[98:101], v[86:89]
	v_mfma_f32_16x16x32_bf16 v[82:85], v[178:181], v[114:117], v[82:85]
	v_mfma_f32_16x16x32_bf16 v[78:81], v[190:193], v[102:105], v[78:81]
	v_mfma_f32_16x16x32_bf16 v[74:77], v[190:193], v[118:121], v[74:77]
	v_mfma_f32_16x16x32_bf16 v[70:73], v[194:197], v[98:101], v[70:73]
	v_mfma_f32_16x16x32_bf16 v[66:69], v[194:197], v[114:117], v[66:69]
	v_mfma_f32_16x16x32_bf16 v[164:167], v[182:185], v[102:105], v[86:89]
	v_mfma_f32_16x16x32_bf16 v[174:177], v[182:185], v[118:121], v[82:85]
	v_mfma_f32_16x16x32_bf16 v[178:181], v[198:201], v[102:105], v[70:73]
	v_mfma_f32_16x16x32_bf16 v[182:185], v[198:201], v[118:121], v[66:69]
	s_barrier
	s_nop 1
	ds_read_b128 v[66:69], v138 offset:16384
	ds_read_b128 v[70:73], v138 offset:17408
	ds_read_b128 v[82:85], v137 offset:16384
	ds_read_b128 v[86:89], v137 offset:17408
	ds_read_b128 v[186:189], v136 offset:16384
	ds_read_b128 v[190:193], v136 offset:17408
	ds_read_b128 v[194:197], v135 offset:16384
	ds_read_b128 v[198:201], v135 offset:17408
	s_waitcnt vmcnt(4)
	s_barrier
	s_waitcnt lgkmcnt(0)
	v_mfma_f32_16x16x32_bf16 v[62:65], v[66:69], v[146:149], v[62:65]
	v_mfma_f32_16x16x32_bf16 v[58:61], v[66:69], v[156:159], v[58:61]
	v_mfma_f32_16x16x32_bf16 v[46:49], v[186:189], v[146:149], v[46:49]
	v_mfma_f32_16x16x32_bf16 v[42:45], v[186:189], v[156:159], v[42:45]
	v_mfma_f32_16x16x32_bf16 v[62:65], v[70:73], v[150:153], v[62:65]
	v_mfma_f32_16x16x32_bf16 v[58:61], v[70:73], v[160:163], v[58:61]
	v_mfma_f32_16x16x32_bf16 v[54:57], v[82:85], v[146:149], v[54:57]
	v_mfma_f32_16x16x32_bf16 v[50:53], v[82:85], v[156:159], v[50:53]
	v_mfma_f32_16x16x32_bf16 v[46:49], v[190:193], v[150:153], v[46:49]
	v_mfma_f32_16x16x32_bf16 v[42:45], v[190:193], v[160:163], v[42:45]
	v_mfma_f32_16x16x32_bf16 v[38:41], v[194:197], v[146:149], v[38:41]
	v_mfma_f32_16x16x32_bf16 v[34:37], v[194:197], v[156:159], v[34:37]
	v_mfma_f32_16x16x32_bf16 v[214:217], v[86:89], v[150:153], v[54:57]
	v_mfma_f32_16x16x32_bf16 v[218:221], v[86:89], v[160:163], v[50:53]
	v_mfma_f32_16x16x32_bf16 v[146:149], v[198:201], v[150:153], v[38:41]
	v_mfma_f32_16x16x32_bf16 v[150:153], v[198:201], v[160:163], v[34:37]
	v_mfma_f32_16x16x32_bf16 v[30:33], v[66:69], v[98:101], v[30:33]
	v_mfma_f32_16x16x32_bf16 v[26:29], v[66:69], v[114:117], v[26:29]
	v_mfma_f32_16x16x32_bf16 v[14:17], v[186:189], v[98:101], v[14:17]
	v_mfma_f32_16x16x32_bf16 v[10:13], v[186:189], v[114:117], v[10:13]
	v_mfma_f32_16x16x32_bf16 v[30:33], v[70:73], v[102:105], v[30:33]
	v_mfma_f32_16x16x32_bf16 v[26:29], v[70:73], v[118:121], v[26:29]
	v_mfma_f32_16x16x32_bf16 v[22:25], v[82:85], v[98:101], v[22:25]
	v_mfma_f32_16x16x32_bf16 v[18:21], v[82:85], v[114:117], v[18:21]
	v_mfma_f32_16x16x32_bf16 v[14:17], v[190:193], v[102:105], v[14:17]
	v_mfma_f32_16x16x32_bf16 v[10:13], v[190:193], v[118:121], v[10:13]
	v_mfma_f32_16x16x32_bf16 v[6:9], v[194:197], v[98:101], v[6:9]
	v_mfma_f32_16x16x32_bf16 v[2:5], v[194:197], v[114:117], v[2:5]
	v_mfma_f32_16x16x32_bf16 v[156:159], v[86:89], v[102:105], v[22:25]
	v_mfma_f32_16x16x32_bf16 v[160:163], v[86:89], v[118:121], v[18:21]
	v_mfma_f32_16x16x32_bf16 v[186:189], v[198:201], v[102:105], v[6:9]
	v_mfma_f32_16x16x32_bf16 v[190:193], v[198:201], v[118:121], v[2:5]
	s_barrier
	s_nop 1
	ds_read_b128 v[2:5], v140
	ds_read_b128 v[6:9], v140 offset:1024
	ds_read_b128 v[194:197], v140 offset:2048
	ds_read_b128 v[198:201], v140 offset:3072
	ds_read_b128 v[18:21], v138 offset:32768
	ds_read_b128 v[22:25], v138 offset:33792
	ds_read_b128 v[34:37], v137 offset:32768
	ds_read_b128 v[38:41], v137 offset:33792
	ds_read_b128 v[50:53], v136 offset:32768
	ds_read_b128 v[54:57], v136 offset:33792
	ds_read_b128 v[222:225], v135 offset:32768
	ds_read_b128 v[226:229], v135 offset:33792
	s_waitcnt vmcnt(2)
	s_barrier
; #define WAIT_V(n) asm volatile("s_waitcnt vmcnt(" #n ")" ::: "memory")
; #define WAIT_L(n) asm volatile("s_waitcnt lgkmcnt(" #n ")" ::: "memory")
; #define BAR __builtin_amdgcn_s_barrier()
; #define LDA(dst, b, h) for (int m = 0; m < 4; ++m) for (int k = 0; k < 2; ++k) \
;     dst[m][k] = *reinterpret_cast<const bf16x8*>((char*)SA(b, h) + lds_byte(wr * 64 + m * 16 + fr, k * 32 + fq * 8))
; #define LDB(dst, b, h) for (int n = 0; n < 2; ++n) for (int k = 0; k < 2; ++k) \
;     dst[n][k] = *reinterpret_cast<const bf16x8*>((char*)SB(b, h) + lds_byte(wc * 32 + n * 16 + fr, k * 32 + fq * 8))
; #define MMA(ai, bj, At_, Bt_) do { __builtin_amdgcn_s_setprio(1); \
;     for (int m = 0; m < 4; ++m) for (int n = 0; n < 2; ++n) for (int k = 0; k < 2; ++k) \
;       acc[ai][bj][m][n] = __builtin_amdgcn_mfma_f32_16x16x32_bf16(At_[m][k], Bt_[n][k], acc[ai][bj][m][n], 0, 0, 0); \
;     __builtin_amdgcn_s_setprio(0); } while (0)
; template <int K, int LD = K>
; __device__ __forceinline__ void gemm_main(const GAS bf16* A, const GAS bf16* Bt, int brow, int bcol, f32x4 (&acc)[2][2][4][2]) {
;     ...
;     LDB(B1, 1, 1); WAIT_V(0); BAR; WAIT_L(0); MMA(0, 1, At, B1); BAR;
;     LDA(At, 1, 1); BAR; WAIT_L(0); MMA(1, 0, At, B0); MMA(1, 1, At, B1); BAR; }
;   if (wr == 0) BAR;
	s_waitcnt lgkmcnt(0)
	v_mfma_f32_16x16x32_bf16 v[66:69], v[18:21], v[2:5], v[126:129]
	v_mfma_f32_16x16x32_bf16 v[118:121], v[22:25], v[6:9], v[66:69]
	v_mfma_f32_16x16x32_bf16 v[66:69], v[18:21], v[194:197], v[122:125]
	v_mfma_f32_16x16x32_bf16 v[114:117], v[22:25], v[198:201], v[66:69]
	v_mfma_f32_16x16x32_bf16 v[66:69], v[34:37], v[2:5], v[142:145]
	v_mfma_f32_16x16x32_bf16 v[102:105], v[38:41], v[6:9], v[66:69]
	v_mfma_f32_16x16x32_bf16 v[66:69], v[34:37], v[194:197], v[202:205]
	v_mfma_f32_16x16x32_bf16 v[98:101], v[38:41], v[198:201], v[66:69]
	v_mfma_f32_16x16x32_bf16 v[66:69], v[50:53], v[2:5], v[110:113]
	v_mfma_f32_16x16x32_bf16 v[86:89], v[54:57], v[6:9], v[66:69]
	v_mfma_f32_16x16x32_bf16 v[66:69], v[50:53], v[194:197], v[106:109]
	v_mfma_f32_16x16x32_bf16 v[82:85], v[54:57], v[198:201], v[66:69]
	v_mfma_f32_16x16x32_bf16 v[66:69], v[222:225], v[2:5], v[206:209]
	v_mfma_f32_16x16x32_bf16 v[70:73], v[226:229], v[6:9], v[66:69]
	v_mfma_f32_16x16x32_bf16 v[66:69], v[222:225], v[194:197], v[210:213]
	v_mfma_f32_16x16x32_bf16 v[66:69], v[226:229], v[198:201], v[66:69]
	s_barrier
	ds_read_b128 v[140:143], v139
	ds_read_b128 v[202:205], v139 offset:1024
	ds_read_b128 v[206:209], v139 offset:2048
	ds_read_b128 v[210:213], v139 offset:3072
	s_waitcnt vmcnt(0)
	s_barrier
	s_waitcnt lgkmcnt(0)
	v_mfma_f32_16x16x32_bf16 v[94:97], v[18:21], v[140:143], v[94:97]
	v_mfma_f32_16x16x32_bf16 v[18:21], v[18:21], v[206:209], v[90:93]
	v_mfma_f32_16x16x32_bf16 v[122:125], v[22:25], v[210:213], v[18:21]
	v_mfma_f32_16x16x32_bf16 v[18:21], v[34:37], v[140:143], v[164:167]
	v_mfma_f32_16x16x32_bf16 v[110:113], v[38:41], v[202:205], v[18:21]
	v_mfma_f32_16x16x32_bf16 v[18:21], v[34:37], v[206:209], v[174:177]
	v_mfma_f32_16x16x32_bf16 v[106:109], v[38:41], v[210:213], v[18:21]
	v_mfma_f32_16x16x32_bf16 v[18:21], v[50:53], v[140:143], v[78:81]
	v_mfma_f32_16x16x32_bf16 v[126:129], v[22:25], v[202:205], v[94:97]
	v_mfma_f32_16x16x32_bf16 v[94:97], v[54:57], v[202:205], v[18:21]
	v_mfma_f32_16x16x32_bf16 v[18:21], v[50:53], v[206:209], v[74:77]
	v_mfma_f32_16x16x32_bf16 v[90:93], v[54:57], v[210:213], v[18:21]
	v_mfma_f32_16x16x32_bf16 v[18:21], v[222:225], v[140:143], v[178:181]
	v_mfma_f32_16x16x32_bf16 v[78:81], v[226:229], v[202:205], v[18:21]
	v_mfma_f32_16x16x32_bf16 v[18:21], v[222:225], v[206:209], v[182:185]
	v_mfma_f32_16x16x32_bf16 v[74:77], v[226:229], v[210:213], v[18:21]
	s_barrier
	ds_read_b128 v[164:167], v138 offset:49152
	ds_read_b128 v[174:177], v138 offset:50176
	ds_read_b128 v[178:181], v137 offset:49152
	ds_read_b128 v[182:185], v137 offset:50176
	ds_read_b128 v[222:225], v136 offset:49152
	ds_read_b128 v[136:139], v136 offset:50176
	ds_read_b128 v[226:229], v135 offset:49152
	ds_read_b128 v[230:233], v135 offset:50176
	s_barrier
	s_waitcnt lgkmcnt(0)
	v_mfma_f32_16x16x32_bf16 v[18:21], v[164:167], v[2:5], v[62:65]
	v_mfma_f32_16x16x32_bf16 v[54:57], v[174:177], v[6:9], v[18:21]
	v_mfma_f32_16x16x32_bf16 v[18:21], v[164:167], v[194:197], v[58:61]
	v_mfma_f32_16x16x32_bf16 v[50:53], v[174:177], v[198:201], v[18:21]
	v_mfma_f32_16x16x32_bf16 v[18:21], v[178:181], v[2:5], v[214:217]
	v_mfma_f32_16x16x32_bf16 v[38:41], v[182:185], v[6:9], v[18:21]
	v_mfma_f32_16x16x32_bf16 v[18:21], v[178:181], v[194:197], v[218:221]
	v_mfma_f32_16x16x32_bf16 v[34:37], v[182:185], v[198:201], v[18:21]
	v_mfma_f32_16x16x32_bf16 v[18:21], v[222:225], v[2:5], v[46:49]
	v_mfma_f32_16x16x32_bf16 v[2:5], v[226:229], v[2:5], v[146:149]
	v_mfma_f32_16x16x32_bf16 v[22:25], v[136:139], v[6:9], v[18:21]
	v_mfma_f32_16x16x32_bf16 v[18:21], v[222:225], v[194:197], v[42:45]
	v_mfma_f32_16x16x32_bf16 v[6:9], v[230:233], v[6:9], v[2:5]
	v_mfma_f32_16x16x32_bf16 v[2:5], v[226:229], v[194:197], v[150:153]
	v_mfma_f32_16x16x32_bf16 v[18:21], v[136:139], v[198:201], v[18:21]
	v_mfma_f32_16x16x32_bf16 v[2:5], v[230:233], v[198:201], v[2:5]
	v_mfma_f32_16x16x32_bf16 v[26:29], v[164:167], v[206:209], v[26:29]
	v_mfma_f32_16x16x32_bf16 v[58:61], v[174:177], v[210:213], v[26:29]
	v_mfma_f32_16x16x32_bf16 v[26:29], v[178:181], v[140:143], v[156:159]
	v_mfma_f32_16x16x32_bf16 v[46:49], v[182:185], v[202:205], v[26:29]
	v_mfma_f32_16x16x32_bf16 v[26:29], v[178:181], v[206:209], v[160:163]
	v_mfma_f32_16x16x32_bf16 v[10:13], v[222:225], v[206:209], v[10:13]
	v_mfma_f32_16x16x32_bf16 v[30:33], v[164:167], v[140:143], v[30:33]
	v_mfma_f32_16x16x32_bf16 v[42:45], v[182:185], v[210:213], v[26:29]
	v_mfma_f32_16x16x32_bf16 v[14:17], v[222:225], v[140:143], v[14:17]
	v_mfma_f32_16x16x32_bf16 v[26:29], v[136:139], v[210:213], v[10:13]
	v_mfma_f32_16x16x32_bf16 v[10:13], v[226:229], v[140:143], v[186:189]
	v_mfma_f32_16x16x32_bf16 v[62:65], v[174:177], v[202:205], v[30:33]
	v_mfma_f32_16x16x32_bf16 v[30:33], v[136:139], v[202:205], v[14:17]
	v_mfma_f32_16x16x32_bf16 v[14:17], v[230:233], v[202:205], v[10:13]
	v_mfma_f32_16x16x32_bf16 v[10:13], v[226:229], v[206:209], v[190:193]
	v_mfma_f32_16x16x32_bf16 v[10:13], v[230:233], v[210:213], v[10:13]
	v_cmp_gt_u32_e32 vcc, s35, v134
	s_barrier
	s_and_saveexec_b64 s[12:13], vcc
	s_cbranch_execz .LBB0_233
	s_barrier

; #define STAGE(P, GP, ktrel) do { const GAS char* _g = (GP) + (ktrel) * (BK * 2); \
;     __builtin_amdgcn_global_load_lds((const GAS unsigned*)(_g + so0), (unsigned*)((char*)(P) + tid_ * 16), 16, 0, 0); \
;     __builtin_amdgcn_global_load_lds((const GAS unsigned*)(_g + so1), (unsigned*)((char*)(P) + tid_ * 16 + 8192), 16, 0, 0); } while (0)
; #define WAIT_V(n) asm volatile("s_waitcnt vmcnt(" #n ")" ::: "memory")
; #define WAIT_L(n) asm volatile("s_waitcnt lgkmcnt(" #n ")" ::: "memory")
; #define BAR __builtin_amdgcn_s_barrier()
; #define SCHED __builtin_amdgcn_sched_barrier(0)
; #define LDA(dst, b, h) for (int m = 0; m < 4; ++m) for (int k = 0; k < 2; ++k) \
;     dst[m][k] = *reinterpret_cast<const bf16x8*>((char*)SA(b, h) + lds_byte(wr * 64 + m * 16 + fr, k * 32 + fq * 8))
; #define LDB(dst, b, h) for (int n = 0; n < 2; ++n) for (int k = 0; k < 2; ++k) \
;     dst[n][k] = *reinterpret_cast<const bf16x8*>((char*)SB(b, h) + lds_byte(wc * 32 + n * 16 + fr, k * 32 + fq * 8))
; #define MMA(ai, bj, At_, Bt_) do { __builtin_amdgcn_s_setprio(1); \
;     for (int m = 0; m < 4; ++m) for (int n = 0; n < 2; ++n) for (int k = 0; k < 2; ++k) \
;       acc[ai][bj][m][n] = __builtin_amdgcn_mfma_f32_16x16x32_bf16(At_[m][k], Bt_[n][k], acc[ai][bj][m][n], 0, 0, 0); \
;     __builtin_amdgcn_s_setprio(0); } while (0)
; template <int K, int LD = K>
; __device__ __forceinline__ void gemm_main(const GAS bf16* A, const GAS bf16* Bt, int brow, int bcol, f32x4 (&acc)[2][2][4][2]) {
;     ...
;     LDB(B0, 0, 0); SCHED; LDA(At, 0, 0); STAGE(SA(1, 1), pA1, 1);
;     WAIT_L(8); BAR; WAIT_L(0); MMA(0, 0, At, B0); BAR; SCHED;
;     LDB(B1, 0, 1); STAGE(SB(0, 0), pB0, 2);
;     BAR; WAIT_L(0); MMA(0, 1, At, B1); BAR;
;     LDA(At, 0, 1); STAGE(SA(0, 0), pA0, 2);
;     BAR; WAIT_L(0); MMA(1, 0, At, B0); BAR; SCHED;
;     STAGE(SB(0, 1), pB1, 2);
;     WAIT_V(6); BAR; MMA(1, 1, At, B1); BAR;
.LBB0_346:
	ds_read_b128 v[162:165], v146
	ds_read_b128 v[166:169], v146 offset:1024
	ds_read_b128 v[174:177], v146 offset:2048
	ds_read_b128 v[178:181], v146 offset:3072
	v_lshl_add_u64 v[230:231], s[26:27], 0, v[130:131]
	v_readfirstlane_b32 s20, v143
	v_lshl_add_u64 v[214:215], v[230:231], 0, s[14:15]
	s_mov_b32 m0, s20
	v_lshl_add_u64 v[232:233], s[26:27], 0, v[132:133]
	v_readfirstlane_b32 s20, v142
	ds_read_b128 v[182:185], v138
	ds_read_b128 v[186:189], v138 offset:1024
	ds_read_b128 v[190:193], v137
	ds_read_b128 v[194:197], v137 offset:1024
	ds_read_b128 v[198:201], v136
	ds_read_b128 v[202:205], v136 offset:1024
	ds_read_b128 v[206:209], v135
	ds_read_b128 v[210:213], v135 offset:1024
	global_load_lds_dwordx4 v[214:215], off
	v_lshl_add_u64 v[214:215], v[232:233], 0, s[14:15]
	s_mov_b32 m0, s20
	s_nop 0
	global_load_lds_dwordx4 v[214:215], off
	s_waitcnt lgkmcnt(8)
	s_waitcnt vmcnt(10)
	s_barrier
	s_waitcnt lgkmcnt(0)
	v_mfma_f32_16x16x32_bf16 v[126:129], v[182:185], v[162:165], v[126:129]
	v_mfma_f32_16x16x32_bf16 v[122:125], v[182:185], v[174:177], v[122:125]
	v_mfma_f32_16x16x32_bf16 v[118:121], v[190:193], v[162:165], v[118:121]
	v_mfma_f32_16x16x32_bf16 v[114:117], v[190:193], v[174:177], v[114:117]
	v_mfma_f32_16x16x32_bf16 v[110:113], v[198:201], v[162:165], v[110:113]
	v_mfma_f32_16x16x32_bf16 v[106:109], v[198:201], v[174:177], v[106:109]
	v_mfma_f32_16x16x32_bf16 v[102:105], v[206:209], v[162:165], v[102:105]
	v_mfma_f32_16x16x32_bf16 v[98:101], v[206:209], v[174:177], v[98:101]
	v_mfma_f32_16x16x32_bf16 v[126:129], v[186:189], v[166:169], v[126:129]
	v_mfma_f32_16x16x32_bf16 v[122:125], v[186:189], v[178:181], v[122:125]
	v_mfma_f32_16x16x32_bf16 v[118:121], v[194:197], v[166:169], v[118:121]
	v_mfma_f32_16x16x32_bf16 v[114:117], v[194:197], v[178:181], v[114:117]
	v_mfma_f32_16x16x32_bf16 v[110:113], v[202:205], v[166:169], v[110:113]
	v_mfma_f32_16x16x32_bf16 v[106:109], v[202:205], v[178:181], v[106:109]
	v_mfma_f32_16x16x32_bf16 v[102:105], v[210:213], v[166:169], v[102:105]
	v_mfma_f32_16x16x32_bf16 v[98:101], v[210:213], v[178:181], v[98:101]
	s_barrier
	v_lshl_add_u64 v[234:235], s[36:37], 0, v[130:131]
	v_readfirstlane_b32 s20, v153
	v_lshl_add_u64 v[236:237], v[234:235], 0, s[22:23]
	s_mov_b32 m0, s20
	ds_read_b128 v[214:217], v141
	ds_read_b128 v[218:221], v141 offset:1024
	ds_read_b128 v[222:225], v141 offset:2048
	ds_read_b128 v[226:229], v141 offset:3072
	global_load_lds_dwordx4 v[236:237], off
	v_lshl_add_u64 v[236:237], s[36:37], 0, v[132:133]
	v_readfirstlane_b32 s20, v154
	v_lshl_add_u64 v[238:239], v[236:237], 0, s[22:23]
	s_mov_b32 m0, s20
	s_add_u32 s36, s36, 0x100
	global_load_lds_dwordx4 v[238:239], off
	s_waitcnt vmcnt(10)
	s_barrier
	s_waitcnt lgkmcnt(0)
	s_addc_u32 s37, s37, 0
	s_waitcnt lgkmcnt(0)
	v_mfma_f32_16x16x32_bf16 v[94:97], v[182:185], v[214:217], v[94:97]
	v_mfma_f32_16x16x32_bf16 v[90:93], v[182:185], v[222:225], v[90:93]
	v_mfma_f32_16x16x32_bf16 v[86:89], v[190:193], v[214:217], v[86:89]
	v_mfma_f32_16x16x32_bf16 v[82:85], v[190:193], v[222:225], v[82:85]
	v_mfma_f32_16x16x32_bf16 v[78:81], v[198:201], v[214:217], v[78:81]
	v_mfma_f32_16x16x32_bf16 v[74:77], v[198:201], v[222:225], v[74:77]
	v_mfma_f32_16x16x32_bf16 v[70:73], v[206:209], v[214:217], v[70:73]
	v_mfma_f32_16x16x32_bf16 v[66:69], v[206:209], v[222:225], v[66:69]
	v_mfma_f32_16x16x32_bf16 v[94:97], v[186:189], v[218:221], v[94:97]
	v_mfma_f32_16x16x32_bf16 v[90:93], v[186:189], v[226:229], v[90:93]
	v_mfma_f32_16x16x32_bf16 v[86:89], v[194:197], v[218:221], v[86:89]
	v_mfma_f32_16x16x32_bf16 v[82:85], v[194:197], v[226:229], v[82:85]
	v_mfma_f32_16x16x32_bf16 v[78:81], v[202:205], v[218:221], v[78:81]
	v_mfma_f32_16x16x32_bf16 v[74:77], v[202:205], v[226:229], v[74:77]
	v_mfma_f32_16x16x32_bf16 v[70:73], v[210:213], v[218:221], v[70:73]
	v_mfma_f32_16x16x32_bf16 v[66:69], v[210:213], v[226:229], v[66:69]
	v_lshl_add_u64 v[238:239], s[34:35], 0, v[130:131]
	v_readfirstlane_b32 s20, v147
	v_lshl_add_u64 v[240:241], v[238:239], 0, s[22:23]
	s_mov_b32 m0, s20
	s_barrier
	ds_read_b128 v[182:185], v138 offset:16384
	ds_read_b128 v[186:189], v138 offset:17408
	ds_read_b128 v[190:193], v137 offset:16384
	ds_read_b128 v[194:197], v137 offset:17408
	ds_read_b128 v[198:201], v136 offset:16384
	ds_read_b128 v[202:205], v136 offset:17408
	ds_read_b128 v[206:209], v135 offset:16384
	ds_read_b128 v[210:213], v135 offset:17408
	global_load_lds_dwordx4 v[240:241], off
	v_lshl_add_u64 v[240:241], s[34:35], 0, v[132:133]
	v_readfirstlane_b32 s20, v148
	v_lshl_add_u64 v[242:243], v[240:241], 0, s[22:23]
	s_mov_b32 m0, s20
	s_add_u32 s34, s34, 0x100
	global_load_lds_dwordx4 v[242:243], off
	s_barrier
	s_waitcnt lgkmcnt(0)
	s_addc_u32 s35, s35, 0
	s_waitcnt lgkmcnt(0)
	v_mfma_f32_16x16x32_bf16 v[62:65], v[182:185], v[162:165], v[62:65]
	v_mfma_f32_16x16x32_bf16 v[58:61], v[182:185], v[174:177], v[58:61]
	v_mfma_f32_16x16x32_bf16 v[54:57], v[190:193], v[162:165], v[54:57]
	v_mfma_f32_16x16x32_bf16 v[50:53], v[190:193], v[174:177], v[50:53]
	v_mfma_f32_16x16x32_bf16 v[46:49], v[198:201], v[162:165], v[46:49]
	v_mfma_f32_16x16x32_bf16 v[42:45], v[198:201], v[174:177], v[42:45]
	v_mfma_f32_16x16x32_bf16 v[38:41], v[206:209], v[162:165], v[38:41]
	v_mfma_f32_16x16x32_bf16 v[34:37], v[206:209], v[174:177], v[34:37]
	v_mfma_f32_16x16x32_bf16 v[62:65], v[186:189], v[166:169], v[62:65]
	v_mfma_f32_16x16x32_bf16 v[58:61], v[186:189], v[178:181], v[58:61]
	v_mfma_f32_16x16x32_bf16 v[54:57], v[194:197], v[166:169], v[54:57]
	v_mfma_f32_16x16x32_bf16 v[50:53], v[194:197], v[178:181], v[50:53]
	v_mfma_f32_16x16x32_bf16 v[46:49], v[202:205], v[166:169], v[46:49]
	v_mfma_f32_16x16x32_bf16 v[42:45], v[202:205], v[178:181], v[42:45]
	v_mfma_f32_16x16x32_bf16 v[38:41], v[210:213], v[166:169], v[38:41]
	v_mfma_f32_16x16x32_bf16 v[34:37], v[210:213], v[178:181], v[34:37]
	s_barrier
; #define STAGE(P, GP, ktrel) do { const GAS char* _g = (GP) + (ktrel) * (BK * 2); \
;     __builtin_amdgcn_global_load_lds((const GAS unsigned*)(_g + so0), (unsigned*)((char*)(P) + tid_ * 16), 16, 0, 0); \
;     __builtin_amdgcn_global_load_lds((const GAS unsigned*)(_g + so1), (unsigned*)((char*)(P) + tid_ * 16 + 8192), 16, 0, 0); } while (0)
; #define WAIT_V(n) asm volatile("s_waitcnt vmcnt(" #n ")" ::: "memory")
; #define WAIT_L(n) asm volatile("s_waitcnt lgkmcnt(" #n ")" ::: "memory")
; #define BAR __builtin_amdgcn_s_barrier()
; #define SCHED __builtin_amdgcn_sched_barrier(0)
; #define LDA(dst, b, h) for (int m = 0; m < 4; ++m) for (int k = 0; k < 2; ++k) \
;     dst[m][k] = *reinterpret_cast<const bf16x8*>((char*)SA(b, h) + lds_byte(wr * 64 + m * 16 + fr, k * 32 + fq * 8))
; #define LDB(dst, b, h) for (int n = 0; n < 2; ++n) for (int k = 0; k < 2; ++k) \
;     dst[n][k] = *reinterpret_cast<const bf16x8*>((char*)SB(b, h) + lds_byte(wc * 32 + n * 16 + fr, k * 32 + fq * 8))
; #define MMA(ai, bj, At_, Bt_) do { __builtin_amdgcn_s_setprio(1); \
;     for (int m = 0; m < 4; ++m) for (int n = 0; n < 2; ++n) for (int k = 0; k < 2; ++k) \
;       acc[ai][bj][m][n] = __builtin_amdgcn_mfma_f32_16x16x32_bf16(At_[m][k], Bt_[n][k], acc[ai][bj][m][n], 0, 0, 0); \
;     __builtin_amdgcn_s_setprio(0); } while (0)
; template <int K, int LD = K>
; __device__ __forceinline__ void gemm_main(const GAS bf16* A, const GAS bf16* Bt, int brow, int bcol, f32x4 (&acc)[2][2][4][2]) {
;     ...
;     WAIT_V(6); BAR; MMA(1, 1, At, B1); BAR;
;     LDB(B0, 1, 0); SCHED; LDA(At, 1, 0); STAGE(SA(0, 1), pA1, 2);
;     WAIT_L(8); BAR; WAIT_L(0); MMA(0, 0, At, B0); BAR; SCHED;
;     LDB(B1, 1, 1); STAGE(SB(1, 0), pB0, 3);
;     BAR; WAIT_L(0); MMA(0, 1, At, B1); BAR;
;     LDA(At, 1, 1); STAGE(SA(1, 0), pA0, 3);
	v_lshl_add_u64 v[242:243], s[28:29], 0, v[130:131]
	v_readfirstlane_b32 s20, v155
	v_lshl_add_u64 v[162:163], v[242:243], 0, s[22:23]
	s_mov_b32 m0, s20
	v_lshl_add_u64 v[244:245], s[28:29], 0, v[132:133]
	v_readfirstlane_b32 s20, v156
	global_load_lds_dwordx4 v[162:163], off
	v_lshl_add_u64 v[162:163], v[244:245], 0, s[22:23]
	s_mov_b32 m0, s20
	s_add_u32 s28, s28, 0x100
	global_load_lds_dwordx4 v[162:163], off
	s_waitcnt vmcnt(10)
	s_addc_u32 s29, s29, 0
	s_barrier
	v_mfma_f32_16x16x32_bf16 v[30:33], v[182:185], v[214:217], v[30:33]
	v_mfma_f32_16x16x32_bf16 v[26:29], v[182:185], v[222:225], v[26:29]
	v_mfma_f32_16x16x32_bf16 v[22:25], v[190:193], v[214:217], v[22:25]
	v_mfma_f32_16x16x32_bf16 v[18:21], v[190:193], v[222:225], v[18:21]
	v_mfma_f32_16x16x32_bf16 v[14:17], v[198:201], v[214:217], v[14:17]
	v_mfma_f32_16x16x32_bf16 v[10:13], v[198:201], v[222:225], v[10:13]
	v_mfma_f32_16x16x32_bf16 v[6:9], v[206:209], v[214:217], v[6:9]
	v_mfma_f32_16x16x32_bf16 v[2:5], v[206:209], v[222:225], v[2:5]
	v_mfma_f32_16x16x32_bf16 v[30:33], v[186:189], v[218:221], v[30:33]
	v_mfma_f32_16x16x32_bf16 v[26:29], v[186:189], v[226:229], v[26:29]
	v_mfma_f32_16x16x32_bf16 v[22:25], v[194:197], v[218:221], v[22:25]
	v_mfma_f32_16x16x32_bf16 v[18:21], v[194:197], v[226:229], v[18:21]
	v_mfma_f32_16x16x32_bf16 v[14:17], v[202:205], v[218:221], v[14:17]
	v_mfma_f32_16x16x32_bf16 v[10:13], v[202:205], v[226:229], v[10:13]
	v_mfma_f32_16x16x32_bf16 v[6:9], v[210:213], v[218:221], v[6:9]
	v_mfma_f32_16x16x32_bf16 v[2:5], v[210:213], v[226:229], v[2:5]
	s_barrier
	ds_read_b128 v[162:165], v140
	ds_read_b128 v[166:169], v140 offset:1024
	ds_read_b128 v[174:177], v140 offset:2048
	ds_read_b128 v[178:181], v140 offset:3072
	v_readfirstlane_b32 s20, v149
	v_lshl_add_u64 v[214:215], v[230:231], 0, s[22:23]
	s_mov_b32 m0, s20
	v_readfirstlane_b32 s20, v150
	ds_read_b128 v[182:185], v138 offset:32768
	ds_read_b128 v[186:189], v138 offset:33792
	ds_read_b128 v[190:193], v137 offset:32768
	ds_read_b128 v[194:197], v137 offset:33792
	ds_read_b128 v[198:201], v136 offset:32768
	ds_read_b128 v[202:205], v136 offset:33792
	ds_read_b128 v[206:209], v135 offset:32768
	ds_read_b128 v[210:213], v135 offset:33792
	global_load_lds_dwordx4 v[214:215], off
	v_lshl_add_u64 v[214:215], v[232:233], 0, s[22:23]
	s_mov_b32 m0, s20
	s_add_u32 s26, s26, 0x100
	global_load_lds_dwordx4 v[214:215], off
	s_waitcnt lgkmcnt(8)
	s_waitcnt vmcnt(10)
	s_barrier
	s_waitcnt lgkmcnt(0)
	s_addc_u32 s27, s27, 0
	s_waitcnt lgkmcnt(0)
	v_mfma_f32_16x16x32_bf16 v[126:129], v[182:185], v[162:165], v[126:129]
	v_mfma_f32_16x16x32_bf16 v[122:125], v[182:185], v[174:177], v[122:125]
	v_mfma_f32_16x16x32_bf16 v[118:121], v[190:193], v[162:165], v[118:121]
	v_mfma_f32_16x16x32_bf16 v[114:117], v[190:193], v[174:177], v[114:117]
	v_mfma_f32_16x16x32_bf16 v[110:113], v[198:201], v[162:165], v[110:113]
	v_mfma_f32_16x16x32_bf16 v[106:109], v[198:201], v[174:177], v[106:109]
	v_mfma_f32_16x16x32_bf16 v[102:105], v[206:209], v[162:165], v[102:105]
	v_mfma_f32_16x16x32_bf16 v[98:101], v[206:209], v[174:177], v[98:101]
	v_mfma_f32_16x16x32_bf16 v[126:129], v[186:189], v[166:169], v[126:129]
	v_mfma_f32_16x16x32_bf16 v[122:125], v[186:189], v[178:181], v[122:125]
	v_mfma_f32_16x16x32_bf16 v[118:121], v[194:197], v[166:169], v[118:121]
	v_mfma_f32_16x16x32_bf16 v[114:117], v[194:197], v[178:181], v[114:117]
	v_mfma_f32_16x16x32_bf16 v[110:113], v[202:205], v[166:169], v[110:113]
	v_mfma_f32_16x16x32_bf16 v[106:109], v[202:205], v[178:181], v[106:109]
	v_mfma_f32_16x16x32_bf16 v[102:105], v[210:213], v[166:169], v[102:105]
	v_mfma_f32_16x16x32_bf16 v[98:101], v[210:213], v[178:181], v[98:101]
	s_barrier
	v_readfirstlane_b32 s20, v157
	v_lshl_add_u64 v[230:231], v[234:235], 0, s[24:25]
	s_mov_b32 m0, s20
	v_readfirstlane_b32 s20, v158
	ds_read_b128 v[214:217], v139
	ds_read_b128 v[218:221], v139 offset:1024
	ds_read_b128 v[222:225], v139 offset:2048
	ds_read_b128 v[226:229], v139 offset:3072
	global_load_lds_dwordx4 v[230:231], off
	v_lshl_add_u64 v[230:231], v[236:237], 0, s[24:25]
	s_mov_b32 m0, s20
	s_nop 0
	global_load_lds_dwordx4 v[230:231], off
	s_waitcnt vmcnt(10)
	s_barrier
	s_waitcnt lgkmcnt(0)
	v_mfma_f32_16x16x32_bf16 v[94:97], v[182:185], v[214:217], v[94:97]
	v_mfma_f32_16x16x32_bf16 v[90:93], v[182:185], v[222:225], v[90:93]
	v_mfma_f32_16x16x32_bf16 v[86:89], v[190:193], v[214:217], v[86:89]
	v_mfma_f32_16x16x32_bf16 v[82:85], v[190:193], v[222:225], v[82:85]
	v_mfma_f32_16x16x32_bf16 v[78:81], v[198:201], v[214:217], v[78:81]
	v_mfma_f32_16x16x32_bf16 v[74:77], v[198:201], v[222:225], v[74:77]
	v_mfma_f32_16x16x32_bf16 v[70:73], v[206:209], v[214:217], v[70:73]
	v_mfma_f32_16x16x32_bf16 v[66:69], v[206:209], v[222:225], v[66:69]
	v_mfma_f32_16x16x32_bf16 v[94:97], v[186:189], v[218:221], v[94:97]
	v_mfma_f32_16x16x32_bf16 v[90:93], v[186:189], v[226:229], v[90:93]
	v_mfma_f32_16x16x32_bf16 v[86:89], v[194:197], v[218:221], v[86:89]
	v_mfma_f32_16x16x32_bf16 v[82:85], v[194:197], v[226:229], v[82:85]
	v_mfma_f32_16x16x32_bf16 v[78:81], v[202:205], v[218:221], v[78:81]
	v_mfma_f32_16x16x32_bf16 v[74:77], v[202:205], v[226:229], v[74:77]
	v_mfma_f32_16x16x32_bf16 v[70:73], v[210:213], v[218:221], v[70:73]
	v_mfma_f32_16x16x32_bf16 v[66:69], v[210:213], v[226:229], v[66:69]
	v_readfirstlane_b32 s20, v151
	v_lshl_add_u64 v[230:231], v[238:239], 0, s[24:25]
	s_mov_b32 m0, s20
	v_readfirstlane_b32 s20, v152
	s_barrier
; #define STAGE(P, GP, ktrel) do { const GAS char* _g = (GP) + (ktrel) * (BK * 2); \
;     __builtin_amdgcn_global_load_lds((const GAS unsigned*)(_g + so0), (unsigned*)((char*)(P) + tid_ * 16), 16, 0, 0); \
;     __builtin_amdgcn_global_load_lds((const GAS unsigned*)(_g + so1), (unsigned*)((char*)(P) + tid_ * 16 + 8192), 16, 0, 0); } while (0)
; #define WAIT_V(n) asm volatile("s_waitcnt vmcnt(" #n ")" ::: "memory")
; #define WAIT_L(n) asm volatile("s_waitcnt lgkmcnt(" #n ")" ::: "memory")
; #define BAR __builtin_amdgcn_s_barrier()
; #define SCHED __builtin_amdgcn_sched_barrier(0)
; #define LDA(dst, b, h) for (int m = 0; m < 4; ++m) for (int k = 0; k < 2; ++k) \
;     dst[m][k] = *reinterpret_cast<const bf16x8*>((char*)SA(b, h) + lds_byte(wr * 64 + m * 16 + fr, k * 32 + fq * 8))
; #define LDB(dst, b, h) for (int n = 0; n < 2; ++n) for (int k = 0; k < 2; ++k) \
;     dst[n][k] = *reinterpret_cast<const bf16x8*>((char*)SB(b, h) + lds_byte(wc * 32 + n * 16 + fr, k * 32 + fq * 8))
; #define MMA(ai, bj, At_, Bt_) do { __builtin_amdgcn_s_setprio(1); \
;     for (int m = 0; m < 4; ++m) for (int n = 0; n < 2; ++n) for (int k = 0; k < 2; ++k) \
;       acc[ai][bj][m][n] = __builtin_amdgcn_mfma_f32_16x16x32_bf16(At_[m][k], Bt_[n][k], acc[ai][bj][m][n], 0, 0, 0); \
;     __builtin_amdgcn_s_setprio(0); } while (0)
; template <int K, int LD = K>
; __device__ __forceinline__ void gemm_main(const GAS bf16* A, const GAS bf16* Bt, int brow, int bcol, f32x4 (&acc)[2][2][4][2]) {
;     ...
;     LDA(At, 1, 1); STAGE(SA(1, 0), pA0, 3);
;     BAR; WAIT_L(0); MMA(1, 0, At, B0); BAR; SCHED;
;     STAGE(SB(1, 1), pB1, 3);
;     WAIT_V(6); BAR; MMA(1, 1, At, B1); BAR;
;     pA0 += 4 * BK; pA1 += 4 * BK; pB0 += 4 * BK; pB1 += 4 * BK;
;     asm volatile("" : "+s"(pA0), "+s"(pA1), "+s"(pB0), "+s"(pB1));
;   }
;   { LDB(B0, 0, 0); LDA(At, 0, 0); STAGE(SA(1, 1), pA1, 1);
;     BAR; WAIT_L(0); MMA(0, 0, At, B0); BAR;
;     LDB(B1, 0, 1); BAR; WAIT_L(0); MMA(0, 1, At, B1); BAR;
;     LDA(At, 0, 1); WAIT_V(4); BAR; WAIT_L(0); MMA(1, 0, At, B0); MMA(1, 1, At, B1); BAR; }
	ds_read_b128 v[182:185], v138 offset:49152
	ds_read_b128 v[186:189], v138 offset:50176
	ds_read_b128 v[190:193], v137 offset:49152
	ds_read_b128 v[194:197], v137 offset:50176
	ds_read_b128 v[198:201], v136 offset:49152
	ds_read_b128 v[202:205], v136 offset:50176
	ds_read_b128 v[206:209], v135 offset:49152
	ds_read_b128 v[210:213], v135 offset:50176
	global_load_lds_dwordx4 v[230:231], off
	v_lshl_add_u64 v[230:231], v[240:241], 0, s[24:25]
	s_mov_b32 m0, s20
	s_nop 0
	global_load_lds_dwordx4 v[230:231], off
	s_barrier
	s_waitcnt lgkmcnt(0)
	v_mfma_f32_16x16x32_bf16 v[62:65], v[182:185], v[162:165], v[62:65]
	v_mfma_f32_16x16x32_bf16 v[58:61], v[182:185], v[174:177], v[58:61]
	v_mfma_f32_16x16x32_bf16 v[54:57], v[190:193], v[162:165], v[54:57]
	v_mfma_f32_16x16x32_bf16 v[50:53], v[190:193], v[174:177], v[50:53]
	v_mfma_f32_16x16x32_bf16 v[46:49], v[198:201], v[162:165], v[46:49]
	v_mfma_f32_16x16x32_bf16 v[42:45], v[198:201], v[174:177], v[42:45]
	v_mfma_f32_16x16x32_bf16 v[38:41], v[206:209], v[162:165], v[38:41]
	v_mfma_f32_16x16x32_bf16 v[34:37], v[206:209], v[174:177], v[34:37]
	v_mfma_f32_16x16x32_bf16 v[62:65], v[186:189], v[166:169], v[62:65]
	v_mfma_f32_16x16x32_bf16 v[58:61], v[186:189], v[178:181], v[58:61]
	v_mfma_f32_16x16x32_bf16 v[54:57], v[194:197], v[166:169], v[54:57]
	v_mfma_f32_16x16x32_bf16 v[50:53], v[194:197], v[178:181], v[50:53]
	v_mfma_f32_16x16x32_bf16 v[46:49], v[202:205], v[166:169], v[46:49]
	v_mfma_f32_16x16x32_bf16 v[42:45], v[202:205], v[178:181], v[42:45]
	v_mfma_f32_16x16x32_bf16 v[38:41], v[210:213], v[166:169], v[38:41]
	v_mfma_f32_16x16x32_bf16 v[34:37], v[210:213], v[178:181], v[34:37]
	s_barrier
	v_readfirstlane_b32 s20, v159
	v_lshl_add_u64 v[162:163], v[242:243], 0, s[24:25]
	s_mov_b32 m0, s20
	v_readfirstlane_b32 s20, v160
	global_load_lds_dwordx4 v[162:163], off
	v_lshl_add_u64 v[162:163], v[244:245], 0, s[24:25]
	s_mov_b32 m0, s20
	s_nop 0
	global_load_lds_dwordx4 v[162:163], off
	s_waitcnt vmcnt(10)
	s_barrier
	v_mfma_f32_16x16x32_bf16 v[30:33], v[182:185], v[214:217], v[30:33]
	v_mfma_f32_16x16x32_bf16 v[26:29], v[182:185], v[222:225], v[26:29]
	v_mfma_f32_16x16x32_bf16 v[22:25], v[190:193], v[214:217], v[22:25]
	v_mfma_f32_16x16x32_bf16 v[18:21], v[190:193], v[222:225], v[18:21]
	v_mfma_f32_16x16x32_bf16 v[14:17], v[198:201], v[214:217], v[14:17]
	v_mfma_f32_16x16x32_bf16 v[10:13], v[198:201], v[222:225], v[10:13]
	v_mfma_f32_16x16x32_bf16 v[6:9], v[206:209], v[214:217], v[6:9]
	v_mfma_f32_16x16x32_bf16 v[2:5], v[206:209], v[222:225], v[2:5]
	v_mfma_f32_16x16x32_bf16 v[30:33], v[186:189], v[218:221], v[30:33]
	v_mfma_f32_16x16x32_bf16 v[26:29], v[186:189], v[226:229], v[26:29]
	v_mfma_f32_16x16x32_bf16 v[22:25], v[194:197], v[218:221], v[22:25]
	v_mfma_f32_16x16x32_bf16 v[18:21], v[194:197], v[226:229], v[18:21]
	v_mfma_f32_16x16x32_bf16 v[14:17], v[202:205], v[218:221], v[14:17]
	v_mfma_f32_16x16x32_bf16 v[10:13], v[202:205], v[226:229], v[10:13]
	v_mfma_f32_16x16x32_bf16 v[6:9], v[210:213], v[218:221], v[6:9]
	v_mfma_f32_16x16x32_bf16 v[2:5], v[210:213], v[226:229], v[2:5]
	s_add_i32 s5, s5, 2
	s_cmp_lt_u32 s5, 12
	s_barrier
	s_cbranch_scc1 .LBB0_346
	ds_read_b128 v[148:151], v146
	ds_read_b128 v[152:155], v146 offset:1024
	ds_read_b128 v[156:159], v146 offset:2048
	ds_read_b128 v[160:163], v146 offset:3072
	ds_read_b128 v[164:167], v138
	ds_read_b128 v[174:177], v138 offset:1024
	ds_read_b128 v[178:181], v137
	ds_read_b128 v[182:185], v137 offset:1024
	ds_read_b128 v[186:189], v136
	ds_read_b128 v[190:193], v136 offset:1024
	ds_read_b128 v[194:197], v135
	ds_read_b128 v[198:201], v135 offset:1024
	v_lshl_add_u64 v[146:147], s[26:27], 0, v[130:131]
	v_readfirstlane_b32 s5, v143
	v_lshl_add_u64 v[146:147], v[146:147], 0, s[14:15]
	s_mov_b32 m0, s5
	v_lshl_add_u64 v[132:133], s[26:27], 0, v[132:133]
	v_readfirstlane_b32 s5, v142
	global_load_lds_dwordx4 v[146:147], off
	v_lshl_add_u64 v[132:133], v[132:133], 0, s[14:15]
	s_mov_b32 m0, s5
	s_nop 0
	global_load_lds_dwordx4 v[132:133], off
	s_waitcnt vmcnt(10)
	s_barrier
	s_waitcnt lgkmcnt(0)
	v_mfma_f32_16x16x32_bf16 v[126:129], v[164:167], v[148:151], v[126:129]
	v_mfma_f32_16x16x32_bf16 v[122:125], v[164:167], v[156:159], v[122:125]
	v_mfma_f32_16x16x32_bf16 v[110:113], v[186:189], v[148:151], v[110:113]
	v_mfma_f32_16x16x32_bf16 v[106:109], v[186:189], v[156:159], v[106:109]
	v_mfma_f32_16x16x32_bf16 v[126:129], v[174:177], v[152:155], v[126:129]
	v_mfma_f32_16x16x32_bf16 v[122:125], v[174:177], v[160:163], v[122:125]
	v_mfma_f32_16x16x32_bf16 v[118:121], v[178:181], v[148:151], v[118:121]
	v_mfma_f32_16x16x32_bf16 v[114:117], v[178:181], v[156:159], v[114:117]
	v_mfma_f32_16x16x32_bf16 v[110:113], v[190:193], v[152:155], v[110:113]
	v_mfma_f32_16x16x32_bf16 v[106:109], v[190:193], v[160:163], v[106:109]
	v_mfma_f32_16x16x32_bf16 v[102:105], v[194:197], v[148:151], v[102:105]
	v_mfma_f32_16x16x32_bf16 v[98:101], v[194:197], v[156:159], v[98:101]
	v_mfma_f32_16x16x32_bf16 v[202:205], v[182:185], v[152:155], v[118:121]
	v_mfma_f32_16x16x32_bf16 v[206:209], v[182:185], v[160:163], v[114:117]
	v_mfma_f32_16x16x32_bf16 v[210:213], v[198:201], v[152:155], v[102:105]
	v_mfma_f32_16x16x32_bf16 v[214:217], v[198:201], v[160:163], v[98:101]
	s_barrier
	s_nop 1
	ds_read_b128 v[98:101], v141
	ds_read_b128 v[102:105], v141 offset:1024
	ds_read_b128 v[114:117], v141 offset:2048
	ds_read_b128 v[118:121], v141 offset:3072
	s_waitcnt vmcnt(8)
	s_barrier
; #define WAIT_V(n) asm volatile("s_waitcnt vmcnt(" #n ")" ::: "memory")
; #define WAIT_L(n) asm volatile("s_waitcnt lgkmcnt(" #n ")" ::: "memory")
; #define BAR __builtin_amdgcn_s_barrier()
; #define LDA(dst, b, h) for (int m = 0; m < 4; ++m) for (int k = 0; k < 2; ++k) \
;     dst[m][k] = *reinterpret_cast<const bf16x8*>((char*)SA(b, h) + lds_byte(wr * 64 + m * 16 + fr, k * 32 + fq * 8))
; #define LDB(dst, b, h) for (int n = 0; n < 2; ++n) for (int k = 0; k < 2; ++k) \
;     dst[n][k] = *reinterpret_cast<const bf16x8*>((char*)SB(b, h) + lds_byte(wc * 32 + n * 16 + fr, k * 32 + fq * 8))
; #define MMA(ai, bj, At_, Bt_) do { __builtin_amdgcn_s_setprio(1); \
;     for (int m = 0; m < 4; ++m) for (int n = 0; n < 2; ++n) for (int k = 0; k < 2; ++k) \
;       acc[ai][bj][m][n] = __builtin_amdgcn_mfma_f32_16x16x32_bf16(At_[m][k], Bt_[n][k], acc[ai][bj][m][n], 0, 0, 0); \
;     __builtin_amdgcn_s_setprio(0); } while (0)
; template <int K, int LD = K>
; __device__ __forceinline__ void gemm_main(const GAS bf16* A, const GAS bf16* Bt, int brow, int bcol, f32x4 (&acc)[2][2][4][2]) {
;     ...
;     LDB(B1, 0, 1); BAR; WAIT_L(0); MMA(0, 1, At, B1); BAR;
;     LDA(At, 0, 1); WAIT_V(4); BAR; WAIT_L(0); MMA(1, 0, At, B0); MMA(1, 1, At, B1); BAR; }
	s_waitcnt lgkmcnt(0)
	v_mfma_f32_16x16x32_bf16 v[94:97], v[164:167], v[98:101], v[94:97]
	v_mfma_f32_16x16x32_bf16 v[90:93], v[164:167], v[114:117], v[90:93]
	v_mfma_f32_16x16x32_bf16 v[78:81], v[186:189], v[98:101], v[78:81]
	v_mfma_f32_16x16x32_bf16 v[74:77], v[186:189], v[114:117], v[74:77]
	v_mfma_f32_16x16x32_bf16 v[94:97], v[174:177], v[102:105], v[94:97]
	v_mfma_f32_16x16x32_bf16 v[90:93], v[174:177], v[118:121], v[90:93]
	v_mfma_f32_16x16x32_bf16 v[86:89], v[178:181], v[98:101], v[86:89]
	v_mfma_f32_16x16x32_bf16 v[82:85], v[178:181], v[114:117], v[82:85]
	v_mfma_f32_16x16x32_bf16 v[78:81], v[190:193], v[102:105], v[78:81]
	v_mfma_f32_16x16x32_bf16 v[74:77], v[190:193], v[118:121], v[74:77]
	v_mfma_f32_16x16x32_bf16 v[70:73], v[194:197], v[98:101], v[70:73]
	v_mfma_f32_16x16x32_bf16 v[66:69], v[194:197], v[114:117], v[66:69]
	v_mfma_f32_16x16x32_bf16 v[164:167], v[182:185], v[102:105], v[86:89]
	v_mfma_f32_16x16x32_bf16 v[174:177], v[182:185], v[118:121], v[82:85]
	v_mfma_f32_16x16x32_bf16 v[178:181], v[198:201], v[102:105], v[70:73]
	v_mfma_f32_16x16x32_bf16 v[182:185], v[198:201], v[118:121], v[66:69]
	s_barrier
	s_nop 1
	ds_read_b128 v[66:69], v138 offset:16384
	ds_read_b128 v[70:73], v138 offset:17408
	ds_read_b128 v[82:85], v137 offset:16384
	ds_read_b128 v[86:89], v137 offset:17408
	ds_read_b128 v[186:189], v136 offset:16384
	ds_read_b128 v[190:193], v136 offset:17408
	ds_read_b128 v[194:197], v135 offset:16384
	ds_read_b128 v[198:201], v135 offset:17408
	s_waitcnt vmcnt(4)
	s_barrier
	s_waitcnt lgkmcnt(0)
	v_mfma_f32_16x16x32_bf16 v[62:65], v[66:69], v[148:151], v[62:65]
	v_mfma_f32_16x16x32_bf16 v[58:61], v[66:69], v[156:159], v[58:61]
	v_mfma_f32_16x16x32_bf16 v[46:49], v[186:189], v[148:151], v[46:49]
	v_mfma_f32_16x16x32_bf16 v[42:45], v[186:189], v[156:159], v[42:45]
	v_mfma_f32_16x16x32_bf16 v[62:65], v[70:73], v[152:155], v[62:65]
	v_mfma_f32_16x16x32_bf16 v[58:61], v[70:73], v[160:163], v[58:61]
	v_mfma_f32_16x16x32_bf16 v[54:57], v[82:85], v[148:151], v[54:57]
	v_mfma_f32_16x16x32_bf16 v[50:53], v[82:85], v[156:159], v[50:53]
	v_mfma_f32_16x16x32_bf16 v[46:49], v[190:193], v[152:155], v[46:49]
	v_mfma_f32_16x16x32_bf16 v[42:45], v[190:193], v[160:163], v[42:45]
	v_mfma_f32_16x16x32_bf16 v[38:41], v[194:197], v[148:151], v[38:41]
	v_mfma_f32_16x16x32_bf16 v[34:37], v[194:197], v[156:159], v[34:37]
	v_mfma_f32_16x16x32_bf16 v[218:221], v[86:89], v[152:155], v[54:57]
	v_mfma_f32_16x16x32_bf16 v[222:225], v[86:89], v[160:163], v[50:53]
	v_mfma_f32_16x16x32_bf16 v[146:149], v[198:201], v[152:155], v[38:41]
	v_mfma_f32_16x16x32_bf16 v[150:153], v[198:201], v[160:163], v[34:37]
	v_mfma_f32_16x16x32_bf16 v[30:33], v[66:69], v[98:101], v[30:33]
	v_mfma_f32_16x16x32_bf16 v[26:29], v[66:69], v[114:117], v[26:29]
	v_mfma_f32_16x16x32_bf16 v[14:17], v[186:189], v[98:101], v[14:17]
	v_mfma_f32_16x16x32_bf16 v[10:13], v[186:189], v[114:117], v[10:13]
	v_mfma_f32_16x16x32_bf16 v[30:33], v[70:73], v[102:105], v[30:33]
	v_mfma_f32_16x16x32_bf16 v[26:29], v[70:73], v[118:121], v[26:29]
	v_mfma_f32_16x16x32_bf16 v[22:25], v[82:85], v[98:101], v[22:25]
	v_mfma_f32_16x16x32_bf16 v[18:21], v[82:85], v[114:117], v[18:21]
	v_mfma_f32_16x16x32_bf16 v[14:17], v[190:193], v[102:105], v[14:17]
	v_mfma_f32_16x16x32_bf16 v[10:13], v[190:193], v[118:121], v[10:13]
	v_mfma_f32_16x16x32_bf16 v[6:9], v[194:197], v[98:101], v[6:9]
	v_mfma_f32_16x16x32_bf16 v[2:5], v[194:197], v[114:117], v[2:5]
	v_mfma_f32_16x16x32_bf16 v[154:157], v[86:89], v[102:105], v[22:25]
	v_mfma_f32_16x16x32_bf16 v[158:161], v[86:89], v[118:121], v[18:21]
	v_mfma_f32_16x16x32_bf16 v[186:189], v[198:201], v[102:105], v[6:9]
	v_mfma_f32_16x16x32_bf16 v[190:193], v[198:201], v[118:121], v[2:5]
	s_barrier
	s_nop 1
	ds_read_b128 v[2:5], v140
	ds_read_b128 v[6:9], v140 offset:1024
	ds_read_b128 v[194:197], v140 offset:2048
	ds_read_b128 v[140:143], v140 offset:3072
	ds_read_b128 v[18:21], v138 offset:32768
	ds_read_b128 v[22:25], v138 offset:33792
	ds_read_b128 v[34:37], v137 offset:32768
	ds_read_b128 v[38:41], v137 offset:33792
	ds_read_b128 v[50:53], v136 offset:32768
	ds_read_b128 v[54:57], v136 offset:33792
	ds_read_b128 v[198:201], v135 offset:32768
	ds_read_b128 v[226:229], v135 offset:33792
	s_waitcnt vmcnt(2)
	s_barrier
; #define WAIT_V(n) asm volatile("s_waitcnt vmcnt(" #n ")" ::: "memory")
; #define WAIT_L(n) asm volatile("s_waitcnt lgkmcnt(" #n ")" ::: "memory")
; #define BAR __builtin_amdgcn_s_barrier()
; #define LDA(dst, b, h) for (int m = 0; m < 4; ++m) for (int k = 0; k < 2; ++k) \
;     dst[m][k] = *reinterpret_cast<const bf16x8*>((char*)SA(b, h) + lds_byte(wr * 64 + m * 16 + fr, k * 32 + fq * 8))
; #define LDB(dst, b, h) for (int n = 0; n < 2; ++n) for (int k = 0; k < 2; ++k) \
;     dst[n][k] = *reinterpret_cast<const bf16x8*>((char*)SB(b, h) + lds_byte(wc * 32 + n * 16 + fr, k * 32 + fq * 8))
; #define MMA(ai, bj, At_, Bt_) do { __builtin_amdgcn_s_setprio(1); \
;     for (int m = 0; m < 4; ++m) for (int n = 0; n < 2; ++n) for (int k = 0; k < 2; ++k) \
;       acc[ai][bj][m][n] = __builtin_amdgcn_mfma_f32_16x16x32_bf16(At_[m][k], Bt_[n][k], acc[ai][bj][m][n], 0, 0, 0); \
;     __builtin_amdgcn_s_setprio(0); } while (0)
; template <int K, int LD = K>
; __device__ __forceinline__ void gemm_main(const GAS bf16* A, const GAS bf16* Bt, int brow, int bcol, f32x4 (&acc)[2][2][4][2]) {
;     ...
;   { LDB(B0, 1, 0); LDA(At, 1, 0); WAIT_V(2); BAR; WAIT_L(0); MMA(0, 0, At, B0); BAR;
;     LDB(B1, 1, 1); WAIT_V(0); BAR; WAIT_L(0); MMA(0, 1, At, B1); BAR;
;     LDA(At, 1, 1); BAR; WAIT_L(0); MMA(1, 0, At, B0); MMA(1, 1, At, B1); BAR; }
;   if (wr == 0) BAR;
	s_waitcnt lgkmcnt(0)
	v_mfma_f32_16x16x32_bf16 v[66:69], v[18:21], v[2:5], v[126:129]
	v_mfma_f32_16x16x32_bf16 v[114:117], v[22:25], v[6:9], v[66:69]
	v_mfma_f32_16x16x32_bf16 v[66:69], v[18:21], v[194:197], v[122:125]
	v_mfma_f32_16x16x32_bf16 v[118:121], v[22:25], v[140:143], v[66:69]
	v_mfma_f32_16x16x32_bf16 v[66:69], v[34:37], v[2:5], v[202:205]
	v_mfma_f32_16x16x32_bf16 v[102:105], v[38:41], v[6:9], v[66:69]
	v_mfma_f32_16x16x32_bf16 v[66:69], v[34:37], v[194:197], v[206:209]
	v_mfma_f32_16x16x32_bf16 v[98:101], v[38:41], v[140:143], v[66:69]
	v_mfma_f32_16x16x32_bf16 v[66:69], v[50:53], v[2:5], v[110:113]
	v_mfma_f32_16x16x32_bf16 v[82:85], v[54:57], v[6:9], v[66:69]
	v_mfma_f32_16x16x32_bf16 v[66:69], v[50:53], v[194:197], v[106:109]
	v_mfma_f32_16x16x32_bf16 v[86:89], v[54:57], v[140:143], v[66:69]
	v_mfma_f32_16x16x32_bf16 v[66:69], v[198:201], v[2:5], v[210:213]
	v_mfma_f32_16x16x32_bf16 v[70:73], v[226:229], v[6:9], v[66:69]
	v_mfma_f32_16x16x32_bf16 v[66:69], v[198:201], v[194:197], v[214:217]
	v_mfma_f32_16x16x32_bf16 v[66:69], v[226:229], v[140:143], v[66:69]
	s_barrier
	ds_read_b128 v[202:205], v139
	ds_read_b128 v[206:209], v139 offset:1024
	ds_read_b128 v[210:213], v139 offset:2048
	ds_read_b128 v[214:217], v139 offset:3072
	s_waitcnt vmcnt(0)
	s_barrier
	s_waitcnt lgkmcnt(0)
	v_mfma_f32_16x16x32_bf16 v[94:97], v[18:21], v[202:205], v[94:97]
	v_mfma_f32_16x16x32_bf16 v[18:21], v[18:21], v[210:213], v[90:93]
	v_mfma_f32_16x16x32_bf16 v[126:129], v[22:25], v[214:217], v[18:21]
	v_mfma_f32_16x16x32_bf16 v[18:21], v[34:37], v[202:205], v[164:167]
	v_mfma_f32_16x16x32_bf16 v[106:109], v[38:41], v[206:209], v[18:21]
	v_mfma_f32_16x16x32_bf16 v[18:21], v[34:37], v[210:213], v[174:177]
	v_mfma_f32_16x16x32_bf16 v[110:113], v[38:41], v[214:217], v[18:21]
	v_mfma_f32_16x16x32_bf16 v[18:21], v[50:53], v[202:205], v[78:81]
	v_mfma_f32_16x16x32_bf16 v[90:93], v[54:57], v[206:209], v[18:21]
	v_mfma_f32_16x16x32_bf16 v[18:21], v[50:53], v[210:213], v[74:77]
	v_mfma_f32_16x16x32_bf16 v[122:125], v[22:25], v[206:209], v[94:97]
	v_mfma_f32_16x16x32_bf16 v[94:97], v[54:57], v[214:217], v[18:21]
	v_mfma_f32_16x16x32_bf16 v[18:21], v[198:201], v[202:205], v[178:181]
	v_mfma_f32_16x16x32_bf16 v[74:77], v[226:229], v[206:209], v[18:21]
	v_mfma_f32_16x16x32_bf16 v[18:21], v[198:201], v[210:213], v[182:185]
	v_mfma_f32_16x16x32_bf16 v[78:81], v[226:229], v[214:217], v[18:21]
	s_barrier
	ds_read_b128 v[162:165], v138 offset:49152
	ds_read_b128 v[166:169], v138 offset:50176
	ds_read_b128 v[174:177], v137 offset:49152
	ds_read_b128 v[178:181], v137 offset:50176
	ds_read_b128 v[182:185], v136 offset:49152
	ds_read_b128 v[136:139], v136 offset:50176
	ds_read_b128 v[198:201], v135 offset:49152
	ds_read_b128 v[226:229], v135 offset:50176
	s_barrier
	s_waitcnt lgkmcnt(0)
	v_mfma_f32_16x16x32_bf16 v[18:21], v[162:165], v[2:5], v[62:65]
	v_mfma_f32_16x16x32_bf16 v[50:53], v[166:169], v[6:9], v[18:21]
	v_mfma_f32_16x16x32_bf16 v[18:21], v[162:165], v[194:197], v[58:61]
	v_mfma_f32_16x16x32_bf16 v[54:57], v[166:169], v[140:143], v[18:21]
	v_mfma_f32_16x16x32_bf16 v[18:21], v[174:177], v[2:5], v[218:221]
	v_mfma_f32_16x16x32_bf16 v[38:41], v[178:181], v[6:9], v[18:21]
	v_mfma_f32_16x16x32_bf16 v[18:21], v[174:177], v[194:197], v[222:225]
	v_mfma_f32_16x16x32_bf16 v[34:37], v[178:181], v[140:143], v[18:21]
	v_mfma_f32_16x16x32_bf16 v[18:21], v[182:185], v[2:5], v[46:49]
	v_mfma_f32_16x16x32_bf16 v[2:5], v[198:201], v[2:5], v[146:149]
	v_mfma_f32_16x16x32_bf16 v[18:21], v[136:139], v[6:9], v[18:21]
	v_mfma_f32_16x16x32_bf16 v[22:25], v[182:185], v[194:197], v[42:45]
	v_mfma_f32_16x16x32_bf16 v[6:9], v[226:229], v[6:9], v[2:5]
	v_mfma_f32_16x16x32_bf16 v[2:5], v[198:201], v[194:197], v[150:153]
	v_mfma_f32_16x16x32_bf16 v[22:25], v[136:139], v[140:143], v[22:25]
	v_mfma_f32_16x16x32_bf16 v[2:5], v[226:229], v[140:143], v[2:5]
	v_mfma_f32_16x16x32_bf16 v[26:29], v[162:165], v[210:213], v[26:29]
	v_mfma_f32_16x16x32_bf16 v[62:65], v[166:169], v[214:217], v[26:29]
	v_mfma_f32_16x16x32_bf16 v[26:29], v[174:177], v[202:205], v[154:157]
	v_mfma_f32_16x16x32_bf16 v[30:33], v[162:165], v[202:205], v[30:33]
	v_mfma_f32_16x16x32_bf16 v[42:45], v[178:181], v[206:209], v[26:29]
	v_mfma_f32_16x16x32_bf16 v[26:29], v[174:177], v[210:213], v[158:161]
	v_mfma_f32_16x16x32_bf16 v[14:17], v[182:185], v[202:205], v[14:17]
	v_mfma_f32_16x16x32_bf16 v[10:13], v[182:185], v[210:213], v[10:13]
	v_mfma_f32_16x16x32_bf16 v[58:61], v[166:169], v[206:209], v[30:33]
	v_mfma_f32_16x16x32_bf16 v[46:49], v[178:181], v[214:217], v[26:29]
	v_mfma_f32_16x16x32_bf16 v[26:29], v[136:139], v[206:209], v[14:17]
	v_mfma_f32_16x16x32_bf16 v[30:33], v[136:139], v[214:217], v[10:13]
	v_mfma_f32_16x16x32_bf16 v[10:13], v[198:201], v[202:205], v[186:189]
	v_mfma_f32_16x16x32_bf16 v[14:17], v[198:201], v[210:213], v[190:193]
	v_mfma_f32_16x16x32_bf16 v[10:13], v[226:229], v[206:209], v[10:13]
	v_mfma_f32_16x16x32_bf16 v[14:17], v[226:229], v[214:217], v[14:17]
	v_cmp_gt_u32_e32 vcc, s48, v134
	s_barrier
	s_and_saveexec_b64 s[26:27], vcc
	s_cbranch_execz .LBB0_349
	s_barrier

; #define STAGE(P, GP, ktrel) do { const GAS char* _g = (GP) + (ktrel) * (BK * 2); \
;     __builtin_amdgcn_global_load_lds((const GAS unsigned*)(_g + so0), (unsigned*)((char*)(P) + tid_ * 16), 16, 0, 0); \
;     __builtin_amdgcn_global_load_lds((const GAS unsigned*)(_g + so1), (unsigned*)((char*)(P) + tid_ * 16 + 8192), 16, 0, 0); } while (0)
; #define WAIT_L(n) asm volatile("s_waitcnt lgkmcnt(" #n ")" ::: "memory")
; #define BAR __builtin_amdgcn_s_barrier()
; #define SCHED __builtin_amdgcn_sched_barrier(0)
; #define LDA(dst, b, h) for (int m = 0; m < 4; ++m) for (int k = 0; k < 2; ++k) \
;     dst[m][k] = *reinterpret_cast<const bf16x8*>((char*)SA(b, h) + lds_byte(wr * 64 + m * 16 + fr, k * 32 + fq * 8))
; #define LDB(dst, b, h) for (int n = 0; n < 2; ++n) for (int k = 0; k < 2; ++k) \
;     dst[n][k] = *reinterpret_cast<const bf16x8*>((char*)SB(b, h) + lds_byte(wc * 32 + n * 16 + fr, k * 32 + fq * 8))
; #define MMA(ai, bj, At_, Bt_) do { __builtin_amdgcn_s_setprio(1); \
;     for (int m = 0; m < 4; ++m) for (int n = 0; n < 2; ++n) for (int k = 0; k < 2; ++k) \
;       acc[ai][bj][m][n] = __builtin_amdgcn_mfma_f32_16x16x32_bf16(At_[m][k], Bt_[n][k], acc[ai][bj][m][n], 0, 0, 0); \
;     __builtin_amdgcn_s_setprio(0); } while (0)
; template <int K, int LD = K>
; __device__ __forceinline__ void gemm_main(const GAS bf16* A, const GAS bf16* Bt, int brow, int bcol, f32x4 (&acc)[2][2][4][2]) {
;     ...
;     LDB(B0, 0, 0); SCHED; LDA(At, 0, 0); STAGE(SA(1, 1), pA1, 1);
;     WAIT_L(8); BAR; WAIT_L(0); MMA(0, 0, At, B0); BAR; SCHED;
;     LDB(B1, 0, 1); STAGE(SB(0, 0), pB0, 2);
;     BAR; WAIT_L(0); MMA(0, 1, At, B1); BAR;
;     LDA(At, 0, 1); STAGE(SA(0, 0), pA0, 2);
;     BAR; WAIT_L(0); MMA(1, 0, At, B0); BAR; SCHED;
.LBB0_709:
	ds_read_b128 v[146:149], v143
	ds_read_b128 v[150:153], v143 offset:1024
	ds_read_b128 v[154:157], v143 offset:2048
	ds_read_b128 v[158:161], v143 offset:3072
	v_add_u32_e32 v230, 0x100, v141
	v_add_u32_e32 v144, 0xc000, v230
	v_lshl_add_u64 v[214:215], s[20:21], 0, v[130:131]
	v_readfirstlane_b32 s30, v144
	v_add_u32_e32 v145, 0xe000, v230
	v_lshl_add_u64 v[198:199], v[214:215], 0, s[6:7]
	s_mov_b32 m0, s30
	v_lshl_add_u64 v[216:217], s[20:21], 0, v[132:133]
	v_readfirstlane_b32 s30, v145
	ds_read_b128 v[162:165], v138
	ds_read_b128 v[166:169], v138 offset:1024
	ds_read_b128 v[174:177], v137
	ds_read_b128 v[178:181], v137 offset:1024
	ds_read_b128 v[182:185], v136
	ds_read_b128 v[186:189], v136 offset:1024
	ds_read_b128 v[190:193], v135
	ds_read_b128 v[194:197], v135 offset:1024
	global_load_lds_dwordx4 v[198:199], off
	v_lshl_add_u64 v[198:199], v[216:217], 0, s[6:7]
	s_mov_b32 m0, s30
	s_nop 0
	global_load_lds_dwordx4 v[198:199], off
	s_waitcnt lgkmcnt(8)
	s_waitcnt vmcnt(10)
	s_barrier
	s_waitcnt lgkmcnt(0)
	v_mfma_f32_16x16x32_bf16 v[126:129], v[162:165], v[146:149], v[126:129]
	v_mfma_f32_16x16x32_bf16 v[122:125], v[162:165], v[154:157], v[122:125]
	v_mfma_f32_16x16x32_bf16 v[118:121], v[174:177], v[146:149], v[118:121]
	v_mfma_f32_16x16x32_bf16 v[114:117], v[174:177], v[154:157], v[114:117]
	v_mfma_f32_16x16x32_bf16 v[110:113], v[182:185], v[146:149], v[110:113]
	v_mfma_f32_16x16x32_bf16 v[106:109], v[182:185], v[154:157], v[106:109]
	v_mfma_f32_16x16x32_bf16 v[102:105], v[190:193], v[146:149], v[102:105]
	v_mfma_f32_16x16x32_bf16 v[98:101], v[190:193], v[154:157], v[98:101]
	v_mfma_f32_16x16x32_bf16 v[126:129], v[166:169], v[150:153], v[126:129]
	v_mfma_f32_16x16x32_bf16 v[122:125], v[166:169], v[158:161], v[122:125]
	v_mfma_f32_16x16x32_bf16 v[118:121], v[178:181], v[150:153], v[118:121]
	v_mfma_f32_16x16x32_bf16 v[114:117], v[178:181], v[158:161], v[114:117]
	v_mfma_f32_16x16x32_bf16 v[110:113], v[186:189], v[150:153], v[110:113]
	v_mfma_f32_16x16x32_bf16 v[106:109], v[186:189], v[158:161], v[106:109]
	v_mfma_f32_16x16x32_bf16 v[102:105], v[194:197], v[150:153], v[102:105]
	v_mfma_f32_16x16x32_bf16 v[98:101], v[194:197], v[158:161], v[98:101]
	s_barrier
	v_add_u32_e32 v224, s47, v141
	v_lshl_add_u64 v[218:219], s[28:29], 0, v[130:131]
	v_readfirstlane_b32 s30, v224
	v_lshl_add_u64 v[220:221], v[218:219], 0, s[10:11]
	s_mov_b32 m0, s30
	v_add_u32_e32 v224, 0x2000, v224
	ds_read_b128 v[198:201], v142
	ds_read_b128 v[202:205], v142 offset:1024
	ds_read_b128 v[206:209], v142 offset:2048
	ds_read_b128 v[210:213], v142 offset:3072
	global_load_lds_dwordx4 v[220:221], off
	v_lshl_add_u64 v[220:221], s[28:29], 0, v[132:133]
	v_readfirstlane_b32 s30, v224
	v_lshl_add_u64 v[222:223], v[220:221], 0, s[10:11]
	s_mov_b32 m0, s30
	s_add_u32 s28, s28, 0x100
	global_load_lds_dwordx4 v[222:223], off
	s_waitcnt vmcnt(10)
	s_barrier
	s_waitcnt lgkmcnt(0)
	s_addc_u32 s29, s29, 0
	s_waitcnt lgkmcnt(0)
	v_mfma_f32_16x16x32_bf16 v[94:97], v[162:165], v[198:201], v[94:97]
	v_mfma_f32_16x16x32_bf16 v[90:93], v[162:165], v[206:209], v[90:93]
	v_mfma_f32_16x16x32_bf16 v[86:89], v[174:177], v[198:201], v[86:89]
	v_mfma_f32_16x16x32_bf16 v[82:85], v[174:177], v[206:209], v[82:85]
	v_mfma_f32_16x16x32_bf16 v[78:81], v[182:185], v[198:201], v[78:81]
	v_mfma_f32_16x16x32_bf16 v[74:77], v[182:185], v[206:209], v[74:77]
	v_mfma_f32_16x16x32_bf16 v[70:73], v[190:193], v[198:201], v[70:73]
	v_mfma_f32_16x16x32_bf16 v[66:69], v[190:193], v[206:209], v[66:69]
	v_mfma_f32_16x16x32_bf16 v[94:97], v[166:169], v[202:205], v[94:97]
	v_mfma_f32_16x16x32_bf16 v[90:93], v[166:169], v[210:213], v[90:93]
	v_mfma_f32_16x16x32_bf16 v[86:89], v[178:181], v[202:205], v[86:89]
	v_mfma_f32_16x16x32_bf16 v[82:85], v[178:181], v[210:213], v[82:85]
	v_mfma_f32_16x16x32_bf16 v[78:81], v[186:189], v[202:205], v[78:81]
	v_mfma_f32_16x16x32_bf16 v[74:77], v[186:189], v[210:213], v[74:77]
	v_mfma_f32_16x16x32_bf16 v[70:73], v[194:197], v[202:205], v[70:73]
	v_mfma_f32_16x16x32_bf16 v[66:69], v[194:197], v[210:213], v[66:69]
	v_lshl_add_u64 v[222:223], s[26:27], 0, v[130:131]
	v_readfirstlane_b32 s30, v230
	v_lshl_add_u64 v[224:225], v[222:223], 0, s[10:11]
	s_mov_b32 m0, s30
	v_add_u32_e32 v228, 0x2000, v230
	s_barrier
	ds_read_b128 v[162:165], v138 offset:16384
	ds_read_b128 v[166:169], v138 offset:17408
	ds_read_b128 v[174:177], v137 offset:16384
	ds_read_b128 v[178:181], v137 offset:17408
	ds_read_b128 v[182:185], v136 offset:16384
	ds_read_b128 v[186:189], v136 offset:17408
	ds_read_b128 v[190:193], v135 offset:16384
	ds_read_b128 v[194:197], v135 offset:17408
	global_load_lds_dwordx4 v[224:225], off
	v_lshl_add_u64 v[224:225], s[26:27], 0, v[132:133]
	v_readfirstlane_b32 s30, v228
	v_lshl_add_u64 v[226:227], v[224:225], 0, s[10:11]
	s_mov_b32 m0, s30
	s_add_u32 s26, s26, 0x100
	global_load_lds_dwordx4 v[226:227], off
	s_barrier
	s_waitcnt lgkmcnt(0)
	s_addc_u32 s27, s27, 0
	s_waitcnt lgkmcnt(0)
	v_mfma_f32_16x16x32_bf16 v[62:65], v[162:165], v[146:149], v[62:65]
	v_mfma_f32_16x16x32_bf16 v[58:61], v[162:165], v[154:157], v[58:61]
	v_mfma_f32_16x16x32_bf16 v[54:57], v[174:177], v[146:149], v[54:57]
	v_mfma_f32_16x16x32_bf16 v[50:53], v[174:177], v[154:157], v[50:53]
	v_mfma_f32_16x16x32_bf16 v[46:49], v[182:185], v[146:149], v[46:49]
	v_mfma_f32_16x16x32_bf16 v[42:45], v[182:185], v[154:157], v[42:45]
	v_mfma_f32_16x16x32_bf16 v[38:41], v[190:193], v[146:149], v[38:41]
	v_mfma_f32_16x16x32_bf16 v[34:37], v[190:193], v[154:157], v[34:37]
	v_mfma_f32_16x16x32_bf16 v[62:65], v[166:169], v[150:153], v[62:65]
	v_mfma_f32_16x16x32_bf16 v[58:61], v[166:169], v[158:161], v[58:61]
	v_mfma_f32_16x16x32_bf16 v[54:57], v[178:181], v[150:153], v[54:57]
	v_mfma_f32_16x16x32_bf16 v[50:53], v[178:181], v[158:161], v[50:53]
	v_mfma_f32_16x16x32_bf16 v[46:49], v[186:189], v[150:153], v[46:49]
	v_mfma_f32_16x16x32_bf16 v[42:45], v[186:189], v[158:161], v[42:45]
	v_mfma_f32_16x16x32_bf16 v[38:41], v[194:197], v[150:153], v[38:41]
	v_mfma_f32_16x16x32_bf16 v[34:37], v[194:197], v[158:161], v[34:37]
	s_barrier
; #define STAGE(P, GP, ktrel) do { const GAS char* _g = (GP) + (ktrel) * (BK * 2); \
;     __builtin_amdgcn_global_load_lds((const GAS unsigned*)(_g + so0), (unsigned*)((char*)(P) + tid_ * 16), 16, 0, 0); \
;     __builtin_amdgcn_global_load_lds((const GAS unsigned*)(_g + so1), (unsigned*)((char*)(P) + tid_ * 16 + 8192), 16, 0, 0); } while (0)
; #define WAIT_V(n) asm volatile("s_waitcnt vmcnt(" #n ")" ::: "memory")
; #define WAIT_L(n) asm volatile("s_waitcnt lgkmcnt(" #n ")" ::: "memory")
; #define BAR __builtin_amdgcn_s_barrier()
; #define SCHED __builtin_amdgcn_sched_barrier(0)
; #define LDA(dst, b, h) for (int m = 0; m < 4; ++m) for (int k = 0; k < 2; ++k) \
;     dst[m][k] = *reinterpret_cast<const bf16x8*>((char*)SA(b, h) + lds_byte(wr * 64 + m * 16 + fr, k * 32 + fq * 8))
; #define LDB(dst, b, h) for (int n = 0; n < 2; ++n) for (int k = 0; k < 2; ++k) \
;     dst[n][k] = *reinterpret_cast<const bf16x8*>((char*)SB(b, h) + lds_byte(wc * 32 + n * 16 + fr, k * 32 + fq * 8))
; #define MMA(ai, bj, At_, Bt_) do { __builtin_amdgcn_s_setprio(1); \
;     for (int m = 0; m < 4; ++m) for (int n = 0; n < 2; ++n) for (int k = 0; k < 2; ++k) \
;       acc[ai][bj][m][n] = __builtin_amdgcn_mfma_f32_16x16x32_bf16(At_[m][k], Bt_[n][k], acc[ai][bj][m][n], 0, 0, 0); \
;     __builtin_amdgcn_s_setprio(0); } while (0)
; template <int K, int LD = K>
; __device__ __forceinline__ void gemm_main(const GAS bf16* A, const GAS bf16* Bt, int brow, int bcol, f32x4 (&acc)[2][2][4][2]) {
;     ...
;     STAGE(SB(0, 1), pB1, 2);
;     WAIT_V(6); BAR; MMA(1, 1, At, B1); BAR;
;     LDB(B0, 1, 0); SCHED; LDA(At, 1, 0); STAGE(SA(0, 1), pA1, 2);
;     WAIT_L(8); BAR; WAIT_L(0); MMA(0, 0, At, B0); BAR; SCHED;
;     LDB(B1, 1, 1); STAGE(SB(1, 0), pB0, 3);
;     BAR; WAIT_L(0); MMA(0, 1, At, B1); BAR;
	v_add_u32_e32 v148, s48, v141
	v_lshl_add_u64 v[226:227], s[24:25], 0, v[130:131]
	v_readfirstlane_b32 s30, v148
	v_add_u32_e32 v148, 0x2000, v148
	v_lshl_add_u64 v[146:147], v[226:227], 0, s[10:11]
	s_mov_b32 m0, s30
	v_lshl_add_u64 v[228:229], s[24:25], 0, v[132:133]
	v_readfirstlane_b32 s30, v148
	global_load_lds_dwordx4 v[146:147], off
	v_lshl_add_u64 v[146:147], v[228:229], 0, s[10:11]
	s_mov_b32 m0, s30
	s_add_u32 s24, s24, 0x100
	global_load_lds_dwordx4 v[146:147], off
	s_waitcnt vmcnt(10)
	s_addc_u32 s25, s25, 0
	s_barrier
	v_mfma_f32_16x16x32_bf16 v[30:33], v[162:165], v[198:201], v[30:33]
	v_mfma_f32_16x16x32_bf16 v[26:29], v[162:165], v[206:209], v[26:29]
	v_mfma_f32_16x16x32_bf16 v[22:25], v[174:177], v[198:201], v[22:25]
	v_mfma_f32_16x16x32_bf16 v[18:21], v[174:177], v[206:209], v[18:21]
	v_mfma_f32_16x16x32_bf16 v[14:17], v[182:185], v[198:201], v[14:17]
	v_mfma_f32_16x16x32_bf16 v[10:13], v[182:185], v[206:209], v[10:13]
	v_mfma_f32_16x16x32_bf16 v[6:9], v[190:193], v[198:201], v[6:9]
	v_mfma_f32_16x16x32_bf16 v[2:5], v[190:193], v[206:209], v[2:5]
	v_mfma_f32_16x16x32_bf16 v[30:33], v[166:169], v[202:205], v[30:33]
	v_mfma_f32_16x16x32_bf16 v[26:29], v[166:169], v[210:213], v[26:29]
	v_mfma_f32_16x16x32_bf16 v[22:25], v[178:181], v[202:205], v[22:25]
	v_mfma_f32_16x16x32_bf16 v[18:21], v[178:181], v[210:213], v[18:21]
	v_mfma_f32_16x16x32_bf16 v[14:17], v[186:189], v[202:205], v[14:17]
	v_mfma_f32_16x16x32_bf16 v[10:13], v[186:189], v[210:213], v[10:13]
	v_mfma_f32_16x16x32_bf16 v[6:9], v[194:197], v[202:205], v[6:9]
	v_mfma_f32_16x16x32_bf16 v[2:5], v[194:197], v[210:213], v[2:5]
	s_barrier
	ds_read_b128 v[146:149], v140
	ds_read_b128 v[150:153], v140 offset:1024
	ds_read_b128 v[154:157], v140 offset:2048
	ds_read_b128 v[158:161], v140 offset:3072
	v_add_u32_e32 v200, 0x4000, v230
	v_lshl_add_u64 v[198:199], v[214:215], 0, s[10:11]
	v_readfirstlane_b32 s30, v200
	v_add_u32_e32 v200, 0x6000, v230
	s_mov_b32 m0, s30
	v_readfirstlane_b32 s30, v200
	ds_read_b128 v[162:165], v138 offset:32768
	ds_read_b128 v[166:169], v138 offset:33792
	ds_read_b128 v[174:177], v137 offset:32768
	ds_read_b128 v[178:181], v137 offset:33792
	ds_read_b128 v[182:185], v136 offset:32768
	ds_read_b128 v[186:189], v136 offset:33792
	ds_read_b128 v[190:193], v135 offset:32768
	ds_read_b128 v[194:197], v135 offset:33792
	global_load_lds_dwordx4 v[198:199], off
	v_lshl_add_u64 v[198:199], v[216:217], 0, s[10:11]
	s_mov_b32 m0, s30
	s_add_u32 s20, s20, 0x100
	global_load_lds_dwordx4 v[198:199], off
	s_waitcnt lgkmcnt(8)
	s_waitcnt vmcnt(10)
	s_barrier
	s_waitcnt lgkmcnt(0)
	s_addc_u32 s21, s21, 0
	s_waitcnt lgkmcnt(0)
	v_mfma_f32_16x16x32_bf16 v[126:129], v[162:165], v[146:149], v[126:129]
	v_mfma_f32_16x16x32_bf16 v[122:125], v[162:165], v[154:157], v[122:125]
	v_mfma_f32_16x16x32_bf16 v[118:121], v[174:177], v[146:149], v[118:121]
	v_mfma_f32_16x16x32_bf16 v[114:117], v[174:177], v[154:157], v[114:117]
	v_mfma_f32_16x16x32_bf16 v[110:113], v[182:185], v[146:149], v[110:113]
	v_mfma_f32_16x16x32_bf16 v[106:109], v[182:185], v[154:157], v[106:109]
	v_mfma_f32_16x16x32_bf16 v[102:105], v[190:193], v[146:149], v[102:105]
	v_mfma_f32_16x16x32_bf16 v[98:101], v[190:193], v[154:157], v[98:101]
	v_mfma_f32_16x16x32_bf16 v[126:129], v[166:169], v[150:153], v[126:129]
	v_mfma_f32_16x16x32_bf16 v[122:125], v[166:169], v[158:161], v[122:125]
	v_mfma_f32_16x16x32_bf16 v[118:121], v[178:181], v[150:153], v[118:121]
	v_mfma_f32_16x16x32_bf16 v[114:117], v[178:181], v[158:161], v[114:117]
	v_mfma_f32_16x16x32_bf16 v[110:113], v[186:189], v[150:153], v[110:113]
	v_mfma_f32_16x16x32_bf16 v[106:109], v[186:189], v[158:161], v[106:109]
	v_mfma_f32_16x16x32_bf16 v[102:105], v[194:197], v[150:153], v[102:105]
	v_mfma_f32_16x16x32_bf16 v[98:101], v[194:197], v[158:161], v[98:101]
	s_barrier
	v_add_u32_e32 v216, s49, v141
	v_lshl_add_u64 v[214:215], v[218:219], 0, s[12:13]
	v_readfirstlane_b32 s30, v216
	v_add_u32_e32 v216, 0x2000, v216
	s_mov_b32 m0, s30
	v_readfirstlane_b32 s30, v216
	ds_read_b128 v[198:201], v139
	ds_read_b128 v[202:205], v139 offset:1024
	ds_read_b128 v[206:209], v139 offset:2048
	ds_read_b128 v[210:213], v139 offset:3072
	global_load_lds_dwordx4 v[214:215], off
	v_lshl_add_u64 v[214:215], v[220:221], 0, s[12:13]
	s_mov_b32 m0, s30
	s_nop 0
	global_load_lds_dwordx4 v[214:215], off
	s_waitcnt vmcnt(10)
	s_barrier
	s_waitcnt lgkmcnt(0)
	v_mfma_f32_16x16x32_bf16 v[94:97], v[162:165], v[198:201], v[94:97]
	v_mfma_f32_16x16x32_bf16 v[90:93], v[162:165], v[206:209], v[90:93]
	v_mfma_f32_16x16x32_bf16 v[86:89], v[174:177], v[198:201], v[86:89]
	v_mfma_f32_16x16x32_bf16 v[82:85], v[174:177], v[206:209], v[82:85]
	v_mfma_f32_16x16x32_bf16 v[78:81], v[182:185], v[198:201], v[78:81]
	v_mfma_f32_16x16x32_bf16 v[74:77], v[182:185], v[206:209], v[74:77]
	v_mfma_f32_16x16x32_bf16 v[70:73], v[190:193], v[198:201], v[70:73]
	v_mfma_f32_16x16x32_bf16 v[66:69], v[190:193], v[206:209], v[66:69]
	v_mfma_f32_16x16x32_bf16 v[94:97], v[166:169], v[202:205], v[94:97]
	v_mfma_f32_16x16x32_bf16 v[90:93], v[166:169], v[210:213], v[90:93]
	v_mfma_f32_16x16x32_bf16 v[86:89], v[178:181], v[202:205], v[86:89]
	v_mfma_f32_16x16x32_bf16 v[82:85], v[178:181], v[210:213], v[82:85]
	v_mfma_f32_16x16x32_bf16 v[78:81], v[186:189], v[202:205], v[78:81]
	v_mfma_f32_16x16x32_bf16 v[74:77], v[186:189], v[210:213], v[74:77]
	v_mfma_f32_16x16x32_bf16 v[70:73], v[194:197], v[202:205], v[70:73]
	v_mfma_f32_16x16x32_bf16 v[66:69], v[194:197], v[210:213], v[66:69]
	v_add_u32_e32 v216, 0x8000, v230
	v_lshl_add_u64 v[214:215], v[222:223], 0, s[12:13]
	v_readfirstlane_b32 s30, v216
	v_add_u32_e32 v216, 0xa000, v230
	s_mov_b32 m0, s30
	v_readfirstlane_b32 s30, v216
	s_barrier
; #define STAGE(P, GP, ktrel) do { const GAS char* _g = (GP) + (ktrel) * (BK * 2); \
;     __builtin_amdgcn_global_load_lds((const GAS unsigned*)(_g + so0), (unsigned*)((char*)(P) + tid_ * 16), 16, 0, 0); \
;     __builtin_amdgcn_global_load_lds((const GAS unsigned*)(_g + so1), (unsigned*)((char*)(P) + tid_ * 16 + 8192), 16, 0, 0); } while (0)
; #define WAIT_V(n) asm volatile("s_waitcnt vmcnt(" #n ")" ::: "memory")
; #define WAIT_L(n) asm volatile("s_waitcnt lgkmcnt(" #n ")" ::: "memory")
; #define BAR __builtin_amdgcn_s_barrier()
; #define SCHED __builtin_amdgcn_sched_barrier(0)
; #define LDA(dst, b, h) for (int m = 0; m < 4; ++m) for (int k = 0; k < 2; ++k) \
;     dst[m][k] = *reinterpret_cast<const bf16x8*>((char*)SA(b, h) + lds_byte(wr * 64 + m * 16 + fr, k * 32 + fq * 8))
; #define LDB(dst, b, h) for (int n = 0; n < 2; ++n) for (int k = 0; k < 2; ++k) \
;     dst[n][k] = *reinterpret_cast<const bf16x8*>((char*)SB(b, h) + lds_byte(wc * 32 + n * 16 + fr, k * 32 + fq * 8))
; #define MMA(ai, bj, At_, Bt_) do { __builtin_amdgcn_s_setprio(1); \
;     for (int m = 0; m < 4; ++m) for (int n = 0; n < 2; ++n) for (int k = 0; k < 2; ++k) \
;       acc[ai][bj][m][n] = __builtin_amdgcn_mfma_f32_16x16x32_bf16(At_[m][k], Bt_[n][k], acc[ai][bj][m][n], 0, 0, 0); \
;     __builtin_amdgcn_s_setprio(0); } while (0)
; template <int K, int LD = K>
; __device__ __forceinline__ void gemm_main(const GAS bf16* A, const GAS bf16* Bt, int brow, int bcol, f32x4 (&acc)[2][2][4][2]) {
;     ...
;     LDA(At, 1, 1); STAGE(SA(1, 0), pA0, 3);
;     BAR; WAIT_L(0); MMA(1, 0, At, B0); BAR; SCHED;
;     STAGE(SB(1, 1), pB1, 3);
;     WAIT_V(6); BAR; MMA(1, 1, At, B1); BAR;
;     pA0 += 4 * BK; pA1 += 4 * BK; pB0 += 4 * BK; pB1 += 4 * BK;
;     asm volatile("" : "+s"(pA0), "+s"(pA1), "+s"(pB0), "+s"(pB1));
;   }
;   { LDB(B0, 0, 0); LDA(At, 0, 0); STAGE(SA(1, 1), pA1, 1);
;     BAR; WAIT_L(0); MMA(0, 0, At, B0); BAR;
;     LDB(B1, 0, 1); BAR; WAIT_L(0); MMA(0, 1, At, B1); BAR;
	ds_read_b128 v[162:165], v138 offset:49152
	ds_read_b128 v[166:169], v138 offset:50176
	ds_read_b128 v[174:177], v137 offset:49152
	ds_read_b128 v[178:181], v137 offset:50176
	ds_read_b128 v[182:185], v136 offset:49152
	ds_read_b128 v[186:189], v136 offset:50176
	ds_read_b128 v[190:193], v135 offset:49152
	ds_read_b128 v[194:197], v135 offset:50176
	global_load_lds_dwordx4 v[214:215], off
	v_lshl_add_u64 v[214:215], v[224:225], 0, s[12:13]
	s_mov_b32 m0, s30
	s_nop 0
	global_load_lds_dwordx4 v[214:215], off
	s_barrier
	s_waitcnt lgkmcnt(0)
	v_mfma_f32_16x16x32_bf16 v[62:65], v[162:165], v[146:149], v[62:65]
	v_mfma_f32_16x16x32_bf16 v[58:61], v[162:165], v[154:157], v[58:61]
	v_mfma_f32_16x16x32_bf16 v[54:57], v[174:177], v[146:149], v[54:57]
	v_mfma_f32_16x16x32_bf16 v[50:53], v[174:177], v[154:157], v[50:53]
	v_mfma_f32_16x16x32_bf16 v[46:49], v[182:185], v[146:149], v[46:49]
	v_mfma_f32_16x16x32_bf16 v[42:45], v[182:185], v[154:157], v[42:45]
	v_mfma_f32_16x16x32_bf16 v[38:41], v[190:193], v[146:149], v[38:41]
	v_mfma_f32_16x16x32_bf16 v[34:37], v[190:193], v[154:157], v[34:37]
	v_mfma_f32_16x16x32_bf16 v[62:65], v[166:169], v[150:153], v[62:65]
	v_mfma_f32_16x16x32_bf16 v[58:61], v[166:169], v[158:161], v[58:61]
	v_mfma_f32_16x16x32_bf16 v[54:57], v[178:181], v[150:153], v[54:57]
	v_mfma_f32_16x16x32_bf16 v[50:53], v[178:181], v[158:161], v[50:53]
	v_mfma_f32_16x16x32_bf16 v[46:49], v[186:189], v[150:153], v[46:49]
	v_mfma_f32_16x16x32_bf16 v[42:45], v[186:189], v[158:161], v[42:45]
	v_mfma_f32_16x16x32_bf16 v[38:41], v[194:197], v[150:153], v[38:41]
	v_mfma_f32_16x16x32_bf16 v[34:37], v[194:197], v[158:161], v[34:37]
	s_barrier
	v_add_u32_e32 v148, s50, v141
	v_lshl_add_u64 v[146:147], v[226:227], 0, s[12:13]
	v_readfirstlane_b32 s30, v148
	v_add_u32_e32 v148, 0x2000, v148
	s_mov_b32 m0, s30
	v_readfirstlane_b32 s30, v148
	global_load_lds_dwordx4 v[146:147], off
	v_lshl_add_u64 v[146:147], v[228:229], 0, s[12:13]
	s_mov_b32 m0, s30
	s_nop 0
	global_load_lds_dwordx4 v[146:147], off
	s_waitcnt vmcnt(10)
	s_barrier
	v_mfma_f32_16x16x32_bf16 v[30:33], v[162:165], v[198:201], v[30:33]
	v_mfma_f32_16x16x32_bf16 v[26:29], v[162:165], v[206:209], v[26:29]
	v_mfma_f32_16x16x32_bf16 v[22:25], v[174:177], v[198:201], v[22:25]
	v_mfma_f32_16x16x32_bf16 v[18:21], v[174:177], v[206:209], v[18:21]
	v_mfma_f32_16x16x32_bf16 v[14:17], v[182:185], v[198:201], v[14:17]
	v_mfma_f32_16x16x32_bf16 v[10:13], v[182:185], v[206:209], v[10:13]
	v_mfma_f32_16x16x32_bf16 v[6:9], v[190:193], v[198:201], v[6:9]
	v_mfma_f32_16x16x32_bf16 v[2:5], v[190:193], v[206:209], v[2:5]
	v_mfma_f32_16x16x32_bf16 v[30:33], v[166:169], v[202:205], v[30:33]
	v_mfma_f32_16x16x32_bf16 v[26:29], v[166:169], v[210:213], v[26:29]
	v_mfma_f32_16x16x32_bf16 v[22:25], v[178:181], v[202:205], v[22:25]
	v_mfma_f32_16x16x32_bf16 v[18:21], v[178:181], v[210:213], v[18:21]
	v_mfma_f32_16x16x32_bf16 v[14:17], v[186:189], v[202:205], v[14:17]
	v_mfma_f32_16x16x32_bf16 v[10:13], v[186:189], v[210:213], v[10:13]
	v_mfma_f32_16x16x32_bf16 v[6:9], v[194:197], v[202:205], v[6:9]
	v_mfma_f32_16x16x32_bf16 v[2:5], v[194:197], v[210:213], v[2:5]
	s_add_i32 s17, s17, 2
	s_cmp_lt_u32 s17, 4
	s_barrier
	s_cbranch_scc1 .LBB0_709
	v_lshl_add_u64 v[198:199], s[20:21], 0, v[130:131]
	v_readfirstlane_b32 s17, v144
	v_lshl_add_u64 v[198:199], v[198:199], 0, s[6:7]
	s_mov_b32 m0, s17
	v_lshl_add_u64 v[132:133], s[20:21], 0, v[132:133]
	v_readfirstlane_b32 s17, v145
	ds_read_b128 v[146:149], v143
	ds_read_b128 v[150:153], v143 offset:1024
	ds_read_b128 v[154:157], v143 offset:2048
	ds_read_b128 v[158:161], v143 offset:3072
	ds_read_b128 v[162:165], v138
	ds_read_b128 v[166:169], v138 offset:1024
	ds_read_b128 v[174:177], v137
	ds_read_b128 v[178:181], v137 offset:1024
	ds_read_b128 v[182:185], v136
	ds_read_b128 v[186:189], v136 offset:1024
	ds_read_b128 v[190:193], v135
	ds_read_b128 v[194:197], v135 offset:1024
	global_load_lds_dwordx4 v[198:199], off
	v_lshl_add_u64 v[132:133], v[132:133], 0, s[6:7]
	s_mov_b32 m0, s17
	s_nop 0
	global_load_lds_dwordx4 v[132:133], off
	s_waitcnt vmcnt(10)
	s_barrier
	s_waitcnt lgkmcnt(0)
	v_mfma_f32_16x16x32_bf16 v[126:129], v[162:165], v[146:149], v[126:129]
	v_mfma_f32_16x16x32_bf16 v[122:125], v[162:165], v[154:157], v[122:125]
	v_mfma_f32_16x16x32_bf16 v[110:113], v[182:185], v[146:149], v[110:113]
	v_mfma_f32_16x16x32_bf16 v[106:109], v[182:185], v[154:157], v[106:109]
	v_mfma_f32_16x16x32_bf16 v[126:129], v[166:169], v[150:153], v[126:129]
	v_mfma_f32_16x16x32_bf16 v[122:125], v[166:169], v[158:161], v[122:125]
	v_mfma_f32_16x16x32_bf16 v[118:121], v[174:177], v[146:149], v[118:121]
	v_mfma_f32_16x16x32_bf16 v[114:117], v[174:177], v[154:157], v[114:117]
	v_mfma_f32_16x16x32_bf16 v[110:113], v[186:189], v[150:153], v[110:113]
	v_mfma_f32_16x16x32_bf16 v[106:109], v[186:189], v[158:161], v[106:109]
	v_mfma_f32_16x16x32_bf16 v[102:105], v[190:193], v[146:149], v[102:105]
	v_mfma_f32_16x16x32_bf16 v[98:101], v[190:193], v[154:157], v[98:101]
	v_mfma_f32_16x16x32_bf16 v[198:201], v[178:181], v[150:153], v[118:121]
	v_mfma_f32_16x16x32_bf16 v[202:205], v[178:181], v[158:161], v[114:117]
	v_mfma_f32_16x16x32_bf16 v[206:209], v[194:197], v[150:153], v[102:105]
	v_mfma_f32_16x16x32_bf16 v[210:213], v[194:197], v[158:161], v[98:101]
	s_barrier
	s_nop 1
	ds_read_b128 v[98:101], v142
	ds_read_b128 v[102:105], v142 offset:1024
	ds_read_b128 v[114:117], v142 offset:2048
	ds_read_b128 v[118:121], v142 offset:3072
	s_waitcnt vmcnt(8)
	s_barrier
; #define WAIT_V(n) asm volatile("s_waitcnt vmcnt(" #n ")" ::: "memory")
; #define WAIT_L(n) asm volatile("s_waitcnt lgkmcnt(" #n ")" ::: "memory")
; #define BAR __builtin_amdgcn_s_barrier()
; #define LDA(dst, b, h) for (int m = 0; m < 4; ++m) for (int k = 0; k < 2; ++k) \
;     dst[m][k] = *reinterpret_cast<const bf16x8*>((char*)SA(b, h) + lds_byte(wr * 64 + m * 16 + fr, k * 32 + fq * 8))
; #define LDB(dst, b, h) for (int n = 0; n < 2; ++n) for (int k = 0; k < 2; ++k) \
;     dst[n][k] = *reinterpret_cast<const bf16x8*>((char*)SB(b, h) + lds_byte(wc * 32 + n * 16 + fr, k * 32 + fq * 8))
; #define MMA(ai, bj, At_, Bt_) do { __builtin_amdgcn_s_setprio(1); \
;     for (int m = 0; m < 4; ++m) for (int n = 0; n < 2; ++n) for (int k = 0; k < 2; ++k) \
;       acc[ai][bj][m][n] = __builtin_amdgcn_mfma_f32_16x16x32_bf16(At_[m][k], Bt_[n][k], acc[ai][bj][m][n], 0, 0, 0); \
;     __builtin_amdgcn_s_setprio(0); } while (0)
; template <int K, int LD = K>
; __device__ __forceinline__ void gemm_main(const GAS bf16* A, const GAS bf16* Bt, int brow, int bcol, f32x4 (&acc)[2][2][4][2]) {
;     ...
;     LDB(B1, 0, 1); BAR; WAIT_L(0); MMA(0, 1, At, B1); BAR;
;     LDA(At, 0, 1); WAIT_V(4); BAR; WAIT_L(0); MMA(1, 0, At, B0); MMA(1, 1, At, B1); BAR; }
	s_waitcnt lgkmcnt(0)
	v_mfma_f32_16x16x32_bf16 v[94:97], v[162:165], v[98:101], v[94:97]
	v_mfma_f32_16x16x32_bf16 v[90:93], v[162:165], v[114:117], v[90:93]
	v_mfma_f32_16x16x32_bf16 v[70:73], v[190:193], v[98:101], v[70:73]
	v_mfma_f32_16x16x32_bf16 v[66:69], v[190:193], v[114:117], v[66:69]
	v_mfma_f32_16x16x32_bf16 v[94:97], v[166:169], v[102:105], v[94:97]
	v_mfma_f32_16x16x32_bf16 v[90:93], v[166:169], v[118:121], v[90:93]
	v_mfma_f32_16x16x32_bf16 v[86:89], v[174:177], v[98:101], v[86:89]
	v_mfma_f32_16x16x32_bf16 v[82:85], v[174:177], v[114:117], v[82:85]
	v_mfma_f32_16x16x32_bf16 v[78:81], v[182:185], v[98:101], v[78:81]
	v_mfma_f32_16x16x32_bf16 v[74:77], v[182:185], v[114:117], v[74:77]
	v_mfma_f32_16x16x32_bf16 v[70:73], v[194:197], v[102:105], v[70:73]
	v_mfma_f32_16x16x32_bf16 v[66:69], v[194:197], v[118:121], v[66:69]
	v_mfma_f32_16x16x32_bf16 v[142:145], v[178:181], v[102:105], v[86:89]
	v_mfma_f32_16x16x32_bf16 v[162:165], v[178:181], v[118:121], v[82:85]
	v_mfma_f32_16x16x32_bf16 v[166:169], v[186:189], v[102:105], v[78:81]
	v_mfma_f32_16x16x32_bf16 v[174:177], v[186:189], v[118:121], v[74:77]
	s_barrier
	s_nop 0
	ds_read_b128 v[74:77], v138 offset:16384
	ds_read_b128 v[78:81], v138 offset:17408
	ds_read_b128 v[82:85], v137 offset:16384
	ds_read_b128 v[86:89], v137 offset:17408
	ds_read_b128 v[178:181], v136 offset:16384
	ds_read_b128 v[182:185], v136 offset:17408
	ds_read_b128 v[186:189], v135 offset:16384
	ds_read_b128 v[190:193], v135 offset:17408
	s_waitcnt vmcnt(4)
	s_barrier
	s_waitcnt lgkmcnt(0)
	v_mfma_f32_16x16x32_bf16 v[62:65], v[74:77], v[146:149], v[62:65]
	v_mfma_f32_16x16x32_bf16 v[58:61], v[74:77], v[154:157], v[58:61]
	v_mfma_f32_16x16x32_bf16 v[54:57], v[82:85], v[146:149], v[54:57]
	v_mfma_f32_16x16x32_bf16 v[50:53], v[82:85], v[154:157], v[50:53]
	v_mfma_f32_16x16x32_bf16 v[38:41], v[186:189], v[146:149], v[38:41]
	v_mfma_f32_16x16x32_bf16 v[34:37], v[186:189], v[154:157], v[34:37]
	v_mfma_f32_16x16x32_bf16 v[62:65], v[78:81], v[150:153], v[62:65]
	v_mfma_f32_16x16x32_bf16 v[58:61], v[78:81], v[158:161], v[58:61]
	v_mfma_f32_16x16x32_bf16 v[54:57], v[86:89], v[150:153], v[54:57]
	v_mfma_f32_16x16x32_bf16 v[50:53], v[86:89], v[158:161], v[50:53]
	v_mfma_f32_16x16x32_bf16 v[46:49], v[178:181], v[146:149], v[46:49]
	v_mfma_f32_16x16x32_bf16 v[42:45], v[178:181], v[154:157], v[42:45]
	v_mfma_f32_16x16x32_bf16 v[38:41], v[190:193], v[150:153], v[38:41]
	v_mfma_f32_16x16x32_bf16 v[34:37], v[190:193], v[158:161], v[34:37]
	v_mfma_f32_16x16x32_bf16 v[194:197], v[182:185], v[150:153], v[46:49]
	v_mfma_f32_16x16x32_bf16 v[214:217], v[182:185], v[158:161], v[42:45]
	v_mfma_f32_16x16x32_bf16 v[22:25], v[82:85], v[98:101], v[22:25]
	v_mfma_f32_16x16x32_bf16 v[18:21], v[82:85], v[114:117], v[18:21]
	v_mfma_f32_16x16x32_bf16 v[14:17], v[178:181], v[98:101], v[14:17]
	v_mfma_f32_16x16x32_bf16 v[10:13], v[178:181], v[114:117], v[10:13]
	v_mfma_f32_16x16x32_bf16 v[30:33], v[74:77], v[98:101], v[30:33]
	v_mfma_f32_16x16x32_bf16 v[26:29], v[74:77], v[114:117], v[26:29]
	v_mfma_f32_16x16x32_bf16 v[22:25], v[86:89], v[102:105], v[22:25]
	v_mfma_f32_16x16x32_bf16 v[18:21], v[86:89], v[118:121], v[18:21]
	v_mfma_f32_16x16x32_bf16 v[14:17], v[182:185], v[102:105], v[14:17]
	v_mfma_f32_16x16x32_bf16 v[10:13], v[182:185], v[118:121], v[10:13]
	v_mfma_f32_16x16x32_bf16 v[6:9], v[186:189], v[98:101], v[6:9]
	v_mfma_f32_16x16x32_bf16 v[2:5], v[186:189], v[114:117], v[2:5]
	v_mfma_f32_16x16x32_bf16 v[146:149], v[78:81], v[102:105], v[30:33]
	v_mfma_f32_16x16x32_bf16 v[150:153], v[78:81], v[118:121], v[26:29]
	v_mfma_f32_16x16x32_bf16 v[154:157], v[190:193], v[102:105], v[6:9]
	v_mfma_f32_16x16x32_bf16 v[158:161], v[190:193], v[118:121], v[2:5]
	s_barrier
	s_nop 1
	ds_read_b128 v[2:5], v140
	ds_read_b128 v[6:9], v140 offset:1024
	ds_read_b128 v[178:181], v140 offset:2048
	ds_read_b128 v[182:185], v140 offset:3072
	ds_read_b128 v[26:29], v138 offset:32768
	ds_read_b128 v[30:33], v138 offset:33792
	ds_read_b128 v[42:45], v137 offset:32768
	ds_read_b128 v[46:49], v137 offset:33792
	ds_read_b128 v[186:189], v136 offset:32768
	ds_read_b128 v[190:193], v136 offset:33792
	ds_read_b128 v[218:221], v135 offset:32768
	ds_read_b128 v[222:225], v135 offset:33792
	s_waitcnt vmcnt(2)
	s_barrier
; #define WAIT_V(n) asm volatile("s_waitcnt vmcnt(" #n ")" ::: "memory")
; #define WAIT_L(n) asm volatile("s_waitcnt lgkmcnt(" #n ")" ::: "memory")
; #define BAR __builtin_amdgcn_s_barrier()
; #define LDA(dst, b, h) for (int m = 0; m < 4; ++m) for (int k = 0; k < 2; ++k) \
;     dst[m][k] = *reinterpret_cast<const bf16x8*>((char*)SA(b, h) + lds_byte(wr * 64 + m * 16 + fr, k * 32 + fq * 8))
; #define LDB(dst, b, h) for (int n = 0; n < 2; ++n) for (int k = 0; k < 2; ++k) \
;     dst[n][k] = *reinterpret_cast<const bf16x8*>((char*)SB(b, h) + lds_byte(wc * 32 + n * 16 + fr, k * 32 + fq * 8))
; #define MMA(ai, bj, At_, Bt_) do { __builtin_amdgcn_s_setprio(1); \
;     for (int m = 0; m < 4; ++m) for (int n = 0; n < 2; ++n) for (int k = 0; k < 2; ++k) \
;       acc[ai][bj][m][n] = __builtin_amdgcn_mfma_f32_16x16x32_bf16(At_[m][k], Bt_[n][k], acc[ai][bj][m][n], 0, 0, 0); \
;     __builtin_amdgcn_s_setprio(0); } while (0)
; template <int K, int LD = K>
; __device__ __forceinline__ void gemm_main(const GAS bf16* A, const GAS bf16* Bt, int brow, int bcol, f32x4 (&acc)[2][2][4][2]) {
;     ...
;   { LDB(B0, 1, 0); LDA(At, 1, 0); WAIT_V(2); BAR; WAIT_L(0); MMA(0, 0, At, B0); BAR;
;     LDB(B1, 1, 1); WAIT_V(0); BAR; WAIT_L(0); MMA(0, 1, At, B1); BAR;
;     LDA(At, 1, 1); BAR; WAIT_L(0); MMA(1, 0, At, B0); MMA(1, 1, At, B1); BAR; }
;   if (wr == 0) BAR;
	s_waitcnt lgkmcnt(0)
	v_mfma_f32_16x16x32_bf16 v[74:77], v[26:29], v[2:5], v[126:129]
	v_mfma_f32_16x16x32_bf16 v[118:121], v[30:33], v[6:9], v[74:77]
	v_mfma_f32_16x16x32_bf16 v[74:77], v[26:29], v[178:181], v[122:125]
	v_mfma_f32_16x16x32_bf16 v[114:117], v[30:33], v[182:185], v[74:77]
	v_mfma_f32_16x16x32_bf16 v[74:77], v[42:45], v[2:5], v[198:201]
	v_mfma_f32_16x16x32_bf16 v[102:105], v[46:49], v[6:9], v[74:77]
	v_mfma_f32_16x16x32_bf16 v[74:77], v[42:45], v[178:181], v[202:205]
	v_mfma_f32_16x16x32_bf16 v[98:101], v[46:49], v[182:185], v[74:77]
	v_mfma_f32_16x16x32_bf16 v[74:77], v[186:189], v[2:5], v[110:113]
	v_mfma_f32_16x16x32_bf16 v[86:89], v[190:193], v[6:9], v[74:77]
	v_mfma_f32_16x16x32_bf16 v[74:77], v[186:189], v[178:181], v[106:109]
	v_mfma_f32_16x16x32_bf16 v[82:85], v[190:193], v[182:185], v[74:77]
	v_mfma_f32_16x16x32_bf16 v[74:77], v[218:221], v[2:5], v[206:209]
	v_mfma_f32_16x16x32_bf16 v[78:81], v[222:225], v[6:9], v[74:77]
	v_mfma_f32_16x16x32_bf16 v[74:77], v[218:221], v[178:181], v[210:213]
	v_mfma_f32_16x16x32_bf16 v[74:77], v[222:225], v[182:185], v[74:77]
	s_barrier
	ds_read_b128 v[198:201], v139
	ds_read_b128 v[202:205], v139 offset:1024
	ds_read_b128 v[206:209], v139 offset:2048
	ds_read_b128 v[210:213], v139 offset:3072
	s_waitcnt vmcnt(0)
	s_barrier
	s_waitcnt lgkmcnt(0)
	v_mfma_f32_16x16x32_bf16 v[94:97], v[26:29], v[198:201], v[94:97]
	v_mfma_f32_16x16x32_bf16 v[26:29], v[26:29], v[206:209], v[90:93]
	v_mfma_f32_16x16x32_bf16 v[122:125], v[30:33], v[210:213], v[26:29]
	v_mfma_f32_16x16x32_bf16 v[26:29], v[42:45], v[198:201], v[142:145]
	v_mfma_f32_16x16x32_bf16 v[110:113], v[46:49], v[202:205], v[26:29]
	v_mfma_f32_16x16x32_bf16 v[26:29], v[42:45], v[206:209], v[162:165]
	v_mfma_f32_16x16x32_bf16 v[106:109], v[46:49], v[210:213], v[26:29]
	v_mfma_f32_16x16x32_bf16 v[26:29], v[186:189], v[198:201], v[166:169]
	v_mfma_f32_16x16x32_bf16 v[126:129], v[30:33], v[202:205], v[94:97]
	v_mfma_f32_16x16x32_bf16 v[94:97], v[190:193], v[202:205], v[26:29]
	v_mfma_f32_16x16x32_bf16 v[26:29], v[186:189], v[206:209], v[174:177]
	v_mfma_f32_16x16x32_bf16 v[90:93], v[190:193], v[210:213], v[26:29]
	v_mfma_f32_16x16x32_bf16 v[26:29], v[218:221], v[198:201], v[70:73]
	v_mfma_f32_16x16x32_bf16 v[70:73], v[222:225], v[202:205], v[26:29]
	v_mfma_f32_16x16x32_bf16 v[26:29], v[218:221], v[206:209], v[66:69]
	v_mfma_f32_16x16x32_bf16 v[66:69], v[222:225], v[210:213], v[26:29]
	s_barrier
	ds_read_b128 v[140:143], v138 offset:49152
	ds_read_b128 v[162:165], v138 offset:50176
	ds_read_b128 v[166:169], v137 offset:49152
	ds_read_b128 v[174:177], v137 offset:50176
	ds_read_b128 v[186:189], v136 offset:49152
	ds_read_b128 v[136:139], v136 offset:50176
	ds_read_b128 v[190:193], v135 offset:49152
	ds_read_b128 v[218:221], v135 offset:50176
	s_barrier
	s_waitcnt lgkmcnt(0)
	v_mfma_f32_16x16x32_bf16 v[26:29], v[140:143], v[2:5], v[62:65]
	v_mfma_f32_16x16x32_bf16 v[62:65], v[162:165], v[6:9], v[26:29]
	v_mfma_f32_16x16x32_bf16 v[26:29], v[140:143], v[178:181], v[58:61]
	v_mfma_f32_16x16x32_bf16 v[58:61], v[162:165], v[182:185], v[26:29]
	v_mfma_f32_16x16x32_bf16 v[26:29], v[166:169], v[2:5], v[54:57]
	v_mfma_f32_16x16x32_bf16 v[46:49], v[174:177], v[6:9], v[26:29]
	v_mfma_f32_16x16x32_bf16 v[26:29], v[166:169], v[178:181], v[50:53]
	v_mfma_f32_16x16x32_bf16 v[42:45], v[174:177], v[182:185], v[26:29]
	v_mfma_f32_16x16x32_bf16 v[26:29], v[186:189], v[2:5], v[194:197]
	v_mfma_f32_16x16x32_bf16 v[2:5], v[190:193], v[2:5], v[38:41]
	v_mfma_f32_16x16x32_bf16 v[30:33], v[136:139], v[6:9], v[26:29]
	v_mfma_f32_16x16x32_bf16 v[26:29], v[186:189], v[178:181], v[214:217]
	v_mfma_f32_16x16x32_bf16 v[6:9], v[218:221], v[6:9], v[2:5]
	v_mfma_f32_16x16x32_bf16 v[2:5], v[190:193], v[178:181], v[34:37]
	v_mfma_f32_16x16x32_bf16 v[26:29], v[136:139], v[182:185], v[26:29]
	v_mfma_f32_16x16x32_bf16 v[2:5], v[218:221], v[182:185], v[2:5]
	v_mfma_f32_16x16x32_bf16 v[34:37], v[140:143], v[198:201], v[146:149]
	v_mfma_f32_16x16x32_bf16 v[54:57], v[162:165], v[202:205], v[34:37]
	v_mfma_f32_16x16x32_bf16 v[34:37], v[140:143], v[206:209], v[150:153]
	v_mfma_f32_16x16x32_bf16 v[18:21], v[166:169], v[206:209], v[18:21]
	v_mfma_f32_16x16x32_bf16 v[10:13], v[186:189], v[206:209], v[10:13]
	v_mfma_f32_16x16x32_bf16 v[50:53], v[162:165], v[210:213], v[34:37]
	v_mfma_f32_16x16x32_bf16 v[22:25], v[166:169], v[198:201], v[22:25]
	v_mfma_f32_16x16x32_bf16 v[34:37], v[174:177], v[210:213], v[18:21]
	v_mfma_f32_16x16x32_bf16 v[14:17], v[186:189], v[198:201], v[14:17]
	v_mfma_f32_16x16x32_bf16 v[18:21], v[136:139], v[210:213], v[10:13]
	v_mfma_f32_16x16x32_bf16 v[10:13], v[190:193], v[198:201], v[154:157]
	v_mfma_f32_16x16x32_bf16 v[38:41], v[174:177], v[202:205], v[22:25]
	v_mfma_f32_16x16x32_bf16 v[22:25], v[136:139], v[202:205], v[14:17]
	v_mfma_f32_16x16x32_bf16 v[14:17], v[218:221], v[202:205], v[10:13]
	v_mfma_f32_16x16x32_bf16 v[10:13], v[190:193], v[206:209], v[158:161]
	v_mfma_f32_16x16x32_bf16 v[10:13], v[218:221], v[210:213], v[10:13]
	v_cmp_gt_u32_e32 vcc, s51, v134
	s_barrier
	s_and_saveexec_b64 s[20:21], vcc
	s_cbranch_execz .LBB0_712
	s_barrier

; #define STAGE(P, GP, ktrel) do { const GAS char* _g = (GP) + (ktrel) * (BK * 2); \
;     __builtin_amdgcn_global_load_lds((const GAS unsigned*)(_g + so0), (unsigned*)((char*)(P) + tid_ * 16), 16, 0, 0); \
;     __builtin_amdgcn_global_load_lds((const GAS unsigned*)(_g + so1), (unsigned*)((char*)(P) + tid_ * 16 + 8192), 16, 0, 0); } while (0)
; #define WAIT_L(n) asm volatile("s_waitcnt lgkmcnt(" #n ")" ::: "memory")
; #define BAR __builtin_amdgcn_s_barrier()
; #define SCHED __builtin_amdgcn_sched_barrier(0)
; #define LDA(dst, b, h) for (int m = 0; m < 4; ++m) for (int k = 0; k < 2; ++k) \
;     dst[m][k] = *reinterpret_cast<const bf16x8*>((char*)SA(b, h) + lds_byte(wr * 64 + m * 16 + fr, k * 32 + fq * 8))
; #define LDB(dst, b, h) for (int n = 0; n < 2; ++n) for (int k = 0; k < 2; ++k) \
;     dst[n][k] = *reinterpret_cast<const bf16x8*>((char*)SB(b, h) + lds_byte(wc * 32 + n * 16 + fr, k * 32 + fq * 8))
; #define MMA(ai, bj, At_, Bt_) do { __builtin_amdgcn_s_setprio(1); \
;     for (int m = 0; m < 4; ++m) for (int n = 0; n < 2; ++n) for (int k = 0; k < 2; ++k) \
;       acc[ai][bj][m][n] = __builtin_amdgcn_mfma_f32_16x16x32_bf16(At_[m][k], Bt_[n][k], acc[ai][bj][m][n], 0, 0, 0); \
;     __builtin_amdgcn_s_setprio(0); } while (0)
; template <int K, int LD = K>
; __device__ __forceinline__ void gemm_main(const GAS bf16* A, const GAS bf16* Bt, int brow, int bcol, f32x4 (&acc)[2][2][4][2]) {
;     ...
;     LDB(B0, 0, 0); SCHED; LDA(At, 0, 0); STAGE(SA(1, 1), pA1, 1);
;     WAIT_L(8); BAR; WAIT_L(0); MMA(0, 0, At, B0); BAR; SCHED;
;     LDB(B1, 0, 1); STAGE(SB(0, 0), pB0, 2);
;     BAR; WAIT_L(0); MMA(0, 1, At, B1); BAR;
;     LDA(At, 0, 1); STAGE(SA(0, 0), pA0, 2);
;     BAR; WAIT_L(0); MMA(1, 0, At, B0); BAR; SCHED;
.LBB0_715:
	ds_read_b128 v[146:149], v143
	ds_read_b128 v[150:153], v143 offset:1024
	ds_read_b128 v[154:157], v143 offset:2048
	ds_read_b128 v[158:161], v143 offset:3072
	v_add_u32_e32 v230, 0x100, v141
	v_add_u32_e32 v144, 0xc000, v230
	v_lshl_add_u64 v[214:215], s[20:21], 0, v[130:131]
	v_readfirstlane_b32 s28, v144
	v_add_u32_e32 v145, 0xe000, v230
	v_lshl_add_u64 v[198:199], v[214:215], 0, s[6:7]
	s_mov_b32 m0, s28
	v_lshl_add_u64 v[216:217], s[20:21], 0, v[132:133]
	v_readfirstlane_b32 s28, v145
	ds_read_b128 v[162:165], v138
	ds_read_b128 v[166:169], v138 offset:1024
	ds_read_b128 v[174:177], v137
	ds_read_b128 v[178:181], v137 offset:1024
	ds_read_b128 v[182:185], v136
	ds_read_b128 v[186:189], v136 offset:1024
	ds_read_b128 v[190:193], v135
	ds_read_b128 v[194:197], v135 offset:1024
	global_load_lds_dwordx4 v[198:199], off
	v_lshl_add_u64 v[198:199], v[216:217], 0, s[6:7]
	s_mov_b32 m0, s28
	s_nop 0
	global_load_lds_dwordx4 v[198:199], off
	s_waitcnt lgkmcnt(8)
	s_waitcnt vmcnt(10)
	s_barrier
	s_waitcnt lgkmcnt(0)
	v_mfma_f32_16x16x32_bf16 v[126:129], v[162:165], v[146:149], v[126:129]
	v_mfma_f32_16x16x32_bf16 v[122:125], v[162:165], v[154:157], v[122:125]
	v_mfma_f32_16x16x32_bf16 v[118:121], v[174:177], v[146:149], v[118:121]
	v_mfma_f32_16x16x32_bf16 v[114:117], v[174:177], v[154:157], v[114:117]
	v_mfma_f32_16x16x32_bf16 v[110:113], v[182:185], v[146:149], v[110:113]
	v_mfma_f32_16x16x32_bf16 v[106:109], v[182:185], v[154:157], v[106:109]
	v_mfma_f32_16x16x32_bf16 v[102:105], v[190:193], v[146:149], v[102:105]
	v_mfma_f32_16x16x32_bf16 v[98:101], v[190:193], v[154:157], v[98:101]
	v_mfma_f32_16x16x32_bf16 v[126:129], v[166:169], v[150:153], v[126:129]
	v_mfma_f32_16x16x32_bf16 v[122:125], v[166:169], v[158:161], v[122:125]
	v_mfma_f32_16x16x32_bf16 v[118:121], v[178:181], v[150:153], v[118:121]
	v_mfma_f32_16x16x32_bf16 v[114:117], v[178:181], v[158:161], v[114:117]
	v_mfma_f32_16x16x32_bf16 v[110:113], v[186:189], v[150:153], v[110:113]
	v_mfma_f32_16x16x32_bf16 v[106:109], v[186:189], v[158:161], v[106:109]
	v_mfma_f32_16x16x32_bf16 v[102:105], v[194:197], v[150:153], v[102:105]
	v_mfma_f32_16x16x32_bf16 v[98:101], v[194:197], v[158:161], v[98:101]
	s_barrier
	v_add_u32_e32 v224, s47, v141
	v_lshl_add_u64 v[218:219], s[26:27], 0, v[130:131]
	v_readfirstlane_b32 s28, v224
	v_lshl_add_u64 v[220:221], v[218:219], 0, s[10:11]
	s_mov_b32 m0, s28
	v_add_u32_e32 v224, 0x2000, v224
	ds_read_b128 v[198:201], v142
	ds_read_b128 v[202:205], v142 offset:1024
	ds_read_b128 v[206:209], v142 offset:2048
	ds_read_b128 v[210:213], v142 offset:3072
	global_load_lds_dwordx4 v[220:221], off
	v_lshl_add_u64 v[220:221], s[26:27], 0, v[132:133]
	v_readfirstlane_b32 s28, v224
	v_lshl_add_u64 v[222:223], v[220:221], 0, s[10:11]
	s_mov_b32 m0, s28
	s_add_u32 s26, s26, 0x100
	global_load_lds_dwordx4 v[222:223], off
	s_waitcnt vmcnt(10)
	s_barrier
	s_waitcnt lgkmcnt(0)
	s_addc_u32 s27, s27, 0
	s_waitcnt lgkmcnt(0)
	v_mfma_f32_16x16x32_bf16 v[94:97], v[162:165], v[198:201], v[94:97]
	v_mfma_f32_16x16x32_bf16 v[90:93], v[162:165], v[206:209], v[90:93]
	v_mfma_f32_16x16x32_bf16 v[86:89], v[174:177], v[198:201], v[86:89]
	v_mfma_f32_16x16x32_bf16 v[82:85], v[174:177], v[206:209], v[82:85]
	v_mfma_f32_16x16x32_bf16 v[78:81], v[182:185], v[198:201], v[78:81]
	v_mfma_f32_16x16x32_bf16 v[74:77], v[182:185], v[206:209], v[74:77]
	v_mfma_f32_16x16x32_bf16 v[70:73], v[190:193], v[198:201], v[70:73]
	v_mfma_f32_16x16x32_bf16 v[66:69], v[190:193], v[206:209], v[66:69]
	v_mfma_f32_16x16x32_bf16 v[94:97], v[166:169], v[202:205], v[94:97]
	v_mfma_f32_16x16x32_bf16 v[90:93], v[166:169], v[210:213], v[90:93]
	v_mfma_f32_16x16x32_bf16 v[86:89], v[178:181], v[202:205], v[86:89]
	v_mfma_f32_16x16x32_bf16 v[82:85], v[178:181], v[210:213], v[82:85]
	v_mfma_f32_16x16x32_bf16 v[78:81], v[186:189], v[202:205], v[78:81]
	v_mfma_f32_16x16x32_bf16 v[74:77], v[186:189], v[210:213], v[74:77]
	v_mfma_f32_16x16x32_bf16 v[70:73], v[194:197], v[202:205], v[70:73]
	v_mfma_f32_16x16x32_bf16 v[66:69], v[194:197], v[210:213], v[66:69]
	v_lshl_add_u64 v[222:223], s[24:25], 0, v[130:131]
	v_readfirstlane_b32 s28, v230
	v_lshl_add_u64 v[224:225], v[222:223], 0, s[10:11]
	s_mov_b32 m0, s28
	v_add_u32_e32 v228, 0x2000, v230
	s_barrier
	ds_read_b128 v[162:165], v138 offset:16384
	ds_read_b128 v[166:169], v138 offset:17408
	ds_read_b128 v[174:177], v137 offset:16384
	ds_read_b128 v[178:181], v137 offset:17408
	ds_read_b128 v[182:185], v136 offset:16384
	ds_read_b128 v[186:189], v136 offset:17408
	ds_read_b128 v[190:193], v135 offset:16384
	ds_read_b128 v[194:197], v135 offset:17408
	global_load_lds_dwordx4 v[224:225], off
	v_lshl_add_u64 v[224:225], s[24:25], 0, v[132:133]
	v_readfirstlane_b32 s28, v228
	v_lshl_add_u64 v[226:227], v[224:225], 0, s[10:11]
	s_mov_b32 m0, s28
	s_add_u32 s24, s24, 0x100
	global_load_lds_dwordx4 v[226:227], off
	s_barrier
	s_waitcnt lgkmcnt(0)
	s_addc_u32 s25, s25, 0
	s_waitcnt lgkmcnt(0)
	v_mfma_f32_16x16x32_bf16 v[62:65], v[162:165], v[146:149], v[62:65]
	v_mfma_f32_16x16x32_bf16 v[58:61], v[162:165], v[154:157], v[58:61]
	v_mfma_f32_16x16x32_bf16 v[54:57], v[174:177], v[146:149], v[54:57]
	v_mfma_f32_16x16x32_bf16 v[50:53], v[174:177], v[154:157], v[50:53]
	v_mfma_f32_16x16x32_bf16 v[46:49], v[182:185], v[146:149], v[46:49]
	v_mfma_f32_16x16x32_bf16 v[42:45], v[182:185], v[154:157], v[42:45]
	v_mfma_f32_16x16x32_bf16 v[38:41], v[190:193], v[146:149], v[38:41]
	v_mfma_f32_16x16x32_bf16 v[34:37], v[190:193], v[154:157], v[34:37]
	v_mfma_f32_16x16x32_bf16 v[62:65], v[166:169], v[150:153], v[62:65]
	v_mfma_f32_16x16x32_bf16 v[58:61], v[166:169], v[158:161], v[58:61]
	v_mfma_f32_16x16x32_bf16 v[54:57], v[178:181], v[150:153], v[54:57]
	v_mfma_f32_16x16x32_bf16 v[50:53], v[178:181], v[158:161], v[50:53]
	v_mfma_f32_16x16x32_bf16 v[46:49], v[186:189], v[150:153], v[46:49]
	v_mfma_f32_16x16x32_bf16 v[42:45], v[186:189], v[158:161], v[42:45]
	v_mfma_f32_16x16x32_bf16 v[38:41], v[194:197], v[150:153], v[38:41]
	v_mfma_f32_16x16x32_bf16 v[34:37], v[194:197], v[158:161], v[34:37]
	s_barrier
; #define STAGE(P, GP, ktrel) do { const GAS char* _g = (GP) + (ktrel) * (BK * 2); \
;     __builtin_amdgcn_global_load_lds((const GAS unsigned*)(_g + so0), (unsigned*)((char*)(P) + tid_ * 16), 16, 0, 0); \
;     __builtin_amdgcn_global_load_lds((const GAS unsigned*)(_g + so1), (unsigned*)((char*)(P) + tid_ * 16 + 8192), 16, 0, 0); } while (0)
; #define WAIT_V(n) asm volatile("s_waitcnt vmcnt(" #n ")" ::: "memory")
; #define WAIT_L(n) asm volatile("s_waitcnt lgkmcnt(" #n ")" ::: "memory")
; #define BAR __builtin_amdgcn_s_barrier()
; #define SCHED __builtin_amdgcn_sched_barrier(0)
; #define LDA(dst, b, h) for (int m = 0; m < 4; ++m) for (int k = 0; k < 2; ++k) \
;     dst[m][k] = *reinterpret_cast<const bf16x8*>((char*)SA(b, h) + lds_byte(wr * 64 + m * 16 + fr, k * 32 + fq * 8))
; #define LDB(dst, b, h) for (int n = 0; n < 2; ++n) for (int k = 0; k < 2; ++k) \
;     dst[n][k] = *reinterpret_cast<const bf16x8*>((char*)SB(b, h) + lds_byte(wc * 32 + n * 16 + fr, k * 32 + fq * 8))
; #define MMA(ai, bj, At_, Bt_) do { __builtin_amdgcn_s_setprio(1); \
;     for (int m = 0; m < 4; ++m) for (int n = 0; n < 2; ++n) for (int k = 0; k < 2; ++k) \
;       acc[ai][bj][m][n] = __builtin_amdgcn_mfma_f32_16x16x32_bf16(At_[m][k], Bt_[n][k], acc[ai][bj][m][n], 0, 0, 0); \
;     __builtin_amdgcn_s_setprio(0); } while (0)
; template <int K, int LD = K>
; __device__ __forceinline__ void gemm_main(const GAS bf16* A, const GAS bf16* Bt, int brow, int bcol, f32x4 (&acc)[2][2][4][2]) {
;     ...
;     STAGE(SB(0, 1), pB1, 2);
;     WAIT_V(6); BAR; MMA(1, 1, At, B1); BAR;
;     LDB(B0, 1, 0); SCHED; LDA(At, 1, 0); STAGE(SA(0, 1), pA1, 2);
;     WAIT_L(8); BAR; WAIT_L(0); MMA(0, 0, At, B0); BAR; SCHED;
;     LDB(B1, 1, 1); STAGE(SB(1, 0), pB0, 3);
;     BAR; WAIT_L(0); MMA(0, 1, At, B1); BAR;
	v_add_u32_e32 v148, s48, v141
	v_lshl_add_u64 v[226:227], s[22:23], 0, v[130:131]
	v_readfirstlane_b32 s28, v148
	v_add_u32_e32 v148, 0x2000, v148
	v_lshl_add_u64 v[146:147], v[226:227], 0, s[10:11]
	s_mov_b32 m0, s28
	v_lshl_add_u64 v[228:229], s[22:23], 0, v[132:133]
	v_readfirstlane_b32 s28, v148
	global_load_lds_dwordx4 v[146:147], off
	v_lshl_add_u64 v[146:147], v[228:229], 0, s[10:11]
	s_mov_b32 m0, s28
	s_add_u32 s22, s22, 0x100
	global_load_lds_dwordx4 v[146:147], off
	s_waitcnt vmcnt(10)
	s_addc_u32 s23, s23, 0
	s_barrier
	v_mfma_f32_16x16x32_bf16 v[30:33], v[162:165], v[198:201], v[30:33]
	v_mfma_f32_16x16x32_bf16 v[26:29], v[162:165], v[206:209], v[26:29]
	v_mfma_f32_16x16x32_bf16 v[22:25], v[174:177], v[198:201], v[22:25]
	v_mfma_f32_16x16x32_bf16 v[18:21], v[174:177], v[206:209], v[18:21]
	v_mfma_f32_16x16x32_bf16 v[14:17], v[182:185], v[198:201], v[14:17]
	v_mfma_f32_16x16x32_bf16 v[10:13], v[182:185], v[206:209], v[10:13]
	v_mfma_f32_16x16x32_bf16 v[6:9], v[190:193], v[198:201], v[6:9]
	v_mfma_f32_16x16x32_bf16 v[2:5], v[190:193], v[206:209], v[2:5]
	v_mfma_f32_16x16x32_bf16 v[30:33], v[166:169], v[202:205], v[30:33]
	v_mfma_f32_16x16x32_bf16 v[26:29], v[166:169], v[210:213], v[26:29]
	v_mfma_f32_16x16x32_bf16 v[22:25], v[178:181], v[202:205], v[22:25]
	v_mfma_f32_16x16x32_bf16 v[18:21], v[178:181], v[210:213], v[18:21]
	v_mfma_f32_16x16x32_bf16 v[14:17], v[186:189], v[202:205], v[14:17]
	v_mfma_f32_16x16x32_bf16 v[10:13], v[186:189], v[210:213], v[10:13]
	v_mfma_f32_16x16x32_bf16 v[6:9], v[194:197], v[202:205], v[6:9]
	v_mfma_f32_16x16x32_bf16 v[2:5], v[194:197], v[210:213], v[2:5]
	s_barrier
	ds_read_b128 v[146:149], v140
	ds_read_b128 v[150:153], v140 offset:1024
	ds_read_b128 v[154:157], v140 offset:2048
	ds_read_b128 v[158:161], v140 offset:3072
	v_add_u32_e32 v200, 0x4000, v230
	v_lshl_add_u64 v[198:199], v[214:215], 0, s[10:11]
	v_readfirstlane_b32 s28, v200
	v_add_u32_e32 v200, 0x6000, v230
	s_mov_b32 m0, s28
	v_readfirstlane_b32 s28, v200
	ds_read_b128 v[162:165], v138 offset:32768
	ds_read_b128 v[166:169], v138 offset:33792
	ds_read_b128 v[174:177], v137 offset:32768
	ds_read_b128 v[178:181], v137 offset:33792
	ds_read_b128 v[182:185], v136 offset:32768
	ds_read_b128 v[186:189], v136 offset:33792
	ds_read_b128 v[190:193], v135 offset:32768
	ds_read_b128 v[194:197], v135 offset:33792
	global_load_lds_dwordx4 v[198:199], off
	v_lshl_add_u64 v[198:199], v[216:217], 0, s[10:11]
	s_mov_b32 m0, s28
	s_add_u32 s20, s20, 0x100
	global_load_lds_dwordx4 v[198:199], off
	s_waitcnt lgkmcnt(8)
	s_waitcnt vmcnt(10)
	s_barrier
	s_waitcnt lgkmcnt(0)
	s_addc_u32 s21, s21, 0
	s_waitcnt lgkmcnt(0)
	v_mfma_f32_16x16x32_bf16 v[126:129], v[162:165], v[146:149], v[126:129]
	v_mfma_f32_16x16x32_bf16 v[122:125], v[162:165], v[154:157], v[122:125]
	v_mfma_f32_16x16x32_bf16 v[118:121], v[174:177], v[146:149], v[118:121]
	v_mfma_f32_16x16x32_bf16 v[114:117], v[174:177], v[154:157], v[114:117]
	v_mfma_f32_16x16x32_bf16 v[110:113], v[182:185], v[146:149], v[110:113]
	v_mfma_f32_16x16x32_bf16 v[106:109], v[182:185], v[154:157], v[106:109]
	v_mfma_f32_16x16x32_bf16 v[102:105], v[190:193], v[146:149], v[102:105]
	v_mfma_f32_16x16x32_bf16 v[98:101], v[190:193], v[154:157], v[98:101]
	v_mfma_f32_16x16x32_bf16 v[126:129], v[166:169], v[150:153], v[126:129]
	v_mfma_f32_16x16x32_bf16 v[122:125], v[166:169], v[158:161], v[122:125]
	v_mfma_f32_16x16x32_bf16 v[118:121], v[178:181], v[150:153], v[118:121]
	v_mfma_f32_16x16x32_bf16 v[114:117], v[178:181], v[158:161], v[114:117]
	v_mfma_f32_16x16x32_bf16 v[110:113], v[186:189], v[150:153], v[110:113]
	v_mfma_f32_16x16x32_bf16 v[106:109], v[186:189], v[158:161], v[106:109]
	v_mfma_f32_16x16x32_bf16 v[102:105], v[194:197], v[150:153], v[102:105]
	v_mfma_f32_16x16x32_bf16 v[98:101], v[194:197], v[158:161], v[98:101]
	s_barrier
	v_add_u32_e32 v216, s49, v141
	v_lshl_add_u64 v[214:215], v[218:219], 0, s[12:13]
	v_readfirstlane_b32 s28, v216
	v_add_u32_e32 v216, 0x2000, v216
	s_mov_b32 m0, s28
	v_readfirstlane_b32 s28, v216
	ds_read_b128 v[198:201], v139
	ds_read_b128 v[202:205], v139 offset:1024
	ds_read_b128 v[206:209], v139 offset:2048
	ds_read_b128 v[210:213], v139 offset:3072
	global_load_lds_dwordx4 v[214:215], off
	v_lshl_add_u64 v[214:215], v[220:221], 0, s[12:13]
	s_mov_b32 m0, s28
	s_nop 0
	global_load_lds_dwordx4 v[214:215], off
	s_waitcnt vmcnt(10)
	s_barrier
	s_waitcnt lgkmcnt(0)
	v_mfma_f32_16x16x32_bf16 v[94:97], v[162:165], v[198:201], v[94:97]
	v_mfma_f32_16x16x32_bf16 v[90:93], v[162:165], v[206:209], v[90:93]
	v_mfma_f32_16x16x32_bf16 v[86:89], v[174:177], v[198:201], v[86:89]
	v_mfma_f32_16x16x32_bf16 v[82:85], v[174:177], v[206:209], v[82:85]
	v_mfma_f32_16x16x32_bf16 v[78:81], v[182:185], v[198:201], v[78:81]
	v_mfma_f32_16x16x32_bf16 v[74:77], v[182:185], v[206:209], v[74:77]
	v_mfma_f32_16x16x32_bf16 v[70:73], v[190:193], v[198:201], v[70:73]
	v_mfma_f32_16x16x32_bf16 v[66:69], v[190:193], v[206:209], v[66:69]
	v_mfma_f32_16x16x32_bf16 v[94:97], v[166:169], v[202:205], v[94:97]
	v_mfma_f32_16x16x32_bf16 v[90:93], v[166:169], v[210:213], v[90:93]
	v_mfma_f32_16x16x32_bf16 v[86:89], v[178:181], v[202:205], v[86:89]
	v_mfma_f32_16x16x32_bf16 v[82:85], v[178:181], v[210:213], v[82:85]
	v_mfma_f32_16x16x32_bf16 v[78:81], v[186:189], v[202:205], v[78:81]
	v_mfma_f32_16x16x32_bf16 v[74:77], v[186:189], v[210:213], v[74:77]
	v_mfma_f32_16x16x32_bf16 v[70:73], v[194:197], v[202:205], v[70:73]
	v_mfma_f32_16x16x32_bf16 v[66:69], v[194:197], v[210:213], v[66:69]
	v_add_u32_e32 v216, 0x8000, v230
	v_lshl_add_u64 v[214:215], v[222:223], 0, s[12:13]
	v_readfirstlane_b32 s28, v216
	v_add_u32_e32 v216, 0xa000, v230
	s_mov_b32 m0, s28
	v_readfirstlane_b32 s28, v216
	s_barrier
; #define STAGE(P, GP, ktrel) do { const GAS char* _g = (GP) + (ktrel) * (BK * 2); \
;     __builtin_amdgcn_global_load_lds((const GAS unsigned*)(_g + so0), (unsigned*)((char*)(P) + tid_ * 16), 16, 0, 0); \
;     __builtin_amdgcn_global_load_lds((const GAS unsigned*)(_g + so1), (unsigned*)((char*)(P) + tid_ * 16 + 8192), 16, 0, 0); } while (0)
; #define WAIT_V(n) asm volatile("s_waitcnt vmcnt(" #n ")" ::: "memory")
; #define WAIT_L(n) asm volatile("s_waitcnt lgkmcnt(" #n ")" ::: "memory")
; #define BAR __builtin_amdgcn_s_barrier()
; #define SCHED __builtin_amdgcn_sched_barrier(0)
; #define LDA(dst, b, h) for (int m = 0; m < 4; ++m) for (int k = 0; k < 2; ++k) \
;     dst[m][k] = *reinterpret_cast<const bf16x8*>((char*)SA(b, h) + lds_byte(wr * 64 + m * 16 + fr, k * 32 + fq * 8))
; #define LDB(dst, b, h) for (int n = 0; n < 2; ++n) for (int k = 0; k < 2; ++k) \
;     dst[n][k] = *reinterpret_cast<const bf16x8*>((char*)SB(b, h) + lds_byte(wc * 32 + n * 16 + fr, k * 32 + fq * 8))
; #define MMA(ai, bj, At_, Bt_) do { __builtin_amdgcn_s_setprio(1); \
;     for (int m = 0; m < 4; ++m) for (int n = 0; n < 2; ++n) for (int k = 0; k < 2; ++k) \
;       acc[ai][bj][m][n] = __builtin_amdgcn_mfma_f32_16x16x32_bf16(At_[m][k], Bt_[n][k], acc[ai][bj][m][n], 0, 0, 0); \
;     __builtin_amdgcn_s_setprio(0); } while (0)
; template <int K, int LD = K>
; __device__ __forceinline__ void gemm_main(const GAS bf16* A, const GAS bf16* Bt, int brow, int bcol, f32x4 (&acc)[2][2][4][2]) {
;     ...
;     LDA(At, 1, 1); STAGE(SA(1, 0), pA0, 3);
;     BAR; WAIT_L(0); MMA(1, 0, At, B0); BAR; SCHED;
;     STAGE(SB(1, 1), pB1, 3);
;     WAIT_V(6); BAR; MMA(1, 1, At, B1); BAR;
;     pA0 += 4 * BK; pA1 += 4 * BK; pB0 += 4 * BK; pB1 += 4 * BK;
;     asm volatile("" : "+s"(pA0), "+s"(pA1), "+s"(pB0), "+s"(pB1));
;   }
;   { LDB(B0, 0, 0); LDA(At, 0, 0); STAGE(SA(1, 1), pA1, 1);
;     BAR; WAIT_L(0); MMA(0, 0, At, B0); BAR;
;     LDB(B1, 0, 1); BAR; WAIT_L(0); MMA(0, 1, At, B1); BAR;
	ds_read_b128 v[162:165], v138 offset:49152
	ds_read_b128 v[166:169], v138 offset:50176
	ds_read_b128 v[174:177], v137 offset:49152
	ds_read_b128 v[178:181], v137 offset:50176
	ds_read_b128 v[182:185], v136 offset:49152
	ds_read_b128 v[186:189], v136 offset:50176
	ds_read_b128 v[190:193], v135 offset:49152
	ds_read_b128 v[194:197], v135 offset:50176
	global_load_lds_dwordx4 v[214:215], off
	v_lshl_add_u64 v[214:215], v[224:225], 0, s[12:13]
	s_mov_b32 m0, s28
	s_nop 0
	global_load_lds_dwordx4 v[214:215], off
	s_barrier
	s_waitcnt lgkmcnt(0)
	v_mfma_f32_16x16x32_bf16 v[62:65], v[162:165], v[146:149], v[62:65]
	v_mfma_f32_16x16x32_bf16 v[58:61], v[162:165], v[154:157], v[58:61]
	v_mfma_f32_16x16x32_bf16 v[54:57], v[174:177], v[146:149], v[54:57]
	v_mfma_f32_16x16x32_bf16 v[50:53], v[174:177], v[154:157], v[50:53]
	v_mfma_f32_16x16x32_bf16 v[46:49], v[182:185], v[146:149], v[46:49]
	v_mfma_f32_16x16x32_bf16 v[42:45], v[182:185], v[154:157], v[42:45]
	v_mfma_f32_16x16x32_bf16 v[38:41], v[190:193], v[146:149], v[38:41]
	v_mfma_f32_16x16x32_bf16 v[34:37], v[190:193], v[154:157], v[34:37]
	v_mfma_f32_16x16x32_bf16 v[62:65], v[166:169], v[150:153], v[62:65]
	v_mfma_f32_16x16x32_bf16 v[58:61], v[166:169], v[158:161], v[58:61]
	v_mfma_f32_16x16x32_bf16 v[54:57], v[178:181], v[150:153], v[54:57]
	v_mfma_f32_16x16x32_bf16 v[50:53], v[178:181], v[158:161], v[50:53]
	v_mfma_f32_16x16x32_bf16 v[46:49], v[186:189], v[150:153], v[46:49]
	v_mfma_f32_16x16x32_bf16 v[42:45], v[186:189], v[158:161], v[42:45]
	v_mfma_f32_16x16x32_bf16 v[38:41], v[194:197], v[150:153], v[38:41]
	v_mfma_f32_16x16x32_bf16 v[34:37], v[194:197], v[158:161], v[34:37]
	s_barrier
	v_add_u32_e32 v148, s50, v141
	v_lshl_add_u64 v[146:147], v[226:227], 0, s[12:13]
	v_readfirstlane_b32 s28, v148
	v_add_u32_e32 v148, 0x2000, v148
	s_mov_b32 m0, s28
	v_readfirstlane_b32 s28, v148
	global_load_lds_dwordx4 v[146:147], off
	v_lshl_add_u64 v[146:147], v[228:229], 0, s[12:13]
	s_mov_b32 m0, s28
	s_nop 0
	global_load_lds_dwordx4 v[146:147], off
	s_waitcnt vmcnt(10)
	s_barrier
	v_mfma_f32_16x16x32_bf16 v[30:33], v[162:165], v[198:201], v[30:33]
	v_mfma_f32_16x16x32_bf16 v[26:29], v[162:165], v[206:209], v[26:29]
	v_mfma_f32_16x16x32_bf16 v[22:25], v[174:177], v[198:201], v[22:25]
	v_mfma_f32_16x16x32_bf16 v[18:21], v[174:177], v[206:209], v[18:21]
	v_mfma_f32_16x16x32_bf16 v[14:17], v[182:185], v[198:201], v[14:17]
	v_mfma_f32_16x16x32_bf16 v[10:13], v[182:185], v[206:209], v[10:13]
	v_mfma_f32_16x16x32_bf16 v[6:9], v[190:193], v[198:201], v[6:9]
	v_mfma_f32_16x16x32_bf16 v[2:5], v[190:193], v[206:209], v[2:5]
	v_mfma_f32_16x16x32_bf16 v[30:33], v[166:169], v[202:205], v[30:33]
	v_mfma_f32_16x16x32_bf16 v[26:29], v[166:169], v[210:213], v[26:29]
	v_mfma_f32_16x16x32_bf16 v[22:25], v[178:181], v[202:205], v[22:25]
	v_mfma_f32_16x16x32_bf16 v[18:21], v[178:181], v[210:213], v[18:21]
	v_mfma_f32_16x16x32_bf16 v[14:17], v[186:189], v[202:205], v[14:17]
	v_mfma_f32_16x16x32_bf16 v[10:13], v[186:189], v[210:213], v[10:13]
	v_mfma_f32_16x16x32_bf16 v[6:9], v[194:197], v[202:205], v[6:9]
	v_mfma_f32_16x16x32_bf16 v[2:5], v[194:197], v[210:213], v[2:5]
	s_add_i32 s17, s17, 2
	s_cmp_lt_u32 s17, 4
	s_barrier
	s_cbranch_scc1 .LBB0_715
	v_lshl_add_u64 v[198:199], s[20:21], 0, v[130:131]
	v_readfirstlane_b32 s17, v144
	v_lshl_add_u64 v[198:199], v[198:199], 0, s[6:7]
	s_mov_b32 m0, s17
	v_lshl_add_u64 v[132:133], s[20:21], 0, v[132:133]
	v_readfirstlane_b32 s17, v145
	ds_read_b128 v[146:149], v143
	ds_read_b128 v[150:153], v143 offset:1024
	ds_read_b128 v[154:157], v143 offset:2048
	ds_read_b128 v[158:161], v143 offset:3072
	ds_read_b128 v[162:165], v138
	ds_read_b128 v[166:169], v138 offset:1024
	ds_read_b128 v[174:177], v137
	ds_read_b128 v[178:181], v137 offset:1024
	ds_read_b128 v[182:185], v136
	ds_read_b128 v[186:189], v136 offset:1024
	ds_read_b128 v[190:193], v135
	ds_read_b128 v[194:197], v135 offset:1024
	global_load_lds_dwordx4 v[198:199], off
	v_lshl_add_u64 v[132:133], v[132:133], 0, s[6:7]
	s_mov_b32 m0, s17
	s_nop 0
	global_load_lds_dwordx4 v[132:133], off
	s_waitcnt vmcnt(10)
	s_barrier
	s_waitcnt lgkmcnt(0)
	v_mfma_f32_16x16x32_bf16 v[126:129], v[162:165], v[146:149], v[126:129]
	v_mfma_f32_16x16x32_bf16 v[122:125], v[162:165], v[154:157], v[122:125]
	v_mfma_f32_16x16x32_bf16 v[110:113], v[182:185], v[146:149], v[110:113]
	v_mfma_f32_16x16x32_bf16 v[106:109], v[182:185], v[154:157], v[106:109]
	v_mfma_f32_16x16x32_bf16 v[126:129], v[166:169], v[150:153], v[126:129]
	v_mfma_f32_16x16x32_bf16 v[122:125], v[166:169], v[158:161], v[122:125]
	v_mfma_f32_16x16x32_bf16 v[118:121], v[174:177], v[146:149], v[118:121]
	v_mfma_f32_16x16x32_bf16 v[114:117], v[174:177], v[154:157], v[114:117]
	v_mfma_f32_16x16x32_bf16 v[110:113], v[186:189], v[150:153], v[110:113]
	v_mfma_f32_16x16x32_bf16 v[106:109], v[186:189], v[158:161], v[106:109]
	v_mfma_f32_16x16x32_bf16 v[102:105], v[190:193], v[146:149], v[102:105]
	v_mfma_f32_16x16x32_bf16 v[98:101], v[190:193], v[154:157], v[98:101]
	v_mfma_f32_16x16x32_bf16 v[198:201], v[178:181], v[150:153], v[118:121]
	v_mfma_f32_16x16x32_bf16 v[202:205], v[178:181], v[158:161], v[114:117]
	v_mfma_f32_16x16x32_bf16 v[206:209], v[194:197], v[150:153], v[102:105]
	v_mfma_f32_16x16x32_bf16 v[210:213], v[194:197], v[158:161], v[98:101]
	s_barrier
	s_nop 1
	ds_read_b128 v[98:101], v142
	ds_read_b128 v[102:105], v142 offset:1024
	ds_read_b128 v[114:117], v142 offset:2048
	ds_read_b128 v[118:121], v142 offset:3072
	s_waitcnt vmcnt(8)
	s_barrier
; #define WAIT_V(n) asm volatile("s_waitcnt vmcnt(" #n ")" ::: "memory")
; #define WAIT_L(n) asm volatile("s_waitcnt lgkmcnt(" #n ")" ::: "memory")
; #define BAR __builtin_amdgcn_s_barrier()
; #define LDA(dst, b, h) for (int m = 0; m < 4; ++m) for (int k = 0; k < 2; ++k) \
;     dst[m][k] = *reinterpret_cast<const bf16x8*>((char*)SA(b, h) + lds_byte(wr * 64 + m * 16 + fr, k * 32 + fq * 8))
; #define LDB(dst, b, h) for (int n = 0; n < 2; ++n) for (int k = 0; k < 2; ++k) \
;     dst[n][k] = *reinterpret_cast<const bf16x8*>((char*)SB(b, h) + lds_byte(wc * 32 + n * 16 + fr, k * 32 + fq * 8))
; #define MMA(ai, bj, At_, Bt_) do { __builtin_amdgcn_s_setprio(1); \
;     for (int m = 0; m < 4; ++m) for (int n = 0; n < 2; ++n) for (int k = 0; k < 2; ++k) \
;       acc[ai][bj][m][n] = __builtin_amdgcn_mfma_f32_16x16x32_bf16(At_[m][k], Bt_[n][k], acc[ai][bj][m][n], 0, 0, 0); \
;     __builtin_amdgcn_s_setprio(0); } while (0)
; template <int K, int LD = K>
; __device__ __forceinline__ void gemm_main(const GAS bf16* A, const GAS bf16* Bt, int brow, int bcol, f32x4 (&acc)[2][2][4][2]) {
;     ...
;     LDB(B1, 0, 1); BAR; WAIT_L(0); MMA(0, 1, At, B1); BAR;
;     LDA(At, 0, 1); WAIT_V(4); BAR; WAIT_L(0); MMA(1, 0, At, B0); MMA(1, 1, At, B1); BAR; }
	s_waitcnt lgkmcnt(0)
	v_mfma_f32_16x16x32_bf16 v[94:97], v[162:165], v[98:101], v[94:97]
	v_mfma_f32_16x16x32_bf16 v[90:93], v[162:165], v[114:117], v[90:93]
	v_mfma_f32_16x16x32_bf16 v[78:81], v[182:185], v[98:101], v[78:81]
	v_mfma_f32_16x16x32_bf16 v[74:77], v[182:185], v[114:117], v[74:77]
	v_mfma_f32_16x16x32_bf16 v[94:97], v[166:169], v[102:105], v[94:97]
	v_mfma_f32_16x16x32_bf16 v[90:93], v[166:169], v[118:121], v[90:93]
	v_mfma_f32_16x16x32_bf16 v[86:89], v[174:177], v[98:101], v[86:89]
	v_mfma_f32_16x16x32_bf16 v[82:85], v[174:177], v[114:117], v[82:85]
	v_mfma_f32_16x16x32_bf16 v[78:81], v[186:189], v[102:105], v[78:81]
	v_mfma_f32_16x16x32_bf16 v[74:77], v[186:189], v[118:121], v[74:77]
	v_mfma_f32_16x16x32_bf16 v[70:73], v[190:193], v[98:101], v[70:73]
	v_mfma_f32_16x16x32_bf16 v[66:69], v[190:193], v[114:117], v[66:69]
	v_mfma_f32_16x16x32_bf16 v[142:145], v[178:181], v[102:105], v[86:89]
	v_mfma_f32_16x16x32_bf16 v[162:165], v[178:181], v[118:121], v[82:85]
	v_mfma_f32_16x16x32_bf16 v[166:169], v[194:197], v[102:105], v[70:73]
	v_mfma_f32_16x16x32_bf16 v[174:177], v[194:197], v[118:121], v[66:69]
	s_barrier
	s_nop 1
	ds_read_b128 v[66:69], v138 offset:16384
	ds_read_b128 v[70:73], v138 offset:17408
	ds_read_b128 v[82:85], v137 offset:16384
	ds_read_b128 v[86:89], v137 offset:17408
	ds_read_b128 v[178:181], v136 offset:16384
	ds_read_b128 v[182:185], v136 offset:17408
	ds_read_b128 v[186:189], v135 offset:16384
	ds_read_b128 v[190:193], v135 offset:17408
	s_waitcnt vmcnt(4)
	s_barrier
	s_waitcnt lgkmcnt(0)
	v_mfma_f32_16x16x32_bf16 v[62:65], v[66:69], v[146:149], v[62:65]
	v_mfma_f32_16x16x32_bf16 v[54:57], v[82:85], v[146:149], v[54:57]
	v_mfma_f32_16x16x32_bf16 v[46:49], v[178:181], v[146:149], v[46:49]
	v_mfma_f32_16x16x32_bf16 v[38:41], v[186:189], v[146:149], v[38:41]
	v_mfma_f32_16x16x32_bf16 v[62:65], v[70:73], v[150:153], v[62:65]
	v_mfma_f32_16x16x32_bf16 v[58:61], v[66:69], v[154:157], v[58:61]
	v_mfma_f32_16x16x32_bf16 v[54:57], v[86:89], v[150:153], v[54:57]
	v_mfma_f32_16x16x32_bf16 v[50:53], v[82:85], v[154:157], v[50:53]
	v_mfma_f32_16x16x32_bf16 v[46:49], v[182:185], v[150:153], v[46:49]
	v_mfma_f32_16x16x32_bf16 v[42:45], v[178:181], v[154:157], v[42:45]
	v_mfma_f32_16x16x32_bf16 v[38:41], v[190:193], v[150:153], v[38:41]
	v_mfma_f32_16x16x32_bf16 v[34:37], v[186:189], v[154:157], v[34:37]
	v_mfma_f32_16x16x32_bf16 v[194:197], v[70:73], v[158:161], v[58:61]
	v_mfma_f32_16x16x32_bf16 v[214:217], v[86:89], v[158:161], v[50:53]
	v_mfma_f32_16x16x32_bf16 v[218:221], v[182:185], v[158:161], v[42:45]
	v_mfma_f32_16x16x32_bf16 v[146:149], v[190:193], v[158:161], v[34:37]
	v_mfma_f32_16x16x32_bf16 v[30:33], v[66:69], v[98:101], v[30:33]
	v_mfma_f32_16x16x32_bf16 v[22:25], v[82:85], v[98:101], v[22:25]
	v_mfma_f32_16x16x32_bf16 v[14:17], v[178:181], v[98:101], v[14:17]
	v_mfma_f32_16x16x32_bf16 v[6:9], v[186:189], v[98:101], v[6:9]
	v_mfma_f32_16x16x32_bf16 v[30:33], v[70:73], v[102:105], v[30:33]
	v_mfma_f32_16x16x32_bf16 v[26:29], v[66:69], v[114:117], v[26:29]
	v_mfma_f32_16x16x32_bf16 v[22:25], v[86:89], v[102:105], v[22:25]
	v_mfma_f32_16x16x32_bf16 v[18:21], v[82:85], v[114:117], v[18:21]
	v_mfma_f32_16x16x32_bf16 v[14:17], v[182:185], v[102:105], v[14:17]
	v_mfma_f32_16x16x32_bf16 v[10:13], v[178:181], v[114:117], v[10:13]
	v_mfma_f32_16x16x32_bf16 v[6:9], v[190:193], v[102:105], v[6:9]
	v_mfma_f32_16x16x32_bf16 v[2:5], v[186:189], v[114:117], v[2:5]
	v_mfma_f32_16x16x32_bf16 v[150:153], v[70:73], v[118:121], v[26:29]
	v_mfma_f32_16x16x32_bf16 v[154:157], v[86:89], v[118:121], v[18:21]
	v_mfma_f32_16x16x32_bf16 v[158:161], v[182:185], v[118:121], v[10:13]
	v_mfma_f32_16x16x32_bf16 v[178:181], v[190:193], v[118:121], v[2:5]
	s_barrier
	s_nop 1
	ds_read_b128 v[2:5], v140
	ds_read_b128 v[10:13], v140 offset:1024
	ds_read_b128 v[182:185], v140 offset:2048
	ds_read_b128 v[186:189], v140 offset:3072
	ds_read_b128 v[18:21], v138 offset:32768
	ds_read_b128 v[26:29], v138 offset:33792
	ds_read_b128 v[34:37], v137 offset:32768
	ds_read_b128 v[42:45], v137 offset:33792
	ds_read_b128 v[50:53], v136 offset:32768
	ds_read_b128 v[58:61], v136 offset:33792
	ds_read_b128 v[190:193], v135 offset:32768
	ds_read_b128 v[222:225], v135 offset:33792
	s_waitcnt vmcnt(2)
	s_barrier
; #define WAIT_V(n) asm volatile("s_waitcnt vmcnt(" #n ")" ::: "memory")
; #define WAIT_L(n) asm volatile("s_waitcnt lgkmcnt(" #n ")" ::: "memory")
; #define BAR __builtin_amdgcn_s_barrier()
; #define LDA(dst, b, h) for (int m = 0; m < 4; ++m) for (int k = 0; k < 2; ++k) \
;     dst[m][k] = *reinterpret_cast<const bf16x8*>((char*)SA(b, h) + lds_byte(wr * 64 + m * 16 + fr, k * 32 + fq * 8))
; #define LDB(dst, b, h) for (int n = 0; n < 2; ++n) for (int k = 0; k < 2; ++k) \
;     dst[n][k] = *reinterpret_cast<const bf16x8*>((char*)SB(b, h) + lds_byte(wc * 32 + n * 16 + fr, k * 32 + fq * 8))
; #define MMA(ai, bj, At_, Bt_) do { __builtin_amdgcn_s_setprio(1); \
;     for (int m = 0; m < 4; ++m) for (int n = 0; n < 2; ++n) for (int k = 0; k < 2; ++k) \
;       acc[ai][bj][m][n] = __builtin_amdgcn_mfma_f32_16x16x32_bf16(At_[m][k], Bt_[n][k], acc[ai][bj][m][n], 0, 0, 0); \
;     __builtin_amdgcn_s_setprio(0); } while (0)
; template <int K, int LD = K>
; __device__ __forceinline__ void gemm_main(const GAS bf16* A, const GAS bf16* Bt, int brow, int bcol, f32x4 (&acc)[2][2][4][2]) {
;     ...
;   { LDB(B0, 1, 0); LDA(At, 1, 0); WAIT_V(2); BAR; WAIT_L(0); MMA(0, 0, At, B0); BAR;
;     LDB(B1, 1, 1); WAIT_V(0); BAR; WAIT_L(0); MMA(0, 1, At, B1); BAR;
;     LDA(At, 1, 1); BAR; WAIT_L(0); MMA(1, 0, At, B0); MMA(1, 1, At, B1); BAR; }
;   if (wr == 0) BAR;
	s_waitcnt lgkmcnt(0)
	v_mfma_f32_16x16x32_bf16 v[66:69], v[18:21], v[2:5], v[126:129]
	v_mfma_f32_16x16x32_bf16 v[118:121], v[26:29], v[10:13], v[66:69]
	v_mfma_f32_16x16x32_bf16 v[66:69], v[18:21], v[182:185], v[122:125]
	v_mfma_f32_16x16x32_bf16 v[114:117], v[26:29], v[186:189], v[66:69]
	v_mfma_f32_16x16x32_bf16 v[66:69], v[34:37], v[2:5], v[198:201]
	v_mfma_f32_16x16x32_bf16 v[102:105], v[42:45], v[10:13], v[66:69]
	v_mfma_f32_16x16x32_bf16 v[66:69], v[34:37], v[182:185], v[202:205]
	v_mfma_f32_16x16x32_bf16 v[98:101], v[42:45], v[186:189], v[66:69]
	v_mfma_f32_16x16x32_bf16 v[66:69], v[50:53], v[2:5], v[110:113]
	v_mfma_f32_16x16x32_bf16 v[86:89], v[58:61], v[10:13], v[66:69]
	v_mfma_f32_16x16x32_bf16 v[66:69], v[50:53], v[182:185], v[106:109]
	v_mfma_f32_16x16x32_bf16 v[82:85], v[58:61], v[186:189], v[66:69]
	v_mfma_f32_16x16x32_bf16 v[66:69], v[190:193], v[2:5], v[206:209]
	v_mfma_f32_16x16x32_bf16 v[70:73], v[222:225], v[10:13], v[66:69]
	v_mfma_f32_16x16x32_bf16 v[66:69], v[190:193], v[182:185], v[210:213]
	v_mfma_f32_16x16x32_bf16 v[66:69], v[222:225], v[186:189], v[66:69]
	s_barrier
	ds_read_b128 v[198:201], v139
	ds_read_b128 v[202:205], v139 offset:1024
	ds_read_b128 v[206:209], v139 offset:2048
	ds_read_b128 v[210:213], v139 offset:3072
	s_waitcnt vmcnt(0)
	s_barrier
	s_waitcnt lgkmcnt(0)
	v_mfma_f32_16x16x32_bf16 v[94:97], v[18:21], v[198:201], v[94:97]
	v_mfma_f32_16x16x32_bf16 v[18:21], v[18:21], v[206:209], v[90:93]
	v_mfma_f32_16x16x32_bf16 v[122:125], v[26:29], v[210:213], v[18:21]
	v_mfma_f32_16x16x32_bf16 v[18:21], v[34:37], v[198:201], v[142:145]
	v_mfma_f32_16x16x32_bf16 v[110:113], v[42:45], v[202:205], v[18:21]
	v_mfma_f32_16x16x32_bf16 v[18:21], v[34:37], v[206:209], v[162:165]
	v_mfma_f32_16x16x32_bf16 v[106:109], v[42:45], v[210:213], v[18:21]
	v_mfma_f32_16x16x32_bf16 v[18:21], v[50:53], v[198:201], v[78:81]
	v_mfma_f32_16x16x32_bf16 v[126:129], v[26:29], v[202:205], v[94:97]
	v_mfma_f32_16x16x32_bf16 v[94:97], v[58:61], v[202:205], v[18:21]
	v_mfma_f32_16x16x32_bf16 v[18:21], v[50:53], v[206:209], v[74:77]
	v_mfma_f32_16x16x32_bf16 v[90:93], v[58:61], v[210:213], v[18:21]
	v_mfma_f32_16x16x32_bf16 v[18:21], v[190:193], v[198:201], v[166:169]
	v_mfma_f32_16x16x32_bf16 v[78:81], v[222:225], v[202:205], v[18:21]
	v_mfma_f32_16x16x32_bf16 v[18:21], v[190:193], v[206:209], v[174:177]
	v_mfma_f32_16x16x32_bf16 v[74:77], v[222:225], v[210:213], v[18:21]
	s_barrier
	ds_read_b128 v[140:143], v138 offset:49152
	ds_read_b128 v[162:165], v138 offset:50176
	ds_read_b128 v[166:169], v137 offset:49152
	ds_read_b128 v[174:177], v137 offset:50176
	ds_read_b128 v[190:193], v136 offset:49152
	ds_read_b128 v[136:139], v136 offset:50176
	ds_read_b128 v[222:225], v135 offset:49152
	ds_read_b128 v[226:229], v135 offset:50176
	s_barrier
	s_waitcnt lgkmcnt(0)
	v_mfma_f32_16x16x32_bf16 v[18:21], v[140:143], v[2:5], v[62:65]
	v_mfma_f32_16x16x32_bf16 v[58:61], v[162:165], v[10:13], v[18:21]
	v_mfma_f32_16x16x32_bf16 v[18:21], v[140:143], v[182:185], v[194:197]
	v_mfma_f32_16x16x32_bf16 v[50:53], v[162:165], v[186:189], v[18:21]
	v_mfma_f32_16x16x32_bf16 v[18:21], v[166:169], v[2:5], v[54:57]
	v_mfma_f32_16x16x32_bf16 v[42:45], v[174:177], v[10:13], v[18:21]
	v_mfma_f32_16x16x32_bf16 v[18:21], v[166:169], v[182:185], v[214:217]
	v_mfma_f32_16x16x32_bf16 v[34:37], v[174:177], v[186:189], v[18:21]
	v_mfma_f32_16x16x32_bf16 v[18:21], v[190:193], v[2:5], v[46:49]
	v_mfma_f32_16x16x32_bf16 v[2:5], v[222:225], v[2:5], v[38:41]
	v_mfma_f32_16x16x32_bf16 v[26:29], v[136:139], v[10:13], v[18:21]
	v_mfma_f32_16x16x32_bf16 v[18:21], v[190:193], v[182:185], v[218:221]
	v_mfma_f32_16x16x32_bf16 v[10:13], v[226:229], v[10:13], v[2:5]
	v_mfma_f32_16x16x32_bf16 v[2:5], v[222:225], v[182:185], v[146:149]
	v_mfma_f32_16x16x32_bf16 v[18:21], v[136:139], v[186:189], v[18:21]
	v_mfma_f32_16x16x32_bf16 v[2:5], v[226:229], v[186:189], v[2:5]
	v_mfma_f32_16x16x32_bf16 v[30:33], v[140:143], v[198:201], v[30:33]
	v_mfma_f32_16x16x32_bf16 v[62:65], v[162:165], v[202:205], v[30:33]
	v_mfma_f32_16x16x32_bf16 v[30:33], v[140:143], v[206:209], v[150:153]
	v_mfma_f32_16x16x32_bf16 v[22:25], v[166:169], v[198:201], v[22:25]
	v_mfma_f32_16x16x32_bf16 v[14:17], v[190:193], v[198:201], v[14:17]
	v_mfma_f32_16x16x32_bf16 v[54:57], v[162:165], v[210:213], v[30:33]
	v_mfma_f32_16x16x32_bf16 v[46:49], v[174:177], v[202:205], v[22:25]
	v_mfma_f32_16x16x32_bf16 v[22:25], v[166:169], v[206:209], v[154:157]
	v_mfma_f32_16x16x32_bf16 v[30:33], v[136:139], v[202:205], v[14:17]
	v_mfma_f32_16x16x32_bf16 v[14:17], v[190:193], v[206:209], v[158:161]
	v_mfma_f32_16x16x32_bf16 v[6:9], v[222:225], v[198:201], v[6:9]
	v_mfma_f32_16x16x32_bf16 v[38:41], v[174:177], v[210:213], v[22:25]
	v_mfma_f32_16x16x32_bf16 v[22:25], v[136:139], v[210:213], v[14:17]
	v_mfma_f32_16x16x32_bf16 v[14:17], v[226:229], v[202:205], v[6:9]
	v_mfma_f32_16x16x32_bf16 v[6:9], v[222:225], v[206:209], v[178:181]
	v_mfma_f32_16x16x32_bf16 v[6:9], v[226:229], v[210:213], v[6:9]
	v_cmp_gt_u32_e32 vcc, s51, v134
	s_barrier
	s_and_saveexec_b64 s[20:21], vcc
	s_cbranch_execz .LBB0_718
	s_barrier

; #define STAGE(P, GP, ktrel) do { const GAS char* _g = (GP) + (ktrel) * (BK * 2); \
;     __builtin_amdgcn_global_load_lds((const GAS unsigned*)(_g + so0), (unsigned*)((char*)(P) + tid_ * 16), 16, 0, 0); \
;     __builtin_amdgcn_global_load_lds((const GAS unsigned*)(_g + so1), (unsigned*)((char*)(P) + tid_ * 16 + 8192), 16, 0, 0); } while (0)
; #define WAIT_L(n) asm volatile("s_waitcnt lgkmcnt(" #n ")" ::: "memory")
; #define BAR __builtin_amdgcn_s_barrier()
; #define SCHED __builtin_amdgcn_sched_barrier(0)
; #define LDA(dst, b, h) for (int m = 0; m < 4; ++m) for (int k = 0; k < 2; ++k) \
;     dst[m][k] = *reinterpret_cast<const bf16x8*>((char*)SA(b, h) + lds_byte(wr * 64 + m * 16 + fr, k * 32 + fq * 8))
; #define LDB(dst, b, h) for (int n = 0; n < 2; ++n) for (int k = 0; k < 2; ++k) \
;     dst[n][k] = *reinterpret_cast<const bf16x8*>((char*)SB(b, h) + lds_byte(wc * 32 + n * 16 + fr, k * 32 + fq * 8))
; #define MMA(ai, bj, At_, Bt_) do { __builtin_amdgcn_s_setprio(1); \
;     for (int m = 0; m < 4; ++m) for (int n = 0; n < 2; ++n) for (int k = 0; k < 2; ++k) \
;       acc[ai][bj][m][n] = __builtin_amdgcn_mfma_f32_16x16x32_bf16(At_[m][k], Bt_[n][k], acc[ai][bj][m][n], 0, 0, 0); \
;     __builtin_amdgcn_s_setprio(0); } while (0)
; template <int K, int LD = K>
; __device__ __forceinline__ void gemm_main(const GAS bf16* A, const GAS bf16* Bt, int brow, int bcol, f32x4 (&acc)[2][2][4][2]) {
;     ...
;     LDB(B0, 0, 0); SCHED; LDA(At, 0, 0); STAGE(SA(1, 1), pA1, 1);
;     WAIT_L(8); BAR; WAIT_L(0); MMA(0, 0, At, B0); BAR; SCHED;
;     LDB(B1, 0, 1); STAGE(SB(0, 0), pB0, 2);
;     BAR; WAIT_L(0); MMA(0, 1, At, B1); BAR;
;     LDA(At, 0, 1); STAGE(SA(0, 0), pA0, 2);
;     BAR; WAIT_L(0); MMA(1, 0, At, B0); BAR; SCHED;
.LBB0_767:
	ds_read_b128 v[160:163], v144
	ds_read_b128 v[164:167], v144 offset:1024
	ds_read_b128 v[174:177], v144 offset:2048
	ds_read_b128 v[178:181], v144 offset:3072
	v_lshl_add_u64 v[168:169], s[10:11], 0, v[130:131]
	v_readfirstlane_b32 s22, v143
	v_lshl_add_u64 v[214:215], v[168:169], 0, s[4:5]
	s_mov_b32 m0, s22
	v_lshl_add_u64 v[230:231], s[10:11], 0, v[132:133]
	v_readfirstlane_b32 s22, v142
	ds_read_b128 v[182:185], v138
	ds_read_b128 v[186:189], v138 offset:1024
	ds_read_b128 v[190:193], v137
	ds_read_b128 v[194:197], v137 offset:1024
	ds_read_b128 v[198:201], v136
	ds_read_b128 v[202:205], v136 offset:1024
	ds_read_b128 v[206:209], v135
	ds_read_b128 v[210:213], v135 offset:1024
	global_load_lds_dwordx4 v[214:215], off
	v_lshl_add_u64 v[214:215], v[230:231], 0, s[4:5]
	s_mov_b32 m0, s22
	s_nop 0
	global_load_lds_dwordx4 v[214:215], off
	s_waitcnt lgkmcnt(8)
	s_waitcnt vmcnt(10)
	s_barrier
	s_waitcnt lgkmcnt(0)
	v_mfma_f32_16x16x32_bf16 v[126:129], v[182:185], v[160:163], v[126:129]
	v_mfma_f32_16x16x32_bf16 v[122:125], v[182:185], v[174:177], v[122:125]
	v_mfma_f32_16x16x32_bf16 v[118:121], v[190:193], v[160:163], v[118:121]
	v_mfma_f32_16x16x32_bf16 v[114:117], v[190:193], v[174:177], v[114:117]
	v_mfma_f32_16x16x32_bf16 v[110:113], v[198:201], v[160:163], v[110:113]
	v_mfma_f32_16x16x32_bf16 v[106:109], v[198:201], v[174:177], v[106:109]
	v_mfma_f32_16x16x32_bf16 v[102:105], v[206:209], v[160:163], v[102:105]
	v_mfma_f32_16x16x32_bf16 v[98:101], v[206:209], v[174:177], v[98:101]
	v_mfma_f32_16x16x32_bf16 v[126:129], v[186:189], v[164:167], v[126:129]
	v_mfma_f32_16x16x32_bf16 v[122:125], v[186:189], v[178:181], v[122:125]
	v_mfma_f32_16x16x32_bf16 v[118:121], v[194:197], v[164:167], v[118:121]
	v_mfma_f32_16x16x32_bf16 v[114:117], v[194:197], v[178:181], v[114:117]
	v_mfma_f32_16x16x32_bf16 v[110:113], v[202:205], v[164:167], v[110:113]
	v_mfma_f32_16x16x32_bf16 v[106:109], v[202:205], v[178:181], v[106:109]
	v_mfma_f32_16x16x32_bf16 v[102:105], v[210:213], v[164:167], v[102:105]
	v_mfma_f32_16x16x32_bf16 v[98:101], v[210:213], v[178:181], v[98:101]
	s_barrier
	v_lshl_add_u64 v[232:233], s[20:21], 0, v[130:131]
	v_readfirstlane_b32 s22, v151
	v_lshl_add_u64 v[234:235], v[232:233], 0, s[6:7]
	s_mov_b32 m0, s22
	ds_read_b128 v[214:217], v141
	ds_read_b128 v[218:221], v141 offset:1024
	ds_read_b128 v[222:225], v141 offset:2048
	ds_read_b128 v[226:229], v141 offset:3072
	global_load_lds_dwordx4 v[234:235], off
	v_lshl_add_u64 v[234:235], s[20:21], 0, v[132:133]
	v_readfirstlane_b32 s22, v152
	v_lshl_add_u64 v[236:237], v[234:235], 0, s[6:7]
	s_mov_b32 m0, s22
	s_add_u32 s20, s20, 0x100
	global_load_lds_dwordx4 v[236:237], off
	s_waitcnt vmcnt(10)
	s_barrier
	s_waitcnt lgkmcnt(0)
	s_addc_u32 s21, s21, 0
	s_waitcnt lgkmcnt(0)
	v_mfma_f32_16x16x32_bf16 v[94:97], v[182:185], v[214:217], v[94:97]
	v_mfma_f32_16x16x32_bf16 v[90:93], v[182:185], v[222:225], v[90:93]
	v_mfma_f32_16x16x32_bf16 v[86:89], v[190:193], v[214:217], v[86:89]
	v_mfma_f32_16x16x32_bf16 v[82:85], v[190:193], v[222:225], v[82:85]
	v_mfma_f32_16x16x32_bf16 v[78:81], v[198:201], v[214:217], v[78:81]
	v_mfma_f32_16x16x32_bf16 v[74:77], v[198:201], v[222:225], v[74:77]
	v_mfma_f32_16x16x32_bf16 v[70:73], v[206:209], v[214:217], v[70:73]
	v_mfma_f32_16x16x32_bf16 v[66:69], v[206:209], v[222:225], v[66:69]
	v_mfma_f32_16x16x32_bf16 v[94:97], v[186:189], v[218:221], v[94:97]
	v_mfma_f32_16x16x32_bf16 v[90:93], v[186:189], v[226:229], v[90:93]
	v_mfma_f32_16x16x32_bf16 v[86:89], v[194:197], v[218:221], v[86:89]
	v_mfma_f32_16x16x32_bf16 v[82:85], v[194:197], v[226:229], v[82:85]
	v_mfma_f32_16x16x32_bf16 v[78:81], v[202:205], v[218:221], v[78:81]
	v_mfma_f32_16x16x32_bf16 v[74:77], v[202:205], v[226:229], v[74:77]
	v_mfma_f32_16x16x32_bf16 v[70:73], v[210:213], v[218:221], v[70:73]
	v_mfma_f32_16x16x32_bf16 v[66:69], v[210:213], v[226:229], v[66:69]
	v_lshl_add_u64 v[236:237], s[18:19], 0, v[130:131]
	v_readfirstlane_b32 s22, v145
	v_lshl_add_u64 v[238:239], v[236:237], 0, s[6:7]
	s_mov_b32 m0, s22
	s_barrier
	ds_read_b128 v[182:185], v138 offset:16384
	ds_read_b128 v[186:189], v138 offset:17408
	ds_read_b128 v[190:193], v137 offset:16384
	ds_read_b128 v[194:197], v137 offset:17408
	ds_read_b128 v[198:201], v136 offset:16384
	ds_read_b128 v[202:205], v136 offset:17408
	ds_read_b128 v[206:209], v135 offset:16384
	ds_read_b128 v[210:213], v135 offset:17408
	global_load_lds_dwordx4 v[238:239], off
	v_lshl_add_u64 v[238:239], s[18:19], 0, v[132:133]
	v_readfirstlane_b32 s22, v146
	v_lshl_add_u64 v[240:241], v[238:239], 0, s[6:7]
	s_mov_b32 m0, s22
	s_add_u32 s18, s18, 0x100
	global_load_lds_dwordx4 v[240:241], off
	s_barrier
	s_waitcnt lgkmcnt(0)
	s_addc_u32 s19, s19, 0
	s_waitcnt lgkmcnt(0)
	v_mfma_f32_16x16x32_bf16 v[62:65], v[182:185], v[160:163], v[62:65]
	v_mfma_f32_16x16x32_bf16 v[58:61], v[182:185], v[174:177], v[58:61]
	v_mfma_f32_16x16x32_bf16 v[54:57], v[190:193], v[160:163], v[54:57]
	v_mfma_f32_16x16x32_bf16 v[50:53], v[190:193], v[174:177], v[50:53]
	v_mfma_f32_16x16x32_bf16 v[46:49], v[198:201], v[160:163], v[46:49]
	v_mfma_f32_16x16x32_bf16 v[42:45], v[198:201], v[174:177], v[42:45]
	v_mfma_f32_16x16x32_bf16 v[38:41], v[206:209], v[160:163], v[38:41]
	v_mfma_f32_16x16x32_bf16 v[34:37], v[206:209], v[174:177], v[34:37]
	v_mfma_f32_16x16x32_bf16 v[62:65], v[186:189], v[164:167], v[62:65]
	v_mfma_f32_16x16x32_bf16 v[58:61], v[186:189], v[178:181], v[58:61]
	v_mfma_f32_16x16x32_bf16 v[54:57], v[194:197], v[164:167], v[54:57]
	v_mfma_f32_16x16x32_bf16 v[50:53], v[194:197], v[178:181], v[50:53]
	v_mfma_f32_16x16x32_bf16 v[46:49], v[202:205], v[164:167], v[46:49]
	v_mfma_f32_16x16x32_bf16 v[42:45], v[202:205], v[178:181], v[42:45]
	v_mfma_f32_16x16x32_bf16 v[38:41], v[210:213], v[164:167], v[38:41]
	v_mfma_f32_16x16x32_bf16 v[34:37], v[210:213], v[178:181], v[34:37]
	s_barrier
; #define STAGE(P, GP, ktrel) do { const GAS char* _g = (GP) + (ktrel) * (BK * 2); \
;     __builtin_amdgcn_global_load_lds((const GAS unsigned*)(_g + so0), (unsigned*)((char*)(P) + tid_ * 16), 16, 0, 0); \
;     __builtin_amdgcn_global_load_lds((const GAS unsigned*)(_g + so1), (unsigned*)((char*)(P) + tid_ * 16 + 8192), 16, 0, 0); } while (0)
; #define WAIT_V(n) asm volatile("s_waitcnt vmcnt(" #n ")" ::: "memory")
; #define WAIT_L(n) asm volatile("s_waitcnt lgkmcnt(" #n ")" ::: "memory")
; #define BAR __builtin_amdgcn_s_barrier()
; #define SCHED __builtin_amdgcn_sched_barrier(0)
; #define LDA(dst, b, h) for (int m = 0; m < 4; ++m) for (int k = 0; k < 2; ++k) \
;     dst[m][k] = *reinterpret_cast<const bf16x8*>((char*)SA(b, h) + lds_byte(wr * 64 + m * 16 + fr, k * 32 + fq * 8))
; #define LDB(dst, b, h) for (int n = 0; n < 2; ++n) for (int k = 0; k < 2; ++k) \
;     dst[n][k] = *reinterpret_cast<const bf16x8*>((char*)SB(b, h) + lds_byte(wc * 32 + n * 16 + fr, k * 32 + fq * 8))
; #define MMA(ai, bj, At_, Bt_) do { __builtin_amdgcn_s_setprio(1); \
;     for (int m = 0; m < 4; ++m) for (int n = 0; n < 2; ++n) for (int k = 0; k < 2; ++k) \
;       acc[ai][bj][m][n] = __builtin_amdgcn_mfma_f32_16x16x32_bf16(At_[m][k], Bt_[n][k], acc[ai][bj][m][n], 0, 0, 0); \
;     __builtin_amdgcn_s_setprio(0); } while (0)
; template <int K, int LD = K>
; __device__ __forceinline__ void gemm_main(const GAS bf16* A, const GAS bf16* Bt, int brow, int bcol, f32x4 (&acc)[2][2][4][2]) {
;     ...
;     STAGE(SB(0, 1), pB1, 2);
;     WAIT_V(6); BAR; MMA(1, 1, At, B1); BAR;
;     LDB(B0, 1, 0); SCHED; LDA(At, 1, 0); STAGE(SA(0, 1), pA1, 2);
;     WAIT_L(8); BAR; WAIT_L(0); MMA(0, 0, At, B0); BAR; SCHED;
;     LDB(B1, 1, 1); STAGE(SB(1, 0), pB0, 3);
;     BAR; WAIT_L(0); MMA(0, 1, At, B1); BAR;
	v_lshl_add_u64 v[240:241], s[16:17], 0, v[130:131]
	v_readfirstlane_b32 s22, v153
	v_lshl_add_u64 v[160:161], v[240:241], 0, s[6:7]
	s_mov_b32 m0, s22
	v_lshl_add_u64 v[242:243], s[16:17], 0, v[132:133]
	v_readfirstlane_b32 s22, v154
	global_load_lds_dwordx4 v[160:161], off
	v_lshl_add_u64 v[160:161], v[242:243], 0, s[6:7]
	s_mov_b32 m0, s22
	s_add_u32 s16, s16, 0x100
	global_load_lds_dwordx4 v[160:161], off
	s_waitcnt vmcnt(10)
	s_addc_u32 s17, s17, 0
	s_barrier
	v_mfma_f32_16x16x32_bf16 v[30:33], v[182:185], v[214:217], v[30:33]
	v_mfma_f32_16x16x32_bf16 v[26:29], v[182:185], v[222:225], v[26:29]
	v_mfma_f32_16x16x32_bf16 v[22:25], v[190:193], v[214:217], v[22:25]
	v_mfma_f32_16x16x32_bf16 v[18:21], v[190:193], v[222:225], v[18:21]
	v_mfma_f32_16x16x32_bf16 v[14:17], v[198:201], v[214:217], v[14:17]
	v_mfma_f32_16x16x32_bf16 v[10:13], v[198:201], v[222:225], v[10:13]
	v_mfma_f32_16x16x32_bf16 v[6:9], v[206:209], v[214:217], v[6:9]
	v_mfma_f32_16x16x32_bf16 v[2:5], v[206:209], v[222:225], v[2:5]
	v_mfma_f32_16x16x32_bf16 v[30:33], v[186:189], v[218:221], v[30:33]
	v_mfma_f32_16x16x32_bf16 v[26:29], v[186:189], v[226:229], v[26:29]
	v_mfma_f32_16x16x32_bf16 v[22:25], v[194:197], v[218:221], v[22:25]
	v_mfma_f32_16x16x32_bf16 v[18:21], v[194:197], v[226:229], v[18:21]
	v_mfma_f32_16x16x32_bf16 v[14:17], v[202:205], v[218:221], v[14:17]
	v_mfma_f32_16x16x32_bf16 v[10:13], v[202:205], v[226:229], v[10:13]
	v_mfma_f32_16x16x32_bf16 v[6:9], v[210:213], v[218:221], v[6:9]
	v_mfma_f32_16x16x32_bf16 v[2:5], v[210:213], v[226:229], v[2:5]
	s_barrier
	ds_read_b128 v[160:163], v140
	ds_read_b128 v[164:167], v140 offset:1024
	ds_read_b128 v[174:177], v140 offset:2048
	ds_read_b128 v[178:181], v140 offset:3072
	v_readfirstlane_b32 s22, v147
	v_lshl_add_u64 v[168:169], v[168:169], 0, s[6:7]
	s_mov_b32 m0, s22
	v_readfirstlane_b32 s22, v148
	ds_read_b128 v[182:185], v138 offset:32768
	ds_read_b128 v[186:189], v138 offset:33792
	ds_read_b128 v[190:193], v137 offset:32768
	ds_read_b128 v[194:197], v137 offset:33792
	ds_read_b128 v[198:201], v136 offset:32768
	ds_read_b128 v[202:205], v136 offset:33792
	ds_read_b128 v[206:209], v135 offset:32768
	ds_read_b128 v[210:213], v135 offset:33792
	global_load_lds_dwordx4 v[168:169], off
	v_lshl_add_u64 v[168:169], v[230:231], 0, s[6:7]
	s_mov_b32 m0, s22
	s_add_u32 s10, s10, 0x100
	global_load_lds_dwordx4 v[168:169], off
	s_waitcnt lgkmcnt(8)
	s_waitcnt vmcnt(10)
	s_barrier
	s_waitcnt lgkmcnt(0)
	s_addc_u32 s11, s11, 0
	s_waitcnt lgkmcnt(0)
	v_mfma_f32_16x16x32_bf16 v[126:129], v[182:185], v[160:163], v[126:129]
	v_mfma_f32_16x16x32_bf16 v[122:125], v[182:185], v[174:177], v[122:125]
	v_mfma_f32_16x16x32_bf16 v[118:121], v[190:193], v[160:163], v[118:121]
	v_mfma_f32_16x16x32_bf16 v[114:117], v[190:193], v[174:177], v[114:117]
	v_mfma_f32_16x16x32_bf16 v[110:113], v[198:201], v[160:163], v[110:113]
	v_mfma_f32_16x16x32_bf16 v[106:109], v[198:201], v[174:177], v[106:109]
	v_mfma_f32_16x16x32_bf16 v[102:105], v[206:209], v[160:163], v[102:105]
	v_mfma_f32_16x16x32_bf16 v[98:101], v[206:209], v[174:177], v[98:101]
	v_mfma_f32_16x16x32_bf16 v[126:129], v[186:189], v[164:167], v[126:129]
	v_mfma_f32_16x16x32_bf16 v[122:125], v[186:189], v[178:181], v[122:125]
	v_mfma_f32_16x16x32_bf16 v[118:121], v[194:197], v[164:167], v[118:121]
	v_mfma_f32_16x16x32_bf16 v[114:117], v[194:197], v[178:181], v[114:117]
	v_mfma_f32_16x16x32_bf16 v[110:113], v[202:205], v[164:167], v[110:113]
	v_mfma_f32_16x16x32_bf16 v[106:109], v[202:205], v[178:181], v[106:109]
	v_mfma_f32_16x16x32_bf16 v[102:105], v[210:213], v[164:167], v[102:105]
	v_mfma_f32_16x16x32_bf16 v[98:101], v[210:213], v[178:181], v[98:101]
	s_barrier
	v_readfirstlane_b32 s22, v155
	v_lshl_add_u64 v[168:169], v[232:233], 0, s[8:9]
	s_mov_b32 m0, s22
	v_readfirstlane_b32 s22, v156
	ds_read_b128 v[214:217], v139
	ds_read_b128 v[218:221], v139 offset:1024
	ds_read_b128 v[222:225], v139 offset:2048
	ds_read_b128 v[226:229], v139 offset:3072
	global_load_lds_dwordx4 v[168:169], off
	v_lshl_add_u64 v[168:169], v[234:235], 0, s[8:9]
	s_mov_b32 m0, s22
	s_nop 0
	global_load_lds_dwordx4 v[168:169], off
	s_waitcnt vmcnt(10)
	s_barrier
	s_waitcnt lgkmcnt(0)
	v_mfma_f32_16x16x32_bf16 v[94:97], v[182:185], v[214:217], v[94:97]
	v_mfma_f32_16x16x32_bf16 v[90:93], v[182:185], v[222:225], v[90:93]
	v_mfma_f32_16x16x32_bf16 v[86:89], v[190:193], v[214:217], v[86:89]
	v_mfma_f32_16x16x32_bf16 v[82:85], v[190:193], v[222:225], v[82:85]
	v_mfma_f32_16x16x32_bf16 v[78:81], v[198:201], v[214:217], v[78:81]
	v_mfma_f32_16x16x32_bf16 v[74:77], v[198:201], v[222:225], v[74:77]
	v_mfma_f32_16x16x32_bf16 v[70:73], v[206:209], v[214:217], v[70:73]
	v_mfma_f32_16x16x32_bf16 v[66:69], v[206:209], v[222:225], v[66:69]
	v_mfma_f32_16x16x32_bf16 v[94:97], v[186:189], v[218:221], v[94:97]
	v_mfma_f32_16x16x32_bf16 v[90:93], v[186:189], v[226:229], v[90:93]
	v_mfma_f32_16x16x32_bf16 v[86:89], v[194:197], v[218:221], v[86:89]
	v_mfma_f32_16x16x32_bf16 v[82:85], v[194:197], v[226:229], v[82:85]
	v_mfma_f32_16x16x32_bf16 v[78:81], v[202:205], v[218:221], v[78:81]
	v_mfma_f32_16x16x32_bf16 v[74:77], v[202:205], v[226:229], v[74:77]
	v_mfma_f32_16x16x32_bf16 v[70:73], v[210:213], v[218:221], v[70:73]
	v_mfma_f32_16x16x32_bf16 v[66:69], v[210:213], v[226:229], v[66:69]
	v_readfirstlane_b32 s22, v149
	v_lshl_add_u64 v[168:169], v[236:237], 0, s[8:9]
	s_mov_b32 m0, s22
	v_readfirstlane_b32 s22, v150
	s_barrier
; #define STAGE(P, GP, ktrel) do { const GAS char* _g = (GP) + (ktrel) * (BK * 2); \
;     __builtin_amdgcn_global_load_lds((const GAS unsigned*)(_g + so0), (unsigned*)((char*)(P) + tid_ * 16), 16, 0, 0); \
;     __builtin_amdgcn_global_load_lds((const GAS unsigned*)(_g + so1), (unsigned*)((char*)(P) + tid_ * 16 + 8192), 16, 0, 0); } while (0)
; #define WAIT_V(n) asm volatile("s_waitcnt vmcnt(" #n ")" ::: "memory")
; #define WAIT_L(n) asm volatile("s_waitcnt lgkmcnt(" #n ")" ::: "memory")
; #define BAR __builtin_amdgcn_s_barrier()
; #define SCHED __builtin_amdgcn_sched_barrier(0)
; #define LDA(dst, b, h) for (int m = 0; m < 4; ++m) for (int k = 0; k < 2; ++k) \
;     dst[m][k] = *reinterpret_cast<const bf16x8*>((char*)SA(b, h) + lds_byte(wr * 64 + m * 16 + fr, k * 32 + fq * 8))
; #define LDB(dst, b, h) for (int n = 0; n < 2; ++n) for (int k = 0; k < 2; ++k) \
;     dst[n][k] = *reinterpret_cast<const bf16x8*>((char*)SB(b, h) + lds_byte(wc * 32 + n * 16 + fr, k * 32 + fq * 8))
; #define MMA(ai, bj, At_, Bt_) do { __builtin_amdgcn_s_setprio(1); \
;     for (int m = 0; m < 4; ++m) for (int n = 0; n < 2; ++n) for (int k = 0; k < 2; ++k) \
;       acc[ai][bj][m][n] = __builtin_amdgcn_mfma_f32_16x16x32_bf16(At_[m][k], Bt_[n][k], acc[ai][bj][m][n], 0, 0, 0); \
;     __builtin_amdgcn_s_setprio(0); } while (0)
; template <int K, int LD = K>
; __device__ __forceinline__ void gemm_main(const GAS bf16* A, const GAS bf16* Bt, int brow, int bcol, f32x4 (&acc)[2][2][4][2]) {
;     ...
;     LDA(At, 1, 1); STAGE(SA(1, 0), pA0, 3);
;     BAR; WAIT_L(0); MMA(1, 0, At, B0); BAR; SCHED;
;     STAGE(SB(1, 1), pB1, 3);
;     WAIT_V(6); BAR; MMA(1, 1, At, B1); BAR;
;     pA0 += 4 * BK; pA1 += 4 * BK; pB0 += 4 * BK; pB1 += 4 * BK;
;     asm volatile("" : "+s"(pA0), "+s"(pA1), "+s"(pB0), "+s"(pB1));
;   }
;   { LDB(B0, 0, 0); LDA(At, 0, 0); STAGE(SA(1, 1), pA1, 1);
;     BAR; WAIT_L(0); MMA(0, 0, At, B0); BAR;
;     LDB(B1, 0, 1); BAR; WAIT_L(0); MMA(0, 1, At, B1); BAR;
	ds_read_b128 v[182:185], v138 offset:49152
	ds_read_b128 v[186:189], v138 offset:50176
	ds_read_b128 v[190:193], v137 offset:49152
	ds_read_b128 v[194:197], v137 offset:50176
	ds_read_b128 v[198:201], v136 offset:49152
	ds_read_b128 v[202:205], v136 offset:50176
	ds_read_b128 v[206:209], v135 offset:49152
	ds_read_b128 v[210:213], v135 offset:50176
	global_load_lds_dwordx4 v[168:169], off
	v_lshl_add_u64 v[168:169], v[238:239], 0, s[8:9]
	s_mov_b32 m0, s22
	s_nop 0
	global_load_lds_dwordx4 v[168:169], off
	s_barrier
	s_waitcnt lgkmcnt(0)
	v_mfma_f32_16x16x32_bf16 v[62:65], v[182:185], v[160:163], v[62:65]
	v_mfma_f32_16x16x32_bf16 v[58:61], v[182:185], v[174:177], v[58:61]
	v_mfma_f32_16x16x32_bf16 v[54:57], v[190:193], v[160:163], v[54:57]
	v_mfma_f32_16x16x32_bf16 v[50:53], v[190:193], v[174:177], v[50:53]
	v_mfma_f32_16x16x32_bf16 v[46:49], v[198:201], v[160:163], v[46:49]
	v_mfma_f32_16x16x32_bf16 v[42:45], v[198:201], v[174:177], v[42:45]
	v_mfma_f32_16x16x32_bf16 v[38:41], v[206:209], v[160:163], v[38:41]
	v_mfma_f32_16x16x32_bf16 v[34:37], v[206:209], v[174:177], v[34:37]
	v_mfma_f32_16x16x32_bf16 v[62:65], v[186:189], v[164:167], v[62:65]
	v_mfma_f32_16x16x32_bf16 v[58:61], v[186:189], v[178:181], v[58:61]
	v_mfma_f32_16x16x32_bf16 v[54:57], v[194:197], v[164:167], v[54:57]
	v_mfma_f32_16x16x32_bf16 v[50:53], v[194:197], v[178:181], v[50:53]
	v_mfma_f32_16x16x32_bf16 v[46:49], v[202:205], v[164:167], v[46:49]
	v_mfma_f32_16x16x32_bf16 v[42:45], v[202:205], v[178:181], v[42:45]
	v_mfma_f32_16x16x32_bf16 v[38:41], v[210:213], v[164:167], v[38:41]
	v_mfma_f32_16x16x32_bf16 v[34:37], v[210:213], v[178:181], v[34:37]
	s_barrier
	v_readfirstlane_b32 s22, v157
	v_lshl_add_u64 v[160:161], v[240:241], 0, s[8:9]
	s_mov_b32 m0, s22
	v_readfirstlane_b32 s22, v158
	global_load_lds_dwordx4 v[160:161], off
	v_lshl_add_u64 v[160:161], v[242:243], 0, s[8:9]
	s_mov_b32 m0, s22
	s_nop 0
	global_load_lds_dwordx4 v[160:161], off
	s_waitcnt vmcnt(10)
	s_barrier
	v_mfma_f32_16x16x32_bf16 v[30:33], v[182:185], v[214:217], v[30:33]
	v_mfma_f32_16x16x32_bf16 v[26:29], v[182:185], v[222:225], v[26:29]
	v_mfma_f32_16x16x32_bf16 v[22:25], v[190:193], v[214:217], v[22:25]
	v_mfma_f32_16x16x32_bf16 v[18:21], v[190:193], v[222:225], v[18:21]
	v_mfma_f32_16x16x32_bf16 v[14:17], v[198:201], v[214:217], v[14:17]
	v_mfma_f32_16x16x32_bf16 v[10:13], v[198:201], v[222:225], v[10:13]
	v_mfma_f32_16x16x32_bf16 v[6:9], v[206:209], v[214:217], v[6:9]
	v_mfma_f32_16x16x32_bf16 v[2:5], v[206:209], v[222:225], v[2:5]
	v_mfma_f32_16x16x32_bf16 v[30:33], v[186:189], v[218:221], v[30:33]
	v_mfma_f32_16x16x32_bf16 v[26:29], v[186:189], v[226:229], v[26:29]
	v_mfma_f32_16x16x32_bf16 v[22:25], v[194:197], v[218:221], v[22:25]
	v_mfma_f32_16x16x32_bf16 v[18:21], v[194:197], v[226:229], v[18:21]
	v_mfma_f32_16x16x32_bf16 v[14:17], v[202:205], v[218:221], v[14:17]
	v_mfma_f32_16x16x32_bf16 v[10:13], v[202:205], v[226:229], v[10:13]
	v_mfma_f32_16x16x32_bf16 v[6:9], v[210:213], v[218:221], v[6:9]
	v_mfma_f32_16x16x32_bf16 v[2:5], v[210:213], v[226:229], v[2:5]
	s_add_i32 s15, s15, 2
	s_cmp_lt_u32 s15, 12
	s_barrier
	s_cbranch_scc1 .LBB0_767
	ds_read_b128 v[146:149], v144
	ds_read_b128 v[150:153], v144 offset:1024
	ds_read_b128 v[154:157], v144 offset:2048
	ds_read_b128 v[158:161], v144 offset:3072
	ds_read_b128 v[162:165], v138
	ds_read_b128 v[166:169], v138 offset:1024
	ds_read_b128 v[174:177], v137
	ds_read_b128 v[178:181], v137 offset:1024
	ds_read_b128 v[182:185], v136
	ds_read_b128 v[186:189], v136 offset:1024
	ds_read_b128 v[190:193], v135
	ds_read_b128 v[194:197], v135 offset:1024
	v_lshl_add_u64 v[144:145], s[10:11], 0, v[130:131]
	v_readfirstlane_b32 s15, v143
	v_lshl_add_u64 v[144:145], v[144:145], 0, s[4:5]
	s_mov_b32 m0, s15
	v_lshl_add_u64 v[132:133], s[10:11], 0, v[132:133]
	v_readfirstlane_b32 s10, v142
	global_load_lds_dwordx4 v[144:145], off
	v_lshl_add_u64 v[132:133], v[132:133], 0, s[4:5]
	s_mov_b32 m0, s10
	s_nop 0
	global_load_lds_dwordx4 v[132:133], off
	s_waitcnt vmcnt(10)
	s_barrier
	s_waitcnt lgkmcnt(0)
	v_mfma_f32_16x16x32_bf16 v[126:129], v[162:165], v[146:149], v[126:129]
	v_mfma_f32_16x16x32_bf16 v[122:125], v[162:165], v[154:157], v[122:125]
	v_mfma_f32_16x16x32_bf16 v[110:113], v[182:185], v[146:149], v[110:113]
	v_mfma_f32_16x16x32_bf16 v[106:109], v[182:185], v[154:157], v[106:109]
	v_mfma_f32_16x16x32_bf16 v[126:129], v[166:169], v[150:153], v[126:129]
	v_mfma_f32_16x16x32_bf16 v[122:125], v[166:169], v[158:161], v[122:125]
	v_mfma_f32_16x16x32_bf16 v[118:121], v[174:177], v[146:149], v[118:121]
	v_mfma_f32_16x16x32_bf16 v[114:117], v[174:177], v[154:157], v[114:117]
	v_mfma_f32_16x16x32_bf16 v[110:113], v[186:189], v[150:153], v[110:113]
	v_mfma_f32_16x16x32_bf16 v[106:109], v[186:189], v[158:161], v[106:109]
	v_mfma_f32_16x16x32_bf16 v[102:105], v[190:193], v[146:149], v[102:105]
	v_mfma_f32_16x16x32_bf16 v[98:101], v[190:193], v[154:157], v[98:101]
	v_mfma_f32_16x16x32_bf16 v[142:145], v[178:181], v[150:153], v[118:121]
	v_mfma_f32_16x16x32_bf16 v[198:201], v[178:181], v[158:161], v[114:117]
	v_mfma_f32_16x16x32_bf16 v[202:205], v[194:197], v[150:153], v[102:105]
	v_mfma_f32_16x16x32_bf16 v[206:209], v[194:197], v[158:161], v[98:101]
	s_barrier
	s_nop 1
	ds_read_b128 v[98:101], v141
	ds_read_b128 v[102:105], v141 offset:1024
	ds_read_b128 v[114:117], v141 offset:2048
	ds_read_b128 v[118:121], v141 offset:3072
	s_waitcnt vmcnt(8)
	s_barrier
; #define WAIT_V(n) asm volatile("s_waitcnt vmcnt(" #n ")" ::: "memory")
; #define WAIT_L(n) asm volatile("s_waitcnt lgkmcnt(" #n ")" ::: "memory")
; #define BAR __builtin_amdgcn_s_barrier()
; #define LDA(dst, b, h) for (int m = 0; m < 4; ++m) for (int k = 0; k < 2; ++k) \
;     dst[m][k] = *reinterpret_cast<const bf16x8*>((char*)SA(b, h) + lds_byte(wr * 64 + m * 16 + fr, k * 32 + fq * 8))
; #define LDB(dst, b, h) for (int n = 0; n < 2; ++n) for (int k = 0; k < 2; ++k) \
;     dst[n][k] = *reinterpret_cast<const bf16x8*>((char*)SB(b, h) + lds_byte(wc * 32 + n * 16 + fr, k * 32 + fq * 8))
; #define MMA(ai, bj, At_, Bt_) do { __builtin_amdgcn_s_setprio(1); \
;     for (int m = 0; m < 4; ++m) for (int n = 0; n < 2; ++n) for (int k = 0; k < 2; ++k) \
;       acc[ai][bj][m][n] = __builtin_amdgcn_mfma_f32_16x16x32_bf16(At_[m][k], Bt_[n][k], acc[ai][bj][m][n], 0, 0, 0); \
;     __builtin_amdgcn_s_setprio(0); } while (0)
; template <int K, int LD = K>
; __device__ __forceinline__ void gemm_main(const GAS bf16* A, const GAS bf16* Bt, int brow, int bcol, f32x4 (&acc)[2][2][4][2]) {
;     ...
;     LDB(B1, 0, 1); BAR; WAIT_L(0); MMA(0, 1, At, B1); BAR;
;     LDA(At, 0, 1); WAIT_V(4); BAR; WAIT_L(0); MMA(1, 0, At, B0); MMA(1, 1, At, B1); BAR; }
	s_waitcnt lgkmcnt(0)
	v_mfma_f32_16x16x32_bf16 v[94:97], v[162:165], v[98:101], v[94:97]
	v_mfma_f32_16x16x32_bf16 v[90:93], v[162:165], v[114:117], v[90:93]
	v_mfma_f32_16x16x32_bf16 v[78:81], v[182:185], v[98:101], v[78:81]
	v_mfma_f32_16x16x32_bf16 v[74:77], v[182:185], v[114:117], v[74:77]
	v_mfma_f32_16x16x32_bf16 v[94:97], v[166:169], v[102:105], v[94:97]
	v_mfma_f32_16x16x32_bf16 v[90:93], v[166:169], v[118:121], v[90:93]
	v_mfma_f32_16x16x32_bf16 v[86:89], v[174:177], v[98:101], v[86:89]
	v_mfma_f32_16x16x32_bf16 v[82:85], v[174:177], v[114:117], v[82:85]
	v_mfma_f32_16x16x32_bf16 v[78:81], v[186:189], v[102:105], v[78:81]
	v_mfma_f32_16x16x32_bf16 v[74:77], v[186:189], v[118:121], v[74:77]
	v_mfma_f32_16x16x32_bf16 v[70:73], v[190:193], v[98:101], v[70:73]
	v_mfma_f32_16x16x32_bf16 v[66:69], v[190:193], v[114:117], v[66:69]
	v_mfma_f32_16x16x32_bf16 v[162:165], v[178:181], v[102:105], v[86:89]
	v_mfma_f32_16x16x32_bf16 v[166:169], v[178:181], v[118:121], v[82:85]
	v_mfma_f32_16x16x32_bf16 v[174:177], v[194:197], v[102:105], v[70:73]
	v_mfma_f32_16x16x32_bf16 v[178:181], v[194:197], v[118:121], v[66:69]
	s_barrier
	s_nop 1
	ds_read_b128 v[66:69], v138 offset:16384
	ds_read_b128 v[70:73], v138 offset:17408
	ds_read_b128 v[82:85], v137 offset:16384
	ds_read_b128 v[86:89], v137 offset:17408
	ds_read_b128 v[182:185], v136 offset:16384
	ds_read_b128 v[186:189], v136 offset:17408
	ds_read_b128 v[190:193], v135 offset:16384
	ds_read_b128 v[194:197], v135 offset:17408
	s_waitcnt vmcnt(4)
	s_barrier
	s_waitcnt lgkmcnt(0)
	v_mfma_f32_16x16x32_bf16 v[62:65], v[66:69], v[146:149], v[62:65]
	v_mfma_f32_16x16x32_bf16 v[58:61], v[66:69], v[154:157], v[58:61]
	v_mfma_f32_16x16x32_bf16 v[46:49], v[182:185], v[146:149], v[46:49]
	v_mfma_f32_16x16x32_bf16 v[42:45], v[182:185], v[154:157], v[42:45]
	v_mfma_f32_16x16x32_bf16 v[62:65], v[70:73], v[150:153], v[62:65]
	v_mfma_f32_16x16x32_bf16 v[58:61], v[70:73], v[158:161], v[58:61]
	v_mfma_f32_16x16x32_bf16 v[54:57], v[82:85], v[146:149], v[54:57]
	v_mfma_f32_16x16x32_bf16 v[50:53], v[82:85], v[154:157], v[50:53]
	v_mfma_f32_16x16x32_bf16 v[46:49], v[186:189], v[150:153], v[46:49]
	v_mfma_f32_16x16x32_bf16 v[42:45], v[186:189], v[158:161], v[42:45]
	v_mfma_f32_16x16x32_bf16 v[38:41], v[190:193], v[146:149], v[38:41]
	v_mfma_f32_16x16x32_bf16 v[34:37], v[190:193], v[154:157], v[34:37]
	v_mfma_f32_16x16x32_bf16 v[210:213], v[86:89], v[150:153], v[54:57]
	v_mfma_f32_16x16x32_bf16 v[214:217], v[86:89], v[158:161], v[50:53]
	v_mfma_f32_16x16x32_bf16 v[146:149], v[194:197], v[150:153], v[38:41]
	v_mfma_f32_16x16x32_bf16 v[150:153], v[194:197], v[158:161], v[34:37]
	v_mfma_f32_16x16x32_bf16 v[30:33], v[66:69], v[98:101], v[30:33]
	v_mfma_f32_16x16x32_bf16 v[26:29], v[66:69], v[114:117], v[26:29]
	v_mfma_f32_16x16x32_bf16 v[14:17], v[182:185], v[98:101], v[14:17]
	v_mfma_f32_16x16x32_bf16 v[10:13], v[182:185], v[114:117], v[10:13]
	v_mfma_f32_16x16x32_bf16 v[30:33], v[70:73], v[102:105], v[30:33]
	v_mfma_f32_16x16x32_bf16 v[26:29], v[70:73], v[118:121], v[26:29]
	v_mfma_f32_16x16x32_bf16 v[22:25], v[82:85], v[98:101], v[22:25]
	v_mfma_f32_16x16x32_bf16 v[18:21], v[82:85], v[114:117], v[18:21]
	v_mfma_f32_16x16x32_bf16 v[14:17], v[186:189], v[102:105], v[14:17]
	v_mfma_f32_16x16x32_bf16 v[10:13], v[186:189], v[118:121], v[10:13]
	v_mfma_f32_16x16x32_bf16 v[6:9], v[190:193], v[98:101], v[6:9]
	v_mfma_f32_16x16x32_bf16 v[2:5], v[190:193], v[114:117], v[2:5]
	v_mfma_f32_16x16x32_bf16 v[154:157], v[86:89], v[102:105], v[22:25]
	v_mfma_f32_16x16x32_bf16 v[158:161], v[86:89], v[118:121], v[18:21]
	v_mfma_f32_16x16x32_bf16 v[182:185], v[194:197], v[102:105], v[6:9]
	v_mfma_f32_16x16x32_bf16 v[186:189], v[194:197], v[118:121], v[2:5]
	s_barrier
	s_nop 1
	ds_read_b128 v[2:5], v140
	ds_read_b128 v[6:9], v140 offset:1024
	ds_read_b128 v[190:193], v140 offset:2048
	ds_read_b128 v[194:197], v140 offset:3072
	ds_read_b128 v[18:21], v138 offset:32768
	ds_read_b128 v[22:25], v138 offset:33792
	ds_read_b128 v[34:37], v137 offset:32768
	ds_read_b128 v[38:41], v137 offset:33792
	ds_read_b128 v[50:53], v136 offset:32768
	ds_read_b128 v[54:57], v136 offset:33792
	ds_read_b128 v[218:221], v135 offset:32768
	ds_read_b128 v[222:225], v135 offset:33792
	s_waitcnt vmcnt(2)
	s_barrier
; #define WAIT_V(n) asm volatile("s_waitcnt vmcnt(" #n ")" ::: "memory")
; #define WAIT_L(n) asm volatile("s_waitcnt lgkmcnt(" #n ")" ::: "memory")
; #define BAR __builtin_amdgcn_s_barrier()
; #define LDA(dst, b, h) for (int m = 0; m < 4; ++m) for (int k = 0; k < 2; ++k) \
;     dst[m][k] = *reinterpret_cast<const bf16x8*>((char*)SA(b, h) + lds_byte(wr * 64 + m * 16 + fr, k * 32 + fq * 8))
; #define LDB(dst, b, h) for (int n = 0; n < 2; ++n) for (int k = 0; k < 2; ++k) \
;     dst[n][k] = *reinterpret_cast<const bf16x8*>((char*)SB(b, h) + lds_byte(wc * 32 + n * 16 + fr, k * 32 + fq * 8))
; #define MMA(ai, bj, At_, Bt_) do { __builtin_amdgcn_s_setprio(1); \
;     for (int m = 0; m < 4; ++m) for (int n = 0; n < 2; ++n) for (int k = 0; k < 2; ++k) \
;       acc[ai][bj][m][n] = __builtin_amdgcn_mfma_f32_16x16x32_bf16(At_[m][k], Bt_[n][k], acc[ai][bj][m][n], 0, 0, 0); \
;     __builtin_amdgcn_s_setprio(0); } while (0)
; template <int K, int LD = K>
; __device__ __forceinline__ void gemm_main(const GAS bf16* A, const GAS bf16* Bt, int brow, int bcol, f32x4 (&acc)[2][2][4][2]) {
;     ...
;   { LDB(B0, 1, 0); LDA(At, 1, 0); WAIT_V(2); BAR; WAIT_L(0); MMA(0, 0, At, B0); BAR;
;     LDB(B1, 1, 1); WAIT_V(0); BAR; WAIT_L(0); MMA(0, 1, At, B1); BAR;
;     LDA(At, 1, 1); BAR; WAIT_L(0); MMA(1, 0, At, B0); MMA(1, 1, At, B1); BAR; }
;   if (wr == 0) BAR;
	s_waitcnt lgkmcnt(0)
	v_mfma_f32_16x16x32_bf16 v[66:69], v[18:21], v[2:5], v[126:129]
	v_mfma_f32_16x16x32_bf16 v[118:121], v[22:25], v[6:9], v[66:69]
	v_mfma_f32_16x16x32_bf16 v[66:69], v[18:21], v[190:193], v[122:125]
	v_mfma_f32_16x16x32_bf16 v[114:117], v[22:25], v[194:197], v[66:69]
	v_mfma_f32_16x16x32_bf16 v[66:69], v[34:37], v[2:5], v[142:145]
	v_mfma_f32_16x16x32_bf16 v[102:105], v[38:41], v[6:9], v[66:69]
	v_mfma_f32_16x16x32_bf16 v[66:69], v[34:37], v[190:193], v[198:201]
	v_mfma_f32_16x16x32_bf16 v[98:101], v[38:41], v[194:197], v[66:69]
	v_mfma_f32_16x16x32_bf16 v[66:69], v[50:53], v[2:5], v[110:113]
	v_mfma_f32_16x16x32_bf16 v[86:89], v[54:57], v[6:9], v[66:69]
	v_mfma_f32_16x16x32_bf16 v[66:69], v[50:53], v[190:193], v[106:109]
	v_mfma_f32_16x16x32_bf16 v[82:85], v[54:57], v[194:197], v[66:69]
	v_mfma_f32_16x16x32_bf16 v[66:69], v[218:221], v[2:5], v[202:205]
	v_mfma_f32_16x16x32_bf16 v[70:73], v[222:225], v[6:9], v[66:69]
	v_mfma_f32_16x16x32_bf16 v[66:69], v[218:221], v[190:193], v[206:209]
	v_mfma_f32_16x16x32_bf16 v[66:69], v[222:225], v[194:197], v[66:69]
	s_barrier
	ds_read_b128 v[140:143], v139
	ds_read_b128 v[198:201], v139 offset:1024
	ds_read_b128 v[202:205], v139 offset:2048
	ds_read_b128 v[206:209], v139 offset:3072
	s_waitcnt vmcnt(0)
	s_barrier
	s_waitcnt lgkmcnt(0)
	v_mfma_f32_16x16x32_bf16 v[94:97], v[18:21], v[140:143], v[94:97]
	v_mfma_f32_16x16x32_bf16 v[18:21], v[18:21], v[202:205], v[90:93]
	v_mfma_f32_16x16x32_bf16 v[122:125], v[22:25], v[206:209], v[18:21]
	v_mfma_f32_16x16x32_bf16 v[18:21], v[34:37], v[140:143], v[162:165]
	v_mfma_f32_16x16x32_bf16 v[110:113], v[38:41], v[198:201], v[18:21]
	v_mfma_f32_16x16x32_bf16 v[18:21], v[34:37], v[202:205], v[166:169]
	v_mfma_f32_16x16x32_bf16 v[106:109], v[38:41], v[206:209], v[18:21]
	v_mfma_f32_16x16x32_bf16 v[18:21], v[50:53], v[140:143], v[78:81]
	v_mfma_f32_16x16x32_bf16 v[126:129], v[22:25], v[198:201], v[94:97]
	v_mfma_f32_16x16x32_bf16 v[94:97], v[54:57], v[198:201], v[18:21]
	v_mfma_f32_16x16x32_bf16 v[18:21], v[50:53], v[202:205], v[74:77]
	v_mfma_f32_16x16x32_bf16 v[90:93], v[54:57], v[206:209], v[18:21]
	v_mfma_f32_16x16x32_bf16 v[18:21], v[218:221], v[140:143], v[174:177]
	v_mfma_f32_16x16x32_bf16 v[78:81], v[222:225], v[198:201], v[18:21]
	v_mfma_f32_16x16x32_bf16 v[18:21], v[218:221], v[202:205], v[178:181]
	v_mfma_f32_16x16x32_bf16 v[74:77], v[222:225], v[206:209], v[18:21]
	s_barrier
	ds_read_b128 v[162:165], v138 offset:49152
	ds_read_b128 v[166:169], v138 offset:50176
	ds_read_b128 v[174:177], v137 offset:49152
	ds_read_b128 v[178:181], v137 offset:50176
	ds_read_b128 v[218:221], v136 offset:49152
	ds_read_b128 v[136:139], v136 offset:50176
	ds_read_b128 v[222:225], v135 offset:49152
	ds_read_b128 v[226:229], v135 offset:50176
	s_barrier
	s_waitcnt lgkmcnt(0)
	v_mfma_f32_16x16x32_bf16 v[18:21], v[162:165], v[2:5], v[62:65]
	v_mfma_f32_16x16x32_bf16 v[54:57], v[166:169], v[6:9], v[18:21]
	v_mfma_f32_16x16x32_bf16 v[18:21], v[162:165], v[190:193], v[58:61]
	v_mfma_f32_16x16x32_bf16 v[50:53], v[166:169], v[194:197], v[18:21]
	v_mfma_f32_16x16x32_bf16 v[18:21], v[174:177], v[2:5], v[210:213]
	v_mfma_f32_16x16x32_bf16 v[38:41], v[178:181], v[6:9], v[18:21]
	v_mfma_f32_16x16x32_bf16 v[18:21], v[174:177], v[190:193], v[214:217]
	v_mfma_f32_16x16x32_bf16 v[34:37], v[178:181], v[194:197], v[18:21]
	v_mfma_f32_16x16x32_bf16 v[18:21], v[218:221], v[2:5], v[46:49]
	v_mfma_f32_16x16x32_bf16 v[2:5], v[222:225], v[2:5], v[146:149]
	v_mfma_f32_16x16x32_bf16 v[22:25], v[136:139], v[6:9], v[18:21]
	v_mfma_f32_16x16x32_bf16 v[18:21], v[218:221], v[190:193], v[42:45]
	v_mfma_f32_16x16x32_bf16 v[6:9], v[226:229], v[6:9], v[2:5]
	v_mfma_f32_16x16x32_bf16 v[2:5], v[222:225], v[190:193], v[150:153]
	v_mfma_f32_16x16x32_bf16 v[18:21], v[136:139], v[194:197], v[18:21]
	v_mfma_f32_16x16x32_bf16 v[2:5], v[226:229], v[194:197], v[2:5]
	v_mfma_f32_16x16x32_bf16 v[26:29], v[162:165], v[202:205], v[26:29]
	v_mfma_f32_16x16x32_bf16 v[58:61], v[166:169], v[206:209], v[26:29]
	v_mfma_f32_16x16x32_bf16 v[26:29], v[174:177], v[140:143], v[154:157]
	v_mfma_f32_16x16x32_bf16 v[46:49], v[178:181], v[198:201], v[26:29]
	v_mfma_f32_16x16x32_bf16 v[26:29], v[174:177], v[202:205], v[158:161]
	v_mfma_f32_16x16x32_bf16 v[10:13], v[218:221], v[202:205], v[10:13]
	v_mfma_f32_16x16x32_bf16 v[30:33], v[162:165], v[140:143], v[30:33]
	v_mfma_f32_16x16x32_bf16 v[42:45], v[178:181], v[206:209], v[26:29]
	v_mfma_f32_16x16x32_bf16 v[14:17], v[218:221], v[140:143], v[14:17]
	v_mfma_f32_16x16x32_bf16 v[26:29], v[136:139], v[206:209], v[10:13]
	v_mfma_f32_16x16x32_bf16 v[10:13], v[222:225], v[140:143], v[182:185]
	v_mfma_f32_16x16x32_bf16 v[62:65], v[166:169], v[198:201], v[30:33]
	v_mfma_f32_16x16x32_bf16 v[30:33], v[136:139], v[198:201], v[14:17]
	v_mfma_f32_16x16x32_bf16 v[14:17], v[226:229], v[198:201], v[10:13]
	v_mfma_f32_16x16x32_bf16 v[10:13], v[222:225], v[202:205], v[186:189]
	v_mfma_f32_16x16x32_bf16 v[10:13], v[226:229], v[206:209], v[10:13]
	v_cmp_gt_u32_e32 vcc, s34, v134
	s_barrier
	s_and_saveexec_b64 s[10:11], vcc
	s_cbranch_execz .LBB0_770
	s_barrier

; #define STAGE(P, GP, ktrel) do { const GAS char* _g = (GP) + (ktrel) * (BK * 2); \
;     __builtin_amdgcn_global_load_lds((const GAS unsigned*)(_g + so0), (unsigned*)((char*)(P) + tid_ * 16), 16, 0, 0); \
;     __builtin_amdgcn_global_load_lds((const GAS unsigned*)(_g + so1), (unsigned*)((char*)(P) + tid_ * 16 + 8192), 16, 0, 0); } while (0)
; #define WAIT_L(n) asm volatile("s_waitcnt lgkmcnt(" #n ")" ::: "memory")
; #define BAR __builtin_amdgcn_s_barrier()
; #define SCHED __builtin_amdgcn_sched_barrier(0)
; #define LDA(dst, b, h) for (int m = 0; m < 4; ++m) for (int k = 0; k < 2; ++k) \
;     dst[m][k] = *reinterpret_cast<const bf16x8*>((char*)SA(b, h) + lds_byte(wr * 64 + m * 16 + fr, k * 32 + fq * 8))
; #define LDB(dst, b, h) for (int n = 0; n < 2; ++n) for (int k = 0; k < 2; ++k) \
;     dst[n][k] = *reinterpret_cast<const bf16x8*>((char*)SB(b, h) + lds_byte(wc * 32 + n * 16 + fr, k * 32 + fq * 8))
; #define MMA(ai, bj, At_, Bt_) do { __builtin_amdgcn_s_setprio(1); \
;     for (int m = 0; m < 4; ++m) for (int n = 0; n < 2; ++n) for (int k = 0; k < 2; ++k) \
;       acc[ai][bj][m][n] = __builtin_amdgcn_mfma_f32_16x16x32_bf16(At_[m][k], Bt_[n][k], acc[ai][bj][m][n], 0, 0, 0); \
;     __builtin_amdgcn_s_setprio(0); } while (0)
; template <int K, int LD = K>
; __device__ __forceinline__ void gemm_main(const GAS bf16* A, const GAS bf16* Bt, int brow, int bcol, f32x4 (&acc)[2][2][4][2]) {
;     ...
;     LDB(B0, 0, 0); SCHED; LDA(At, 0, 0); STAGE(SA(1, 1), pA1, 1);
;     WAIT_L(8); BAR; WAIT_L(0); MMA(0, 0, At, B0); BAR; SCHED;
;     LDB(B1, 0, 1); STAGE(SB(0, 0), pB0, 2);
;     BAR; WAIT_L(0); MMA(0, 1, At, B1); BAR;
;     LDA(At, 0, 1); STAGE(SA(0, 0), pA0, 2);
;     BAR; WAIT_L(0); MMA(1, 0, At, B0); BAR; SCHED;
.LBB0_884:
	ds_read_b128 v[160:163], v145
	ds_read_b128 v[164:167], v145 offset:1024
	ds_read_b128 v[174:177], v145 offset:2048
	ds_read_b128 v[178:181], v145 offset:3072
	v_lshl_add_u64 v[168:169], s[12:13], 0, v[130:131]
	v_readfirstlane_b32 s22, v144
	v_lshl_add_u64 v[214:215], v[168:169], 0, s[6:7]
	s_mov_b32 m0, s22
	v_lshl_add_u64 v[230:231], s[12:13], 0, v[132:133]
	v_readfirstlane_b32 s22, v143
	ds_read_b128 v[182:185], v139
	ds_read_b128 v[186:189], v139 offset:1024
	ds_read_b128 v[190:193], v138
	ds_read_b128 v[194:197], v138 offset:1024
	ds_read_b128 v[198:201], v137
	ds_read_b128 v[202:205], v137 offset:1024
	ds_read_b128 v[206:209], v136
	ds_read_b128 v[210:213], v136 offset:1024
	global_load_lds_dwordx4 v[214:215], off
	v_lshl_add_u64 v[214:215], v[230:231], 0, s[6:7]
	s_mov_b32 m0, s22
	s_nop 0
	global_load_lds_dwordx4 v[214:215], off
	s_waitcnt lgkmcnt(8)
	s_waitcnt vmcnt(10)
	s_barrier
	s_waitcnt lgkmcnt(0)
	v_mfma_f32_16x16x32_bf16 v[126:129], v[182:185], v[160:163], v[126:129]
	v_mfma_f32_16x16x32_bf16 v[122:125], v[182:185], v[174:177], v[122:125]
	v_mfma_f32_16x16x32_bf16 v[118:121], v[190:193], v[160:163], v[118:121]
	v_mfma_f32_16x16x32_bf16 v[114:117], v[190:193], v[174:177], v[114:117]
	v_mfma_f32_16x16x32_bf16 v[110:113], v[198:201], v[160:163], v[110:113]
	v_mfma_f32_16x16x32_bf16 v[106:109], v[198:201], v[174:177], v[106:109]
	v_mfma_f32_16x16x32_bf16 v[102:105], v[206:209], v[160:163], v[102:105]
	v_mfma_f32_16x16x32_bf16 v[98:101], v[206:209], v[174:177], v[98:101]
	v_mfma_f32_16x16x32_bf16 v[126:129], v[186:189], v[164:167], v[126:129]
	v_mfma_f32_16x16x32_bf16 v[122:125], v[186:189], v[178:181], v[122:125]
	v_mfma_f32_16x16x32_bf16 v[118:121], v[194:197], v[164:167], v[118:121]
	v_mfma_f32_16x16x32_bf16 v[114:117], v[194:197], v[178:181], v[114:117]
	v_mfma_f32_16x16x32_bf16 v[110:113], v[202:205], v[164:167], v[110:113]
	v_mfma_f32_16x16x32_bf16 v[106:109], v[202:205], v[178:181], v[106:109]
	v_mfma_f32_16x16x32_bf16 v[102:105], v[210:213], v[164:167], v[102:105]
	v_mfma_f32_16x16x32_bf16 v[98:101], v[210:213], v[178:181], v[98:101]
	s_barrier
	v_lshl_add_u64 v[232:233], s[20:21], 0, v[130:131]
	v_readfirstlane_b32 s22, v152
	v_lshl_add_u64 v[234:235], v[232:233], 0, s[8:9]
	s_mov_b32 m0, s22
	ds_read_b128 v[214:217], v142
	ds_read_b128 v[218:221], v142 offset:1024
	ds_read_b128 v[222:225], v142 offset:2048
	ds_read_b128 v[226:229], v142 offset:3072
	global_load_lds_dwordx4 v[234:235], off
	v_lshl_add_u64 v[234:235], s[20:21], 0, v[132:133]
	v_readfirstlane_b32 s22, v153
	v_lshl_add_u64 v[236:237], v[234:235], 0, s[8:9]
	s_mov_b32 m0, s22
	s_add_u32 s20, s20, 0x100
	global_load_lds_dwordx4 v[236:237], off
	s_waitcnt vmcnt(10)
	s_barrier
	s_waitcnt lgkmcnt(0)
	s_addc_u32 s21, s21, 0
	s_waitcnt lgkmcnt(0)
	v_mfma_f32_16x16x32_bf16 v[94:97], v[182:185], v[214:217], v[94:97]
	v_mfma_f32_16x16x32_bf16 v[90:93], v[182:185], v[222:225], v[90:93]
	v_mfma_f32_16x16x32_bf16 v[86:89], v[190:193], v[214:217], v[86:89]
	v_mfma_f32_16x16x32_bf16 v[82:85], v[190:193], v[222:225], v[82:85]
	v_mfma_f32_16x16x32_bf16 v[78:81], v[198:201], v[214:217], v[78:81]
	v_mfma_f32_16x16x32_bf16 v[74:77], v[198:201], v[222:225], v[74:77]
	v_mfma_f32_16x16x32_bf16 v[70:73], v[206:209], v[214:217], v[70:73]
	v_mfma_f32_16x16x32_bf16 v[66:69], v[206:209], v[222:225], v[66:69]
	v_mfma_f32_16x16x32_bf16 v[94:97], v[186:189], v[218:221], v[94:97]
	v_mfma_f32_16x16x32_bf16 v[90:93], v[186:189], v[226:229], v[90:93]
	v_mfma_f32_16x16x32_bf16 v[86:89], v[194:197], v[218:221], v[86:89]
	v_mfma_f32_16x16x32_bf16 v[82:85], v[194:197], v[226:229], v[82:85]
	v_mfma_f32_16x16x32_bf16 v[78:81], v[202:205], v[218:221], v[78:81]
	v_mfma_f32_16x16x32_bf16 v[74:77], v[202:205], v[226:229], v[74:77]
	v_mfma_f32_16x16x32_bf16 v[70:73], v[210:213], v[218:221], v[70:73]
	v_mfma_f32_16x16x32_bf16 v[66:69], v[210:213], v[226:229], v[66:69]
	v_lshl_add_u64 v[236:237], s[18:19], 0, v[130:131]
	v_readfirstlane_b32 s22, v146
	v_lshl_add_u64 v[238:239], v[236:237], 0, s[8:9]
	s_mov_b32 m0, s22
	s_barrier
	ds_read_b128 v[182:185], v139 offset:16384
	ds_read_b128 v[186:189], v139 offset:17408
	ds_read_b128 v[190:193], v138 offset:16384
	ds_read_b128 v[194:197], v138 offset:17408
	ds_read_b128 v[198:201], v137 offset:16384
	ds_read_b128 v[202:205], v137 offset:17408
	ds_read_b128 v[206:209], v136 offset:16384
	ds_read_b128 v[210:213], v136 offset:17408
	global_load_lds_dwordx4 v[238:239], off
	v_lshl_add_u64 v[238:239], s[18:19], 0, v[132:133]
	v_readfirstlane_b32 s22, v147
	v_lshl_add_u64 v[240:241], v[238:239], 0, s[8:9]
	s_mov_b32 m0, s22
	s_add_u32 s18, s18, 0x100
	global_load_lds_dwordx4 v[240:241], off
	s_barrier
	s_waitcnt lgkmcnt(0)
	s_addc_u32 s19, s19, 0
	s_waitcnt lgkmcnt(0)
	v_mfma_f32_16x16x32_bf16 v[62:65], v[182:185], v[160:163], v[62:65]
	v_mfma_f32_16x16x32_bf16 v[58:61], v[182:185], v[174:177], v[58:61]
	v_mfma_f32_16x16x32_bf16 v[54:57], v[190:193], v[160:163], v[54:57]
	v_mfma_f32_16x16x32_bf16 v[50:53], v[190:193], v[174:177], v[50:53]
	v_mfma_f32_16x16x32_bf16 v[46:49], v[198:201], v[160:163], v[46:49]
	v_mfma_f32_16x16x32_bf16 v[42:45], v[198:201], v[174:177], v[42:45]
	v_mfma_f32_16x16x32_bf16 v[38:41], v[206:209], v[160:163], v[38:41]
	v_mfma_f32_16x16x32_bf16 v[34:37], v[206:209], v[174:177], v[34:37]
	v_mfma_f32_16x16x32_bf16 v[62:65], v[186:189], v[164:167], v[62:65]
	v_mfma_f32_16x16x32_bf16 v[58:61], v[186:189], v[178:181], v[58:61]
	v_mfma_f32_16x16x32_bf16 v[54:57], v[194:197], v[164:167], v[54:57]
	v_mfma_f32_16x16x32_bf16 v[50:53], v[194:197], v[178:181], v[50:53]
	v_mfma_f32_16x16x32_bf16 v[46:49], v[202:205], v[164:167], v[46:49]
	v_mfma_f32_16x16x32_bf16 v[42:45], v[202:205], v[178:181], v[42:45]
	v_mfma_f32_16x16x32_bf16 v[38:41], v[210:213], v[164:167], v[38:41]
	v_mfma_f32_16x16x32_bf16 v[34:37], v[210:213], v[178:181], v[34:37]
	s_barrier
; #define STAGE(P, GP, ktrel) do { const GAS char* _g = (GP) + (ktrel) * (BK * 2); \
;     __builtin_amdgcn_global_load_lds((const GAS unsigned*)(_g + so0), (unsigned*)((char*)(P) + tid_ * 16), 16, 0, 0); \
;     __builtin_amdgcn_global_load_lds((const GAS unsigned*)(_g + so1), (unsigned*)((char*)(P) + tid_ * 16 + 8192), 16, 0, 0); } while (0)
; #define WAIT_V(n) asm volatile("s_waitcnt vmcnt(" #n ")" ::: "memory")
; #define WAIT_L(n) asm volatile("s_waitcnt lgkmcnt(" #n ")" ::: "memory")
; #define BAR __builtin_amdgcn_s_barrier()
; #define SCHED __builtin_amdgcn_sched_barrier(0)
; #define LDA(dst, b, h) for (int m = 0; m < 4; ++m) for (int k = 0; k < 2; ++k) \
;     dst[m][k] = *reinterpret_cast<const bf16x8*>((char*)SA(b, h) + lds_byte(wr * 64 + m * 16 + fr, k * 32 + fq * 8))
; #define LDB(dst, b, h) for (int n = 0; n < 2; ++n) for (int k = 0; k < 2; ++k) \
;     dst[n][k] = *reinterpret_cast<const bf16x8*>((char*)SB(b, h) + lds_byte(wc * 32 + n * 16 + fr, k * 32 + fq * 8))
; #define MMA(ai, bj, At_, Bt_) do { __builtin_amdgcn_s_setprio(1); \
;     for (int m = 0; m < 4; ++m) for (int n = 0; n < 2; ++n) for (int k = 0; k < 2; ++k) \
;       acc[ai][bj][m][n] = __builtin_amdgcn_mfma_f32_16x16x32_bf16(At_[m][k], Bt_[n][k], acc[ai][bj][m][n], 0, 0, 0); \
;     __builtin_amdgcn_s_setprio(0); } while (0)
; template <int K, int LD = K>
; __device__ __forceinline__ void gemm_main(const GAS bf16* A, const GAS bf16* Bt, int brow, int bcol, f32x4 (&acc)[2][2][4][2]) {
;     ...
;     STAGE(SB(0, 1), pB1, 2);
;     WAIT_V(6); BAR; MMA(1, 1, At, B1); BAR;
;     LDB(B0, 1, 0); SCHED; LDA(At, 1, 0); STAGE(SA(0, 1), pA1, 2);
;     WAIT_L(8); BAR; WAIT_L(0); MMA(0, 0, At, B0); BAR; SCHED;
;     LDB(B1, 1, 1); STAGE(SB(1, 0), pB0, 3);
;     BAR; WAIT_L(0); MMA(0, 1, At, B1); BAR;
	v_lshl_add_u64 v[240:241], s[16:17], 0, v[130:131]
	v_readfirstlane_b32 s22, v154
	v_lshl_add_u64 v[160:161], v[240:241], 0, s[8:9]
	s_mov_b32 m0, s22
	v_lshl_add_u64 v[242:243], s[16:17], 0, v[132:133]
	v_readfirstlane_b32 s22, v155
	global_load_lds_dwordx4 v[160:161], off
	v_lshl_add_u64 v[160:161], v[242:243], 0, s[8:9]
	s_mov_b32 m0, s22
	s_add_u32 s16, s16, 0x100
	global_load_lds_dwordx4 v[160:161], off
	s_waitcnt vmcnt(10)
	s_addc_u32 s17, s17, 0
	s_barrier
	v_mfma_f32_16x16x32_bf16 v[30:33], v[182:185], v[214:217], v[30:33]
	v_mfma_f32_16x16x32_bf16 v[26:29], v[182:185], v[222:225], v[26:29]
	v_mfma_f32_16x16x32_bf16 v[22:25], v[190:193], v[214:217], v[22:25]
	v_mfma_f32_16x16x32_bf16 v[18:21], v[190:193], v[222:225], v[18:21]
	v_mfma_f32_16x16x32_bf16 v[14:17], v[198:201], v[214:217], v[14:17]
	v_mfma_f32_16x16x32_bf16 v[10:13], v[198:201], v[222:225], v[10:13]
	v_mfma_f32_16x16x32_bf16 v[6:9], v[206:209], v[214:217], v[6:9]
	v_mfma_f32_16x16x32_bf16 v[2:5], v[206:209], v[222:225], v[2:5]
	v_mfma_f32_16x16x32_bf16 v[30:33], v[186:189], v[218:221], v[30:33]
	v_mfma_f32_16x16x32_bf16 v[26:29], v[186:189], v[226:229], v[26:29]
	v_mfma_f32_16x16x32_bf16 v[22:25], v[194:197], v[218:221], v[22:25]
	v_mfma_f32_16x16x32_bf16 v[18:21], v[194:197], v[226:229], v[18:21]
	v_mfma_f32_16x16x32_bf16 v[14:17], v[202:205], v[218:221], v[14:17]
	v_mfma_f32_16x16x32_bf16 v[10:13], v[202:205], v[226:229], v[10:13]
	v_mfma_f32_16x16x32_bf16 v[6:9], v[210:213], v[218:221], v[6:9]
	v_mfma_f32_16x16x32_bf16 v[2:5], v[210:213], v[226:229], v[2:5]
	s_barrier
	ds_read_b128 v[160:163], v141
	ds_read_b128 v[164:167], v141 offset:1024
	ds_read_b128 v[174:177], v141 offset:2048
	ds_read_b128 v[178:181], v141 offset:3072
	v_readfirstlane_b32 s22, v148
	v_lshl_add_u64 v[168:169], v[168:169], 0, s[8:9]
	s_mov_b32 m0, s22
	v_readfirstlane_b32 s22, v149
	ds_read_b128 v[182:185], v139 offset:32768
	ds_read_b128 v[186:189], v139 offset:33792
	ds_read_b128 v[190:193], v138 offset:32768
	ds_read_b128 v[194:197], v138 offset:33792
	ds_read_b128 v[198:201], v137 offset:32768
	ds_read_b128 v[202:205], v137 offset:33792
	ds_read_b128 v[206:209], v136 offset:32768
	ds_read_b128 v[210:213], v136 offset:33792
	global_load_lds_dwordx4 v[168:169], off
	v_lshl_add_u64 v[168:169], v[230:231], 0, s[8:9]
	s_mov_b32 m0, s22
	s_add_u32 s12, s12, 0x100
	global_load_lds_dwordx4 v[168:169], off
	s_waitcnt lgkmcnt(8)
	s_waitcnt vmcnt(10)
	s_barrier
	s_waitcnt lgkmcnt(0)
	s_addc_u32 s13, s13, 0
	s_waitcnt lgkmcnt(0)
	v_mfma_f32_16x16x32_bf16 v[126:129], v[182:185], v[160:163], v[126:129]
	v_mfma_f32_16x16x32_bf16 v[122:125], v[182:185], v[174:177], v[122:125]
	v_mfma_f32_16x16x32_bf16 v[118:121], v[190:193], v[160:163], v[118:121]
	v_mfma_f32_16x16x32_bf16 v[114:117], v[190:193], v[174:177], v[114:117]
	v_mfma_f32_16x16x32_bf16 v[110:113], v[198:201], v[160:163], v[110:113]
	v_mfma_f32_16x16x32_bf16 v[106:109], v[198:201], v[174:177], v[106:109]
	v_mfma_f32_16x16x32_bf16 v[102:105], v[206:209], v[160:163], v[102:105]
	v_mfma_f32_16x16x32_bf16 v[98:101], v[206:209], v[174:177], v[98:101]
	v_mfma_f32_16x16x32_bf16 v[126:129], v[186:189], v[164:167], v[126:129]
	v_mfma_f32_16x16x32_bf16 v[122:125], v[186:189], v[178:181], v[122:125]
	v_mfma_f32_16x16x32_bf16 v[118:121], v[194:197], v[164:167], v[118:121]
	v_mfma_f32_16x16x32_bf16 v[114:117], v[194:197], v[178:181], v[114:117]
	v_mfma_f32_16x16x32_bf16 v[110:113], v[202:205], v[164:167], v[110:113]
	v_mfma_f32_16x16x32_bf16 v[106:109], v[202:205], v[178:181], v[106:109]
	v_mfma_f32_16x16x32_bf16 v[102:105], v[210:213], v[164:167], v[102:105]
	v_mfma_f32_16x16x32_bf16 v[98:101], v[210:213], v[178:181], v[98:101]
	s_barrier
	v_readfirstlane_b32 s22, v156
	v_lshl_add_u64 v[168:169], v[232:233], 0, s[10:11]
	s_mov_b32 m0, s22
	v_readfirstlane_b32 s22, v157
	ds_read_b128 v[214:217], v140
	ds_read_b128 v[218:221], v140 offset:1024
	ds_read_b128 v[222:225], v140 offset:2048
	ds_read_b128 v[226:229], v140 offset:3072
	global_load_lds_dwordx4 v[168:169], off
	v_lshl_add_u64 v[168:169], v[234:235], 0, s[10:11]
	s_mov_b32 m0, s22
	s_nop 0
	global_load_lds_dwordx4 v[168:169], off
	s_waitcnt vmcnt(10)
	s_barrier
	s_waitcnt lgkmcnt(0)
	v_mfma_f32_16x16x32_bf16 v[94:97], v[182:185], v[214:217], v[94:97]
	v_mfma_f32_16x16x32_bf16 v[90:93], v[182:185], v[222:225], v[90:93]
	v_mfma_f32_16x16x32_bf16 v[86:89], v[190:193], v[214:217], v[86:89]
	v_mfma_f32_16x16x32_bf16 v[82:85], v[190:193], v[222:225], v[82:85]
	v_mfma_f32_16x16x32_bf16 v[78:81], v[198:201], v[214:217], v[78:81]
	v_mfma_f32_16x16x32_bf16 v[74:77], v[198:201], v[222:225], v[74:77]
	v_mfma_f32_16x16x32_bf16 v[70:73], v[206:209], v[214:217], v[70:73]
	v_mfma_f32_16x16x32_bf16 v[66:69], v[206:209], v[222:225], v[66:69]
	v_mfma_f32_16x16x32_bf16 v[94:97], v[186:189], v[218:221], v[94:97]
	v_mfma_f32_16x16x32_bf16 v[90:93], v[186:189], v[226:229], v[90:93]
	v_mfma_f32_16x16x32_bf16 v[86:89], v[194:197], v[218:221], v[86:89]
	v_mfma_f32_16x16x32_bf16 v[82:85], v[194:197], v[226:229], v[82:85]
	v_mfma_f32_16x16x32_bf16 v[78:81], v[202:205], v[218:221], v[78:81]
	v_mfma_f32_16x16x32_bf16 v[74:77], v[202:205], v[226:229], v[74:77]
	v_mfma_f32_16x16x32_bf16 v[70:73], v[210:213], v[218:221], v[70:73]
	v_mfma_f32_16x16x32_bf16 v[66:69], v[210:213], v[226:229], v[66:69]
	v_readfirstlane_b32 s22, v150
	v_lshl_add_u64 v[168:169], v[236:237], 0, s[10:11]
	s_mov_b32 m0, s22
	v_readfirstlane_b32 s22, v151
	s_barrier
; #define STAGE(P, GP, ktrel) do { const GAS char* _g = (GP) + (ktrel) * (BK * 2); \
;     __builtin_amdgcn_global_load_lds((const GAS unsigned*)(_g + so0), (unsigned*)((char*)(P) + tid_ * 16), 16, 0, 0); \
;     __builtin_amdgcn_global_load_lds((const GAS unsigned*)(_g + so1), (unsigned*)((char*)(P) + tid_ * 16 + 8192), 16, 0, 0); } while (0)
; #define WAIT_V(n) asm volatile("s_waitcnt vmcnt(" #n ")" ::: "memory")
; #define WAIT_L(n) asm volatile("s_waitcnt lgkmcnt(" #n ")" ::: "memory")
; #define BAR __builtin_amdgcn_s_barrier()
; #define SCHED __builtin_amdgcn_sched_barrier(0)
; #define LDA(dst, b, h) for (int m = 0; m < 4; ++m) for (int k = 0; k < 2; ++k) \
;     dst[m][k] = *reinterpret_cast<const bf16x8*>((char*)SA(b, h) + lds_byte(wr * 64 + m * 16 + fr, k * 32 + fq * 8))
; #define LDB(dst, b, h) for (int n = 0; n < 2; ++n) for (int k = 0; k < 2; ++k) \
;     dst[n][k] = *reinterpret_cast<const bf16x8*>((char*)SB(b, h) + lds_byte(wc * 32 + n * 16 + fr, k * 32 + fq * 8))
; #define MMA(ai, bj, At_, Bt_) do { __builtin_amdgcn_s_setprio(1); \
;     for (int m = 0; m < 4; ++m) for (int n = 0; n < 2; ++n) for (int k = 0; k < 2; ++k) \
;       acc[ai][bj][m][n] = __builtin_amdgcn_mfma_f32_16x16x32_bf16(At_[m][k], Bt_[n][k], acc[ai][bj][m][n], 0, 0, 0); \
;     __builtin_amdgcn_s_setprio(0); } while (0)
; template <int K, int LD = K>
; __device__ __forceinline__ void gemm_main(const GAS bf16* A, const GAS bf16* Bt, int brow, int bcol, f32x4 (&acc)[2][2][4][2]) {
;     ...
;     LDA(At, 1, 1); STAGE(SA(1, 0), pA0, 3);
;     BAR; WAIT_L(0); MMA(1, 0, At, B0); BAR; SCHED;
;     STAGE(SB(1, 1), pB1, 3);
;     WAIT_V(6); BAR; MMA(1, 1, At, B1); BAR;
;     pA0 += 4 * BK; pA1 += 4 * BK; pB0 += 4 * BK; pB1 += 4 * BK;
;     asm volatile("" : "+s"(pA0), "+s"(pA1), "+s"(pB0), "+s"(pB1));
;   }
;   { LDB(B0, 0, 0); LDA(At, 0, 0); STAGE(SA(1, 1), pA1, 1);
;     BAR; WAIT_L(0); MMA(0, 0, At, B0); BAR;
;     LDB(B1, 0, 1); BAR; WAIT_L(0); MMA(0, 1, At, B1); BAR;
	ds_read_b128 v[182:185], v139 offset:49152
	ds_read_b128 v[186:189], v139 offset:50176
	ds_read_b128 v[190:193], v138 offset:49152
	ds_read_b128 v[194:197], v138 offset:50176
	ds_read_b128 v[198:201], v137 offset:49152
	ds_read_b128 v[202:205], v137 offset:50176
	ds_read_b128 v[206:209], v136 offset:49152
	ds_read_b128 v[210:213], v136 offset:50176
	global_load_lds_dwordx4 v[168:169], off
	v_lshl_add_u64 v[168:169], v[238:239], 0, s[10:11]
	s_mov_b32 m0, s22
	s_nop 0
	global_load_lds_dwordx4 v[168:169], off
	s_barrier
	s_waitcnt lgkmcnt(0)
	v_mfma_f32_16x16x32_bf16 v[62:65], v[182:185], v[160:163], v[62:65]
	v_mfma_f32_16x16x32_bf16 v[58:61], v[182:185], v[174:177], v[58:61]
	v_mfma_f32_16x16x32_bf16 v[54:57], v[190:193], v[160:163], v[54:57]
	v_mfma_f32_16x16x32_bf16 v[50:53], v[190:193], v[174:177], v[50:53]
	v_mfma_f32_16x16x32_bf16 v[46:49], v[198:201], v[160:163], v[46:49]
	v_mfma_f32_16x16x32_bf16 v[42:45], v[198:201], v[174:177], v[42:45]
	v_mfma_f32_16x16x32_bf16 v[38:41], v[206:209], v[160:163], v[38:41]
	v_mfma_f32_16x16x32_bf16 v[34:37], v[206:209], v[174:177], v[34:37]
	v_mfma_f32_16x16x32_bf16 v[62:65], v[186:189], v[164:167], v[62:65]
	v_mfma_f32_16x16x32_bf16 v[58:61], v[186:189], v[178:181], v[58:61]
	v_mfma_f32_16x16x32_bf16 v[54:57], v[194:197], v[164:167], v[54:57]
	v_mfma_f32_16x16x32_bf16 v[50:53], v[194:197], v[178:181], v[50:53]
	v_mfma_f32_16x16x32_bf16 v[46:49], v[202:205], v[164:167], v[46:49]
	v_mfma_f32_16x16x32_bf16 v[42:45], v[202:205], v[178:181], v[42:45]
	v_mfma_f32_16x16x32_bf16 v[38:41], v[210:213], v[164:167], v[38:41]
	v_mfma_f32_16x16x32_bf16 v[34:37], v[210:213], v[178:181], v[34:37]
	s_barrier
	v_readfirstlane_b32 s22, v158
	v_lshl_add_u64 v[160:161], v[240:241], 0, s[10:11]
	s_mov_b32 m0, s22
	v_readfirstlane_b32 s22, v159
	global_load_lds_dwordx4 v[160:161], off
	v_lshl_add_u64 v[160:161], v[242:243], 0, s[10:11]
	s_mov_b32 m0, s22
	s_nop 0
	global_load_lds_dwordx4 v[160:161], off
	s_waitcnt vmcnt(10)
	s_barrier
	v_mfma_f32_16x16x32_bf16 v[30:33], v[182:185], v[214:217], v[30:33]
	v_mfma_f32_16x16x32_bf16 v[26:29], v[182:185], v[222:225], v[26:29]
	v_mfma_f32_16x16x32_bf16 v[22:25], v[190:193], v[214:217], v[22:25]
	v_mfma_f32_16x16x32_bf16 v[18:21], v[190:193], v[222:225], v[18:21]
	v_mfma_f32_16x16x32_bf16 v[14:17], v[198:201], v[214:217], v[14:17]
	v_mfma_f32_16x16x32_bf16 v[10:13], v[198:201], v[222:225], v[10:13]
	v_mfma_f32_16x16x32_bf16 v[6:9], v[206:209], v[214:217], v[6:9]
	v_mfma_f32_16x16x32_bf16 v[2:5], v[206:209], v[222:225], v[2:5]
	v_mfma_f32_16x16x32_bf16 v[30:33], v[186:189], v[218:221], v[30:33]
	v_mfma_f32_16x16x32_bf16 v[26:29], v[186:189], v[226:229], v[26:29]
	v_mfma_f32_16x16x32_bf16 v[22:25], v[194:197], v[218:221], v[22:25]
	v_mfma_f32_16x16x32_bf16 v[18:21], v[194:197], v[226:229], v[18:21]
	v_mfma_f32_16x16x32_bf16 v[14:17], v[202:205], v[218:221], v[14:17]
	v_mfma_f32_16x16x32_bf16 v[10:13], v[202:205], v[226:229], v[10:13]
	v_mfma_f32_16x16x32_bf16 v[6:9], v[210:213], v[218:221], v[6:9]
	v_mfma_f32_16x16x32_bf16 v[2:5], v[210:213], v[226:229], v[2:5]
	s_add_i32 s15, s15, 2
	s_cmp_lt_u32 s15, 12
	s_barrier
	s_cbranch_scc1 .LBB0_884
	v_lshl_add_u64 v[198:199], s[12:13], 0, v[130:131]
	v_readfirstlane_b32 s15, v144
	v_lshl_add_u64 v[198:199], v[198:199], 0, s[6:7]
	s_mov_b32 m0, s15
	v_lshl_add_u64 v[132:133], s[12:13], 0, v[132:133]
	v_readfirstlane_b32 s12, v143
	ds_read_b128 v[146:149], v145
	ds_read_b128 v[150:153], v145 offset:1024
	ds_read_b128 v[154:157], v145 offset:2048
	ds_read_b128 v[158:161], v145 offset:3072
	ds_read_b128 v[162:165], v139
	ds_read_b128 v[166:169], v139 offset:1024
	ds_read_b128 v[174:177], v138
	ds_read_b128 v[178:181], v138 offset:1024
	ds_read_b128 v[182:185], v137
	ds_read_b128 v[186:189], v137 offset:1024
	ds_read_b128 v[190:193], v136
	ds_read_b128 v[194:197], v136 offset:1024
	global_load_lds_dwordx4 v[198:199], off
	v_lshl_add_u64 v[132:133], v[132:133], 0, s[6:7]
	s_mov_b32 m0, s12
	s_nop 0
	global_load_lds_dwordx4 v[132:133], off
	s_waitcnt vmcnt(10)
	s_barrier
	s_waitcnt lgkmcnt(0)
	v_mfma_f32_16x16x32_bf16 v[126:129], v[162:165], v[146:149], v[126:129]
	v_mfma_f32_16x16x32_bf16 v[122:125], v[162:165], v[154:157], v[122:125]
	v_mfma_f32_16x16x32_bf16 v[110:113], v[182:185], v[146:149], v[110:113]
	v_mfma_f32_16x16x32_bf16 v[106:109], v[182:185], v[154:157], v[106:109]
	v_mfma_f32_16x16x32_bf16 v[126:129], v[166:169], v[150:153], v[126:129]
	v_mfma_f32_16x16x32_bf16 v[122:125], v[166:169], v[158:161], v[122:125]
	v_mfma_f32_16x16x32_bf16 v[118:121], v[174:177], v[146:149], v[118:121]
	v_mfma_f32_16x16x32_bf16 v[114:117], v[174:177], v[154:157], v[114:117]
	v_mfma_f32_16x16x32_bf16 v[110:113], v[186:189], v[150:153], v[110:113]
	v_mfma_f32_16x16x32_bf16 v[106:109], v[186:189], v[158:161], v[106:109]
	v_mfma_f32_16x16x32_bf16 v[102:105], v[190:193], v[146:149], v[102:105]
	v_mfma_f32_16x16x32_bf16 v[98:101], v[190:193], v[154:157], v[98:101]
	v_mfma_f32_16x16x32_bf16 v[198:201], v[178:181], v[150:153], v[118:121]
	v_mfma_f32_16x16x32_bf16 v[202:205], v[178:181], v[158:161], v[114:117]
	v_mfma_f32_16x16x32_bf16 v[206:209], v[194:197], v[150:153], v[102:105]
	v_mfma_f32_16x16x32_bf16 v[210:213], v[194:197], v[158:161], v[98:101]
	s_barrier
	s_nop 1
	ds_read_b128 v[98:101], v142
	ds_read_b128 v[102:105], v142 offset:1024
	ds_read_b128 v[114:117], v142 offset:2048
	ds_read_b128 v[118:121], v142 offset:3072
	s_waitcnt vmcnt(8)
	s_barrier
; #define WAIT_V(n) asm volatile("s_waitcnt vmcnt(" #n ")" ::: "memory")
; #define WAIT_L(n) asm volatile("s_waitcnt lgkmcnt(" #n ")" ::: "memory")
; #define BAR __builtin_amdgcn_s_barrier()
; #define LDA(dst, b, h) for (int m = 0; m < 4; ++m) for (int k = 0; k < 2; ++k) \
;     dst[m][k] = *reinterpret_cast<const bf16x8*>((char*)SA(b, h) + lds_byte(wr * 64 + m * 16 + fr, k * 32 + fq * 8))
; #define LDB(dst, b, h) for (int n = 0; n < 2; ++n) for (int k = 0; k < 2; ++k) \
;     dst[n][k] = *reinterpret_cast<const bf16x8*>((char*)SB(b, h) + lds_byte(wc * 32 + n * 16 + fr, k * 32 + fq * 8))
; #define MMA(ai, bj, At_, Bt_) do { __builtin_amdgcn_s_setprio(1); \
;     for (int m = 0; m < 4; ++m) for (int n = 0; n < 2; ++n) for (int k = 0; k < 2; ++k) \
;       acc[ai][bj][m][n] = __builtin_amdgcn_mfma_f32_16x16x32_bf16(At_[m][k], Bt_[n][k], acc[ai][bj][m][n], 0, 0, 0); \
;     __builtin_amdgcn_s_setprio(0); } while (0)
; template <int K, int LD = K>
; __device__ __forceinline__ void gemm_main(const GAS bf16* A, const GAS bf16* Bt, int brow, int bcol, f32x4 (&acc)[2][2][4][2]) {
;     ...
;     LDB(B1, 0, 1); BAR; WAIT_L(0); MMA(0, 1, At, B1); BAR;
;     LDA(At, 0, 1); WAIT_V(4); BAR; WAIT_L(0); MMA(1, 0, At, B0); MMA(1, 1, At, B1); BAR; }
	s_waitcnt lgkmcnt(0)
	v_mfma_f32_16x16x32_bf16 v[94:97], v[162:165], v[98:101], v[94:97]
	v_mfma_f32_16x16x32_bf16 v[90:93], v[162:165], v[114:117], v[90:93]
	v_mfma_f32_16x16x32_bf16 v[78:81], v[182:185], v[98:101], v[78:81]
	v_mfma_f32_16x16x32_bf16 v[74:77], v[182:185], v[114:117], v[74:77]
	v_mfma_f32_16x16x32_bf16 v[94:97], v[166:169], v[102:105], v[94:97]
	v_mfma_f32_16x16x32_bf16 v[90:93], v[166:169], v[118:121], v[90:93]
	v_mfma_f32_16x16x32_bf16 v[86:89], v[174:177], v[98:101], v[86:89]
	v_mfma_f32_16x16x32_bf16 v[82:85], v[174:177], v[114:117], v[82:85]
	v_mfma_f32_16x16x32_bf16 v[78:81], v[186:189], v[102:105], v[78:81]
	v_mfma_f32_16x16x32_bf16 v[74:77], v[186:189], v[118:121], v[74:77]
	v_mfma_f32_16x16x32_bf16 v[70:73], v[190:193], v[98:101], v[70:73]
	v_mfma_f32_16x16x32_bf16 v[66:69], v[190:193], v[114:117], v[66:69]
	v_mfma_f32_16x16x32_bf16 v[142:145], v[178:181], v[102:105], v[86:89]
	v_mfma_f32_16x16x32_bf16 v[162:165], v[178:181], v[118:121], v[82:85]
	v_mfma_f32_16x16x32_bf16 v[166:169], v[194:197], v[102:105], v[70:73]
	v_mfma_f32_16x16x32_bf16 v[174:177], v[194:197], v[118:121], v[66:69]
	s_barrier
	s_nop 1
	ds_read_b128 v[66:69], v139 offset:16384
	ds_read_b128 v[70:73], v139 offset:17408
	ds_read_b128 v[82:85], v138 offset:16384
	ds_read_b128 v[86:89], v138 offset:17408
	ds_read_b128 v[178:181], v137 offset:16384
	ds_read_b128 v[182:185], v137 offset:17408
	ds_read_b128 v[186:189], v136 offset:16384
	ds_read_b128 v[190:193], v136 offset:17408
	s_waitcnt vmcnt(4)
	s_barrier
	s_waitcnt lgkmcnt(0)
	v_mfma_f32_16x16x32_bf16 v[62:65], v[66:69], v[146:149], v[62:65]
	v_mfma_f32_16x16x32_bf16 v[58:61], v[66:69], v[154:157], v[58:61]
	v_mfma_f32_16x16x32_bf16 v[46:49], v[178:181], v[146:149], v[46:49]
	v_mfma_f32_16x16x32_bf16 v[38:41], v[186:189], v[146:149], v[38:41]
	v_mfma_f32_16x16x32_bf16 v[62:65], v[70:73], v[150:153], v[62:65]
	v_mfma_f32_16x16x32_bf16 v[58:61], v[70:73], v[158:161], v[58:61]
	v_mfma_f32_16x16x32_bf16 v[54:57], v[82:85], v[146:149], v[54:57]
	v_mfma_f32_16x16x32_bf16 v[50:53], v[82:85], v[154:157], v[50:53]
	v_mfma_f32_16x16x32_bf16 v[46:49], v[182:185], v[150:153], v[46:49]
	v_mfma_f32_16x16x32_bf16 v[42:45], v[178:181], v[154:157], v[42:45]
	v_mfma_f32_16x16x32_bf16 v[38:41], v[190:193], v[150:153], v[38:41]
	v_mfma_f32_16x16x32_bf16 v[34:37], v[186:189], v[154:157], v[34:37]
	v_mfma_f32_16x16x32_bf16 v[194:197], v[86:89], v[150:153], v[54:57]
	v_mfma_f32_16x16x32_bf16 v[214:217], v[86:89], v[158:161], v[50:53]
	v_mfma_f32_16x16x32_bf16 v[218:221], v[182:185], v[158:161], v[42:45]
	v_mfma_f32_16x16x32_bf16 v[146:149], v[190:193], v[158:161], v[34:37]
	v_mfma_f32_16x16x32_bf16 v[30:33], v[66:69], v[98:101], v[30:33]
	v_mfma_f32_16x16x32_bf16 v[26:29], v[66:69], v[114:117], v[26:29]
	v_mfma_f32_16x16x32_bf16 v[14:17], v[178:181], v[98:101], v[14:17]
	v_mfma_f32_16x16x32_bf16 v[6:9], v[186:189], v[98:101], v[6:9]
	v_mfma_f32_16x16x32_bf16 v[30:33], v[70:73], v[102:105], v[30:33]
	v_mfma_f32_16x16x32_bf16 v[26:29], v[70:73], v[118:121], v[26:29]
	v_mfma_f32_16x16x32_bf16 v[22:25], v[82:85], v[98:101], v[22:25]
	v_mfma_f32_16x16x32_bf16 v[18:21], v[82:85], v[114:117], v[18:21]
	v_mfma_f32_16x16x32_bf16 v[14:17], v[182:185], v[102:105], v[14:17]
	v_mfma_f32_16x16x32_bf16 v[10:13], v[178:181], v[114:117], v[10:13]
	v_mfma_f32_16x16x32_bf16 v[6:9], v[190:193], v[102:105], v[6:9]
	v_mfma_f32_16x16x32_bf16 v[2:5], v[186:189], v[114:117], v[2:5]
	v_mfma_f32_16x16x32_bf16 v[150:153], v[86:89], v[102:105], v[22:25]
	v_mfma_f32_16x16x32_bf16 v[154:157], v[86:89], v[118:121], v[18:21]
	v_mfma_f32_16x16x32_bf16 v[158:161], v[182:185], v[118:121], v[10:13]
	v_mfma_f32_16x16x32_bf16 v[178:181], v[190:193], v[118:121], v[2:5]
	s_barrier
	s_nop 1
	ds_read_b128 v[2:5], v141
	ds_read_b128 v[10:13], v141 offset:1024
	ds_read_b128 v[182:185], v141 offset:2048
	ds_read_b128 v[186:189], v141 offset:3072
	ds_read_b128 v[18:21], v139 offset:32768
	ds_read_b128 v[22:25], v139 offset:33792
	ds_read_b128 v[34:37], v138 offset:32768
	ds_read_b128 v[42:45], v138 offset:33792
	ds_read_b128 v[50:53], v137 offset:32768
	ds_read_b128 v[54:57], v137 offset:33792
	ds_read_b128 v[190:193], v136 offset:32768
	ds_read_b128 v[222:225], v136 offset:33792
	s_waitcnt vmcnt(2)
	s_barrier
; #define WAIT_V(n) asm volatile("s_waitcnt vmcnt(" #n ")" ::: "memory")
; #define WAIT_L(n) asm volatile("s_waitcnt lgkmcnt(" #n ")" ::: "memory")
; #define BAR __builtin_amdgcn_s_barrier()
; #define LDA(dst, b, h) for (int m = 0; m < 4; ++m) for (int k = 0; k < 2; ++k) \
;     dst[m][k] = *reinterpret_cast<const bf16x8*>((char*)SA(b, h) + lds_byte(wr * 64 + m * 16 + fr, k * 32 + fq * 8))
; #define LDB(dst, b, h) for (int n = 0; n < 2; ++n) for (int k = 0; k < 2; ++k) \
;     dst[n][k] = *reinterpret_cast<const bf16x8*>((char*)SB(b, h) + lds_byte(wc * 32 + n * 16 + fr, k * 32 + fq * 8))
; #define MMA(ai, bj, At_, Bt_) do { __builtin_amdgcn_s_setprio(1); \
;     for (int m = 0; m < 4; ++m) for (int n = 0; n < 2; ++n) for (int k = 0; k < 2; ++k) \
;       acc[ai][bj][m][n] = __builtin_amdgcn_mfma_f32_16x16x32_bf16(At_[m][k], Bt_[n][k], acc[ai][bj][m][n], 0, 0, 0); \
;     __builtin_amdgcn_s_setprio(0); } while (0)
; template <int K, int LD = K>
; __device__ __forceinline__ void gemm_main(const GAS bf16* A, const GAS bf16* Bt, int brow, int bcol, f32x4 (&acc)[2][2][4][2]) {
;     ...
;   { LDB(B0, 1, 0); LDA(At, 1, 0); WAIT_V(2); BAR; WAIT_L(0); MMA(0, 0, At, B0); BAR;
;     LDB(B1, 1, 1); WAIT_V(0); BAR; WAIT_L(0); MMA(0, 1, At, B1); BAR;
;     LDA(At, 1, 1); BAR; WAIT_L(0); MMA(1, 0, At, B0); MMA(1, 1, At, B1); BAR; }
;   if (wr == 0) BAR;
	s_waitcnt lgkmcnt(0)
	v_mfma_f32_16x16x32_bf16 v[66:69], v[18:21], v[2:5], v[126:129]
	v_mfma_f32_16x16x32_bf16 v[118:121], v[22:25], v[10:13], v[66:69]
	v_mfma_f32_16x16x32_bf16 v[66:69], v[18:21], v[182:185], v[122:125]
	v_mfma_f32_16x16x32_bf16 v[114:117], v[22:25], v[186:189], v[66:69]
	v_mfma_f32_16x16x32_bf16 v[66:69], v[34:37], v[2:5], v[198:201]
	v_mfma_f32_16x16x32_bf16 v[102:105], v[42:45], v[10:13], v[66:69]
	v_mfma_f32_16x16x32_bf16 v[66:69], v[34:37], v[182:185], v[202:205]
	v_mfma_f32_16x16x32_bf16 v[98:101], v[42:45], v[186:189], v[66:69]
	v_mfma_f32_16x16x32_bf16 v[66:69], v[50:53], v[2:5], v[110:113]
	v_mfma_f32_16x16x32_bf16 v[86:89], v[54:57], v[10:13], v[66:69]
	v_mfma_f32_16x16x32_bf16 v[66:69], v[50:53], v[182:185], v[106:109]
	v_mfma_f32_16x16x32_bf16 v[82:85], v[54:57], v[186:189], v[66:69]
	v_mfma_f32_16x16x32_bf16 v[66:69], v[190:193], v[2:5], v[206:209]
	v_mfma_f32_16x16x32_bf16 v[70:73], v[222:225], v[10:13], v[66:69]
	v_mfma_f32_16x16x32_bf16 v[66:69], v[190:193], v[182:185], v[210:213]
	v_mfma_f32_16x16x32_bf16 v[66:69], v[222:225], v[186:189], v[66:69]
	s_barrier
	ds_read_b128 v[198:201], v140
	ds_read_b128 v[202:205], v140 offset:1024
	ds_read_b128 v[206:209], v140 offset:2048
	ds_read_b128 v[210:213], v140 offset:3072
	s_waitcnt vmcnt(0)
	s_barrier
	s_waitcnt lgkmcnt(0)
	v_mfma_f32_16x16x32_bf16 v[94:97], v[18:21], v[198:201], v[94:97]
	v_mfma_f32_16x16x32_bf16 v[18:21], v[18:21], v[206:209], v[90:93]
	v_mfma_f32_16x16x32_bf16 v[122:125], v[22:25], v[210:213], v[18:21]
	v_mfma_f32_16x16x32_bf16 v[18:21], v[34:37], v[198:201], v[142:145]
	v_mfma_f32_16x16x32_bf16 v[110:113], v[42:45], v[202:205], v[18:21]
	v_mfma_f32_16x16x32_bf16 v[18:21], v[34:37], v[206:209], v[162:165]
	v_mfma_f32_16x16x32_bf16 v[106:109], v[42:45], v[210:213], v[18:21]
	v_mfma_f32_16x16x32_bf16 v[18:21], v[50:53], v[198:201], v[78:81]
	v_mfma_f32_16x16x32_bf16 v[126:129], v[22:25], v[202:205], v[94:97]
	v_mfma_f32_16x16x32_bf16 v[94:97], v[54:57], v[202:205], v[18:21]
	v_mfma_f32_16x16x32_bf16 v[18:21], v[50:53], v[206:209], v[74:77]
	v_mfma_f32_16x16x32_bf16 v[90:93], v[54:57], v[210:213], v[18:21]
	v_mfma_f32_16x16x32_bf16 v[18:21], v[190:193], v[198:201], v[166:169]
	v_mfma_f32_16x16x32_bf16 v[78:81], v[222:225], v[202:205], v[18:21]
	v_mfma_f32_16x16x32_bf16 v[18:21], v[190:193], v[206:209], v[174:177]
	v_mfma_f32_16x16x32_bf16 v[74:77], v[222:225], v[210:213], v[18:21]
	s_barrier
	ds_read_b128 v[140:143], v139 offset:49152
	ds_read_b128 v[162:165], v139 offset:50176
	ds_read_b128 v[166:169], v138 offset:49152
	ds_read_b128 v[174:177], v138 offset:50176
	ds_read_b128 v[190:193], v137 offset:49152
	ds_read_b128 v[222:225], v137 offset:50176
	ds_read_b128 v[226:229], v136 offset:49152
	ds_read_b128 v[136:139], v136 offset:50176
	s_barrier
	s_waitcnt lgkmcnt(0)
	v_mfma_f32_16x16x32_bf16 v[18:21], v[140:143], v[2:5], v[62:65]
	v_mfma_f32_16x16x32_bf16 v[54:57], v[162:165], v[10:13], v[18:21]
	v_mfma_f32_16x16x32_bf16 v[18:21], v[140:143], v[182:185], v[58:61]
	v_mfma_f32_16x16x32_bf16 v[50:53], v[162:165], v[186:189], v[18:21]
	v_mfma_f32_16x16x32_bf16 v[18:21], v[166:169], v[2:5], v[194:197]
	v_mfma_f32_16x16x32_bf16 v[42:45], v[174:177], v[10:13], v[18:21]
	v_mfma_f32_16x16x32_bf16 v[18:21], v[166:169], v[182:185], v[214:217]
	v_mfma_f32_16x16x32_bf16 v[34:37], v[174:177], v[186:189], v[18:21]
	v_mfma_f32_16x16x32_bf16 v[18:21], v[190:193], v[2:5], v[46:49]
	v_mfma_f32_16x16x32_bf16 v[2:5], v[226:229], v[2:5], v[38:41]
	v_mfma_f32_16x16x32_bf16 v[22:25], v[222:225], v[10:13], v[18:21]
	v_mfma_f32_16x16x32_bf16 v[18:21], v[190:193], v[182:185], v[218:221]
	v_mfma_f32_16x16x32_bf16 v[10:13], v[136:139], v[10:13], v[2:5]
	v_mfma_f32_16x16x32_bf16 v[2:5], v[226:229], v[182:185], v[146:149]
	v_mfma_f32_16x16x32_bf16 v[18:21], v[222:225], v[186:189], v[18:21]
	v_mfma_f32_16x16x32_bf16 v[2:5], v[136:139], v[186:189], v[2:5]
	v_mfma_f32_16x16x32_bf16 v[26:29], v[140:143], v[206:209], v[26:29]
	v_mfma_f32_16x16x32_bf16 v[30:33], v[140:143], v[198:201], v[30:33]
	v_mfma_f32_16x16x32_bf16 v[58:61], v[162:165], v[210:213], v[26:29]
	v_mfma_f32_16x16x32_bf16 v[26:29], v[166:169], v[198:201], v[150:153]
	v_mfma_f32_16x16x32_bf16 v[14:17], v[190:193], v[198:201], v[14:17]
	v_mfma_f32_16x16x32_bf16 v[62:65], v[162:165], v[202:205], v[30:33]
	v_mfma_f32_16x16x32_bf16 v[46:49], v[174:177], v[202:205], v[26:29]
	v_mfma_f32_16x16x32_bf16 v[26:29], v[166:169], v[206:209], v[154:157]
	v_mfma_f32_16x16x32_bf16 v[30:33], v[222:225], v[202:205], v[14:17]
	v_mfma_f32_16x16x32_bf16 v[14:17], v[190:193], v[206:209], v[158:161]
	v_mfma_f32_16x16x32_bf16 v[6:9], v[226:229], v[198:201], v[6:9]
	v_mfma_f32_16x16x32_bf16 v[38:41], v[174:177], v[210:213], v[26:29]
	v_mfma_f32_16x16x32_bf16 v[26:29], v[222:225], v[210:213], v[14:17]
	v_mfma_f32_16x16x32_bf16 v[14:17], v[136:139], v[202:205], v[6:9]
	v_mfma_f32_16x16x32_bf16 v[6:9], v[226:229], v[206:209], v[178:181]
	v_mfma_f32_16x16x32_bf16 v[6:9], v[136:139], v[210:213], v[6:9]
	v_cmp_gt_u32_e32 vcc, s34, v135
	s_barrier
	s_and_saveexec_b64 s[12:13], vcc
	s_cbranch_execz .LBB0_887
	s_barrier

; #define PARAMS_LOCAL KParams PP_ = kparams(); const __attribute__((address_space(4))) Params& P = *PP_;
; __device__ __forceinline__ unsigned xb_add(unsigned* p, unsigned v) { return __hip_atomic_fetch_add(p, v, __ATOMIC_RELAXED, __HIP_MEMORY_SCOPE_AGENT); }
; __device__ __forceinline__ void xcd_barrier() {
;   asm volatile("s_waitcnt vmcnt(0)" ::: "memory");
;   __syncthreads();
;   if (threadIdx.x == 0) {
;     PARAMS_LOCAL
;     unsigned* bar = (unsigned*)(P.ws + OFF_BAR);
;     const unsigned* st = (const unsigned*)(smem_raw + LDS_XB);
;     const unsigned bx = st[0], nloc = st[1], nx = st[2];
;     __builtin_amdgcn_s_waitcnt(0);
;     const unsigned old = xb_add(&bar[XB_XSUB(bx)], 1u);
.LBB0_1057:
	s_or_b64 exec, exec, s[16:17]
.LBB0_1058:
	s_waitcnt vmcnt(0)
	s_barrier
	s_and_saveexec_b64 s[4:5], s[94:95]
	s_cbranch_execz .LBB0_1095
	s_mov_b64 s[6:7], s[0:1]
	s_load_dwordx2 s[6:7], s[6:7], 0xb0
	s_mov_b32 s10, 0x20800
	s_mov_b64 s[8:9], exec
	s_mov_b32 s13, 0
	s_waitcnt lgkmcnt(0)
	s_add_u32 s3, s6, 0xfc00000
	s_addc_u32 s26, s7, 0
	s_addk_i32 s10, 0x100
	v_mov_b32_e32 v1, s10
	ds_read_b96 v[2:4], v1
	v_mbcnt_lo_u32_b32 v1, s8, 0
	v_mbcnt_hi_u32_b32 v1, s9, v1
	v_cmp_eq_u32_e32 vcc, 0, v1
	s_waitcnt vmcnt(0) expcnt(0) lgkmcnt(0)
	v_readfirstlane_b32 s10, v2
	s_lshl_b32 s27, s10, 6
	s_and_saveexec_b64 s[10:11], vcc
	s_cbranch_execz .LBB0_1061
	s_add_i32 s12, s27, 0x500
	s_lshl_b64 s[12:13], s[12:13], 2
	s_add_u32 s12, s3, s12
	s_addc_u32 s13, s26, s13
	s_bcnt1_i32_b64 s8, s[8:9]
	v_mov_b32_e32 v2, 0
	v_mov_b32_e32 v5, s8
	global_atomic_add v2, v2, v5, s[12:13] sc0

; #define STAGE(P, GP, ktrel) do { const GAS char* _g = (GP) + (ktrel) * (BK * 2); \
;     __builtin_amdgcn_global_load_lds((const GAS unsigned*)(_g + so0), (unsigned*)((char*)(P) + tid_ * 16), 16, 0, 0); \
;     __builtin_amdgcn_global_load_lds((const GAS unsigned*)(_g + so1), (unsigned*)((char*)(P) + tid_ * 16 + 8192), 16, 0, 0); } while (0)
; #define WAIT_L(n) asm volatile("s_waitcnt lgkmcnt(" #n ")" ::: "memory")
; #define BAR __builtin_amdgcn_s_barrier()
; #define SCHED __builtin_amdgcn_sched_barrier(0)
; #define LDA(dst, b, h) for (int m = 0; m < 4; ++m) for (int k = 0; k < 2; ++k) \
;     dst[m][k] = *reinterpret_cast<const bf16x8*>((char*)SA(b, h) + lds_byte(wr * 64 + m * 16 + fr, k * 32 + fq * 8))
; #define LDB(dst, b, h) for (int n = 0; n < 2; ++n) for (int k = 0; k < 2; ++k) \
;     dst[n][k] = *reinterpret_cast<const bf16x8*>((char*)SB(b, h) + lds_byte(wc * 32 + n * 16 + fr, k * 32 + fq * 8))
; #define MMA(ai, bj, At_, Bt_) do { __builtin_amdgcn_s_setprio(1); \
;     for (int m = 0; m < 4; ++m) for (int n = 0; n < 2; ++n) for (int k = 0; k < 2; ++k) \
;       acc[ai][bj][m][n] = __builtin_amdgcn_mfma_f32_16x16x32_bf16(At_[m][k], Bt_[n][k], acc[ai][bj][m][n], 0, 0, 0); \
;     __builtin_amdgcn_s_setprio(0); } while (0)
; template <int K, int LD = K>
; __device__ __forceinline__ void gemm_main(const GAS bf16* A, const GAS bf16* Bt, int brow, int bcol, f32x4 (&acc)[2][2][4][2]) {
;     ...
;     LDB(B0, 0, 0); SCHED; LDA(At, 0, 0); STAGE(SA(1, 1), pA1, 1);
;     WAIT_L(8); BAR; WAIT_L(0); MMA(0, 0, At, B0); BAR; SCHED;
;     LDB(B1, 0, 1); STAGE(SB(0, 0), pB0, 2);
;     BAR; WAIT_L(0); MMA(0, 1, At, B1); BAR;
;     LDA(At, 0, 1); STAGE(SA(0, 0), pA0, 2);
;     BAR; WAIT_L(0); MMA(1, 0, At, B0); BAR; SCHED;
.LBB0_1105:
	ds_read_b128 v[160:163], v144
	ds_read_b128 v[164:167], v144 offset:1024
	ds_read_b128 v[174:177], v144 offset:2048
	ds_read_b128 v[178:181], v144 offset:3072
	v_lshl_add_u64 v[168:169], s[12:13], 0, v[130:131]
	v_readfirstlane_b32 s23, v143
	v_lshl_add_u64 v[214:215], v[168:169], 0, s[6:7]
	s_mov_b32 m0, s23
	v_lshl_add_u64 v[230:231], s[12:13], 0, v[132:133]
	v_readfirstlane_b32 s23, v142
	ds_read_b128 v[182:185], v138
	ds_read_b128 v[186:189], v138 offset:1024
	ds_read_b128 v[190:193], v137
	ds_read_b128 v[194:197], v137 offset:1024
	ds_read_b128 v[198:201], v136
	ds_read_b128 v[202:205], v136 offset:1024
	ds_read_b128 v[206:209], v135
	ds_read_b128 v[210:213], v135 offset:1024
	global_load_lds_dwordx4 v[214:215], off
	v_lshl_add_u64 v[214:215], v[230:231], 0, s[6:7]
	s_mov_b32 m0, s23
	s_nop 0
	global_load_lds_dwordx4 v[214:215], off
	s_waitcnt lgkmcnt(8)
	s_waitcnt vmcnt(10)
	s_barrier
	s_waitcnt lgkmcnt(0)
	v_mfma_f32_16x16x32_bf16 v[126:129], v[182:185], v[160:163], v[126:129]
	v_mfma_f32_16x16x32_bf16 v[122:125], v[182:185], v[174:177], v[122:125]
	v_mfma_f32_16x16x32_bf16 v[118:121], v[190:193], v[160:163], v[118:121]
	v_mfma_f32_16x16x32_bf16 v[114:117], v[190:193], v[174:177], v[114:117]
	v_mfma_f32_16x16x32_bf16 v[110:113], v[198:201], v[160:163], v[110:113]
	v_mfma_f32_16x16x32_bf16 v[106:109], v[198:201], v[174:177], v[106:109]
	v_mfma_f32_16x16x32_bf16 v[102:105], v[206:209], v[160:163], v[102:105]
	v_mfma_f32_16x16x32_bf16 v[98:101], v[206:209], v[174:177], v[98:101]
	v_mfma_f32_16x16x32_bf16 v[126:129], v[186:189], v[164:167], v[126:129]
	v_mfma_f32_16x16x32_bf16 v[122:125], v[186:189], v[178:181], v[122:125]
	v_mfma_f32_16x16x32_bf16 v[118:121], v[194:197], v[164:167], v[118:121]
	v_mfma_f32_16x16x32_bf16 v[114:117], v[194:197], v[178:181], v[114:117]
	v_mfma_f32_16x16x32_bf16 v[110:113], v[202:205], v[164:167], v[110:113]
	v_mfma_f32_16x16x32_bf16 v[106:109], v[202:205], v[178:181], v[106:109]
	v_mfma_f32_16x16x32_bf16 v[102:105], v[210:213], v[164:167], v[102:105]
	v_mfma_f32_16x16x32_bf16 v[98:101], v[210:213], v[178:181], v[98:101]
	s_barrier
	v_lshl_add_u64 v[232:233], s[20:21], 0, v[130:131]
	v_readfirstlane_b32 s23, v151
	v_lshl_add_u64 v[234:235], v[232:233], 0, s[8:9]
	s_mov_b32 m0, s23
	ds_read_b128 v[214:217], v141
	ds_read_b128 v[218:221], v141 offset:1024
	ds_read_b128 v[222:225], v141 offset:2048
	ds_read_b128 v[226:229], v141 offset:3072
	global_load_lds_dwordx4 v[234:235], off
	v_lshl_add_u64 v[234:235], s[20:21], 0, v[132:133]
	v_readfirstlane_b32 s23, v152
	v_lshl_add_u64 v[236:237], v[234:235], 0, s[8:9]
	s_mov_b32 m0, s23
	s_add_u32 s20, s20, 0x100
	global_load_lds_dwordx4 v[236:237], off
	s_waitcnt vmcnt(10)
	s_barrier
	s_waitcnt lgkmcnt(0)
	s_addc_u32 s21, s21, 0
	s_waitcnt lgkmcnt(0)
	v_mfma_f32_16x16x32_bf16 v[94:97], v[182:185], v[214:217], v[94:97]
	v_mfma_f32_16x16x32_bf16 v[90:93], v[182:185], v[222:225], v[90:93]
	v_mfma_f32_16x16x32_bf16 v[86:89], v[190:193], v[214:217], v[86:89]
	v_mfma_f32_16x16x32_bf16 v[82:85], v[190:193], v[222:225], v[82:85]
	v_mfma_f32_16x16x32_bf16 v[78:81], v[198:201], v[214:217], v[78:81]
	v_mfma_f32_16x16x32_bf16 v[74:77], v[198:201], v[222:225], v[74:77]
	v_mfma_f32_16x16x32_bf16 v[70:73], v[206:209], v[214:217], v[70:73]
	v_mfma_f32_16x16x32_bf16 v[66:69], v[206:209], v[222:225], v[66:69]
	v_mfma_f32_16x16x32_bf16 v[94:97], v[186:189], v[218:221], v[94:97]
	v_mfma_f32_16x16x32_bf16 v[90:93], v[186:189], v[226:229], v[90:93]
	v_mfma_f32_16x16x32_bf16 v[86:89], v[194:197], v[218:221], v[86:89]
	v_mfma_f32_16x16x32_bf16 v[82:85], v[194:197], v[226:229], v[82:85]
	v_mfma_f32_16x16x32_bf16 v[78:81], v[202:205], v[218:221], v[78:81]
	v_mfma_f32_16x16x32_bf16 v[74:77], v[202:205], v[226:229], v[74:77]
	v_mfma_f32_16x16x32_bf16 v[70:73], v[210:213], v[218:221], v[70:73]
	v_mfma_f32_16x16x32_bf16 v[66:69], v[210:213], v[226:229], v[66:69]
	v_lshl_add_u64 v[236:237], s[18:19], 0, v[130:131]
	v_readfirstlane_b32 s23, v145
	v_lshl_add_u64 v[238:239], v[236:237], 0, s[8:9]
	s_mov_b32 m0, s23
	s_barrier
	ds_read_b128 v[182:185], v138 offset:16384
	ds_read_b128 v[186:189], v138 offset:17408
	ds_read_b128 v[190:193], v137 offset:16384
	ds_read_b128 v[194:197], v137 offset:17408
	ds_read_b128 v[198:201], v136 offset:16384
	ds_read_b128 v[202:205], v136 offset:17408
	ds_read_b128 v[206:209], v135 offset:16384
	ds_read_b128 v[210:213], v135 offset:17408
	global_load_lds_dwordx4 v[238:239], off
	v_lshl_add_u64 v[238:239], s[18:19], 0, v[132:133]
	v_readfirstlane_b32 s23, v146
	v_lshl_add_u64 v[240:241], v[238:239], 0, s[8:9]
	s_mov_b32 m0, s23
	s_add_u32 s18, s18, 0x100
	global_load_lds_dwordx4 v[240:241], off
	s_barrier
	s_waitcnt lgkmcnt(0)
	s_addc_u32 s19, s19, 0
	s_waitcnt lgkmcnt(0)
	v_mfma_f32_16x16x32_bf16 v[62:65], v[182:185], v[160:163], v[62:65]
	v_mfma_f32_16x16x32_bf16 v[58:61], v[182:185], v[174:177], v[58:61]
	v_mfma_f32_16x16x32_bf16 v[54:57], v[190:193], v[160:163], v[54:57]
	v_mfma_f32_16x16x32_bf16 v[50:53], v[190:193], v[174:177], v[50:53]
	v_mfma_f32_16x16x32_bf16 v[46:49], v[198:201], v[160:163], v[46:49]
	v_mfma_f32_16x16x32_bf16 v[42:45], v[198:201], v[174:177], v[42:45]
	v_mfma_f32_16x16x32_bf16 v[38:41], v[206:209], v[160:163], v[38:41]
	v_mfma_f32_16x16x32_bf16 v[34:37], v[206:209], v[174:177], v[34:37]
	v_mfma_f32_16x16x32_bf16 v[62:65], v[186:189], v[164:167], v[62:65]
	v_mfma_f32_16x16x32_bf16 v[58:61], v[186:189], v[178:181], v[58:61]
	v_mfma_f32_16x16x32_bf16 v[54:57], v[194:197], v[164:167], v[54:57]
	v_mfma_f32_16x16x32_bf16 v[50:53], v[194:197], v[178:181], v[50:53]
	v_mfma_f32_16x16x32_bf16 v[46:49], v[202:205], v[164:167], v[46:49]
	v_mfma_f32_16x16x32_bf16 v[42:45], v[202:205], v[178:181], v[42:45]
	v_mfma_f32_16x16x32_bf16 v[38:41], v[210:213], v[164:167], v[38:41]
	v_mfma_f32_16x16x32_bf16 v[34:37], v[210:213], v[178:181], v[34:37]
	s_barrier
; #define STAGE(P, GP, ktrel) do { const GAS char* _g = (GP) + (ktrel) * (BK * 2); \
;     __builtin_amdgcn_global_load_lds((const GAS unsigned*)(_g + so0), (unsigned*)((char*)(P) + tid_ * 16), 16, 0, 0); \
;     __builtin_amdgcn_global_load_lds((const GAS unsigned*)(_g + so1), (unsigned*)((char*)(P) + tid_ * 16 + 8192), 16, 0, 0); } while (0)
; #define WAIT_V(n) asm volatile("s_waitcnt vmcnt(" #n ")" ::: "memory")
; #define WAIT_L(n) asm volatile("s_waitcnt lgkmcnt(" #n ")" ::: "memory")
; #define BAR __builtin_amdgcn_s_barrier()
; #define SCHED __builtin_amdgcn_sched_barrier(0)
; #define LDA(dst, b, h) for (int m = 0; m < 4; ++m) for (int k = 0; k < 2; ++k) \
;     dst[m][k] = *reinterpret_cast<const bf16x8*>((char*)SA(b, h) + lds_byte(wr * 64 + m * 16 + fr, k * 32 + fq * 8))
; #define LDB(dst, b, h) for (int n = 0; n < 2; ++n) for (int k = 0; k < 2; ++k) \
;     dst[n][k] = *reinterpret_cast<const bf16x8*>((char*)SB(b, h) + lds_byte(wc * 32 + n * 16 + fr, k * 32 + fq * 8))
; #define MMA(ai, bj, At_, Bt_) do { __builtin_amdgcn_s_setprio(1); \
;     for (int m = 0; m < 4; ++m) for (int n = 0; n < 2; ++n) for (int k = 0; k < 2; ++k) \
;       acc[ai][bj][m][n] = __builtin_amdgcn_mfma_f32_16x16x32_bf16(At_[m][k], Bt_[n][k], acc[ai][bj][m][n], 0, 0, 0); \
;     __builtin_amdgcn_s_setprio(0); } while (0)
; template <int K, int LD = K>
; __device__ __forceinline__ void gemm_main(const GAS bf16* A, const GAS bf16* Bt, int brow, int bcol, f32x4 (&acc)[2][2][4][2]) {
;     ...
;     WAIT_V(6); BAR; MMA(1, 1, At, B1); BAR;
;     LDB(B0, 1, 0); SCHED; LDA(At, 1, 0); STAGE(SA(0, 1), pA1, 2);
;     WAIT_L(8); BAR; WAIT_L(0); MMA(0, 0, At, B0); BAR; SCHED;
;     LDB(B1, 1, 1); STAGE(SB(1, 0), pB0, 3);
;     BAR; WAIT_L(0); MMA(0, 1, At, B1); BAR;
;     LDA(At, 1, 1); STAGE(SA(1, 0), pA0, 3);
;     BAR; WAIT_L(0); MMA(1, 0, At, B0); BAR; SCHED;
	v_lshl_add_u64 v[240:241], s[16:17], 0, v[130:131]
	v_readfirstlane_b32 s23, v153
	v_lshl_add_u64 v[160:161], v[240:241], 0, s[8:9]
	s_mov_b32 m0, s23
	v_lshl_add_u64 v[242:243], s[16:17], 0, v[132:133]
	v_readfirstlane_b32 s23, v154
	global_load_lds_dwordx4 v[160:161], off
	v_lshl_add_u64 v[160:161], v[242:243], 0, s[8:9]
	s_mov_b32 m0, s23
	s_add_u32 s16, s16, 0x100
	global_load_lds_dwordx4 v[160:161], off
	s_waitcnt vmcnt(10)
	s_addc_u32 s17, s17, 0
	s_barrier
	v_mfma_f32_16x16x32_bf16 v[30:33], v[182:185], v[214:217], v[30:33]
	v_mfma_f32_16x16x32_bf16 v[26:29], v[182:185], v[222:225], v[26:29]
	v_mfma_f32_16x16x32_bf16 v[22:25], v[190:193], v[214:217], v[22:25]
	v_mfma_f32_16x16x32_bf16 v[18:21], v[190:193], v[222:225], v[18:21]
	v_mfma_f32_16x16x32_bf16 v[14:17], v[198:201], v[214:217], v[14:17]
	v_mfma_f32_16x16x32_bf16 v[10:13], v[198:201], v[222:225], v[10:13]
	v_mfma_f32_16x16x32_bf16 v[6:9], v[206:209], v[214:217], v[6:9]
	v_mfma_f32_16x16x32_bf16 v[2:5], v[206:209], v[222:225], v[2:5]
	v_mfma_f32_16x16x32_bf16 v[30:33], v[186:189], v[218:221], v[30:33]
	v_mfma_f32_16x16x32_bf16 v[26:29], v[186:189], v[226:229], v[26:29]
	v_mfma_f32_16x16x32_bf16 v[22:25], v[194:197], v[218:221], v[22:25]
	v_mfma_f32_16x16x32_bf16 v[18:21], v[194:197], v[226:229], v[18:21]
	v_mfma_f32_16x16x32_bf16 v[14:17], v[202:205], v[218:221], v[14:17]
	v_mfma_f32_16x16x32_bf16 v[10:13], v[202:205], v[226:229], v[10:13]
	v_mfma_f32_16x16x32_bf16 v[6:9], v[210:213], v[218:221], v[6:9]
	v_mfma_f32_16x16x32_bf16 v[2:5], v[210:213], v[226:229], v[2:5]
	s_barrier
	ds_read_b128 v[160:163], v140
	ds_read_b128 v[164:167], v140 offset:1024
	ds_read_b128 v[174:177], v140 offset:2048
	ds_read_b128 v[178:181], v140 offset:3072
	v_readfirstlane_b32 s23, v147
	v_lshl_add_u64 v[168:169], v[168:169], 0, s[8:9]
	s_mov_b32 m0, s23
	v_readfirstlane_b32 s23, v148
	ds_read_b128 v[182:185], v138 offset:32768
	ds_read_b128 v[186:189], v138 offset:33792
	ds_read_b128 v[190:193], v137 offset:32768
	ds_read_b128 v[194:197], v137 offset:33792
	ds_read_b128 v[198:201], v136 offset:32768
	ds_read_b128 v[202:205], v136 offset:33792
	ds_read_b128 v[206:209], v135 offset:32768
	ds_read_b128 v[210:213], v135 offset:33792
	global_load_lds_dwordx4 v[168:169], off
	v_lshl_add_u64 v[168:169], v[230:231], 0, s[8:9]
	s_mov_b32 m0, s23
	s_add_u32 s12, s12, 0x100
	global_load_lds_dwordx4 v[168:169], off
	s_waitcnt lgkmcnt(8)
	s_waitcnt vmcnt(10)
	s_barrier
	s_waitcnt lgkmcnt(0)
	s_addc_u32 s13, s13, 0
	s_waitcnt lgkmcnt(0)
	v_mfma_f32_16x16x32_bf16 v[126:129], v[182:185], v[160:163], v[126:129]
	v_mfma_f32_16x16x32_bf16 v[122:125], v[182:185], v[174:177], v[122:125]
	v_mfma_f32_16x16x32_bf16 v[118:121], v[190:193], v[160:163], v[118:121]
	v_mfma_f32_16x16x32_bf16 v[114:117], v[190:193], v[174:177], v[114:117]
	v_mfma_f32_16x16x32_bf16 v[110:113], v[198:201], v[160:163], v[110:113]
	v_mfma_f32_16x16x32_bf16 v[106:109], v[198:201], v[174:177], v[106:109]
	v_mfma_f32_16x16x32_bf16 v[102:105], v[206:209], v[160:163], v[102:105]
	v_mfma_f32_16x16x32_bf16 v[98:101], v[206:209], v[174:177], v[98:101]
	v_mfma_f32_16x16x32_bf16 v[126:129], v[186:189], v[164:167], v[126:129]
	v_mfma_f32_16x16x32_bf16 v[122:125], v[186:189], v[178:181], v[122:125]
	v_mfma_f32_16x16x32_bf16 v[118:121], v[194:197], v[164:167], v[118:121]
	v_mfma_f32_16x16x32_bf16 v[114:117], v[194:197], v[178:181], v[114:117]
	v_mfma_f32_16x16x32_bf16 v[110:113], v[202:205], v[164:167], v[110:113]
	v_mfma_f32_16x16x32_bf16 v[106:109], v[202:205], v[178:181], v[106:109]
	v_mfma_f32_16x16x32_bf16 v[102:105], v[210:213], v[164:167], v[102:105]
	v_mfma_f32_16x16x32_bf16 v[98:101], v[210:213], v[178:181], v[98:101]
	s_barrier
	v_readfirstlane_b32 s23, v155
	v_lshl_add_u64 v[168:169], v[232:233], 0, s[10:11]
	s_mov_b32 m0, s23
	v_readfirstlane_b32 s23, v156
	ds_read_b128 v[214:217], v139
	ds_read_b128 v[218:221], v139 offset:1024
	ds_read_b128 v[222:225], v139 offset:2048
	ds_read_b128 v[226:229], v139 offset:3072
	global_load_lds_dwordx4 v[168:169], off
	v_lshl_add_u64 v[168:169], v[234:235], 0, s[10:11]
	s_mov_b32 m0, s23
	s_nop 0
	global_load_lds_dwordx4 v[168:169], off
	s_waitcnt vmcnt(10)
	s_barrier
	s_waitcnt lgkmcnt(0)
	v_mfma_f32_16x16x32_bf16 v[94:97], v[182:185], v[214:217], v[94:97]
	v_mfma_f32_16x16x32_bf16 v[90:93], v[182:185], v[222:225], v[90:93]
	v_mfma_f32_16x16x32_bf16 v[86:89], v[190:193], v[214:217], v[86:89]
	v_mfma_f32_16x16x32_bf16 v[82:85], v[190:193], v[222:225], v[82:85]
	v_mfma_f32_16x16x32_bf16 v[78:81], v[198:201], v[214:217], v[78:81]
	v_mfma_f32_16x16x32_bf16 v[74:77], v[198:201], v[222:225], v[74:77]
	v_mfma_f32_16x16x32_bf16 v[70:73], v[206:209], v[214:217], v[70:73]
	v_mfma_f32_16x16x32_bf16 v[66:69], v[206:209], v[222:225], v[66:69]
	v_mfma_f32_16x16x32_bf16 v[94:97], v[186:189], v[218:221], v[94:97]
	v_mfma_f32_16x16x32_bf16 v[90:93], v[186:189], v[226:229], v[90:93]
	v_mfma_f32_16x16x32_bf16 v[86:89], v[194:197], v[218:221], v[86:89]
	v_mfma_f32_16x16x32_bf16 v[82:85], v[194:197], v[226:229], v[82:85]
	v_mfma_f32_16x16x32_bf16 v[78:81], v[202:205], v[218:221], v[78:81]
	v_mfma_f32_16x16x32_bf16 v[74:77], v[202:205], v[226:229], v[74:77]
	v_mfma_f32_16x16x32_bf16 v[70:73], v[210:213], v[218:221], v[70:73]
	v_mfma_f32_16x16x32_bf16 v[66:69], v[210:213], v[226:229], v[66:69]
	v_readfirstlane_b32 s23, v149
	v_lshl_add_u64 v[168:169], v[236:237], 0, s[10:11]
	s_mov_b32 m0, s23
	v_readfirstlane_b32 s23, v150
	s_barrier
; #define STAGE(P, GP, ktrel) do { const GAS char* _g = (GP) + (ktrel) * (BK * 2); \
;     __builtin_amdgcn_global_load_lds((const GAS unsigned*)(_g + so0), (unsigned*)((char*)(P) + tid_ * 16), 16, 0, 0); \
;     __builtin_amdgcn_global_load_lds((const GAS unsigned*)(_g + so1), (unsigned*)((char*)(P) + tid_ * 16 + 8192), 16, 0, 0); } while (0)
; #define WAIT_V(n) asm volatile("s_waitcnt vmcnt(" #n ")" ::: "memory")
; #define WAIT_L(n) asm volatile("s_waitcnt lgkmcnt(" #n ")" ::: "memory")
; #define BAR __builtin_amdgcn_s_barrier()
; #define SCHED __builtin_amdgcn_sched_barrier(0)
; #define LDA(dst, b, h) for (int m = 0; m < 4; ++m) for (int k = 0; k < 2; ++k) \
;     dst[m][k] = *reinterpret_cast<const bf16x8*>((char*)SA(b, h) + lds_byte(wr * 64 + m * 16 + fr, k * 32 + fq * 8))
; #define LDB(dst, b, h) for (int n = 0; n < 2; ++n) for (int k = 0; k < 2; ++k) \
;     dst[n][k] = *reinterpret_cast<const bf16x8*>((char*)SB(b, h) + lds_byte(wc * 32 + n * 16 + fr, k * 32 + fq * 8))
; #define MMA(ai, bj, At_, Bt_) do { __builtin_amdgcn_s_setprio(1); \
;     for (int m = 0; m < 4; ++m) for (int n = 0; n < 2; ++n) for (int k = 0; k < 2; ++k) \
;       acc[ai][bj][m][n] = __builtin_amdgcn_mfma_f32_16x16x32_bf16(At_[m][k], Bt_[n][k], acc[ai][bj][m][n], 0, 0, 0); \
;     __builtin_amdgcn_s_setprio(0); } while (0)
; template <int K, int LD = K>
; __device__ __forceinline__ void gemm_main(const GAS bf16* A, const GAS bf16* Bt, int brow, int bcol, f32x4 (&acc)[2][2][4][2]) {
;     ...
;     BAR; WAIT_L(0); MMA(1, 0, At, B0); BAR; SCHED;
;     STAGE(SB(1, 1), pB1, 3);
;     WAIT_V(6); BAR; MMA(1, 1, At, B1); BAR;
;     pA0 += 4 * BK; pA1 += 4 * BK; pB0 += 4 * BK; pB1 += 4 * BK;
;     asm volatile("" : "+s"(pA0), "+s"(pA1), "+s"(pB0), "+s"(pB1));
;   }
;   { LDB(B0, 0, 0); LDA(At, 0, 0); STAGE(SA(1, 1), pA1, 1);
;     BAR; WAIT_L(0); MMA(0, 0, At, B0); BAR;
;     LDB(B1, 0, 1); BAR; WAIT_L(0); MMA(0, 1, At, B1); BAR;
	ds_read_b128 v[182:185], v138 offset:49152
	ds_read_b128 v[186:189], v138 offset:50176
	ds_read_b128 v[190:193], v137 offset:49152
	ds_read_b128 v[194:197], v137 offset:50176
	ds_read_b128 v[198:201], v136 offset:49152
	ds_read_b128 v[202:205], v136 offset:50176
	ds_read_b128 v[206:209], v135 offset:49152
	ds_read_b128 v[210:213], v135 offset:50176
	global_load_lds_dwordx4 v[168:169], off
	v_lshl_add_u64 v[168:169], v[238:239], 0, s[10:11]
	s_mov_b32 m0, s23
	s_nop 0
	global_load_lds_dwordx4 v[168:169], off
	s_barrier
	s_waitcnt lgkmcnt(0)
	v_mfma_f32_16x16x32_bf16 v[62:65], v[182:185], v[160:163], v[62:65]
	v_mfma_f32_16x16x32_bf16 v[58:61], v[182:185], v[174:177], v[58:61]
	v_mfma_f32_16x16x32_bf16 v[54:57], v[190:193], v[160:163], v[54:57]
	v_mfma_f32_16x16x32_bf16 v[50:53], v[190:193], v[174:177], v[50:53]
	v_mfma_f32_16x16x32_bf16 v[46:49], v[198:201], v[160:163], v[46:49]
	v_mfma_f32_16x16x32_bf16 v[42:45], v[198:201], v[174:177], v[42:45]
	v_mfma_f32_16x16x32_bf16 v[38:41], v[206:209], v[160:163], v[38:41]
	v_mfma_f32_16x16x32_bf16 v[34:37], v[206:209], v[174:177], v[34:37]
	v_mfma_f32_16x16x32_bf16 v[62:65], v[186:189], v[164:167], v[62:65]
	v_mfma_f32_16x16x32_bf16 v[58:61], v[186:189], v[178:181], v[58:61]
	v_mfma_f32_16x16x32_bf16 v[54:57], v[194:197], v[164:167], v[54:57]
	v_mfma_f32_16x16x32_bf16 v[50:53], v[194:197], v[178:181], v[50:53]
	v_mfma_f32_16x16x32_bf16 v[46:49], v[202:205], v[164:167], v[46:49]
	v_mfma_f32_16x16x32_bf16 v[42:45], v[202:205], v[178:181], v[42:45]
	v_mfma_f32_16x16x32_bf16 v[38:41], v[210:213], v[164:167], v[38:41]
	v_mfma_f32_16x16x32_bf16 v[34:37], v[210:213], v[178:181], v[34:37]
	s_barrier
	v_readfirstlane_b32 s23, v157
	v_lshl_add_u64 v[160:161], v[240:241], 0, s[10:11]
	s_mov_b32 m0, s23
	v_readfirstlane_b32 s23, v158
	global_load_lds_dwordx4 v[160:161], off
	v_lshl_add_u64 v[160:161], v[242:243], 0, s[10:11]
	s_mov_b32 m0, s23
	s_nop 0
	global_load_lds_dwordx4 v[160:161], off
	s_waitcnt vmcnt(10)
	s_barrier
	v_mfma_f32_16x16x32_bf16 v[30:33], v[182:185], v[214:217], v[30:33]
	v_mfma_f32_16x16x32_bf16 v[26:29], v[182:185], v[222:225], v[26:29]
	v_mfma_f32_16x16x32_bf16 v[22:25], v[190:193], v[214:217], v[22:25]
	v_mfma_f32_16x16x32_bf16 v[18:21], v[190:193], v[222:225], v[18:21]
	v_mfma_f32_16x16x32_bf16 v[14:17], v[198:201], v[214:217], v[14:17]
	v_mfma_f32_16x16x32_bf16 v[10:13], v[198:201], v[222:225], v[10:13]
	v_mfma_f32_16x16x32_bf16 v[6:9], v[206:209], v[214:217], v[6:9]
	v_mfma_f32_16x16x32_bf16 v[2:5], v[206:209], v[222:225], v[2:5]
	v_mfma_f32_16x16x32_bf16 v[30:33], v[186:189], v[218:221], v[30:33]
	v_mfma_f32_16x16x32_bf16 v[26:29], v[186:189], v[226:229], v[26:29]
	v_mfma_f32_16x16x32_bf16 v[22:25], v[194:197], v[218:221], v[22:25]
	v_mfma_f32_16x16x32_bf16 v[18:21], v[194:197], v[226:229], v[18:21]
	v_mfma_f32_16x16x32_bf16 v[14:17], v[202:205], v[218:221], v[14:17]
	v_mfma_f32_16x16x32_bf16 v[10:13], v[202:205], v[226:229], v[10:13]
	v_mfma_f32_16x16x32_bf16 v[6:9], v[210:213], v[218:221], v[6:9]
	v_mfma_f32_16x16x32_bf16 v[2:5], v[210:213], v[226:229], v[2:5]
	s_add_i32 s22, s22, 2
	s_cmp_lt_u32 s22, 40
	s_barrier
	s_cbranch_scc1 .LBB0_1105
	ds_read_b128 v[146:149], v144
	ds_read_b128 v[150:153], v144 offset:1024
	ds_read_b128 v[154:157], v144 offset:2048
	ds_read_b128 v[158:161], v144 offset:3072
	ds_read_b128 v[162:165], v138
	ds_read_b128 v[166:169], v138 offset:1024
	ds_read_b128 v[174:177], v137
	ds_read_b128 v[178:181], v137 offset:1024
	ds_read_b128 v[182:185], v136
	ds_read_b128 v[186:189], v136 offset:1024
	ds_read_b128 v[190:193], v135
	ds_read_b128 v[194:197], v135 offset:1024
	v_lshl_add_u64 v[144:145], s[12:13], 0, v[130:131]
	v_readfirstlane_b32 s16, v143
	v_lshl_add_u64 v[144:145], v[144:145], 0, s[6:7]
	s_mov_b32 m0, s16
	v_lshl_add_u64 v[132:133], s[12:13], 0, v[132:133]
	v_readfirstlane_b32 s12, v142
	global_load_lds_dwordx4 v[144:145], off
	v_lshl_add_u64 v[132:133], v[132:133], 0, s[6:7]
	s_mov_b32 m0, s12
	s_nop 0
	global_load_lds_dwordx4 v[132:133], off
	s_waitcnt vmcnt(10)
	s_barrier
	s_waitcnt lgkmcnt(0)
	v_mfma_f32_16x16x32_bf16 v[126:129], v[162:165], v[146:149], v[126:129]
	v_mfma_f32_16x16x32_bf16 v[122:125], v[162:165], v[154:157], v[122:125]
	v_mfma_f32_16x16x32_bf16 v[110:113], v[182:185], v[146:149], v[110:113]
	v_mfma_f32_16x16x32_bf16 v[106:109], v[182:185], v[154:157], v[106:109]
	v_mfma_f32_16x16x32_bf16 v[126:129], v[166:169], v[150:153], v[126:129]
	v_mfma_f32_16x16x32_bf16 v[122:125], v[166:169], v[158:161], v[122:125]
	v_mfma_f32_16x16x32_bf16 v[118:121], v[174:177], v[146:149], v[118:121]
	v_mfma_f32_16x16x32_bf16 v[114:117], v[174:177], v[154:157], v[114:117]
	v_mfma_f32_16x16x32_bf16 v[110:113], v[186:189], v[150:153], v[110:113]
	v_mfma_f32_16x16x32_bf16 v[106:109], v[186:189], v[158:161], v[106:109]
	v_mfma_f32_16x16x32_bf16 v[102:105], v[190:193], v[146:149], v[102:105]
	v_mfma_f32_16x16x32_bf16 v[98:101], v[190:193], v[154:157], v[98:101]
	v_mfma_f32_16x16x32_bf16 v[142:145], v[178:181], v[150:153], v[118:121]
	v_mfma_f32_16x16x32_bf16 v[198:201], v[178:181], v[158:161], v[114:117]
	v_mfma_f32_16x16x32_bf16 v[202:205], v[194:197], v[150:153], v[102:105]
	v_mfma_f32_16x16x32_bf16 v[206:209], v[194:197], v[158:161], v[98:101]
	s_barrier
	s_nop 1
	ds_read_b128 v[98:101], v141
	ds_read_b128 v[102:105], v141 offset:1024
	ds_read_b128 v[114:117], v141 offset:2048
	ds_read_b128 v[118:121], v141 offset:3072
	s_waitcnt vmcnt(8)
	s_barrier
; #define WAIT_V(n) asm volatile("s_waitcnt vmcnt(" #n ")" ::: "memory")
; #define WAIT_L(n) asm volatile("s_waitcnt lgkmcnt(" #n ")" ::: "memory")
; #define BAR __builtin_amdgcn_s_barrier()
; #define LDA(dst, b, h) for (int m = 0; m < 4; ++m) for (int k = 0; k < 2; ++k) \
;     dst[m][k] = *reinterpret_cast<const bf16x8*>((char*)SA(b, h) + lds_byte(wr * 64 + m * 16 + fr, k * 32 + fq * 8))
; #define LDB(dst, b, h) for (int n = 0; n < 2; ++n) for (int k = 0; k < 2; ++k) \
;     dst[n][k] = *reinterpret_cast<const bf16x8*>((char*)SB(b, h) + lds_byte(wc * 32 + n * 16 + fr, k * 32 + fq * 8))
; #define MMA(ai, bj, At_, Bt_) do { __builtin_amdgcn_s_setprio(1); \
;     for (int m = 0; m < 4; ++m) for (int n = 0; n < 2; ++n) for (int k = 0; k < 2; ++k) \
;       acc[ai][bj][m][n] = __builtin_amdgcn_mfma_f32_16x16x32_bf16(At_[m][k], Bt_[n][k], acc[ai][bj][m][n], 0, 0, 0); \
;     __builtin_amdgcn_s_setprio(0); } while (0)
; template <int K, int LD = K>
; __device__ __forceinline__ void gemm_main(const GAS bf16* A, const GAS bf16* Bt, int brow, int bcol, f32x4 (&acc)[2][2][4][2]) {
;     ...
;     LDB(B1, 0, 1); BAR; WAIT_L(0); MMA(0, 1, At, B1); BAR;
;     LDA(At, 0, 1); WAIT_V(4); BAR; WAIT_L(0); MMA(1, 0, At, B0); MMA(1, 1, At, B1); BAR; }
;   { LDB(B0, 1, 0); LDA(At, 1, 0); WAIT_V(2); BAR; WAIT_L(0); MMA(0, 0, At, B0); BAR;
	s_waitcnt lgkmcnt(0)
	v_mfma_f32_16x16x32_bf16 v[94:97], v[162:165], v[98:101], v[94:97]
	v_mfma_f32_16x16x32_bf16 v[90:93], v[162:165], v[114:117], v[90:93]
	v_mfma_f32_16x16x32_bf16 v[78:81], v[182:185], v[98:101], v[78:81]
	v_mfma_f32_16x16x32_bf16 v[74:77], v[182:185], v[114:117], v[74:77]
	v_mfma_f32_16x16x32_bf16 v[94:97], v[166:169], v[102:105], v[94:97]
	v_mfma_f32_16x16x32_bf16 v[90:93], v[166:169], v[118:121], v[90:93]
	v_mfma_f32_16x16x32_bf16 v[86:89], v[174:177], v[98:101], v[86:89]
	v_mfma_f32_16x16x32_bf16 v[82:85], v[174:177], v[114:117], v[82:85]
	v_mfma_f32_16x16x32_bf16 v[78:81], v[186:189], v[102:105], v[78:81]
	v_mfma_f32_16x16x32_bf16 v[74:77], v[186:189], v[118:121], v[74:77]
	v_mfma_f32_16x16x32_bf16 v[70:73], v[190:193], v[98:101], v[70:73]
	v_mfma_f32_16x16x32_bf16 v[66:69], v[190:193], v[114:117], v[66:69]
	v_mfma_f32_16x16x32_bf16 v[162:165], v[178:181], v[102:105], v[86:89]
	v_mfma_f32_16x16x32_bf16 v[166:169], v[178:181], v[118:121], v[82:85]
	v_mfma_f32_16x16x32_bf16 v[174:177], v[194:197], v[102:105], v[70:73]
	v_mfma_f32_16x16x32_bf16 v[178:181], v[194:197], v[118:121], v[66:69]
	s_barrier
	s_nop 1
	ds_read_b128 v[66:69], v138 offset:16384
	ds_read_b128 v[70:73], v138 offset:17408
	ds_read_b128 v[82:85], v137 offset:16384
	ds_read_b128 v[86:89], v137 offset:17408
	ds_read_b128 v[182:185], v136 offset:16384
	ds_read_b128 v[186:189], v136 offset:17408
	ds_read_b128 v[190:193], v135 offset:16384
	ds_read_b128 v[194:197], v135 offset:17408
	s_waitcnt vmcnt(4)
	s_barrier
	s_waitcnt lgkmcnt(0)
	v_mfma_f32_16x16x32_bf16 v[62:65], v[66:69], v[146:149], v[62:65]
	v_mfma_f32_16x16x32_bf16 v[58:61], v[66:69], v[154:157], v[58:61]
	v_mfma_f32_16x16x32_bf16 v[46:49], v[182:185], v[146:149], v[46:49]
	v_mfma_f32_16x16x32_bf16 v[42:45], v[182:185], v[154:157], v[42:45]
	v_mfma_f32_16x16x32_bf16 v[62:65], v[70:73], v[150:153], v[62:65]
	v_mfma_f32_16x16x32_bf16 v[58:61], v[70:73], v[158:161], v[58:61]
	v_mfma_f32_16x16x32_bf16 v[54:57], v[82:85], v[146:149], v[54:57]
	v_mfma_f32_16x16x32_bf16 v[50:53], v[82:85], v[154:157], v[50:53]
	v_mfma_f32_16x16x32_bf16 v[46:49], v[186:189], v[150:153], v[46:49]
	v_mfma_f32_16x16x32_bf16 v[42:45], v[186:189], v[158:161], v[42:45]
	v_mfma_f32_16x16x32_bf16 v[38:41], v[190:193], v[146:149], v[38:41]
	v_mfma_f32_16x16x32_bf16 v[34:37], v[190:193], v[154:157], v[34:37]
	v_mfma_f32_16x16x32_bf16 v[210:213], v[86:89], v[150:153], v[54:57]
	v_mfma_f32_16x16x32_bf16 v[214:217], v[86:89], v[158:161], v[50:53]
	v_mfma_f32_16x16x32_bf16 v[146:149], v[194:197], v[150:153], v[38:41]
	v_mfma_f32_16x16x32_bf16 v[150:153], v[194:197], v[158:161], v[34:37]
	v_mfma_f32_16x16x32_bf16 v[30:33], v[66:69], v[98:101], v[30:33]
	v_mfma_f32_16x16x32_bf16 v[26:29], v[66:69], v[114:117], v[26:29]
	v_mfma_f32_16x16x32_bf16 v[14:17], v[182:185], v[98:101], v[14:17]
	v_mfma_f32_16x16x32_bf16 v[10:13], v[182:185], v[114:117], v[10:13]
	v_mfma_f32_16x16x32_bf16 v[30:33], v[70:73], v[102:105], v[30:33]
	v_mfma_f32_16x16x32_bf16 v[26:29], v[70:73], v[118:121], v[26:29]
	v_mfma_f32_16x16x32_bf16 v[22:25], v[82:85], v[98:101], v[22:25]
	v_mfma_f32_16x16x32_bf16 v[18:21], v[82:85], v[114:117], v[18:21]
	v_mfma_f32_16x16x32_bf16 v[14:17], v[186:189], v[102:105], v[14:17]
	v_mfma_f32_16x16x32_bf16 v[10:13], v[186:189], v[118:121], v[10:13]
	v_mfma_f32_16x16x32_bf16 v[6:9], v[190:193], v[98:101], v[6:9]
	v_mfma_f32_16x16x32_bf16 v[2:5], v[190:193], v[114:117], v[2:5]
	v_mfma_f32_16x16x32_bf16 v[154:157], v[86:89], v[102:105], v[22:25]
	v_mfma_f32_16x16x32_bf16 v[158:161], v[86:89], v[118:121], v[18:21]
	v_mfma_f32_16x16x32_bf16 v[182:185], v[194:197], v[102:105], v[6:9]
	v_mfma_f32_16x16x32_bf16 v[186:189], v[194:197], v[118:121], v[2:5]
	s_barrier
	s_nop 1
	ds_read_b128 v[2:5], v140
	ds_read_b128 v[6:9], v140 offset:1024
	ds_read_b128 v[190:193], v140 offset:2048
	ds_read_b128 v[194:197], v140 offset:3072
	ds_read_b128 v[18:21], v138 offset:32768
	ds_read_b128 v[22:25], v138 offset:33792
	ds_read_b128 v[34:37], v137 offset:32768
	ds_read_b128 v[38:41], v137 offset:33792
	ds_read_b128 v[50:53], v136 offset:32768
	ds_read_b128 v[54:57], v136 offset:33792
	ds_read_b128 v[218:221], v135 offset:32768
	ds_read_b128 v[222:225], v135 offset:33792
	s_waitcnt vmcnt(2)
	s_barrier
; #define WAIT_V(n) asm volatile("s_waitcnt vmcnt(" #n ")" ::: "memory")
; #define WAIT_L(n) asm volatile("s_waitcnt lgkmcnt(" #n ")" ::: "memory")
; #define BAR __builtin_amdgcn_s_barrier()
; #define LDA(dst, b, h) for (int m = 0; m < 4; ++m) for (int k = 0; k < 2; ++k) \
;     dst[m][k] = *reinterpret_cast<const bf16x8*>((char*)SA(b, h) + lds_byte(wr * 64 + m * 16 + fr, k * 32 + fq * 8))
; #define LDB(dst, b, h) for (int n = 0; n < 2; ++n) for (int k = 0; k < 2; ++k) \
;     dst[n][k] = *reinterpret_cast<const bf16x8*>((char*)SB(b, h) + lds_byte(wc * 32 + n * 16 + fr, k * 32 + fq * 8))
; #define MMA(ai, bj, At_, Bt_) do { __builtin_amdgcn_s_setprio(1); \
;     for (int m = 0; m < 4; ++m) for (int n = 0; n < 2; ++n) for (int k = 0; k < 2; ++k) \
;       acc[ai][bj][m][n] = __builtin_amdgcn_mfma_f32_16x16x32_bf16(At_[m][k], Bt_[n][k], acc[ai][bj][m][n], 0, 0, 0); \
;     __builtin_amdgcn_s_setprio(0); } while (0)
; template <int K, int LD = K>
; __device__ __forceinline__ void gemm_main(const GAS bf16* A, const GAS bf16* Bt, int brow, int bcol, f32x4 (&acc)[2][2][4][2]) {
;     ...
;   { LDB(B0, 1, 0); LDA(At, 1, 0); WAIT_V(2); BAR; WAIT_L(0); MMA(0, 0, At, B0); BAR;
;     LDB(B1, 1, 1); WAIT_V(0); BAR; WAIT_L(0); MMA(0, 1, At, B1); BAR;
;     LDA(At, 1, 1); BAR; WAIT_L(0); MMA(1, 0, At, B0); MMA(1, 1, At, B1); BAR; }
;   if (wr == 0) BAR;
	s_waitcnt lgkmcnt(0)
	v_mfma_f32_16x16x32_bf16 v[66:69], v[18:21], v[2:5], v[126:129]
	v_mfma_f32_16x16x32_bf16 v[118:121], v[22:25], v[6:9], v[66:69]
	v_mfma_f32_16x16x32_bf16 v[66:69], v[18:21], v[190:193], v[122:125]
	v_mfma_f32_16x16x32_bf16 v[114:117], v[22:25], v[194:197], v[66:69]
	v_mfma_f32_16x16x32_bf16 v[66:69], v[34:37], v[2:5], v[142:145]
	v_mfma_f32_16x16x32_bf16 v[102:105], v[38:41], v[6:9], v[66:69]
	v_mfma_f32_16x16x32_bf16 v[66:69], v[34:37], v[190:193], v[198:201]
	v_mfma_f32_16x16x32_bf16 v[98:101], v[38:41], v[194:197], v[66:69]
	v_mfma_f32_16x16x32_bf16 v[66:69], v[50:53], v[2:5], v[110:113]
	v_mfma_f32_16x16x32_bf16 v[86:89], v[54:57], v[6:9], v[66:69]
	v_mfma_f32_16x16x32_bf16 v[66:69], v[50:53], v[190:193], v[106:109]
	v_mfma_f32_16x16x32_bf16 v[82:85], v[54:57], v[194:197], v[66:69]
	v_mfma_f32_16x16x32_bf16 v[66:69], v[218:221], v[2:5], v[202:205]
	v_mfma_f32_16x16x32_bf16 v[70:73], v[222:225], v[6:9], v[66:69]
	v_mfma_f32_16x16x32_bf16 v[66:69], v[218:221], v[190:193], v[206:209]
	v_mfma_f32_16x16x32_bf16 v[66:69], v[222:225], v[194:197], v[66:69]
	s_barrier
	ds_read_b128 v[140:143], v139
	ds_read_b128 v[198:201], v139 offset:1024
	ds_read_b128 v[202:205], v139 offset:2048
	ds_read_b128 v[206:209], v139 offset:3072
	s_waitcnt vmcnt(0)
	s_barrier
	s_waitcnt lgkmcnt(0)
	v_mfma_f32_16x16x32_bf16 v[94:97], v[18:21], v[140:143], v[94:97]
	v_mfma_f32_16x16x32_bf16 v[18:21], v[18:21], v[202:205], v[90:93]
	v_mfma_f32_16x16x32_bf16 v[122:125], v[22:25], v[206:209], v[18:21]
	v_mfma_f32_16x16x32_bf16 v[18:21], v[34:37], v[140:143], v[162:165]
	v_mfma_f32_16x16x32_bf16 v[110:113], v[38:41], v[198:201], v[18:21]
	v_mfma_f32_16x16x32_bf16 v[18:21], v[34:37], v[202:205], v[166:169]
	v_mfma_f32_16x16x32_bf16 v[106:109], v[38:41], v[206:209], v[18:21]
	v_mfma_f32_16x16x32_bf16 v[18:21], v[50:53], v[140:143], v[78:81]
	v_mfma_f32_16x16x32_bf16 v[126:129], v[22:25], v[198:201], v[94:97]
	v_mfma_f32_16x16x32_bf16 v[94:97], v[54:57], v[198:201], v[18:21]
	v_mfma_f32_16x16x32_bf16 v[18:21], v[50:53], v[202:205], v[74:77]
	v_mfma_f32_16x16x32_bf16 v[90:93], v[54:57], v[206:209], v[18:21]
	v_mfma_f32_16x16x32_bf16 v[18:21], v[218:221], v[140:143], v[174:177]
	v_mfma_f32_16x16x32_bf16 v[78:81], v[222:225], v[198:201], v[18:21]
	v_mfma_f32_16x16x32_bf16 v[18:21], v[218:221], v[202:205], v[178:181]
	v_mfma_f32_16x16x32_bf16 v[74:77], v[222:225], v[206:209], v[18:21]
	s_barrier
	ds_read_b128 v[162:165], v138 offset:49152
	ds_read_b128 v[166:169], v138 offset:50176
	ds_read_b128 v[174:177], v137 offset:49152
	ds_read_b128 v[178:181], v137 offset:50176
	ds_read_b128 v[218:221], v136 offset:49152
	ds_read_b128 v[136:139], v136 offset:50176
	ds_read_b128 v[222:225], v135 offset:49152
	ds_read_b128 v[226:229], v135 offset:50176
	s_barrier
	s_waitcnt lgkmcnt(0)
	v_mfma_f32_16x16x32_bf16 v[18:21], v[162:165], v[2:5], v[62:65]
	v_mfma_f32_16x16x32_bf16 v[54:57], v[166:169], v[6:9], v[18:21]
	v_mfma_f32_16x16x32_bf16 v[18:21], v[162:165], v[190:193], v[58:61]
	v_mfma_f32_16x16x32_bf16 v[50:53], v[166:169], v[194:197], v[18:21]
	v_mfma_f32_16x16x32_bf16 v[18:21], v[174:177], v[2:5], v[210:213]
	v_mfma_f32_16x16x32_bf16 v[38:41], v[178:181], v[6:9], v[18:21]
	v_mfma_f32_16x16x32_bf16 v[18:21], v[174:177], v[190:193], v[214:217]
	v_mfma_f32_16x16x32_bf16 v[34:37], v[178:181], v[194:197], v[18:21]
	v_mfma_f32_16x16x32_bf16 v[18:21], v[218:221], v[2:5], v[46:49]
	v_mfma_f32_16x16x32_bf16 v[2:5], v[222:225], v[2:5], v[146:149]
	v_mfma_f32_16x16x32_bf16 v[22:25], v[136:139], v[6:9], v[18:21]
	v_mfma_f32_16x16x32_bf16 v[18:21], v[218:221], v[190:193], v[42:45]
	v_mfma_f32_16x16x32_bf16 v[6:9], v[226:229], v[6:9], v[2:5]
	v_mfma_f32_16x16x32_bf16 v[2:5], v[222:225], v[190:193], v[150:153]
	v_mfma_f32_16x16x32_bf16 v[18:21], v[136:139], v[194:197], v[18:21]
	v_mfma_f32_16x16x32_bf16 v[2:5], v[226:229], v[194:197], v[2:5]
	v_mfma_f32_16x16x32_bf16 v[26:29], v[162:165], v[202:205], v[26:29]
	v_mfma_f32_16x16x32_bf16 v[58:61], v[166:169], v[206:209], v[26:29]
	v_mfma_f32_16x16x32_bf16 v[26:29], v[174:177], v[140:143], v[154:157]
	v_mfma_f32_16x16x32_bf16 v[46:49], v[178:181], v[198:201], v[26:29]
	v_mfma_f32_16x16x32_bf16 v[26:29], v[174:177], v[202:205], v[158:161]
	v_mfma_f32_16x16x32_bf16 v[10:13], v[218:221], v[202:205], v[10:13]
	v_mfma_f32_16x16x32_bf16 v[30:33], v[162:165], v[140:143], v[30:33]
	v_mfma_f32_16x16x32_bf16 v[42:45], v[178:181], v[206:209], v[26:29]
	v_mfma_f32_16x16x32_bf16 v[14:17], v[218:221], v[140:143], v[14:17]
	v_mfma_f32_16x16x32_bf16 v[26:29], v[136:139], v[206:209], v[10:13]
	v_mfma_f32_16x16x32_bf16 v[10:13], v[222:225], v[140:143], v[182:185]
	v_mfma_f32_16x16x32_bf16 v[62:65], v[166:169], v[198:201], v[30:33]
	v_mfma_f32_16x16x32_bf16 v[30:33], v[136:139], v[198:201], v[14:17]
	v_mfma_f32_16x16x32_bf16 v[14:17], v[226:229], v[198:201], v[10:13]
	v_mfma_f32_16x16x32_bf16 v[10:13], v[222:225], v[202:205], v[186:189]
	v_mfma_f32_16x16x32_bf16 v[10:13], v[226:229], v[206:209], v[10:13]
	v_cmp_gt_u32_e32 vcc, s33, v134
	s_barrier
	s_and_saveexec_b64 s[12:13], vcc
	s_cbranch_execz .LBB0_1108
	s_barrier

; #define GAS __attribute__((address_space(1)))
; #define STAGE(P, GP, ktrel) do { const GAS char* _g = (GP) + (ktrel) * (BK * 2); \
;     __builtin_amdgcn_global_load_lds((const GAS unsigned*)(_g + so0), (unsigned*)((char*)(P) + tid_ * 16), 16, 0, 0); \
;     __builtin_amdgcn_global_load_lds((const GAS unsigned*)(_g + so1), (unsigned*)((char*)(P) + tid_ * 16 + 8192), 16, 0, 0); } while (0)
; #define WAIT_V(n) asm volatile("s_waitcnt vmcnt(" #n ")" ::: "memory")
; #define WAIT_L(n) asm volatile("s_waitcnt lgkmcnt(" #n ")" ::: "memory")
; #define BAR __builtin_amdgcn_s_barrier()
; #define SCHED __builtin_amdgcn_sched_barrier(0)
; #define LDA(dst, b, h) for (int m = 0; m < 4; ++m) for (int k = 0; k < 2; ++k) \
;     dst[m][k] = *reinterpret_cast<const bf16x8*>((char*)SA(b, h) + lds_byte(wr * 64 + m * 16 + fr, k * 32 + fq * 8))
; #define LDB(dst, b, h) for (int n = 0; n < 2; ++n) for (int k = 0; k < 2; ++k) \
;     dst[n][k] = *reinterpret_cast<const bf16x8*>((char*)SB(b, h) + lds_byte(wc * 32 + n * 16 + fr, k * 32 + fq * 8))
; #define MMA(ai, bj, At_, Bt_) do { __builtin_amdgcn_s_setprio(1); \
;     for (int m = 0; m < 4; ++m) for (int n = 0; n < 2; ++n) for (int k = 0; k < 2; ++k) \
;       acc[ai][bj][m][n] = __builtin_amdgcn_mfma_f32_16x16x32_bf16(At_[m][k], Bt_[n][k], acc[ai][bj][m][n], 0, 0, 0); \
;     __builtin_amdgcn_s_setprio(0); } while (0)
; template <int K, int LD = K>
; __device__ __forceinline__ void gemm_main(const GAS bf16* A, const GAS bf16* Bt, int brow, int bcol, f32x4 (&acc)[2][2][4][2]) {
;     ...
;   { int r_, c_; stage_rc(tid_ * 16, r_, c_); so0 = (unsigned)(r_ * LD + c_) * 2u; stage_rc(tid_ * 16 + 8192, r_, c_); so1 = (unsigned)(r_ * LD + c_) * 2u; }
;   const GAS char* pA0 = (const GAS char*)A + (long)brow * LD * 2; const GAS char* pA1 = pA0 + (long)HALF * LD * 2;
;   const GAS char* pB0 = (const GAS char*)Bt + (long)bcol * LD * 2; const GAS char* pB1 = pB0 + (long)HALF * LD * 2;
;   asm volatile("" : "+s"(pA0), "+s"(pA1), "+s"(pB0), "+s"(pB1));
;   constexpr int nt = K / BK;
;   static_assert(K % 128 == 0 && K >= 256, "K");
;   if (wr == 1) BAR;
;   WAIT_V(0); BAR;
;   BAR;
;   for (int t = 0; t < nt - 2; t += 2) {
;     LDB(B0, 0, 0); SCHED; LDA(At, 0, 0); STAGE(SA(1, 1), pA1, 1);
;     WAIT_L(8); BAR; WAIT_L(0); MMA(0, 0, At, B0); BAR; SCHED;
;     LDB(B1, 0, 1); STAGE(SB(0, 0), pB0, 2);
.LBB0_1221:
	s_or_b64 exec, exec, s[30:31]
	v_bfe_i32 v5, v130, 27, 1
	v_lshlrev_b32_e32 v20, 4, v130
	v_lshrrev_b32_e32 v5, 22, v5
	v_add_u32_e32 v5, v20, v5
	v_and_b32_e32 v5, 0xfffffc00, v5
	v_sub_u32_e32 v5, v20, v5
	v_lshrrev_b32_e32 v6, 4, v5
	v_bitop3_b32 v6, v6, v5, 32 bitop3:0x6c
	v_ashrrev_i32_e32 v5, 31, v5
	v_ashrrev_i32_e32 v2, 31, v130
	v_lshrrev_b32_e32 v5, 26, v5
	v_lshrrev_b32_e32 v2, 26, v2
	v_add_u32_e32 v5, v6, v5
	v_add_u32_e32 v2, v130, v2
	v_ashrrev_i32_e32 v5, 6, v5
	v_ashrrev_i32_e32 v2, 6, v2
	v_mul_i32_i24_e32 v8, 64, v5
	v_lshlrev_b32_e32 v7, 3, v2
	v_lshlrev_b32_e32 v2, 5, v2
	v_sub_u32_e32 v6, v6, v8
	v_and_b32_e32 v7, 0x7ffff0, v7
	v_and_b32_e32 v2, 32, v2
	v_ashrrev_i16_sdwa v6, v1, sext(v6) dst_sel:DWORD dst_unused:UNUSED_PAD src0_sel:DWORD src1_sel:BYTE_0
	v_add_u32_sdwa v2, v2, sext(v6) dst_sel:DWORD dst_unused:UNUSED_PAD src0_sel:DWORD src1_sel:WORD_0
	v_add_lshl_u32 v5, v5, v7, 9
	v_lshl_add_u32 v2, v2, 1, v5
	v_add_u32_e32 v5, 0x2000, v20
	v_ashrrev_i32_e32 v6, 31, v5
	v_lshrrev_b32_e32 v6, 22, v6
	v_add_u32_e32 v6, v5, v6
	v_ashrrev_i32_e32 v6, 10, v6
	v_mul_i32_i24_e32 v7, 0x400, v6
	v_sub_u32_e32 v5, v5, v7
	v_lshrrev_b32_e32 v7, 4, v5
	v_bitop3_b32 v5, v7, v5, 32 bitop3:0x6c
	v_ashrrev_i32_e32 v8, 31, v5
	v_lshrrev_b32_e32 v8, 26, v8
	v_add_u32_e32 v8, v5, v8
	v_lshrrev_b32_e32 v9, 6, v8
	v_and_b32_e32 v8, 0xc0, v8
	v_lshlrev_b32_e32 v7, 3, v6
	v_lshlrev_b32_e32 v6, 5, v6
	v_sub_u32_e32 v5, v5, v8
	v_and_b32_e32 v7, 0x7ffff0, v7
	v_and_b32_e32 v6, 32, v6
	v_ashrrev_i16_sdwa v5, v1, sext(v5) dst_sel:DWORD dst_unused:UNUSED_PAD src0_sel:DWORD src1_sel:BYTE_0
	v_add_u32_sdwa v5, v6, sext(v5) dst_sel:DWORD dst_unused:UNUSED_PAD src0_sel:DWORD src1_sel:WORD_0
	v_add_lshl_u32 v6, v9, v7, 9
	v_and_b32_e32 v4, 15, v130
	v_lshl_add_u32 v138, v5, 1, v6
	v_lshlrev_b32_e32 v5, 2, v130
	v_and_b32_e32 v28, 48, v130
	v_lshlrev_b32_e32 v4, 6, v4
	v_and_b32_e32 v29, 32, v5
	v_lshlrev_b32_e32 v30, 6, v130
	v_bitop3_b32 v131, v4, v29, v28 bitop3:0x36
	v_and_b32_e32 v200, 0x3000, v30
	v_add3_u32 v225, s38, v131, v200
	s_waitcnt vmcnt(0)
	s_barrier
	s_barrier
	ds_read_b128 v[4:7], v225
	ds_read_b128 v[8:11], v225 offset:1024
	ds_read_b128 v[12:15], v225 offset:2048
	ds_read_b128 v[16:19], v225 offset:3072
	v_add_u32_e32 v142, 0x100, v20
	v_add_u32_e32 v102, s38, v20
	v_add_u32_e32 v54, 0xc000, v142
	v_add_u32_e32 v55, 0xe000, v142
	v_add_u32_e32 v103, 0x2000, v102
	v_add_u32_e32 v155, s39, v20
	v_add_u32_e32 v222, s40, v20
	v_add_u32_e32 v227, s41, v20
	v_add_u32_e32 v143, 0x2000, v142
	v_add_u32_e32 v198, 0x4000, v142
	v_add_u32_e32 v199, 0x6000, v142
	v_add_u32_e32 v223, 0x2000, v222
	v_add_u32_e32 v224, 0x8000, v142
	v_add_u32_e32 v226, 0xa000, v142
	v_add_u32_e32 v228, 0x2000, v227
	v_add_u32_e32 v174, 0x2000, v155
	v_and_b32_e32 v30, 0x3c0, v30
	v_lshlrev_b32_e32 v3, 13, v3
	v_bitop3_b32 v28, v30, v29, v28 bitop3:0x36
	v_add3_u32 v246, s42, v131, v3
	v_add3_u32 v247, s42, v28, v3
	v_mov_b32_e32 v3, v139
	v_lshl_add_u64 v[128:129], s[18:19], 0, v[2:3]
	v_readfirstlane_b32 s31, v54
	v_lshl_add_u64 v[52:53], v[128:129], 0, s[8:9]
	s_mov_b32 m0, s31
	v_lshl_add_u64 v[136:137], s[18:19], 0, v[138:139]
	v_readfirstlane_b32 s30, v55
	ds_read_b128 v[20:23], v246
	ds_read_b128 v[24:27], v246 offset:1024
	ds_read_b128 v[28:31], v247 offset:2048
	ds_read_b128 v[32:35], v247 offset:3072
	ds_read_b128 v[36:39], v247 offset:4096
	ds_read_b128 v[40:43], v247 offset:5120
	ds_read_b128 v[44:47], v247 offset:6144
	ds_read_b128 v[48:51], v247 offset:7168
	global_load_lds_dwordx4 v[52:53], off
	v_lshl_add_u64 v[52:53], v[136:137], 0, s[8:9]
	s_mov_b32 m0, s30
	s_nop 0
	global_load_lds_dwordx4 v[52:53], off
	s_waitcnt lgkmcnt(8)
	s_barrier
	s_waitcnt lgkmcnt(0)
	v_mfma_f32_16x16x32_bf16 v[52:55], v[20:23], v[4:7], 0
	v_mfma_f32_16x16x32_bf16 v[56:59], v[20:23], v[12:15], 0
	v_mfma_f32_16x16x32_bf16 v[60:63], v[28:31], v[4:7], 0
	v_mfma_f32_16x16x32_bf16 v[64:67], v[28:31], v[12:15], 0
	v_mfma_f32_16x16x32_bf16 v[68:71], v[36:39], v[4:7], 0
	v_mfma_f32_16x16x32_bf16 v[72:75], v[36:39], v[12:15], 0
	v_mfma_f32_16x16x32_bf16 v[76:79], v[44:47], v[4:7], 0
	v_mfma_f32_16x16x32_bf16 v[80:83], v[44:47], v[12:15], 0
	v_mfma_f32_16x16x32_bf16 v[52:55], v[24:27], v[8:11], v[52:55]
	v_mfma_f32_16x16x32_bf16 v[56:59], v[24:27], v[16:19], v[56:59]
	v_mfma_f32_16x16x32_bf16 v[60:63], v[32:35], v[8:11], v[60:63]
	v_mfma_f32_16x16x32_bf16 v[64:67], v[32:35], v[16:19], v[64:67]
	v_mfma_f32_16x16x32_bf16 v[68:71], v[40:43], v[8:11], v[68:71]
	v_mfma_f32_16x16x32_bf16 v[72:75], v[40:43], v[16:19], v[72:75]
	v_mfma_f32_16x16x32_bf16 v[76:79], v[48:51], v[8:11], v[76:79]
	v_mfma_f32_16x16x32_bf16 v[80:83], v[48:51], v[16:19], v[80:83]
	s_barrier
	v_lshl_add_u64 v[152:153], s[24:25], 0, v[2:3]
	v_readfirstlane_b32 s48, v102
	v_add3_u32 v229, s39, v131, v200
	v_lshl_add_u64 v[100:101], v[152:153], 0, s[14:15]
	s_mov_b32 m0, s48
	v_lshl_add_u64 v[168:169], s[24:25], 0, v[138:139]
	v_readfirstlane_b32 s48, v103
	ds_read_b128 v[84:87], v229
	ds_read_b128 v[88:91], v229 offset:1024
	ds_read_b128 v[92:95], v229 offset:2048
	ds_read_b128 v[96:99], v229 offset:3072
	global_load_lds_dwordx4 v[100:101], off
	v_lshl_add_u64 v[100:101], v[168:169], 0, s[14:15]
	s_mov_b32 m0, s48
	s_add_u32 s24, s24, 0x100
	global_load_lds_dwordx4 v[100:101], off
	s_barrier
; #define STAGE(P, GP, ktrel) do { const GAS char* _g = (GP) + (ktrel) * (BK * 2); \
;     __builtin_amdgcn_global_load_lds((const GAS unsigned*)(_g + so0), (unsigned*)((char*)(P) + tid_ * 16), 16, 0, 0); \
;     __builtin_amdgcn_global_load_lds((const GAS unsigned*)(_g + so1), (unsigned*)((char*)(P) + tid_ * 16 + 8192), 16, 0, 0); } while (0)
; #define WAIT_V(n) asm volatile("s_waitcnt vmcnt(" #n ")" ::: "memory")
; #define WAIT_L(n) asm volatile("s_waitcnt lgkmcnt(" #n ")" ::: "memory")
; #define BAR __builtin_amdgcn_s_barrier()
; #define SCHED __builtin_amdgcn_sched_barrier(0)
; #define LDA(dst, b, h) for (int m = 0; m < 4; ++m) for (int k = 0; k < 2; ++k) \
;     dst[m][k] = *reinterpret_cast<const bf16x8*>((char*)SA(b, h) + lds_byte(wr * 64 + m * 16 + fr, k * 32 + fq * 8))
; #define LDB(dst, b, h) for (int n = 0; n < 2; ++n) for (int k = 0; k < 2; ++k) \
;     dst[n][k] = *reinterpret_cast<const bf16x8*>((char*)SB(b, h) + lds_byte(wc * 32 + n * 16 + fr, k * 32 + fq * 8))
; #define MMA(ai, bj, At_, Bt_) do { __builtin_amdgcn_s_setprio(1); \
;     for (int m = 0; m < 4; ++m) for (int n = 0; n < 2; ++n) for (int k = 0; k < 2; ++k) \
;       acc[ai][bj][m][n] = __builtin_amdgcn_mfma_f32_16x16x32_bf16(At_[m][k], Bt_[n][k], acc[ai][bj][m][n], 0, 0, 0); \
;     __builtin_amdgcn_s_setprio(0); } while (0)
; template <int K, int LD = K>
; __device__ __forceinline__ void gemm_main(const GAS bf16* A, const GAS bf16* Bt, int brow, int bcol, f32x4 (&acc)[2][2][4][2]) {
;     ...
;     LDB(B1, 0, 1); STAGE(SB(0, 0), pB0, 2);
;     BAR; WAIT_L(0); MMA(0, 1, At, B1); BAR;
;     LDA(At, 0, 1); STAGE(SA(0, 0), pA0, 2);
;     BAR; WAIT_L(0); MMA(1, 0, At, B0); BAR; SCHED;
;     STAGE(SB(0, 1), pB1, 2);
;     WAIT_V(6); BAR; MMA(1, 1, At, B1); BAR;
;     LDB(B0, 1, 0); SCHED; LDA(At, 1, 0); STAGE(SA(0, 1), pA1, 2);
;     WAIT_L(8); BAR; WAIT_L(0); MMA(0, 0, At, B0); BAR; SCHED;
;     LDB(B1, 1, 1); STAGE(SB(1, 0), pB0, 3);
	s_waitcnt lgkmcnt(0)
	s_addc_u32 s25, s25, 0
	s_waitcnt lgkmcnt(0)
	v_mfma_f32_16x16x32_bf16 v[100:103], v[20:23], v[84:87], 0
	v_mfma_f32_16x16x32_bf16 v[20:23], v[20:23], v[92:95], 0
	v_mfma_f32_16x16x32_bf16 v[100:103], v[24:27], v[88:91], v[100:103]
	v_mfma_f32_16x16x32_bf16 v[20:23], v[24:27], v[96:99], v[20:23]
	v_mfma_f32_16x16x32_bf16 v[24:27], v[28:31], v[84:87], 0
	v_mfma_f32_16x16x32_bf16 v[28:31], v[28:31], v[92:95], 0
	v_mfma_f32_16x16x32_bf16 v[24:27], v[32:35], v[88:91], v[24:27]
	v_mfma_f32_16x16x32_bf16 v[28:31], v[32:35], v[96:99], v[28:31]
	v_mfma_f32_16x16x32_bf16 v[32:35], v[36:39], v[84:87], 0
	v_mfma_f32_16x16x32_bf16 v[36:39], v[36:39], v[92:95], 0
	v_mfma_f32_16x16x32_bf16 v[32:35], v[40:43], v[88:91], v[32:35]
	v_mfma_f32_16x16x32_bf16 v[36:39], v[40:43], v[96:99], v[36:39]
	v_mfma_f32_16x16x32_bf16 v[40:43], v[44:47], v[84:87], 0
	v_mfma_f32_16x16x32_bf16 v[44:47], v[44:47], v[92:95], 0
	v_mfma_f32_16x16x32_bf16 v[40:43], v[48:51], v[88:91], v[40:43]
	v_mfma_f32_16x16x32_bf16 v[44:47], v[48:51], v[96:99], v[44:47]
	v_lshl_add_u64 v[214:215], s[28:29], 0, v[2:3]
	v_readfirstlane_b32 s48, v142
	v_lshl_add_u64 v[140:141], v[214:215], 0, s[14:15]
	s_mov_b32 m0, s48
	v_lshl_add_u64 v[216:217], s[28:29], 0, v[138:139]
	v_readfirstlane_b32 s48, v143
	s_barrier
	ds_read_b128 v[48:51], v246 offset:16384
	ds_read_b128 v[104:107], v246 offset:17408
	ds_read_b128 v[108:111], v247 offset:18432
	ds_read_b128 v[112:115], v247 offset:19456
	ds_read_b128 v[116:119], v247 offset:20480
	ds_read_b128 v[120:123], v247 offset:21504
	ds_read_b128 v[124:127], v247 offset:22528
	ds_read_b128 v[132:135], v247 offset:23552
	global_load_lds_dwordx4 v[140:141], off
	v_lshl_add_u64 v[140:141], v[216:217], 0, s[14:15]
	s_mov_b32 m0, s48
	s_add_u32 s28, s28, 0x100
	global_load_lds_dwordx4 v[140:141], off
	s_barrier
	s_waitcnt lgkmcnt(0)
	s_addc_u32 s29, s29, 0
	s_waitcnt lgkmcnt(0)
	v_mfma_f32_16x16x32_bf16 v[140:143], v[48:51], v[4:7], 0
	v_mfma_f32_16x16x32_bf16 v[148:151], v[108:111], v[4:7], 0
	v_mfma_f32_16x16x32_bf16 v[160:163], v[116:119], v[4:7], 0
	v_mfma_f32_16x16x32_bf16 v[4:7], v[124:127], v[4:7], 0
	v_mfma_f32_16x16x32_bf16 v[140:143], v[104:107], v[8:11], v[140:143]
	v_mfma_f32_16x16x32_bf16 v[148:151], v[112:115], v[8:11], v[148:151]
	v_mfma_f32_16x16x32_bf16 v[160:163], v[120:123], v[8:11], v[160:163]
	v_mfma_f32_16x16x32_bf16 v[4:7], v[132:135], v[8:11], v[4:7]
	v_mfma_f32_16x16x32_bf16 v[8:11], v[124:127], v[12:15], 0
	v_mfma_f32_16x16x32_bf16 v[144:147], v[48:51], v[12:15], 0
	v_mfma_f32_16x16x32_bf16 v[156:159], v[108:111], v[12:15], 0
	v_mfma_f32_16x16x32_bf16 v[164:167], v[116:119], v[12:15], 0
	v_mfma_f32_16x16x32_bf16 v[8:11], v[132:135], v[16:19], v[8:11]
	v_mfma_f32_16x16x32_bf16 v[144:147], v[104:107], v[16:19], v[144:147]
	v_mfma_f32_16x16x32_bf16 v[156:159], v[112:115], v[16:19], v[156:159]
	v_mfma_f32_16x16x32_bf16 v[164:167], v[120:123], v[16:19], v[164:167]
	s_barrier
	v_lshl_add_u64 v[218:219], s[26:27], 0, v[2:3]
	v_readfirstlane_b32 s48, v155
	v_lshl_add_u64 v[12:13], v[218:219], 0, s[14:15]
	s_mov_b32 m0, s48
	v_lshl_add_u64 v[220:221], s[26:27], 0, v[138:139]
	v_readfirstlane_b32 s48, v174
	global_load_lds_dwordx4 v[12:13], off
	v_lshl_add_u64 v[12:13], v[220:221], 0, s[14:15]
	s_mov_b32 m0, s48
	s_add_u32 s26, s26, 0x100
	global_load_lds_dwordx4 v[12:13], off
	s_waitcnt vmcnt(6)
	s_addc_u32 s27, s27, 0
	s_barrier
	v_mfma_f32_16x16x32_bf16 v[12:15], v[48:51], v[84:87], 0
	v_mfma_f32_16x16x32_bf16 v[16:19], v[48:51], v[92:95], 0
	v_mfma_f32_16x16x32_bf16 v[12:15], v[104:107], v[88:91], v[12:15]
	v_mfma_f32_16x16x32_bf16 v[16:19], v[104:107], v[96:99], v[16:19]
	v_mfma_f32_16x16x32_bf16 v[48:51], v[108:111], v[84:87], 0
	v_mfma_f32_16x16x32_bf16 v[104:107], v[108:111], v[92:95], 0
	v_mfma_f32_16x16x32_bf16 v[108:111], v[116:119], v[84:87], 0
	v_mfma_f32_16x16x32_bf16 v[84:87], v[124:127], v[84:87], 0
	v_mfma_f32_16x16x32_bf16 v[48:51], v[112:115], v[88:91], v[48:51]
	v_mfma_f32_16x16x32_bf16 v[104:107], v[112:115], v[96:99], v[104:107]
	v_mfma_f32_16x16x32_bf16 v[108:111], v[120:123], v[88:91], v[108:111]
	v_mfma_f32_16x16x32_bf16 v[112:115], v[116:119], v[92:95], 0
	v_mfma_f32_16x16x32_bf16 v[84:87], v[132:135], v[88:91], v[84:87]
	v_mfma_f32_16x16x32_bf16 v[88:91], v[124:127], v[92:95], 0
	v_mfma_f32_16x16x32_bf16 v[112:115], v[120:123], v[96:99], v[112:115]
	v_mfma_f32_16x16x32_bf16 v[88:91], v[132:135], v[96:99], v[88:91]
	v_add3_u32 v155, s40, v131, v200
	s_barrier
	ds_read_b128 v[92:95], v155
	ds_read_b128 v[96:99], v155 offset:1024
	ds_read_b128 v[116:119], v155 offset:2048
	ds_read_b128 v[120:123], v155 offset:3072
	v_readfirstlane_b32 s48, v198
	v_lshl_add_u64 v[128:129], v[128:129], 0, s[14:15]
	s_mov_b32 m0, s48
	v_readfirstlane_b32 s48, v199
	ds_read_b128 v[124:127], v246 offset:32768
	ds_read_b128 v[132:135], v246 offset:33792
	ds_read_b128 v[174:177], v247 offset:34816
	ds_read_b128 v[178:181], v247 offset:35840
	ds_read_b128 v[182:185], v247 offset:36864
	ds_read_b128 v[186:189], v247 offset:37888
	ds_read_b128 v[190:193], v247 offset:38912
	ds_read_b128 v[194:197], v247 offset:39936
	global_load_lds_dwordx4 v[128:129], off
	v_lshl_add_u64 v[128:129], v[136:137], 0, s[14:15]
	s_mov_b32 m0, s48
	s_add_u32 s18, s18, 0x100
	global_load_lds_dwordx4 v[128:129], off
	s_waitcnt lgkmcnt(8)
	s_barrier
; #define STAGE(P, GP, ktrel) do { const GAS char* _g = (GP) + (ktrel) * (BK * 2); \
;     __builtin_amdgcn_global_load_lds((const GAS unsigned*)(_g + so0), (unsigned*)((char*)(P) + tid_ * 16), 16, 0, 0); \
;     __builtin_amdgcn_global_load_lds((const GAS unsigned*)(_g + so1), (unsigned*)((char*)(P) + tid_ * 16 + 8192), 16, 0, 0); } while (0)
; #define WAIT_V(n) asm volatile("s_waitcnt vmcnt(" #n ")" ::: "memory")
; #define WAIT_L(n) asm volatile("s_waitcnt lgkmcnt(" #n ")" ::: "memory")
; #define BAR __builtin_amdgcn_s_barrier()
; #define SCHED __builtin_amdgcn_sched_barrier(0)
; #define LDA(dst, b, h) for (int m = 0; m < 4; ++m) for (int k = 0; k < 2; ++k) \
;     dst[m][k] = *reinterpret_cast<const bf16x8*>((char*)SA(b, h) + lds_byte(wr * 64 + m * 16 + fr, k * 32 + fq * 8))
; #define LDB(dst, b, h) for (int n = 0; n < 2; ++n) for (int k = 0; k < 2; ++k) \
;     dst[n][k] = *reinterpret_cast<const bf16x8*>((char*)SB(b, h) + lds_byte(wc * 32 + n * 16 + fr, k * 32 + fq * 8))
; #define MMA(ai, bj, At_, Bt_) do { __builtin_amdgcn_s_setprio(1); \
;     for (int m = 0; m < 4; ++m) for (int n = 0; n < 2; ++n) for (int k = 0; k < 2; ++k) \
;       acc[ai][bj][m][n] = __builtin_amdgcn_mfma_f32_16x16x32_bf16(At_[m][k], Bt_[n][k], acc[ai][bj][m][n], 0, 0, 0); \
;     __builtin_amdgcn_s_setprio(0); } while (0)
; template <int K, int LD = K>
; __device__ __forceinline__ void gemm_main(const GAS bf16* A, const GAS bf16* Bt, int brow, int bcol, f32x4 (&acc)[2][2][4][2]) {
;     ...
;     WAIT_L(8); BAR; WAIT_L(0); MMA(0, 0, At, B0); BAR; SCHED;
;     LDB(B1, 1, 1); STAGE(SB(1, 0), pB0, 3);
;     BAR; WAIT_L(0); MMA(0, 1, At, B1); BAR;
;     LDA(At, 1, 1); STAGE(SA(1, 0), pA0, 3);
;     BAR; WAIT_L(0); MMA(1, 0, At, B0); BAR; SCHED;
;     STAGE(SB(1, 1), pB1, 3);
;     WAIT_V(6); BAR; MMA(1, 1, At, B1); BAR;
	s_waitcnt lgkmcnt(0)
	s_addc_u32 s19, s19, 0
	s_waitcnt lgkmcnt(0)
	v_mfma_f32_16x16x32_bf16 v[52:55], v[124:127], v[92:95], v[52:55]
	v_mfma_f32_16x16x32_bf16 v[56:59], v[124:127], v[116:119], v[56:59]
	v_mfma_f32_16x16x32_bf16 v[60:63], v[174:177], v[92:95], v[60:63]
	v_mfma_f32_16x16x32_bf16 v[64:67], v[174:177], v[116:119], v[64:67]
	v_mfma_f32_16x16x32_bf16 v[68:71], v[182:185], v[92:95], v[68:71]
	v_mfma_f32_16x16x32_bf16 v[72:75], v[182:185], v[116:119], v[72:75]
	v_mfma_f32_16x16x32_bf16 v[76:79], v[190:193], v[92:95], v[76:79]
	v_mfma_f32_16x16x32_bf16 v[80:83], v[190:193], v[116:119], v[80:83]
	v_mfma_f32_16x16x32_bf16 v[52:55], v[132:135], v[96:99], v[52:55]
	v_mfma_f32_16x16x32_bf16 v[56:59], v[132:135], v[120:123], v[56:59]
	v_mfma_f32_16x16x32_bf16 v[60:63], v[178:181], v[96:99], v[60:63]
	v_mfma_f32_16x16x32_bf16 v[64:67], v[178:181], v[120:123], v[64:67]
	v_mfma_f32_16x16x32_bf16 v[68:71], v[186:189], v[96:99], v[68:71]
	v_mfma_f32_16x16x32_bf16 v[72:75], v[186:189], v[120:123], v[72:75]
	v_mfma_f32_16x16x32_bf16 v[76:79], v[194:197], v[96:99], v[76:79]
	v_mfma_f32_16x16x32_bf16 v[80:83], v[194:197], v[120:123], v[80:83]
	s_barrier
	v_readfirstlane_b32 s48, v222
	v_add3_u32 v131, s41, v131, v200
	v_lshl_add_u64 v[128:129], v[152:153], 0, s[16:17]
	s_mov_b32 m0, s48
	v_readfirstlane_b32 s48, v223
	ds_read_b128 v[198:201], v131
	ds_read_b128 v[202:205], v131 offset:1024
	ds_read_b128 v[206:209], v131 offset:2048
	ds_read_b128 v[210:213], v131 offset:3072
	global_load_lds_dwordx4 v[128:129], off
	v_lshl_add_u64 v[128:129], v[168:169], 0, s[16:17]
	s_mov_b32 m0, s48
	s_nop 0
	global_load_lds_dwordx4 v[128:129], off
	s_barrier
	s_waitcnt lgkmcnt(0)
	v_mfma_f32_16x16x32_bf16 v[100:103], v[124:127], v[198:201], v[100:103]
	v_mfma_f32_16x16x32_bf16 v[20:23], v[124:127], v[206:209], v[20:23]
	v_mfma_f32_16x16x32_bf16 v[24:27], v[174:177], v[198:201], v[24:27]
	v_mfma_f32_16x16x32_bf16 v[28:31], v[174:177], v[206:209], v[28:31]
	v_mfma_f32_16x16x32_bf16 v[32:35], v[182:185], v[198:201], v[32:35]
	v_mfma_f32_16x16x32_bf16 v[36:39], v[182:185], v[206:209], v[36:39]
	v_mfma_f32_16x16x32_bf16 v[40:43], v[190:193], v[198:201], v[40:43]
	v_mfma_f32_16x16x32_bf16 v[44:47], v[190:193], v[206:209], v[44:47]
	v_mfma_f32_16x16x32_bf16 v[100:103], v[132:135], v[202:205], v[100:103]
	v_mfma_f32_16x16x32_bf16 v[20:23], v[132:135], v[210:213], v[20:23]
	v_mfma_f32_16x16x32_bf16 v[24:27], v[178:181], v[202:205], v[24:27]
	v_mfma_f32_16x16x32_bf16 v[28:31], v[178:181], v[210:213], v[28:31]
	v_mfma_f32_16x16x32_bf16 v[32:35], v[186:189], v[202:205], v[32:35]
	v_mfma_f32_16x16x32_bf16 v[36:39], v[186:189], v[210:213], v[36:39]
	v_mfma_f32_16x16x32_bf16 v[40:43], v[194:197], v[202:205], v[40:43]
	v_mfma_f32_16x16x32_bf16 v[44:47], v[194:197], v[210:213], v[44:47]
	v_readfirstlane_b32 s48, v224
	v_lshl_add_u64 v[128:129], v[214:215], 0, s[16:17]
	s_mov_b32 m0, s48
	v_readfirstlane_b32 s48, v226
	s_barrier
	ds_read_b128 v[124:127], v246 offset:49152
	ds_read_b128 v[132:135], v246 offset:50176
	ds_read_b128 v[174:177], v247 offset:51200
	ds_read_b128 v[178:181], v247 offset:52224
	ds_read_b128 v[182:185], v247 offset:53248
	ds_read_b128 v[186:189], v247 offset:54272
	ds_read_b128 v[190:193], v247 offset:55296
	ds_read_b128 v[194:197], v247 offset:56320
	global_load_lds_dwordx4 v[128:129], off
	v_lshl_add_u64 v[128:129], v[216:217], 0, s[16:17]
	s_mov_b32 m0, s48
	s_nop 0
	global_load_lds_dwordx4 v[128:129], off
	s_barrier
	s_waitcnt lgkmcnt(0)
	v_mfma_f32_16x16x32_bf16 v[4:7], v[190:193], v[92:95], v[4:7]
	v_mfma_f32_16x16x32_bf16 v[8:11], v[190:193], v[116:119], v[8:11]
	v_mfma_f32_16x16x32_bf16 v[140:143], v[124:127], v[92:95], v[140:143]
	v_mfma_f32_16x16x32_bf16 v[144:147], v[124:127], v[116:119], v[144:147]
	v_mfma_f32_16x16x32_bf16 v[148:151], v[174:177], v[92:95], v[148:151]
	v_mfma_f32_16x16x32_bf16 v[156:159], v[174:177], v[116:119], v[156:159]
	v_mfma_f32_16x16x32_bf16 v[160:163], v[182:185], v[92:95], v[160:163]
	v_mfma_f32_16x16x32_bf16 v[164:167], v[182:185], v[116:119], v[164:167]
	v_mfma_f32_16x16x32_bf16 v[4:7], v[194:197], v[96:99], v[4:7]
	v_mfma_f32_16x16x32_bf16 v[8:11], v[194:197], v[120:123], v[8:11]
	v_mfma_f32_16x16x32_bf16 v[140:143], v[132:135], v[96:99], v[140:143]
	v_mfma_f32_16x16x32_bf16 v[144:147], v[132:135], v[120:123], v[144:147]
	v_mfma_f32_16x16x32_bf16 v[148:151], v[178:181], v[96:99], v[148:151]
	v_mfma_f32_16x16x32_bf16 v[156:159], v[178:181], v[120:123], v[156:159]
	v_mfma_f32_16x16x32_bf16 v[160:163], v[186:189], v[96:99], v[160:163]
	v_mfma_f32_16x16x32_bf16 v[164:167], v[186:189], v[120:123], v[164:167]
	s_barrier
	v_readfirstlane_b32 s48, v227
	v_lshl_add_u64 v[92:93], v[218:219], 0, s[16:17]
	s_mov_b32 m0, s48
	v_readfirstlane_b32 s48, v228
	global_load_lds_dwordx4 v[92:93], off
	v_lshl_add_u64 v[92:93], v[220:221], 0, s[16:17]
	s_mov_b32 m0, s48
	s_nop 0
	global_load_lds_dwordx4 v[92:93], off
	s_waitcnt vmcnt(6)
	s_barrier
	v_mfma_f32_16x16x32_bf16 v[12:15], v[124:127], v[198:201], v[12:15]
	v_mfma_f32_16x16x32_bf16 v[16:19], v[124:127], v[206:209], v[16:19]
	v_mfma_f32_16x16x32_bf16 v[48:51], v[174:177], v[198:201], v[48:51]
	v_mfma_f32_16x16x32_bf16 v[92:95], v[174:177], v[206:209], v[104:107]
	v_mfma_f32_16x16x32_bf16 v[96:99], v[182:185], v[198:201], v[108:111]
	v_mfma_f32_16x16x32_bf16 v[104:107], v[182:185], v[206:209], v[112:115]
	v_mfma_f32_16x16x32_bf16 v[84:87], v[190:193], v[198:201], v[84:87]
	v_mfma_f32_16x16x32_bf16 v[88:91], v[190:193], v[206:209], v[88:91]
	v_mfma_f32_16x16x32_bf16 v[12:15], v[132:135], v[202:205], v[12:15]
	v_mfma_f32_16x16x32_bf16 v[16:19], v[132:135], v[210:213], v[16:19]
	v_mfma_f32_16x16x32_bf16 v[48:51], v[178:181], v[202:205], v[48:51]
	v_mfma_f32_16x16x32_bf16 v[92:95], v[178:181], v[210:213], v[92:95]
	v_mfma_f32_16x16x32_bf16 v[96:99], v[186:189], v[202:205], v[96:99]
	v_mfma_f32_16x16x32_bf16 v[104:107], v[186:189], v[210:213], v[104:107]
	v_mfma_f32_16x16x32_bf16 v[84:87], v[194:197], v[202:205], v[84:87]
	v_mfma_f32_16x16x32_bf16 v[88:91], v[194:197], v[210:213], v[88:91]
	s_barrier
; #define STAGE(P, GP, ktrel) do { const GAS char* _g = (GP) + (ktrel) * (BK * 2); \
;     __builtin_amdgcn_global_load_lds((const GAS unsigned*)(_g + so0), (unsigned*)((char*)(P) + tid_ * 16), 16, 0, 0); \
;     __builtin_amdgcn_global_load_lds((const GAS unsigned*)(_g + so1), (unsigned*)((char*)(P) + tid_ * 16 + 8192), 16, 0, 0); } while (0)
; #define WAIT_V(n) asm volatile("s_waitcnt vmcnt(" #n ")" ::: "memory")
; #define WAIT_L(n) asm volatile("s_waitcnt lgkmcnt(" #n ")" ::: "memory")
; #define BAR __builtin_amdgcn_s_barrier()
; #define LDA(dst, b, h) for (int m = 0; m < 4; ++m) for (int k = 0; k < 2; ++k) \
;     dst[m][k] = *reinterpret_cast<const bf16x8*>((char*)SA(b, h) + lds_byte(wr * 64 + m * 16 + fr, k * 32 + fq * 8))
; #define LDB(dst, b, h) for (int n = 0; n < 2; ++n) for (int k = 0; k < 2; ++k) \
;     dst[n][k] = *reinterpret_cast<const bf16x8*>((char*)SB(b, h) + lds_byte(wc * 32 + n * 16 + fr, k * 32 + fq * 8))
; #define MMA(ai, bj, At_, Bt_) do { __builtin_amdgcn_s_setprio(1); \
;     for (int m = 0; m < 4; ++m) for (int n = 0; n < 2; ++n) for (int k = 0; k < 2; ++k) \
;       acc[ai][bj][m][n] = __builtin_amdgcn_mfma_f32_16x16x32_bf16(At_[m][k], Bt_[n][k], acc[ai][bj][m][n], 0, 0, 0); \
;     __builtin_amdgcn_s_setprio(0); } while (0)
; template <int K, int LD = K>
; __device__ __forceinline__ void gemm_main(const GAS bf16* A, const GAS bf16* Bt, int brow, int bcol, f32x4 (&acc)[2][2][4][2]) {
;     ...
;   { LDB(B0, 0, 0); LDA(At, 0, 0); STAGE(SA(1, 1), pA1, 1);
;     BAR; WAIT_L(0); MMA(0, 0, At, B0); BAR;
;     LDB(B1, 0, 1); BAR; WAIT_L(0); MMA(0, 1, At, B1); BAR;
;     LDA(At, 0, 1); WAIT_V(4); BAR; WAIT_L(0); MMA(1, 0, At, B0); MMA(1, 1, At, B1); BAR; }
	s_mov_b32 m0, s31
	v_lshl_add_u64 v[2:3], s[18:19], 0, v[2:3]
	v_lshl_add_u64 v[2:3], v[2:3], 0, s[8:9]
	ds_read_b128 v[108:111], v225
	ds_read_b128 v[112:115], v225 offset:1024
	ds_read_b128 v[116:119], v225 offset:2048
	ds_read_b128 v[120:123], v225 offset:3072
	ds_read_b128 v[124:127], v246
	ds_read_b128 v[132:135], v246 offset:1024
	ds_read_b128 v[174:177], v247 offset:2048
	ds_read_b128 v[178:181], v247 offset:3072
	ds_read_b128 v[182:185], v247 offset:4096
	ds_read_b128 v[186:189], v247 offset:5120
	ds_read_b128 v[190:193], v247 offset:6144
	ds_read_b128 v[194:197], v247 offset:7168
	global_load_lds_dwordx4 v[2:3], off
	v_lshl_add_u64 v[2:3], s[18:19], 0, v[138:139]
	v_lshl_add_u64 v[2:3], v[2:3], 0, s[8:9]
	s_mov_b32 m0, s30
	s_nop 0
	global_load_lds_dwordx4 v[2:3], off
	s_barrier
	s_waitcnt lgkmcnt(0)
	v_mfma_f32_16x16x32_bf16 v[52:55], v[124:127], v[108:111], v[52:55]
	v_mfma_f32_16x16x32_bf16 v[56:59], v[124:127], v[116:119], v[56:59]
	v_mfma_f32_16x16x32_bf16 v[60:63], v[174:177], v[108:111], v[60:63]
	v_mfma_f32_16x16x32_bf16 v[64:67], v[174:177], v[116:119], v[64:67]
	v_mfma_f32_16x16x32_bf16 v[68:71], v[182:185], v[108:111], v[68:71]
	v_mfma_f32_16x16x32_bf16 v[72:75], v[182:185], v[116:119], v[72:75]
	v_mfma_f32_16x16x32_bf16 v[76:79], v[190:193], v[108:111], v[76:79]
	v_mfma_f32_16x16x32_bf16 v[52:55], v[132:135], v[112:115], v[52:55]
	v_mfma_f32_16x16x32_bf16 v[56:59], v[132:135], v[120:123], v[56:59]
	v_mfma_f32_16x16x32_bf16 v[60:63], v[178:181], v[112:115], v[60:63]
	v_mfma_f32_16x16x32_bf16 v[64:67], v[178:181], v[120:123], v[64:67]
	v_mfma_f32_16x16x32_bf16 v[68:71], v[186:189], v[112:115], v[68:71]
	v_mfma_f32_16x16x32_bf16 v[72:75], v[186:189], v[120:123], v[72:75]
	v_mfma_f32_16x16x32_bf16 v[76:79], v[194:197], v[112:115], v[76:79]
	v_mfma_f32_16x16x32_bf16 v[80:83], v[190:193], v[116:119], v[80:83]
	v_mfma_f32_16x16x32_bf16 v[198:201], v[194:197], v[120:123], v[80:83]
	s_barrier
	s_nop 4
	ds_read_b128 v[80:83], v229
	ds_read_b128 v[202:205], v229 offset:1024
	ds_read_b128 v[206:209], v229 offset:2048
	ds_read_b128 v[210:213], v229 offset:3072
	s_barrier
	s_waitcnt lgkmcnt(0)
	v_mfma_f32_16x16x32_bf16 v[20:23], v[124:127], v[206:209], v[20:23]
	v_mfma_f32_16x16x32_bf16 v[24:27], v[174:177], v[80:83], v[24:27]
	v_mfma_f32_16x16x32_bf16 v[28:31], v[174:177], v[206:209], v[28:31]
	v_mfma_f32_16x16x32_bf16 v[32:35], v[182:185], v[80:83], v[32:35]
	v_mfma_f32_16x16x32_bf16 v[36:39], v[182:185], v[206:209], v[36:39]
	v_mfma_f32_16x16x32_bf16 v[40:43], v[190:193], v[80:83], v[40:43]
	v_mfma_f32_16x16x32_bf16 v[44:47], v[190:193], v[206:209], v[44:47]
	v_mfma_f32_16x16x32_bf16 v[100:103], v[124:127], v[80:83], v[100:103]
	v_mfma_f32_16x16x32_bf16 v[20:23], v[132:135], v[210:213], v[20:23]
	v_mfma_f32_16x16x32_bf16 v[24:27], v[178:181], v[202:205], v[24:27]
	v_mfma_f32_16x16x32_bf16 v[28:31], v[178:181], v[210:213], v[28:31]
	v_mfma_f32_16x16x32_bf16 v[32:35], v[186:189], v[202:205], v[32:35]
	v_mfma_f32_16x16x32_bf16 v[36:39], v[186:189], v[210:213], v[36:39]
	v_mfma_f32_16x16x32_bf16 v[40:43], v[194:197], v[202:205], v[40:43]
	v_mfma_f32_16x16x32_bf16 v[44:47], v[194:197], v[210:213], v[44:47]
	v_mfma_f32_16x16x32_bf16 v[214:217], v[132:135], v[202:205], v[100:103]
	s_barrier
	s_nop 0
	ds_read_b128 v[100:103], v246 offset:16384
	ds_read_b128 v[124:127], v246 offset:17408
	ds_read_b128 v[132:135], v247 offset:18432
	ds_read_b128 v[174:177], v247 offset:19456
	ds_read_b128 v[178:181], v247 offset:20480
	ds_read_b128 v[182:185], v247 offset:21504
	ds_read_b128 v[186:189], v247 offset:22528
	ds_read_b128 v[190:193], v247 offset:23552
	s_waitcnt vmcnt(4)
	s_barrier
	s_waitcnt lgkmcnt(0)
	v_mfma_f32_16x16x32_bf16 v[2:5], v[186:189], v[108:111], v[4:7]
	v_mfma_f32_16x16x32_bf16 v[140:143], v[100:103], v[108:111], v[140:143]
	v_mfma_f32_16x16x32_bf16 v[144:147], v[100:103], v[116:119], v[144:147]
	v_mfma_f32_16x16x32_bf16 v[148:151], v[132:135], v[108:111], v[148:151]
	v_mfma_f32_16x16x32_bf16 v[156:159], v[132:135], v[116:119], v[156:159]
	v_mfma_f32_16x16x32_bf16 v[160:163], v[178:181], v[108:111], v[160:163]
	v_mfma_f32_16x16x32_bf16 v[164:167], v[178:181], v[116:119], v[164:167]
	v_mfma_f32_16x16x32_bf16 v[2:5], v[190:193], v[112:115], v[2:5]
	v_mfma_f32_16x16x32_bf16 v[6:9], v[186:189], v[116:119], v[8:11]
	v_mfma_f32_16x16x32_bf16 v[140:143], v[124:127], v[112:115], v[140:143]
	v_mfma_f32_16x16x32_bf16 v[144:147], v[124:127], v[120:123], v[144:147]
	v_mfma_f32_16x16x32_bf16 v[148:151], v[174:177], v[112:115], v[148:151]
	v_mfma_f32_16x16x32_bf16 v[156:159], v[174:177], v[120:123], v[156:159]
	v_mfma_f32_16x16x32_bf16 v[160:163], v[182:185], v[112:115], v[160:163]
	v_mfma_f32_16x16x32_bf16 v[164:167], v[182:185], v[120:123], v[164:167]
	v_mfma_f32_16x16x32_bf16 v[194:197], v[190:193], v[120:123], v[6:9]
	v_mfma_f32_16x16x32_bf16 v[6:9], v[100:103], v[80:83], v[12:15]
	v_mfma_f32_16x16x32_bf16 v[10:13], v[124:127], v[202:205], v[6:9]
	v_mfma_f32_16x16x32_bf16 v[6:9], v[100:103], v[206:209], v[16:19]
	v_mfma_f32_16x16x32_bf16 v[14:17], v[124:127], v[210:213], v[6:9]
	v_mfma_f32_16x16x32_bf16 v[6:9], v[132:135], v[80:83], v[48:51]
	v_mfma_f32_16x16x32_bf16 v[218:221], v[174:177], v[202:205], v[6:9]
	v_mfma_f32_16x16x32_bf16 v[6:9], v[132:135], v[206:209], v[92:95]
	v_mfma_f32_16x16x32_bf16 v[132:135], v[174:177], v[210:213], v[6:9]
	v_mfma_f32_16x16x32_bf16 v[6:9], v[178:181], v[80:83], v[96:99]
	v_mfma_f32_16x16x32_bf16 v[174:177], v[182:185], v[202:205], v[6:9]
	v_mfma_f32_16x16x32_bf16 v[6:9], v[178:181], v[206:209], v[104:107]
	v_mfma_f32_16x16x32_bf16 v[178:181], v[182:185], v[210:213], v[6:9]
	v_mfma_f32_16x16x32_bf16 v[6:9], v[186:189], v[80:83], v[84:87]
	v_mfma_f32_16x16x32_bf16 v[182:185], v[190:193], v[202:205], v[6:9]
	v_mfma_f32_16x16x32_bf16 v[6:9], v[186:189], v[206:209], v[88:91]
	v_mfma_f32_16x16x32_bf16 v[186:189], v[190:193], v[210:213], v[6:9]
	s_barrier
; #define WAIT_V(n) asm volatile("s_waitcnt vmcnt(" #n ")" ::: "memory")
; #define WAIT_L(n) asm volatile("s_waitcnt lgkmcnt(" #n ")" ::: "memory")
; #define BAR __builtin_amdgcn_s_barrier()
; #define LDA(dst, b, h) for (int m = 0; m < 4; ++m) for (int k = 0; k < 2; ++k) \
;     dst[m][k] = *reinterpret_cast<const bf16x8*>((char*)SA(b, h) + lds_byte(wr * 64 + m * 16 + fr, k * 32 + fq * 8))
; #define LDB(dst, b, h) for (int n = 0; n < 2; ++n) for (int k = 0; k < 2; ++k) \
;     dst[n][k] = *reinterpret_cast<const bf16x8*>((char*)SB(b, h) + lds_byte(wc * 32 + n * 16 + fr, k * 32 + fq * 8))
; #define MMA(ai, bj, At_, Bt_) do { __builtin_amdgcn_s_setprio(1); \
;     for (int m = 0; m < 4; ++m) for (int n = 0; n < 2; ++n) for (int k = 0; k < 2; ++k) \
;       acc[ai][bj][m][n] = __builtin_amdgcn_mfma_f32_16x16x32_bf16(At_[m][k], Bt_[n][k], acc[ai][bj][m][n], 0, 0, 0); \
;     __builtin_amdgcn_s_setprio(0); } while (0)
; template <int K, int LD = K>
; __device__ __forceinline__ void gemm_main(const GAS bf16* A, const GAS bf16* Bt, int brow, int bcol, f32x4 (&acc)[2][2][4][2]) {
;     ...
;   { LDB(B0, 1, 0); LDA(At, 1, 0); WAIT_V(2); BAR; WAIT_L(0); MMA(0, 0, At, B0); BAR;
;     LDB(B1, 1, 1); WAIT_V(0); BAR; WAIT_L(0); MMA(0, 1, At, B1); BAR;
;     LDA(At, 1, 1); BAR; WAIT_L(0); MMA(1, 0, At, B0); MMA(1, 1, At, B1); BAR; }
;   if (wr == 0) BAR;
	s_nop 4
	ds_read_b128 v[6:9], v155
	ds_read_b128 v[190:193], v155 offset:1024
	ds_read_b128 v[202:205], v155 offset:2048
	ds_read_b128 v[206:209], v155 offset:3072
	ds_read_b128 v[48:51], v246 offset:32768
	ds_read_b128 v[90:93], v246 offset:33792
	ds_read_b128 v[94:97], v247 offset:34816
	ds_read_b128 v[106:109], v247 offset:35840
	ds_read_b128 v[210:213], v247 offset:36864
	ds_read_b128 v[222:225], v247 offset:37888
	ds_read_b128 v[226:229], v247 offset:38912
	ds_read_b128 v[230:233], v247 offset:39936
	s_waitcnt vmcnt(2)
	s_barrier
	s_waitcnt lgkmcnt(0)
	v_mfma_f32_16x16x32_bf16 v[52:55], v[48:51], v[6:9], v[52:55]
	v_mfma_f32_16x16x32_bf16 v[118:121], v[90:93], v[190:193], v[52:55]
	v_mfma_f32_16x16x32_bf16 v[52:55], v[48:51], v[202:205], v[56:59]
	v_mfma_f32_16x16x32_bf16 v[114:117], v[90:93], v[206:209], v[52:55]
	v_mfma_f32_16x16x32_bf16 v[52:55], v[94:97], v[6:9], v[60:63]
	v_mfma_f32_16x16x32_bf16 v[102:105], v[106:109], v[190:193], v[52:55]
	v_mfma_f32_16x16x32_bf16 v[52:55], v[94:97], v[202:205], v[64:67]
	v_mfma_f32_16x16x32_bf16 v[98:101], v[106:109], v[206:209], v[52:55]
	v_mfma_f32_16x16x32_bf16 v[52:55], v[210:213], v[6:9], v[68:71]
	v_mfma_f32_16x16x32_bf16 v[86:89], v[222:225], v[190:193], v[52:55]
	v_mfma_f32_16x16x32_bf16 v[52:55], v[210:213], v[202:205], v[72:75]
	v_mfma_f32_16x16x32_bf16 v[82:85], v[222:225], v[206:209], v[52:55]
	v_mfma_f32_16x16x32_bf16 v[52:55], v[226:229], v[6:9], v[76:79]
	v_mfma_f32_16x16x32_bf16 v[70:73], v[230:233], v[190:193], v[52:55]
	v_mfma_f32_16x16x32_bf16 v[52:55], v[226:229], v[202:205], v[198:201]
	v_mfma_f32_16x16x32_bf16 v[66:69], v[230:233], v[206:209], v[52:55]
	s_barrier
	ds_read_b128 v[198:201], v131
	ds_read_b128 v[234:237], v131 offset:1024
	ds_read_b128 v[238:241], v131 offset:2048
	ds_read_b128 v[242:245], v131 offset:3072
	s_waitcnt vmcnt(0)
	s_barrier
	s_waitcnt lgkmcnt(0)
	v_mfma_f32_16x16x32_bf16 v[18:21], v[48:51], v[238:241], v[20:23]
	v_mfma_f32_16x16x32_bf16 v[122:125], v[90:93], v[242:245], v[18:21]
	v_mfma_f32_16x16x32_bf16 v[18:21], v[94:97], v[198:201], v[24:27]
	v_mfma_f32_16x16x32_bf16 v[110:113], v[106:109], v[234:237], v[18:21]
	v_mfma_f32_16x16x32_bf16 v[18:21], v[94:97], v[238:241], v[28:31]
	v_mfma_f32_16x16x32_bf16 v[106:109], v[106:109], v[242:245], v[18:21]
	v_mfma_f32_16x16x32_bf16 v[18:21], v[210:213], v[198:201], v[32:35]
	v_mfma_f32_16x16x32_bf16 v[52:55], v[48:51], v[198:201], v[214:217]
	v_mfma_f32_16x16x32_bf16 v[94:97], v[222:225], v[234:237], v[18:21]
	v_mfma_f32_16x16x32_bf16 v[18:21], v[210:213], v[238:241], v[36:39]
	v_mfma_f32_16x16x32_bf16 v[126:129], v[90:93], v[234:237], v[52:55]
	v_mfma_f32_16x16x32_bf16 v[90:93], v[222:225], v[242:245], v[18:21]
	v_mfma_f32_16x16x32_bf16 v[18:21], v[226:229], v[198:201], v[40:43]
	v_mfma_f32_16x16x32_bf16 v[78:81], v[230:233], v[234:237], v[18:21]
	v_mfma_f32_16x16x32_bf16 v[18:21], v[226:229], v[238:241], v[44:47]
	v_mfma_f32_16x16x32_bf16 v[74:77], v[230:233], v[242:245], v[18:21]
	s_barrier
	ds_read_b128 v[26:29], v246 offset:49152
	ds_read_b128 v[30:33], v246 offset:50176
	ds_read_b128 v[42:45], v247 offset:51200
	ds_read_b128 v[210:213], v247 offset:52224
	ds_read_b128 v[214:217], v247 offset:53248
	ds_read_b128 v[222:225], v247 offset:54272
	ds_read_b128 v[226:229], v247 offset:55296
	ds_read_b128 v[230:233], v247 offset:56320
	s_barrier
	s_waitcnt lgkmcnt(0)
	v_mfma_f32_16x16x32_bf16 v[18:21], v[26:29], v[6:9], v[140:143]
	v_mfma_f32_16x16x32_bf16 v[54:57], v[30:33], v[190:193], v[18:21]
	v_mfma_f32_16x16x32_bf16 v[18:21], v[26:29], v[202:205], v[144:147]
	v_mfma_f32_16x16x32_bf16 v[50:53], v[30:33], v[206:209], v[18:21]
	v_mfma_f32_16x16x32_bf16 v[18:21], v[42:45], v[6:9], v[148:151]
	v_mfma_f32_16x16x32_bf16 v[38:41], v[210:213], v[190:193], v[18:21]
	v_mfma_f32_16x16x32_bf16 v[18:21], v[42:45], v[202:205], v[156:159]
	v_mfma_f32_16x16x32_bf16 v[34:37], v[210:213], v[206:209], v[18:21]
	v_mfma_f32_16x16x32_bf16 v[18:21], v[214:217], v[6:9], v[160:163]
	v_mfma_f32_16x16x32_bf16 v[2:5], v[226:229], v[6:9], v[2:5]
	v_mfma_f32_16x16x32_bf16 v[22:25], v[222:225], v[190:193], v[18:21]
	v_mfma_f32_16x16x32_bf16 v[18:21], v[214:217], v[202:205], v[164:167]
	v_mfma_f32_16x16x32_bf16 v[6:9], v[230:233], v[190:193], v[2:5]
	v_mfma_f32_16x16x32_bf16 v[2:5], v[226:229], v[202:205], v[194:197]
	v_mfma_f32_16x16x32_bf16 v[18:21], v[222:225], v[206:209], v[18:21]
	v_mfma_f32_16x16x32_bf16 v[2:5], v[230:233], v[206:209], v[2:5]
	v_mfma_f32_16x16x32_bf16 v[10:13], v[26:29], v[198:201], v[10:13]
	v_mfma_f32_16x16x32_bf16 v[62:65], v[30:33], v[234:237], v[10:13]
	v_mfma_f32_16x16x32_bf16 v[10:13], v[26:29], v[238:241], v[14:17]
	v_mfma_f32_16x16x32_bf16 v[58:61], v[30:33], v[242:245], v[10:13]
	v_mfma_f32_16x16x32_bf16 v[10:13], v[42:45], v[198:201], v[218:221]
	v_mfma_f32_16x16x32_bf16 v[46:49], v[210:213], v[234:237], v[10:13]
	v_mfma_f32_16x16x32_bf16 v[10:13], v[42:45], v[238:241], v[132:135]
	v_mfma_f32_16x16x32_bf16 v[42:45], v[210:213], v[242:245], v[10:13]
	v_mfma_f32_16x16x32_bf16 v[10:13], v[214:217], v[198:201], v[174:177]
	v_mfma_f32_16x16x32_bf16 v[30:33], v[222:225], v[234:237], v[10:13]
	v_mfma_f32_16x16x32_bf16 v[10:13], v[214:217], v[238:241], v[178:181]
	v_mfma_f32_16x16x32_bf16 v[26:29], v[222:225], v[242:245], v[10:13]
	v_mfma_f32_16x16x32_bf16 v[10:13], v[226:229], v[198:201], v[182:185]
	v_mfma_f32_16x16x32_bf16 v[14:17], v[230:233], v[234:237], v[10:13]
	v_mfma_f32_16x16x32_bf16 v[10:13], v[226:229], v[238:241], v[186:189]
	v_mfma_f32_16x16x32_bf16 v[10:13], v[230:233], v[242:245], v[10:13]
	v_cmp_gt_u32_e32 vcc, s42, v130
	s_barrier
	s_and_saveexec_b64 s[18:19], vcc
	s_cbranch_execz .LBB0_1223
	s_barrier

; #define STAGE(P, GP, ktrel) do { const GAS char* _g = (GP) + (ktrel) * (BK * 2); \
;     __builtin_amdgcn_global_load_lds((const GAS unsigned*)(_g + so0), (unsigned*)((char*)(P) + tid_ * 16), 16, 0, 0); \
;     __builtin_amdgcn_global_load_lds((const GAS unsigned*)(_g + so1), (unsigned*)((char*)(P) + tid_ * 16 + 8192), 16, 0, 0); } while (0)
; #define WAIT_L(n) asm volatile("s_waitcnt lgkmcnt(" #n ")" ::: "memory")
; #define BAR __builtin_amdgcn_s_barrier()
; #define SCHED __builtin_amdgcn_sched_barrier(0)
; #define LDA(dst, b, h) for (int m = 0; m < 4; ++m) for (int k = 0; k < 2; ++k) \
;     dst[m][k] = *reinterpret_cast<const bf16x8*>((char*)SA(b, h) + lds_byte(wr * 64 + m * 16 + fr, k * 32 + fq * 8))
; #define LDB(dst, b, h) for (int n = 0; n < 2; ++n) for (int k = 0; k < 2; ++k) \
;     dst[n][k] = *reinterpret_cast<const bf16x8*>((char*)SB(b, h) + lds_byte(wc * 32 + n * 16 + fr, k * 32 + fq * 8))
; #define MMA(ai, bj, At_, Bt_) do { __builtin_amdgcn_s_setprio(1); \
;     for (int m = 0; m < 4; ++m) for (int n = 0; n < 2; ++n) for (int k = 0; k < 2; ++k) \
;       acc[ai][bj][m][n] = __builtin_amdgcn_mfma_f32_16x16x32_bf16(At_[m][k], Bt_[n][k], acc[ai][bj][m][n], 0, 0, 0); \
;     __builtin_amdgcn_s_setprio(0); } while (0)
; template <int K, int LD = K>
; __device__ __forceinline__ void gemm_main(const GAS bf16* A, const GAS bf16* Bt, int brow, int bcol, f32x4 (&acc)[2][2][4][2]) {
;     ...
;     LDB(B0, 0, 0); SCHED; LDA(At, 0, 0); STAGE(SA(1, 1), pA1, 1);
;     WAIT_L(8); BAR; WAIT_L(0); MMA(0, 0, At, B0); BAR; SCHED;
;     LDB(B1, 0, 1); STAGE(SB(0, 0), pB0, 2);
;     BAR; WAIT_L(0); MMA(0, 1, At, B1); BAR;
;     LDA(At, 0, 1); STAGE(SA(0, 0), pA0, 2);
;     BAR; WAIT_L(0); MMA(1, 0, At, B0); BAR; SCHED;
.LBB0_1226:
	ds_read_b128 v[146:149], v143
	ds_read_b128 v[150:153], v143 offset:1024
	ds_read_b128 v[156:159], v143 offset:2048
	ds_read_b128 v[160:163], v143 offset:3072
	v_add_u32_e32 v155, 0x100, v141
	v_add_u32_e32 v144, 0xc000, v155
	v_lshl_add_u64 v[168:169], s[18:19], 0, v[138:139]
	v_readfirstlane_b32 s30, v144
	v_add_u32_e32 v145, 0xe000, v155
	v_lshl_add_u64 v[202:203], v[168:169], 0, s[8:9]
	s_mov_b32 m0, s30
	v_lshl_add_u64 v[218:219], s[18:19], 0, v[130:131]
	v_readfirstlane_b32 s30, v145
	ds_read_b128 v[164:167], v136
	ds_read_b128 v[174:177], v136 offset:1024
	ds_read_b128 v[178:181], v135
	ds_read_b128 v[182:185], v135 offset:1024
	ds_read_b128 v[186:189], v134
	ds_read_b128 v[190:193], v134 offset:1024
	ds_read_b128 v[194:197], v133
	ds_read_b128 v[198:201], v133 offset:1024
	global_load_lds_dwordx4 v[202:203], off
	v_lshl_add_u64 v[202:203], v[218:219], 0, s[8:9]
	s_mov_b32 m0, s30
	s_nop 0
	global_load_lds_dwordx4 v[202:203], off
	s_waitcnt lgkmcnt(8)
	s_waitcnt vmcnt(10)
	s_barrier
	s_waitcnt lgkmcnt(0)
	v_mfma_f32_16x16x32_bf16 v[126:129], v[164:167], v[146:149], v[126:129]
	v_mfma_f32_16x16x32_bf16 v[122:125], v[164:167], v[156:159], v[122:125]
	v_mfma_f32_16x16x32_bf16 v[118:121], v[178:181], v[146:149], v[118:121]
	v_mfma_f32_16x16x32_bf16 v[114:117], v[178:181], v[156:159], v[114:117]
	v_mfma_f32_16x16x32_bf16 v[110:113], v[186:189], v[146:149], v[110:113]
	v_mfma_f32_16x16x32_bf16 v[106:109], v[186:189], v[156:159], v[106:109]
	v_mfma_f32_16x16x32_bf16 v[102:105], v[194:197], v[146:149], v[102:105]
	v_mfma_f32_16x16x32_bf16 v[98:101], v[194:197], v[156:159], v[98:101]
	v_mfma_f32_16x16x32_bf16 v[126:129], v[174:177], v[150:153], v[126:129]
	v_mfma_f32_16x16x32_bf16 v[122:125], v[174:177], v[160:163], v[122:125]
	v_mfma_f32_16x16x32_bf16 v[118:121], v[182:185], v[150:153], v[118:121]
	v_mfma_f32_16x16x32_bf16 v[114:117], v[182:185], v[160:163], v[114:117]
	v_mfma_f32_16x16x32_bf16 v[110:113], v[190:193], v[150:153], v[110:113]
	v_mfma_f32_16x16x32_bf16 v[106:109], v[190:193], v[160:163], v[106:109]
	v_mfma_f32_16x16x32_bf16 v[102:105], v[198:201], v[150:153], v[102:105]
	v_mfma_f32_16x16x32_bf16 v[98:101], v[198:201], v[160:163], v[98:101]
	s_barrier
	v_add_u32_e32 v226, s38, v141
	v_lshl_add_u64 v[220:221], s[28:29], 0, v[138:139]
	v_readfirstlane_b32 s30, v226
	v_lshl_add_u64 v[222:223], v[220:221], 0, s[14:15]
	s_mov_b32 m0, s30
	v_add_u32_e32 v226, 0x2000, v226
	ds_read_b128 v[202:205], v142
	ds_read_b128 v[206:209], v142 offset:1024
	ds_read_b128 v[210:213], v142 offset:2048
	ds_read_b128 v[214:217], v142 offset:3072
	global_load_lds_dwordx4 v[222:223], off
	v_lshl_add_u64 v[222:223], s[28:29], 0, v[130:131]
	v_readfirstlane_b32 s30, v226
	v_lshl_add_u64 v[224:225], v[222:223], 0, s[14:15]
	s_mov_b32 m0, s30
	s_add_u32 s28, s28, 0x100
	global_load_lds_dwordx4 v[224:225], off
	s_waitcnt vmcnt(10)
	s_barrier
	s_waitcnt lgkmcnt(0)
	s_addc_u32 s29, s29, 0
	s_waitcnt lgkmcnt(0)
	v_mfma_f32_16x16x32_bf16 v[94:97], v[164:167], v[202:205], v[94:97]
	v_mfma_f32_16x16x32_bf16 v[90:93], v[164:167], v[210:213], v[90:93]
	v_mfma_f32_16x16x32_bf16 v[86:89], v[178:181], v[202:205], v[86:89]
	v_mfma_f32_16x16x32_bf16 v[82:85], v[178:181], v[210:213], v[82:85]
	v_mfma_f32_16x16x32_bf16 v[78:81], v[186:189], v[202:205], v[78:81]
	v_mfma_f32_16x16x32_bf16 v[74:77], v[186:189], v[210:213], v[74:77]
	v_mfma_f32_16x16x32_bf16 v[70:73], v[194:197], v[202:205], v[70:73]
	v_mfma_f32_16x16x32_bf16 v[66:69], v[194:197], v[210:213], v[66:69]
	v_mfma_f32_16x16x32_bf16 v[94:97], v[174:177], v[206:209], v[94:97]
	v_mfma_f32_16x16x32_bf16 v[90:93], v[174:177], v[214:217], v[90:93]
	v_mfma_f32_16x16x32_bf16 v[86:89], v[182:185], v[206:209], v[86:89]
	v_mfma_f32_16x16x32_bf16 v[82:85], v[182:185], v[214:217], v[82:85]
	v_mfma_f32_16x16x32_bf16 v[78:81], v[190:193], v[206:209], v[78:81]
	v_mfma_f32_16x16x32_bf16 v[74:77], v[190:193], v[214:217], v[74:77]
	v_mfma_f32_16x16x32_bf16 v[70:73], v[198:201], v[206:209], v[70:73]
	v_mfma_f32_16x16x32_bf16 v[66:69], v[198:201], v[214:217], v[66:69]
	v_lshl_add_u64 v[224:225], s[26:27], 0, v[138:139]
	v_readfirstlane_b32 s30, v155
	v_lshl_add_u64 v[226:227], v[224:225], 0, s[14:15]
	s_mov_b32 m0, s30
	v_add_u32_e32 v230, 0x2000, v155
	s_barrier
	ds_read_b128 v[164:167], v136 offset:16384
	ds_read_b128 v[174:177], v136 offset:17408
	ds_read_b128 v[178:181], v135 offset:16384
	ds_read_b128 v[182:185], v135 offset:17408
	ds_read_b128 v[186:189], v134 offset:16384
	ds_read_b128 v[190:193], v134 offset:17408
	ds_read_b128 v[194:197], v133 offset:16384
	ds_read_b128 v[198:201], v133 offset:17408
	global_load_lds_dwordx4 v[226:227], off
	v_lshl_add_u64 v[226:227], s[26:27], 0, v[130:131]
	v_readfirstlane_b32 s30, v230
	v_lshl_add_u64 v[228:229], v[226:227], 0, s[14:15]
	s_mov_b32 m0, s30
	s_add_u32 s26, s26, 0x100
	global_load_lds_dwordx4 v[228:229], off
	s_barrier
	s_waitcnt lgkmcnt(0)
	s_addc_u32 s27, s27, 0
	s_waitcnt lgkmcnt(0)
	v_mfma_f32_16x16x32_bf16 v[62:65], v[164:167], v[146:149], v[62:65]
	v_mfma_f32_16x16x32_bf16 v[58:61], v[164:167], v[156:159], v[58:61]
	v_mfma_f32_16x16x32_bf16 v[54:57], v[178:181], v[146:149], v[54:57]
	v_mfma_f32_16x16x32_bf16 v[50:53], v[178:181], v[156:159], v[50:53]
	v_mfma_f32_16x16x32_bf16 v[46:49], v[186:189], v[146:149], v[46:49]
	v_mfma_f32_16x16x32_bf16 v[42:45], v[186:189], v[156:159], v[42:45]
	v_mfma_f32_16x16x32_bf16 v[38:41], v[194:197], v[146:149], v[38:41]
	v_mfma_f32_16x16x32_bf16 v[34:37], v[194:197], v[156:159], v[34:37]
	v_mfma_f32_16x16x32_bf16 v[62:65], v[174:177], v[150:153], v[62:65]
	v_mfma_f32_16x16x32_bf16 v[58:61], v[174:177], v[160:163], v[58:61]
	v_mfma_f32_16x16x32_bf16 v[54:57], v[182:185], v[150:153], v[54:57]
	v_mfma_f32_16x16x32_bf16 v[50:53], v[182:185], v[160:163], v[50:53]
	v_mfma_f32_16x16x32_bf16 v[46:49], v[190:193], v[150:153], v[46:49]
	v_mfma_f32_16x16x32_bf16 v[42:45], v[190:193], v[160:163], v[42:45]
	v_mfma_f32_16x16x32_bf16 v[38:41], v[198:201], v[150:153], v[38:41]
	v_mfma_f32_16x16x32_bf16 v[34:37], v[198:201], v[160:163], v[34:37]
	s_barrier
; #define STAGE(P, GP, ktrel) do { const GAS char* _g = (GP) + (ktrel) * (BK * 2); \
;     __builtin_amdgcn_global_load_lds((const GAS unsigned*)(_g + so0), (unsigned*)((char*)(P) + tid_ * 16), 16, 0, 0); \
;     __builtin_amdgcn_global_load_lds((const GAS unsigned*)(_g + so1), (unsigned*)((char*)(P) + tid_ * 16 + 8192), 16, 0, 0); } while (0)
; #define WAIT_V(n) asm volatile("s_waitcnt vmcnt(" #n ")" ::: "memory")
; #define WAIT_L(n) asm volatile("s_waitcnt lgkmcnt(" #n ")" ::: "memory")
; #define BAR __builtin_amdgcn_s_barrier()
; #define SCHED __builtin_amdgcn_sched_barrier(0)
; #define LDA(dst, b, h) for (int m = 0; m < 4; ++m) for (int k = 0; k < 2; ++k) \
;     dst[m][k] = *reinterpret_cast<const bf16x8*>((char*)SA(b, h) + lds_byte(wr * 64 + m * 16 + fr, k * 32 + fq * 8))
; #define LDB(dst, b, h) for (int n = 0; n < 2; ++n) for (int k = 0; k < 2; ++k) \
;     dst[n][k] = *reinterpret_cast<const bf16x8*>((char*)SB(b, h) + lds_byte(wc * 32 + n * 16 + fr, k * 32 + fq * 8))
; #define MMA(ai, bj, At_, Bt_) do { __builtin_amdgcn_s_setprio(1); \
;     for (int m = 0; m < 4; ++m) for (int n = 0; n < 2; ++n) for (int k = 0; k < 2; ++k) \
;       acc[ai][bj][m][n] = __builtin_amdgcn_mfma_f32_16x16x32_bf16(At_[m][k], Bt_[n][k], acc[ai][bj][m][n], 0, 0, 0); \
;     __builtin_amdgcn_s_setprio(0); } while (0)
; template <int K, int LD = K>
; __device__ __forceinline__ void gemm_main(const GAS bf16* A, const GAS bf16* Bt, int brow, int bcol, f32x4 (&acc)[2][2][4][2]) {
;     ...
;     STAGE(SB(0, 1), pB1, 2);
;     WAIT_V(6); BAR; MMA(1, 1, At, B1); BAR;
;     LDB(B0, 1, 0); SCHED; LDA(At, 1, 0); STAGE(SA(0, 1), pA1, 2);
;     WAIT_L(8); BAR; WAIT_L(0); MMA(0, 0, At, B0); BAR; SCHED;
;     LDB(B1, 1, 1); STAGE(SB(1, 0), pB0, 3);
;     BAR; WAIT_L(0); MMA(0, 1, At, B1); BAR;
;     LDA(At, 1, 1); STAGE(SA(1, 0), pA0, 3);
	v_add_u32_e32 v148, s39, v141
	v_lshl_add_u64 v[228:229], s[24:25], 0, v[138:139]
	v_readfirstlane_b32 s30, v148
	v_add_u32_e32 v148, 0x2000, v148
	v_lshl_add_u64 v[146:147], v[228:229], 0, s[14:15]
	s_mov_b32 m0, s30
	v_lshl_add_u64 v[230:231], s[24:25], 0, v[130:131]
	v_readfirstlane_b32 s30, v148
	global_load_lds_dwordx4 v[146:147], off
	v_lshl_add_u64 v[146:147], v[230:231], 0, s[14:15]
	s_mov_b32 m0, s30
	s_add_u32 s24, s24, 0x100
	global_load_lds_dwordx4 v[146:147], off
	s_waitcnt vmcnt(10)
	s_addc_u32 s25, s25, 0
	s_barrier
	v_mfma_f32_16x16x32_bf16 v[30:33], v[164:167], v[202:205], v[30:33]
	v_mfma_f32_16x16x32_bf16 v[26:29], v[164:167], v[210:213], v[26:29]
	v_mfma_f32_16x16x32_bf16 v[22:25], v[178:181], v[202:205], v[22:25]
	v_mfma_f32_16x16x32_bf16 v[18:21], v[178:181], v[210:213], v[18:21]
	v_mfma_f32_16x16x32_bf16 v[14:17], v[186:189], v[202:205], v[14:17]
	v_mfma_f32_16x16x32_bf16 v[10:13], v[186:189], v[210:213], v[10:13]
	v_mfma_f32_16x16x32_bf16 v[6:9], v[194:197], v[202:205], v[6:9]
	v_mfma_f32_16x16x32_bf16 v[2:5], v[194:197], v[210:213], v[2:5]
	v_mfma_f32_16x16x32_bf16 v[30:33], v[174:177], v[206:209], v[30:33]
	v_mfma_f32_16x16x32_bf16 v[26:29], v[174:177], v[214:217], v[26:29]
	v_mfma_f32_16x16x32_bf16 v[22:25], v[182:185], v[206:209], v[22:25]
	v_mfma_f32_16x16x32_bf16 v[18:21], v[182:185], v[214:217], v[18:21]
	v_mfma_f32_16x16x32_bf16 v[14:17], v[190:193], v[206:209], v[14:17]
	v_mfma_f32_16x16x32_bf16 v[10:13], v[190:193], v[214:217], v[10:13]
	v_mfma_f32_16x16x32_bf16 v[6:9], v[198:201], v[206:209], v[6:9]
	v_mfma_f32_16x16x32_bf16 v[2:5], v[198:201], v[214:217], v[2:5]
	s_barrier
	ds_read_b128 v[146:149], v140
	ds_read_b128 v[150:153], v140 offset:1024
	ds_read_b128 v[156:159], v140 offset:2048
	ds_read_b128 v[160:163], v140 offset:3072
	v_add_u32_e32 v202, 0x4000, v155
	v_lshl_add_u64 v[168:169], v[168:169], 0, s[14:15]
	v_readfirstlane_b32 s30, v202
	v_add_u32_e32 v202, 0x6000, v155
	s_mov_b32 m0, s30
	v_readfirstlane_b32 s30, v202
	ds_read_b128 v[164:167], v136 offset:32768
	ds_read_b128 v[174:177], v136 offset:33792
	ds_read_b128 v[178:181], v135 offset:32768
	ds_read_b128 v[182:185], v135 offset:33792
	ds_read_b128 v[186:189], v134 offset:32768
	ds_read_b128 v[190:193], v134 offset:33792
	ds_read_b128 v[194:197], v133 offset:32768
	ds_read_b128 v[198:201], v133 offset:33792
	global_load_lds_dwordx4 v[168:169], off
	v_lshl_add_u64 v[168:169], v[218:219], 0, s[14:15]
	s_mov_b32 m0, s30
	s_add_u32 s18, s18, 0x100
	global_load_lds_dwordx4 v[168:169], off
	s_waitcnt lgkmcnt(8)
	s_waitcnt vmcnt(10)
	s_barrier
	s_waitcnt lgkmcnt(0)
	s_addc_u32 s19, s19, 0
	s_waitcnt lgkmcnt(0)
	v_mfma_f32_16x16x32_bf16 v[126:129], v[164:167], v[146:149], v[126:129]
	v_mfma_f32_16x16x32_bf16 v[122:125], v[164:167], v[156:159], v[122:125]
	v_mfma_f32_16x16x32_bf16 v[118:121], v[178:181], v[146:149], v[118:121]
	v_mfma_f32_16x16x32_bf16 v[114:117], v[178:181], v[156:159], v[114:117]
	v_mfma_f32_16x16x32_bf16 v[110:113], v[186:189], v[146:149], v[110:113]
	v_mfma_f32_16x16x32_bf16 v[106:109], v[186:189], v[156:159], v[106:109]
	v_mfma_f32_16x16x32_bf16 v[102:105], v[194:197], v[146:149], v[102:105]
	v_mfma_f32_16x16x32_bf16 v[98:101], v[194:197], v[156:159], v[98:101]
	v_mfma_f32_16x16x32_bf16 v[126:129], v[174:177], v[150:153], v[126:129]
	v_mfma_f32_16x16x32_bf16 v[122:125], v[174:177], v[160:163], v[122:125]
	v_mfma_f32_16x16x32_bf16 v[118:121], v[182:185], v[150:153], v[118:121]
	v_mfma_f32_16x16x32_bf16 v[114:117], v[182:185], v[160:163], v[114:117]
	v_mfma_f32_16x16x32_bf16 v[110:113], v[190:193], v[150:153], v[110:113]
	v_mfma_f32_16x16x32_bf16 v[106:109], v[190:193], v[160:163], v[106:109]
	v_mfma_f32_16x16x32_bf16 v[102:105], v[198:201], v[150:153], v[102:105]
	v_mfma_f32_16x16x32_bf16 v[98:101], v[198:201], v[160:163], v[98:101]
	s_barrier
	v_add_u32_e32 v218, s40, v141
	v_lshl_add_u64 v[168:169], v[220:221], 0, s[16:17]
	v_readfirstlane_b32 s30, v218
	v_add_u32_e32 v218, 0x2000, v218
	s_mov_b32 m0, s30
	v_readfirstlane_b32 s30, v218
	ds_read_b128 v[202:205], v137
	ds_read_b128 v[206:209], v137 offset:1024
	ds_read_b128 v[210:213], v137 offset:2048
	ds_read_b128 v[214:217], v137 offset:3072
	global_load_lds_dwordx4 v[168:169], off
	v_lshl_add_u64 v[168:169], v[222:223], 0, s[16:17]
	s_mov_b32 m0, s30
	s_nop 0
	global_load_lds_dwordx4 v[168:169], off
	s_waitcnt vmcnt(10)
	s_barrier
	s_waitcnt lgkmcnt(0)
	v_mfma_f32_16x16x32_bf16 v[94:97], v[164:167], v[202:205], v[94:97]
	v_mfma_f32_16x16x32_bf16 v[90:93], v[164:167], v[210:213], v[90:93]
	v_mfma_f32_16x16x32_bf16 v[86:89], v[178:181], v[202:205], v[86:89]
	v_mfma_f32_16x16x32_bf16 v[82:85], v[178:181], v[210:213], v[82:85]
	v_mfma_f32_16x16x32_bf16 v[78:81], v[186:189], v[202:205], v[78:81]
	v_mfma_f32_16x16x32_bf16 v[74:77], v[186:189], v[210:213], v[74:77]
	v_mfma_f32_16x16x32_bf16 v[70:73], v[194:197], v[202:205], v[70:73]
	v_mfma_f32_16x16x32_bf16 v[66:69], v[194:197], v[210:213], v[66:69]
	v_mfma_f32_16x16x32_bf16 v[94:97], v[174:177], v[206:209], v[94:97]
	v_mfma_f32_16x16x32_bf16 v[90:93], v[174:177], v[214:217], v[90:93]
	v_mfma_f32_16x16x32_bf16 v[86:89], v[182:185], v[206:209], v[86:89]
	v_mfma_f32_16x16x32_bf16 v[82:85], v[182:185], v[214:217], v[82:85]
	v_mfma_f32_16x16x32_bf16 v[78:81], v[190:193], v[206:209], v[78:81]
	v_mfma_f32_16x16x32_bf16 v[74:77], v[190:193], v[214:217], v[74:77]
	v_mfma_f32_16x16x32_bf16 v[70:73], v[198:201], v[206:209], v[70:73]
	v_mfma_f32_16x16x32_bf16 v[66:69], v[198:201], v[214:217], v[66:69]
	v_add_u32_e32 v218, 0x8000, v155
	v_add_u32_e32 v155, 0xa000, v155
	v_readfirstlane_b32 s30, v218
	v_lshl_add_u64 v[168:169], v[224:225], 0, s[16:17]
	s_mov_b32 m0, s30
	v_readfirstlane_b32 s30, v155
	s_barrier
; #define STAGE(P, GP, ktrel) do { const GAS char* _g = (GP) + (ktrel) * (BK * 2); \
;     __builtin_amdgcn_global_load_lds((const GAS unsigned*)(_g + so0), (unsigned*)((char*)(P) + tid_ * 16), 16, 0, 0); \
;     __builtin_amdgcn_global_load_lds((const GAS unsigned*)(_g + so1), (unsigned*)((char*)(P) + tid_ * 16 + 8192), 16, 0, 0); } while (0)
; #define WAIT_V(n) asm volatile("s_waitcnt vmcnt(" #n ")" ::: "memory")
; #define WAIT_L(n) asm volatile("s_waitcnt lgkmcnt(" #n ")" ::: "memory")
; #define BAR __builtin_amdgcn_s_barrier()
; #define SCHED __builtin_amdgcn_sched_barrier(0)
; #define LDA(dst, b, h) for (int m = 0; m < 4; ++m) for (int k = 0; k < 2; ++k) \
;     dst[m][k] = *reinterpret_cast<const bf16x8*>((char*)SA(b, h) + lds_byte(wr * 64 + m * 16 + fr, k * 32 + fq * 8))
; #define LDB(dst, b, h) for (int n = 0; n < 2; ++n) for (int k = 0; k < 2; ++k) \
;     dst[n][k] = *reinterpret_cast<const bf16x8*>((char*)SB(b, h) + lds_byte(wc * 32 + n * 16 + fr, k * 32 + fq * 8))
; #define MMA(ai, bj, At_, Bt_) do { __builtin_amdgcn_s_setprio(1); \
;     for (int m = 0; m < 4; ++m) for (int n = 0; n < 2; ++n) for (int k = 0; k < 2; ++k) \
;       acc[ai][bj][m][n] = __builtin_amdgcn_mfma_f32_16x16x32_bf16(At_[m][k], Bt_[n][k], acc[ai][bj][m][n], 0, 0, 0); \
;     __builtin_amdgcn_s_setprio(0); } while (0)
; template <int K, int LD = K>
; __device__ __forceinline__ void gemm_main(const GAS bf16* A, const GAS bf16* Bt, int brow, int bcol, f32x4 (&acc)[2][2][4][2]) {
;     ...
;     LDA(At, 1, 1); STAGE(SA(1, 0), pA0, 3);
;     BAR; WAIT_L(0); MMA(1, 0, At, B0); BAR; SCHED;
;     STAGE(SB(1, 1), pB1, 3);
;     WAIT_V(6); BAR; MMA(1, 1, At, B1); BAR;
;     pA0 += 4 * BK; pA1 += 4 * BK; pB0 += 4 * BK; pB1 += 4 * BK;
;     asm volatile("" : "+s"(pA0), "+s"(pA1), "+s"(pB0), "+s"(pB1));
;   }
;   { LDB(B0, 0, 0); LDA(At, 0, 0); STAGE(SA(1, 1), pA1, 1);
;     BAR; WAIT_L(0); MMA(0, 0, At, B0); BAR;
;     LDB(B1, 0, 1); BAR; WAIT_L(0); MMA(0, 1, At, B1); BAR;
	ds_read_b128 v[164:167], v136 offset:49152
	ds_read_b128 v[174:177], v136 offset:50176
	ds_read_b128 v[178:181], v135 offset:49152
	ds_read_b128 v[182:185], v135 offset:50176
	ds_read_b128 v[186:189], v134 offset:49152
	ds_read_b128 v[190:193], v134 offset:50176
	ds_read_b128 v[194:197], v133 offset:49152
	ds_read_b128 v[198:201], v133 offset:50176
	global_load_lds_dwordx4 v[168:169], off
	v_lshl_add_u64 v[168:169], v[226:227], 0, s[16:17]
	s_mov_b32 m0, s30
	s_nop 0
	global_load_lds_dwordx4 v[168:169], off
	s_barrier
	s_waitcnt lgkmcnt(0)
	v_mfma_f32_16x16x32_bf16 v[62:65], v[164:167], v[146:149], v[62:65]
	v_mfma_f32_16x16x32_bf16 v[58:61], v[164:167], v[156:159], v[58:61]
	v_mfma_f32_16x16x32_bf16 v[54:57], v[178:181], v[146:149], v[54:57]
	v_mfma_f32_16x16x32_bf16 v[50:53], v[178:181], v[156:159], v[50:53]
	v_mfma_f32_16x16x32_bf16 v[46:49], v[186:189], v[146:149], v[46:49]
	v_mfma_f32_16x16x32_bf16 v[42:45], v[186:189], v[156:159], v[42:45]
	v_mfma_f32_16x16x32_bf16 v[38:41], v[194:197], v[146:149], v[38:41]
	v_mfma_f32_16x16x32_bf16 v[34:37], v[194:197], v[156:159], v[34:37]
	v_mfma_f32_16x16x32_bf16 v[62:65], v[174:177], v[150:153], v[62:65]
	v_mfma_f32_16x16x32_bf16 v[58:61], v[174:177], v[160:163], v[58:61]
	v_mfma_f32_16x16x32_bf16 v[54:57], v[182:185], v[150:153], v[54:57]
	v_mfma_f32_16x16x32_bf16 v[50:53], v[182:185], v[160:163], v[50:53]
	v_mfma_f32_16x16x32_bf16 v[46:49], v[190:193], v[150:153], v[46:49]
	v_mfma_f32_16x16x32_bf16 v[42:45], v[190:193], v[160:163], v[42:45]
	v_mfma_f32_16x16x32_bf16 v[38:41], v[198:201], v[150:153], v[38:41]
	v_mfma_f32_16x16x32_bf16 v[34:37], v[198:201], v[160:163], v[34:37]
	s_barrier
	v_add_u32_e32 v148, s41, v141
	v_lshl_add_u64 v[146:147], v[228:229], 0, s[16:17]
	v_readfirstlane_b32 s30, v148
	v_add_u32_e32 v148, 0x2000, v148
	s_mov_b32 m0, s30
	v_readfirstlane_b32 s30, v148
	global_load_lds_dwordx4 v[146:147], off
	v_lshl_add_u64 v[146:147], v[230:231], 0, s[16:17]
	s_mov_b32 m0, s30
	s_nop 0
	global_load_lds_dwordx4 v[146:147], off
	s_waitcnt vmcnt(10)
	s_barrier
	v_mfma_f32_16x16x32_bf16 v[30:33], v[164:167], v[202:205], v[30:33]
	v_mfma_f32_16x16x32_bf16 v[26:29], v[164:167], v[210:213], v[26:29]
	v_mfma_f32_16x16x32_bf16 v[22:25], v[178:181], v[202:205], v[22:25]
	v_mfma_f32_16x16x32_bf16 v[18:21], v[178:181], v[210:213], v[18:21]
	v_mfma_f32_16x16x32_bf16 v[14:17], v[186:189], v[202:205], v[14:17]
	v_mfma_f32_16x16x32_bf16 v[10:13], v[186:189], v[210:213], v[10:13]
	v_mfma_f32_16x16x32_bf16 v[6:9], v[194:197], v[202:205], v[6:9]
	v_mfma_f32_16x16x32_bf16 v[2:5], v[194:197], v[210:213], v[2:5]
	v_mfma_f32_16x16x32_bf16 v[30:33], v[174:177], v[206:209], v[30:33]
	v_mfma_f32_16x16x32_bf16 v[26:29], v[174:177], v[214:217], v[26:29]
	v_mfma_f32_16x16x32_bf16 v[22:25], v[182:185], v[206:209], v[22:25]
	v_mfma_f32_16x16x32_bf16 v[18:21], v[182:185], v[214:217], v[18:21]
	v_mfma_f32_16x16x32_bf16 v[14:17], v[190:193], v[206:209], v[14:17]
	v_mfma_f32_16x16x32_bf16 v[10:13], v[190:193], v[214:217], v[10:13]
	v_mfma_f32_16x16x32_bf16 v[6:9], v[198:201], v[206:209], v[6:9]
	v_mfma_f32_16x16x32_bf16 v[2:5], v[198:201], v[214:217], v[2:5]
	s_add_i32 s21, s21, 2
	s_cmp_lt_u32 s21, 12
	s_barrier
	s_cbranch_scc1 .LBB0_1226
	v_lshl_add_u64 v[168:169], s[18:19], 0, v[138:139]
	v_readfirstlane_b32 s21, v144
	v_lshl_add_u64 v[168:169], v[168:169], 0, s[8:9]
	s_mov_b32 m0, s21
	v_lshl_add_u64 v[130:131], s[18:19], 0, v[130:131]
	v_readfirstlane_b32 s18, v145
	ds_read_b128 v[146:149], v143
	ds_read_b128 v[150:153], v143 offset:1024
	ds_read_b128 v[156:159], v143 offset:2048
	ds_read_b128 v[160:163], v143 offset:3072
	ds_read_b128 v[164:167], v136
	ds_read_b128 v[174:177], v136 offset:1024
	ds_read_b128 v[178:181], v135
	ds_read_b128 v[182:185], v135 offset:1024
	ds_read_b128 v[186:189], v134
	ds_read_b128 v[190:193], v134 offset:1024
	ds_read_b128 v[194:197], v133
	ds_read_b128 v[198:201], v133 offset:1024
	global_load_lds_dwordx4 v[168:169], off
	v_lshl_add_u64 v[130:131], v[130:131], 0, s[8:9]
	s_mov_b32 m0, s18
	s_nop 0
	global_load_lds_dwordx4 v[130:131], off
	s_waitcnt vmcnt(10)
	s_barrier
	s_waitcnt lgkmcnt(0)
	v_mfma_f32_16x16x32_bf16 v[126:129], v[164:167], v[146:149], v[126:129]
	v_mfma_f32_16x16x32_bf16 v[122:125], v[164:167], v[156:159], v[122:125]
	v_mfma_f32_16x16x32_bf16 v[110:113], v[186:189], v[146:149], v[110:113]
	v_mfma_f32_16x16x32_bf16 v[106:109], v[186:189], v[156:159], v[106:109]
	v_mfma_f32_16x16x32_bf16 v[126:129], v[174:177], v[150:153], v[126:129]
	v_mfma_f32_16x16x32_bf16 v[122:125], v[174:177], v[160:163], v[122:125]
	v_mfma_f32_16x16x32_bf16 v[118:121], v[178:181], v[146:149], v[118:121]
	v_mfma_f32_16x16x32_bf16 v[114:117], v[178:181], v[156:159], v[114:117]
	v_mfma_f32_16x16x32_bf16 v[110:113], v[190:193], v[150:153], v[110:113]
	v_mfma_f32_16x16x32_bf16 v[106:109], v[190:193], v[160:163], v[106:109]
	v_mfma_f32_16x16x32_bf16 v[102:105], v[194:197], v[146:149], v[102:105]
	v_mfma_f32_16x16x32_bf16 v[98:101], v[194:197], v[156:159], v[98:101]
	v_mfma_f32_16x16x32_bf16 v[202:205], v[182:185], v[150:153], v[118:121]
	v_mfma_f32_16x16x32_bf16 v[206:209], v[182:185], v[160:163], v[114:117]
	v_mfma_f32_16x16x32_bf16 v[210:213], v[198:201], v[150:153], v[102:105]
	v_mfma_f32_16x16x32_bf16 v[214:217], v[198:201], v[160:163], v[98:101]
	s_barrier
	s_nop 1
	ds_read_b128 v[98:101], v142
	ds_read_b128 v[102:105], v142 offset:1024
	ds_read_b128 v[114:117], v142 offset:2048
	ds_read_b128 v[118:121], v142 offset:3072
	s_waitcnt vmcnt(8)
	s_barrier
; #define WAIT_V(n) asm volatile("s_waitcnt vmcnt(" #n ")" ::: "memory")
; #define WAIT_L(n) asm volatile("s_waitcnt lgkmcnt(" #n ")" ::: "memory")
; #define BAR __builtin_amdgcn_s_barrier()
; #define LDA(dst, b, h) for (int m = 0; m < 4; ++m) for (int k = 0; k < 2; ++k) \
;     dst[m][k] = *reinterpret_cast<const bf16x8*>((char*)SA(b, h) + lds_byte(wr * 64 + m * 16 + fr, k * 32 + fq * 8))
; #define LDB(dst, b, h) for (int n = 0; n < 2; ++n) for (int k = 0; k < 2; ++k) \
;     dst[n][k] = *reinterpret_cast<const bf16x8*>((char*)SB(b, h) + lds_byte(wc * 32 + n * 16 + fr, k * 32 + fq * 8))
; #define MMA(ai, bj, At_, Bt_) do { __builtin_amdgcn_s_setprio(1); \
;     for (int m = 0; m < 4; ++m) for (int n = 0; n < 2; ++n) for (int k = 0; k < 2; ++k) \
;       acc[ai][bj][m][n] = __builtin_amdgcn_mfma_f32_16x16x32_bf16(At_[m][k], Bt_[n][k], acc[ai][bj][m][n], 0, 0, 0); \
;     __builtin_amdgcn_s_setprio(0); } while (0)
; template <int K, int LD = K>
; __device__ __forceinline__ void gemm_main(const GAS bf16* A, const GAS bf16* Bt, int brow, int bcol, f32x4 (&acc)[2][2][4][2]) {
;     ...
;     LDB(B1, 0, 1); BAR; WAIT_L(0); MMA(0, 1, At, B1); BAR;
;     LDA(At, 0, 1); WAIT_V(4); BAR; WAIT_L(0); MMA(1, 0, At, B0); MMA(1, 1, At, B1); BAR; }
;   { LDB(B0, 1, 0); LDA(At, 1, 0); WAIT_V(2); BAR; WAIT_L(0); MMA(0, 0, At, B0); BAR;
	s_waitcnt lgkmcnt(0)
	v_mfma_f32_16x16x32_bf16 v[94:97], v[164:167], v[98:101], v[94:97]
	v_mfma_f32_16x16x32_bf16 v[90:93], v[164:167], v[114:117], v[90:93]
	v_mfma_f32_16x16x32_bf16 v[78:81], v[186:189], v[98:101], v[78:81]
	v_mfma_f32_16x16x32_bf16 v[74:77], v[186:189], v[114:117], v[74:77]
	v_mfma_f32_16x16x32_bf16 v[94:97], v[174:177], v[102:105], v[94:97]
	v_mfma_f32_16x16x32_bf16 v[90:93], v[174:177], v[118:121], v[90:93]
	v_mfma_f32_16x16x32_bf16 v[86:89], v[178:181], v[98:101], v[86:89]
	v_mfma_f32_16x16x32_bf16 v[82:85], v[178:181], v[114:117], v[82:85]
	v_mfma_f32_16x16x32_bf16 v[78:81], v[190:193], v[102:105], v[78:81]
	v_mfma_f32_16x16x32_bf16 v[74:77], v[190:193], v[118:121], v[74:77]
	v_mfma_f32_16x16x32_bf16 v[70:73], v[194:197], v[98:101], v[70:73]
	v_mfma_f32_16x16x32_bf16 v[66:69], v[194:197], v[114:117], v[66:69]
	v_mfma_f32_16x16x32_bf16 v[142:145], v[182:185], v[102:105], v[86:89]
	v_mfma_f32_16x16x32_bf16 v[164:167], v[182:185], v[118:121], v[82:85]
	v_mfma_f32_16x16x32_bf16 v[174:177], v[198:201], v[102:105], v[70:73]
	v_mfma_f32_16x16x32_bf16 v[178:181], v[198:201], v[118:121], v[66:69]
	s_barrier
	s_nop 1
	ds_read_b128 v[66:69], v136 offset:16384
	ds_read_b128 v[70:73], v136 offset:17408
	ds_read_b128 v[82:85], v135 offset:16384
	ds_read_b128 v[86:89], v135 offset:17408
	ds_read_b128 v[182:185], v134 offset:16384
	ds_read_b128 v[186:189], v134 offset:17408
	ds_read_b128 v[190:193], v133 offset:16384
	ds_read_b128 v[194:197], v133 offset:17408
	s_waitcnt vmcnt(4)
	s_barrier
	s_waitcnt lgkmcnt(0)
	v_mfma_f32_16x16x32_bf16 v[62:65], v[66:69], v[146:149], v[62:65]
	v_mfma_f32_16x16x32_bf16 v[58:61], v[66:69], v[156:159], v[58:61]
	v_mfma_f32_16x16x32_bf16 v[46:49], v[182:185], v[146:149], v[46:49]
	v_mfma_f32_16x16x32_bf16 v[42:45], v[182:185], v[156:159], v[42:45]
	v_mfma_f32_16x16x32_bf16 v[62:65], v[70:73], v[150:153], v[62:65]
	v_mfma_f32_16x16x32_bf16 v[58:61], v[70:73], v[160:163], v[58:61]
	v_mfma_f32_16x16x32_bf16 v[54:57], v[82:85], v[146:149], v[54:57]
	v_mfma_f32_16x16x32_bf16 v[50:53], v[82:85], v[156:159], v[50:53]
	v_mfma_f32_16x16x32_bf16 v[46:49], v[186:189], v[150:153], v[46:49]
	v_mfma_f32_16x16x32_bf16 v[42:45], v[186:189], v[160:163], v[42:45]
	v_mfma_f32_16x16x32_bf16 v[38:41], v[190:193], v[146:149], v[38:41]
	v_mfma_f32_16x16x32_bf16 v[34:37], v[190:193], v[156:159], v[34:37]
	v_mfma_f32_16x16x32_bf16 v[198:201], v[86:89], v[150:153], v[54:57]
	v_mfma_f32_16x16x32_bf16 v[218:221], v[86:89], v[160:163], v[50:53]
	v_mfma_f32_16x16x32_bf16 v[146:149], v[194:197], v[150:153], v[38:41]
	v_mfma_f32_16x16x32_bf16 v[150:153], v[194:197], v[160:163], v[34:37]
	v_mfma_f32_16x16x32_bf16 v[30:33], v[66:69], v[98:101], v[30:33]
	v_mfma_f32_16x16x32_bf16 v[26:29], v[66:69], v[114:117], v[26:29]
	v_mfma_f32_16x16x32_bf16 v[10:13], v[182:185], v[114:117], v[10:13]
	v_mfma_f32_16x16x32_bf16 v[2:5], v[190:193], v[114:117], v[2:5]
	v_mfma_f32_16x16x32_bf16 v[30:33], v[70:73], v[102:105], v[30:33]
	v_mfma_f32_16x16x32_bf16 v[26:29], v[70:73], v[118:121], v[26:29]
	v_mfma_f32_16x16x32_bf16 v[22:25], v[82:85], v[98:101], v[22:25]
	v_mfma_f32_16x16x32_bf16 v[18:21], v[82:85], v[114:117], v[18:21]
	v_mfma_f32_16x16x32_bf16 v[14:17], v[182:185], v[98:101], v[14:17]
	v_mfma_f32_16x16x32_bf16 v[10:13], v[186:189], v[118:121], v[10:13]
	v_mfma_f32_16x16x32_bf16 v[6:9], v[190:193], v[98:101], v[6:9]
	v_mfma_f32_16x16x32_bf16 v[2:5], v[194:197], v[118:121], v[2:5]
	v_mfma_f32_16x16x32_bf16 v[156:159], v[86:89], v[102:105], v[22:25]
	v_mfma_f32_16x16x32_bf16 v[160:163], v[86:89], v[118:121], v[18:21]
	v_mfma_f32_16x16x32_bf16 v[222:225], v[186:189], v[102:105], v[14:17]
	v_mfma_f32_16x16x32_bf16 v[182:185], v[194:197], v[102:105], v[6:9]
	s_barrier
	s_nop 0
	ds_read_b128 v[6:9], v140
	ds_read_b128 v[14:17], v140 offset:1024
	ds_read_b128 v[186:189], v140 offset:2048
	ds_read_b128 v[190:193], v140 offset:3072
	ds_read_b128 v[18:21], v136 offset:32768
	ds_read_b128 v[22:25], v136 offset:33792
	ds_read_b128 v[34:37], v135 offset:32768
	ds_read_b128 v[38:41], v135 offset:33792
	ds_read_b128 v[50:53], v134 offset:32768
	ds_read_b128 v[54:57], v134 offset:33792
	ds_read_b128 v[194:197], v133 offset:32768
	ds_read_b128 v[226:229], v133 offset:33792
	s_waitcnt vmcnt(2)
	s_barrier
; #define WAIT_V(n) asm volatile("s_waitcnt vmcnt(" #n ")" ::: "memory")
; #define WAIT_L(n) asm volatile("s_waitcnt lgkmcnt(" #n ")" ::: "memory")
; #define BAR __builtin_amdgcn_s_barrier()
; #define LDA(dst, b, h) for (int m = 0; m < 4; ++m) for (int k = 0; k < 2; ++k) \
;     dst[m][k] = *reinterpret_cast<const bf16x8*>((char*)SA(b, h) + lds_byte(wr * 64 + m * 16 + fr, k * 32 + fq * 8))
; #define LDB(dst, b, h) for (int n = 0; n < 2; ++n) for (int k = 0; k < 2; ++k) \
;     dst[n][k] = *reinterpret_cast<const bf16x8*>((char*)SB(b, h) + lds_byte(wc * 32 + n * 16 + fr, k * 32 + fq * 8))
; #define MMA(ai, bj, At_, Bt_) do { __builtin_amdgcn_s_setprio(1); \
;     for (int m = 0; m < 4; ++m) for (int n = 0; n < 2; ++n) for (int k = 0; k < 2; ++k) \
;       acc[ai][bj][m][n] = __builtin_amdgcn_mfma_f32_16x16x32_bf16(At_[m][k], Bt_[n][k], acc[ai][bj][m][n], 0, 0, 0); \
;     __builtin_amdgcn_s_setprio(0); } while (0)
; template <int K, int LD = K>
; __device__ __forceinline__ void gemm_main(const GAS bf16* A, const GAS bf16* Bt, int brow, int bcol, f32x4 (&acc)[2][2][4][2]) {
;     ...
;   { LDB(B0, 1, 0); LDA(At, 1, 0); WAIT_V(2); BAR; WAIT_L(0); MMA(0, 0, At, B0); BAR;
;     LDB(B1, 1, 1); WAIT_V(0); BAR; WAIT_L(0); MMA(0, 1, At, B1); BAR;
;     LDA(At, 1, 1); BAR; WAIT_L(0); MMA(1, 0, At, B0); MMA(1, 1, At, B1); BAR; }
;   if (wr == 0) BAR;
	s_waitcnt lgkmcnt(0)
	v_mfma_f32_16x16x32_bf16 v[66:69], v[18:21], v[6:9], v[126:129]
	v_mfma_f32_16x16x32_bf16 v[118:121], v[22:25], v[14:17], v[66:69]
	v_mfma_f32_16x16x32_bf16 v[66:69], v[18:21], v[186:189], v[122:125]
	v_mfma_f32_16x16x32_bf16 v[114:117], v[22:25], v[190:193], v[66:69]
	v_mfma_f32_16x16x32_bf16 v[66:69], v[34:37], v[6:9], v[202:205]
	v_mfma_f32_16x16x32_bf16 v[102:105], v[38:41], v[14:17], v[66:69]
	v_mfma_f32_16x16x32_bf16 v[66:69], v[34:37], v[186:189], v[206:209]
	v_mfma_f32_16x16x32_bf16 v[98:101], v[38:41], v[190:193], v[66:69]
	v_mfma_f32_16x16x32_bf16 v[66:69], v[50:53], v[6:9], v[110:113]
	v_mfma_f32_16x16x32_bf16 v[86:89], v[54:57], v[14:17], v[66:69]
	v_mfma_f32_16x16x32_bf16 v[66:69], v[50:53], v[186:189], v[106:109]
	v_mfma_f32_16x16x32_bf16 v[82:85], v[54:57], v[190:193], v[66:69]
	v_mfma_f32_16x16x32_bf16 v[66:69], v[194:197], v[6:9], v[210:213]
	v_mfma_f32_16x16x32_bf16 v[70:73], v[226:229], v[14:17], v[66:69]
	v_mfma_f32_16x16x32_bf16 v[66:69], v[194:197], v[186:189], v[214:217]
	v_mfma_f32_16x16x32_bf16 v[66:69], v[226:229], v[190:193], v[66:69]
	s_barrier
	ds_read_b128 v[202:205], v137
	ds_read_b128 v[206:209], v137 offset:1024
	ds_read_b128 v[210:213], v137 offset:2048
	ds_read_b128 v[214:217], v137 offset:3072
	s_waitcnt vmcnt(0)
	s_barrier
	s_waitcnt lgkmcnt(0)
	v_mfma_f32_16x16x32_bf16 v[94:97], v[18:21], v[202:205], v[94:97]
	v_mfma_f32_16x16x32_bf16 v[18:21], v[18:21], v[210:213], v[90:93]
	v_mfma_f32_16x16x32_bf16 v[122:125], v[22:25], v[214:217], v[18:21]
	v_mfma_f32_16x16x32_bf16 v[18:21], v[34:37], v[202:205], v[142:145]
	v_mfma_f32_16x16x32_bf16 v[110:113], v[38:41], v[206:209], v[18:21]
	v_mfma_f32_16x16x32_bf16 v[18:21], v[34:37], v[210:213], v[164:167]
	v_mfma_f32_16x16x32_bf16 v[106:109], v[38:41], v[214:217], v[18:21]
	v_mfma_f32_16x16x32_bf16 v[18:21], v[50:53], v[202:205], v[78:81]
	v_mfma_f32_16x16x32_bf16 v[126:129], v[22:25], v[206:209], v[94:97]
	v_mfma_f32_16x16x32_bf16 v[94:97], v[54:57], v[206:209], v[18:21]
	v_mfma_f32_16x16x32_bf16 v[18:21], v[50:53], v[210:213], v[74:77]
	v_mfma_f32_16x16x32_bf16 v[90:93], v[54:57], v[214:217], v[18:21]
	v_mfma_f32_16x16x32_bf16 v[18:21], v[194:197], v[202:205], v[174:177]
	v_mfma_f32_16x16x32_bf16 v[78:81], v[226:229], v[206:209], v[18:21]
	v_mfma_f32_16x16x32_bf16 v[18:21], v[194:197], v[210:213], v[178:181]
	v_mfma_f32_16x16x32_bf16 v[74:77], v[226:229], v[214:217], v[18:21]
	s_barrier
	ds_read_b128 v[140:143], v136 offset:49152
	ds_read_b128 v[164:167], v136 offset:50176
	ds_read_b128 v[174:177], v135 offset:49152
	ds_read_b128 v[178:181], v135 offset:50176
	ds_read_b128 v[194:197], v134 offset:49152
	ds_read_b128 v[134:137], v134 offset:50176
	ds_read_b128 v[226:229], v133 offset:49152
	ds_read_b128 v[230:233], v133 offset:50176
	s_barrier
	s_waitcnt lgkmcnt(0)
	v_mfma_f32_16x16x32_bf16 v[18:21], v[140:143], v[6:9], v[62:65]
	v_mfma_f32_16x16x32_bf16 v[54:57], v[164:167], v[14:17], v[18:21]
	v_mfma_f32_16x16x32_bf16 v[18:21], v[140:143], v[186:189], v[58:61]
	v_mfma_f32_16x16x32_bf16 v[50:53], v[164:167], v[190:193], v[18:21]
	v_mfma_f32_16x16x32_bf16 v[18:21], v[174:177], v[6:9], v[198:201]
	v_mfma_f32_16x16x32_bf16 v[38:41], v[178:181], v[14:17], v[18:21]
	v_mfma_f32_16x16x32_bf16 v[18:21], v[174:177], v[186:189], v[218:221]
	v_mfma_f32_16x16x32_bf16 v[34:37], v[178:181], v[190:193], v[18:21]
	v_mfma_f32_16x16x32_bf16 v[18:21], v[194:197], v[6:9], v[46:49]
	v_mfma_f32_16x16x32_bf16 v[6:9], v[226:229], v[6:9], v[146:149]
	v_mfma_f32_16x16x32_bf16 v[22:25], v[134:137], v[14:17], v[18:21]
	v_mfma_f32_16x16x32_bf16 v[18:21], v[194:197], v[186:189], v[42:45]
	v_mfma_f32_16x16x32_bf16 v[14:17], v[230:233], v[14:17], v[6:9]
	v_mfma_f32_16x16x32_bf16 v[6:9], v[226:229], v[186:189], v[150:153]
	v_mfma_f32_16x16x32_bf16 v[18:21], v[134:137], v[190:193], v[18:21]
	v_mfma_f32_16x16x32_bf16 v[6:9], v[230:233], v[190:193], v[6:9]
	v_mfma_f32_16x16x32_bf16 v[26:29], v[140:143], v[210:213], v[26:29]
	v_mfma_f32_16x16x32_bf16 v[58:61], v[164:167], v[214:217], v[26:29]
	v_mfma_f32_16x16x32_bf16 v[26:29], v[174:177], v[202:205], v[156:159]
	v_mfma_f32_16x16x32_bf16 v[46:49], v[178:181], v[206:209], v[26:29]
	v_mfma_f32_16x16x32_bf16 v[26:29], v[174:177], v[210:213], v[160:163]
	v_mfma_f32_16x16x32_bf16 v[30:33], v[140:143], v[202:205], v[30:33]
	v_mfma_f32_16x16x32_bf16 v[42:45], v[178:181], v[214:217], v[26:29]
	v_mfma_f32_16x16x32_bf16 v[26:29], v[194:197], v[202:205], v[222:225]
	v_mfma_f32_16x16x32_bf16 v[10:13], v[194:197], v[210:213], v[10:13]
	v_mfma_f32_16x16x32_bf16 v[62:65], v[164:167], v[206:209], v[30:33]
	v_mfma_f32_16x16x32_bf16 v[30:33], v[134:137], v[206:209], v[26:29]
	v_mfma_f32_16x16x32_bf16 v[26:29], v[134:137], v[214:217], v[10:13]
	v_mfma_f32_16x16x32_bf16 v[10:13], v[226:229], v[202:205], v[182:185]
	v_mfma_f32_16x16x32_bf16 v[2:5], v[226:229], v[210:213], v[2:5]
	v_mfma_f32_16x16x32_bf16 v[10:13], v[230:233], v[206:209], v[10:13]
	v_mfma_f32_16x16x32_bf16 v[2:5], v[230:233], v[214:217], v[2:5]
	v_cmp_gt_u32_e32 vcc, s42, v132
	s_barrier
	s_and_saveexec_b64 s[18:19], vcc
	s_cbranch_execz .LBB0_1229
	s_barrier
